# load segments reordered: LDS-DMA issues in front of the ds_read burst
# baseline (speedup 1.0000x reference)
.LBB0_74:
	s_ashr_i32 s27, s26, 31
	s_lshl_b64 s[28:29], s[26:27], 19
	s_add_u32 s28, s3, s28
	s_addc_u32 s29, s35, s29
	s_and_b64 s[30:31], s[4:5], exec
	s_cselect_b32 s27, s29, s49
	s_cselect_b32 s68, s28, s48
	s_ashr_i32 s23, s22, 31
	s_lshl_b64 s[30:31], s[22:23], 19
	s_add_u32 s30, s50, s30
	s_addc_u32 s31, s51, s31
	s_and_b64 s[70:71], s[4:5], exec
	s_cselect_b32 s69, s31, s47
	s_cselect_b32 s70, s30, s46
	s_lshl_b32 s23, s44, 8
	v_add_u32_e32 v0, s23, v148
	s_add_u32 s71, s46, 0x100
	v_ashrrev_i32_e32 v1, 31, v0
	s_addc_u32 s74, s47, 0
	v_lshl_add_u64 v[144:145], v[0:1], 4, s[12:13]
	s_add_u32 s44, s48, 0x40080
	s_addc_u32 s45, s49, 0
	s_mov_b32 s75, -2
	s_mov_b64 s[46:47], 0
	s_cmp_eq_u32 s59, 1
	s_cbranch_scc1 .Lfa_0
	s_add_u32 s48, s44, 0xfffc0080
	s_addc_u32 s49, s45, -1
	s_and_b64 s[46:47], s[46:47], exec
	s_cselect_b32 s49, s27, s49
	s_cselect_b32 s48, s68, s48
	s_cselect_b32 s47, s69, s74
	s_cselect_b32 s46, s70, s71
	v_lshl_add_u64 v[154:155], s[44:45], 0, v[138:139]
	s_add_i32 m0, s55, 0xc000
	s_nop 0
	global_load_lds_dwordx4 v[154:155], off
	v_lshl_add_u64 v[154:155], s[44:45], 0, v[136:137]
	s_add_i32 m0, s55, 0xe000
	s_nop 0
	global_load_lds_dwordx4 v[154:155], off
	v_add_u32_e32 v153, s64, v147
	ds_read_b128 v[160:163], v153
	v_xor_b32_e32 v253, 64, v153
	ds_read_b128 v[164:167], v253
	ds_read_b128 v[168:171], v153 offset:2048
	ds_read_b128 v[172:175], v253 offset:2048
	v_add_u32_e32 v153, s65, v147
	ds_read_b128 v[176:179], v153
	v_xor_b32_e32 v253, 64, v153
	ds_read_b128 v[180:183], v253
	ds_read_b128 v[186:189], v153 offset:2048
	ds_read_b128 v[190:193], v253 offset:2048
	ds_read_b128 v[194:197], v150
	v_xor_b32_e32 v253, 64, v150
	ds_read_b128 v[198:201], v253
	ds_read_b128 v[202:205], v150 offset:2048
	ds_read_b128 v[206:209], v253 offset:2048
	ds_read_b128 v[210:213], v150 offset:4096
	ds_read_b128 v[214:217], v253 offset:4096
	ds_read_b128 v[218:221], v150 offset:6144
	ds_read_b128 v[222:225], v253 offset:6144
	s_waitcnt vmcnt(16)
	s_waitcnt lgkmcnt(0)
	s_setprio 1
	s_barrier
	v_mfma_f32_16x16x32_bf16 v[124:127], v[160:163], v[194:197], 0
	v_mfma_f32_16x16x32_bf16 v[116:119], v[168:171], v[194:197], 0
	v_mfma_f32_16x16x32_bf16 v[108:111], v[160:163], v[202:205], 0
	v_mfma_f32_16x16x32_bf16 v[100:103], v[168:171], v[202:205], 0
	v_mfma_f32_16x16x32_bf16 v[92:95], v[160:163], v[210:213], 0
	v_mfma_f32_16x16x32_bf16 v[84:87], v[168:171], v[210:213], 0
	v_mfma_f32_16x16x32_bf16 v[76:79], v[160:163], v[218:221], 0
	v_mfma_f32_16x16x32_bf16 v[68:71], v[168:171], v[218:221], 0
	v_mfma_f32_16x16x32_bf16 v[124:127], v[164:167], v[198:201], v[124:127]
	v_mfma_f32_16x16x32_bf16 v[116:119], v[172:175], v[198:201], v[116:119]
	v_mfma_f32_16x16x32_bf16 v[108:111], v[164:167], v[206:209], v[108:111]
	v_mfma_f32_16x16x32_bf16 v[100:103], v[172:175], v[206:209], v[100:103]
	v_mfma_f32_16x16x32_bf16 v[92:95], v[164:167], v[214:217], v[92:95]
	v_mfma_f32_16x16x32_bf16 v[84:87], v[172:175], v[214:217], v[84:87]
	v_mfma_f32_16x16x32_bf16 v[76:79], v[164:167], v[222:225], v[76:79]
	v_mfma_f32_16x16x32_bf16 v[68:71], v[172:175], v[222:225], v[68:71]
	s_setprio 0
	s_setprio 1
	v_mfma_f32_16x16x32_bf16 v[120:123], v[176:179], v[194:197], 0
	v_mfma_f32_16x16x32_bf16 v[112:115], v[186:189], v[194:197], 0
	v_mfma_f32_16x16x32_bf16 v[104:107], v[176:179], v[202:205], 0
	v_mfma_f32_16x16x32_bf16 v[96:99], v[186:189], v[202:205], 0
	v_mfma_f32_16x16x32_bf16 v[88:91], v[176:179], v[210:213], 0
	v_mfma_f32_16x16x32_bf16 v[80:83], v[186:189], v[210:213], 0
	v_mfma_f32_16x16x32_bf16 v[72:75], v[176:179], v[218:221], 0
	v_mfma_f32_16x16x32_bf16 v[64:67], v[186:189], v[218:221], 0
	v_mfma_f32_16x16x32_bf16 v[120:123], v[180:183], v[198:201], v[120:123]
	v_mfma_f32_16x16x32_bf16 v[112:115], v[190:193], v[198:201], v[112:115]
	v_mfma_f32_16x16x32_bf16 v[104:107], v[180:183], v[206:209], v[104:107]
	v_mfma_f32_16x16x32_bf16 v[96:99], v[190:193], v[206:209], v[96:99]
	v_mfma_f32_16x16x32_bf16 v[88:91], v[180:183], v[214:217], v[88:91]
	v_mfma_f32_16x16x32_bf16 v[80:83], v[190:193], v[214:217], v[80:83]
	v_mfma_f32_16x16x32_bf16 v[72:75], v[180:183], v[222:225], v[72:75]
	v_mfma_f32_16x16x32_bf16 v[64:67], v[190:193], v[222:225], v[64:67]
	s_barrier
	s_setprio 0
	s_add_i32 s76, s64, s52
	v_lshl_add_u64 v[154:155], s[46:47], 0, v[132:133]
	s_mov_b32 m0, s76
	s_nop 0
	global_load_lds_dwordx4 v[154:155], off
	s_add_i32 m0, s76, 0x2000
	s_add_u32 s76, s46, 0x40000
	v_lshl_add_u64 v[226:227], s[46:47], 0, v[128:129]
	s_addc_u32 s77, s47, 0
	s_add_i32 s78, s65, s52
	global_load_lds_dwordx4 v[226:227], off
	v_lshl_add_u64 v[228:229], s[76:77], 0, v[132:133]
	s_mov_b32 m0, s78
	v_lshl_add_u64 v[230:231], s[48:49], 0, v[130:131]
	global_load_lds_dwordx4 v[228:229], off
	v_lshl_add_u64 v[228:229], s[76:77], 0, v[128:129]
	s_add_i32 m0, s78, 0x2000
	s_nop 0
	global_load_lds_dwordx4 v[228:229], off
	v_lshl_add_u64 v[228:229], s[48:49], 0, v[134:135]
	s_mov_b32 m0, s55
	s_nop 0
	global_load_lds_dwordx4 v[228:229], off
	s_mov_b32 m0, s56
	s_nop 0
	global_load_lds_dwordx4 v[230:231], off
	ds_read_b128 v[194:197], v150 offset:16384
	v_xor_b32_e32 v253, 64, v150
	ds_read_b128 v[198:201], v253 offset:16384
	ds_read_b128 v[202:205], v150 offset:18432
	ds_read_b128 v[206:209], v253 offset:18432
	ds_read_b128 v[210:213], v150 offset:20480
	ds_read_b128 v[214:217], v253 offset:20480
	ds_read_b128 v[218:221], v150 offset:22528
	ds_read_b128 v[222:225], v253 offset:22528
	s_waitcnt vmcnt(16)
	s_waitcnt lgkmcnt(0)
	s_setprio 1
	s_barrier
	v_mfma_f32_16x16x32_bf16 v[60:63], v[160:163], v[194:197], 0
	v_mfma_f32_16x16x32_bf16 v[52:55], v[168:171], v[194:197], 0
	v_mfma_f32_16x16x32_bf16 v[44:47], v[160:163], v[202:205], 0
	v_mfma_f32_16x16x32_bf16 v[36:39], v[168:171], v[202:205], 0
	v_mfma_f32_16x16x32_bf16 v[28:31], v[160:163], v[210:213], 0
	v_mfma_f32_16x16x32_bf16 v[20:23], v[168:171], v[210:213], 0
	v_mfma_f32_16x16x32_bf16 v[12:15], v[160:163], v[218:221], 0
	v_mfma_f32_16x16x32_bf16 v[4:7], v[168:171], v[218:221], 0
	v_mfma_f32_16x16x32_bf16 v[60:63], v[164:167], v[198:201], v[60:63]
	v_mfma_f32_16x16x32_bf16 v[52:55], v[172:175], v[198:201], v[52:55]
	v_mfma_f32_16x16x32_bf16 v[44:47], v[164:167], v[206:209], v[44:47]
	v_mfma_f32_16x16x32_bf16 v[36:39], v[172:175], v[206:209], v[36:39]
	v_mfma_f32_16x16x32_bf16 v[28:31], v[164:167], v[214:217], v[28:31]
	v_mfma_f32_16x16x32_bf16 v[20:23], v[172:175], v[214:217], v[20:23]
	v_mfma_f32_16x16x32_bf16 v[12:15], v[164:167], v[222:225], v[12:15]
	v_mfma_f32_16x16x32_bf16 v[4:7], v[172:175], v[222:225], v[4:7]
	s_setprio 0
	s_setprio 1
	v_mfma_f32_16x16x32_bf16 v[56:59], v[176:179], v[194:197], 0
	v_mfma_f32_16x16x32_bf16 v[48:51], v[186:189], v[194:197], 0
	v_mfma_f32_16x16x32_bf16 v[40:43], v[176:179], v[202:205], 0
	v_mfma_f32_16x16x32_bf16 v[32:35], v[186:189], v[202:205], 0
	v_mfma_f32_16x16x32_bf16 v[24:27], v[176:179], v[210:213], 0
	v_mfma_f32_16x16x32_bf16 v[16:19], v[186:189], v[210:213], 0
	v_mfma_f32_16x16x32_bf16 v[8:11], v[176:179], v[218:221], 0
	v_mfma_f32_16x16x32_bf16 v[0:3], v[186:189], v[218:221], 0
	v_mfma_f32_16x16x32_bf16 v[56:59], v[180:183], v[198:201], v[56:59]
	v_mfma_f32_16x16x32_bf16 v[48:51], v[190:193], v[198:201], v[48:51]
	v_mfma_f32_16x16x32_bf16 v[40:43], v[180:183], v[206:209], v[40:43]
	v_mfma_f32_16x16x32_bf16 v[32:35], v[190:193], v[206:209], v[32:35]
	v_mfma_f32_16x16x32_bf16 v[24:27], v[180:183], v[214:217], v[24:27]
	v_mfma_f32_16x16x32_bf16 v[16:19], v[190:193], v[214:217], v[16:19]
	v_mfma_f32_16x16x32_bf16 v[8:11], v[180:183], v[222:225], v[8:11]
	v_mfma_f32_16x16x32_bf16 v[0:3], v[190:193], v[222:225], v[0:3]
	s_barrier
	s_setprio 0
	s_add_i32 s76, 0, 0x18000
	s_add_i32 s77, 0, 0x1c000
	s_add_u32 s48, s48, 0x40000
	s_addc_u32 s49, s49, 0
	s_mov_b32 m0, s57
	v_lshl_add_u64 v[232:233], s[48:49], 0, v[134:135]
	global_load_lds_dwordx4 v[232:233], off
	v_lshl_add_u64 v[232:233], s[48:49], 0, v[130:131]
	s_mov_b32 m0, s58
	s_nop 0
	global_load_lds_dwordx4 v[232:233], off
	v_add_u32_e32 v153, s76, v147
	ds_read_b128 v[160:163], v153
	v_xor_b32_e32 v253, 64, v153
	ds_read_b128 v[164:167], v253
	ds_read_b128 v[168:171], v153 offset:2048
	ds_read_b128 v[172:175], v253 offset:2048
	v_add_u32_e32 v153, s77, v147
	ds_read_b128 v[176:179], v153
	v_xor_b32_e32 v253, 64, v153
	ds_read_b128 v[180:183], v253
	ds_read_b128 v[186:189], v153 offset:2048
	ds_read_b128 v[190:193], v253 offset:2048
	ds_read_b128 v[194:197], v150 offset:32768
	v_xor_b32_e32 v253, 64, v150
	ds_read_b128 v[198:201], v253 offset:32768
	ds_read_b128 v[202:205], v150 offset:34816
	ds_read_b128 v[206:209], v253 offset:34816
	ds_read_b128 v[210:213], v150 offset:36864
	ds_read_b128 v[214:217], v253 offset:36864
	ds_read_b128 v[218:221], v150 offset:38912
	ds_read_b128 v[222:225], v253 offset:38912
	s_waitcnt vmcnt(8)
	s_waitcnt lgkmcnt(0)
	s_setprio 1
	s_barrier
	v_mfma_f32_16x16x32_bf16 v[124:127], v[160:163], v[194:197], v[124:127]
	v_mfma_f32_16x16x32_bf16 v[124:127], v[164:167], v[198:201], v[124:127]
	v_mfma_f32_16x16x32_bf16 v[116:119], v[172:175], v[198:201], v[116:119]
	v_mfma_f32_16x16x32_bf16 v[116:119], v[168:171], v[194:197], v[116:119]
	v_mfma_f32_16x16x32_bf16 v[100:103], v[168:171], v[202:205], v[100:103]
	v_mfma_f32_16x16x32_bf16 v[100:103], v[172:175], v[206:209], v[100:103]
	v_mfma_f32_16x16x32_bf16 v[108:111], v[164:167], v[206:209], v[108:111]
	v_mfma_f32_16x16x32_bf16 v[108:111], v[160:163], v[202:205], v[108:111]
	v_mfma_f32_16x16x32_bf16 v[92:95], v[160:163], v[210:213], v[92:95]
	v_mfma_f32_16x16x32_bf16 v[92:95], v[164:167], v[214:217], v[92:95]
	v_mfma_f32_16x16x32_bf16 v[84:87], v[172:175], v[214:217], v[84:87]
	v_mfma_f32_16x16x32_bf16 v[84:87], v[168:171], v[210:213], v[84:87]
	v_mfma_f32_16x16x32_bf16 v[68:71], v[168:171], v[218:221], v[68:71]
	v_mfma_f32_16x16x32_bf16 v[68:71], v[172:175], v[222:225], v[68:71]
	v_mfma_f32_16x16x32_bf16 v[76:79], v[164:167], v[222:225], v[76:79]
	v_mfma_f32_16x16x32_bf16 v[76:79], v[160:163], v[218:221], v[76:79]
	s_setprio 0
	s_setprio 1
	v_mfma_f32_16x16x32_bf16 v[120:123], v[176:179], v[194:197], v[120:123]
	v_mfma_f32_16x16x32_bf16 v[120:123], v[180:183], v[198:201], v[120:123]
	v_mfma_f32_16x16x32_bf16 v[112:115], v[190:193], v[198:201], v[112:115]
	v_mfma_f32_16x16x32_bf16 v[112:115], v[186:189], v[194:197], v[112:115]
	v_mfma_f32_16x16x32_bf16 v[96:99], v[186:189], v[202:205], v[96:99]
	v_mfma_f32_16x16x32_bf16 v[96:99], v[190:193], v[206:209], v[96:99]
	v_mfma_f32_16x16x32_bf16 v[104:107], v[180:183], v[206:209], v[104:107]
	v_mfma_f32_16x16x32_bf16 v[104:107], v[176:179], v[202:205], v[104:107]
	v_mfma_f32_16x16x32_bf16 v[88:91], v[176:179], v[210:213], v[88:91]
	v_mfma_f32_16x16x32_bf16 v[88:91], v[180:183], v[214:217], v[88:91]
	v_mfma_f32_16x16x32_bf16 v[80:83], v[190:193], v[214:217], v[80:83]
	v_mfma_f32_16x16x32_bf16 v[80:83], v[186:189], v[210:213], v[80:83]
	v_mfma_f32_16x16x32_bf16 v[64:67], v[186:189], v[218:221], v[64:67]
	v_mfma_f32_16x16x32_bf16 v[64:67], v[190:193], v[222:225], v[64:67]
	v_mfma_f32_16x16x32_bf16 v[72:75], v[180:183], v[222:225], v[72:75]
	v_mfma_f32_16x16x32_bf16 v[72:75], v[176:179], v[218:221], v[72:75]
	s_barrier
	s_setprio 0
	s_add_i32 s48, s76, s52
	v_lshl_add_u64 v[154:155], v[154:155], 0, s[14:15]
	s_mov_b32 m0, s48
	s_nop 0
	global_load_lds_dwordx4 v[154:155], off
	s_add_i32 m0, s48, 0x2000
	s_add_u32 s46, s46, 0x40080
	v_lshl_add_u64 v[154:155], v[226:227], 0, s[14:15]
	s_addc_u32 s47, s47, 0
	s_add_i32 s48, s77, s52
	global_load_lds_dwordx4 v[154:155], off
	v_lshl_add_u64 v[154:155], s[46:47], 0, v[132:133]
	s_mov_b32 m0, s48
	s_nop 0
	global_load_lds_dwordx4 v[154:155], off
	v_lshl_add_u64 v[154:155], s[46:47], 0, v[128:129]
	s_add_i32 m0, s48, 0x2000
	s_nop 0
	global_load_lds_dwordx4 v[154:155], off
	v_lshl_add_u64 v[154:155], v[228:229], 0, s[14:15]
	s_mov_b32 m0, s60
	s_nop 0
	global_load_lds_dwordx4 v[154:155], off
	v_lshl_add_u64 v[154:155], v[230:231], 0, s[14:15]
	s_mov_b32 m0, s61
	s_nop 0
	global_load_lds_dwordx4 v[154:155], off
	ds_read_b128 v[194:197], v150 offset:49152
	v_xor_b32_e32 v253, 64, v150
	ds_read_b128 v[198:201], v253 offset:49152
	ds_read_b128 v[202:205], v150 offset:51200
	ds_read_b128 v[206:209], v253 offset:51200
	ds_read_b128 v[210:213], v150 offset:53248
	ds_read_b128 v[214:217], v253 offset:53248
	ds_read_b128 v[218:221], v150 offset:55296
	ds_read_b128 v[222:225], v253 offset:55296
	s_waitcnt vmcnt(8)
	s_waitcnt lgkmcnt(0)
	s_setprio 1
	s_barrier
	v_mfma_f32_16x16x32_bf16 v[60:63], v[160:163], v[194:197], v[60:63]
	v_mfma_f32_16x16x32_bf16 v[60:63], v[164:167], v[198:201], v[60:63]
	v_mfma_f32_16x16x32_bf16 v[52:55], v[172:175], v[198:201], v[52:55]
	v_mfma_f32_16x16x32_bf16 v[52:55], v[168:171], v[194:197], v[52:55]
	v_mfma_f32_16x16x32_bf16 v[36:39], v[168:171], v[202:205], v[36:39]
	v_mfma_f32_16x16x32_bf16 v[36:39], v[172:175], v[206:209], v[36:39]
	v_mfma_f32_16x16x32_bf16 v[44:47], v[164:167], v[206:209], v[44:47]
	v_mfma_f32_16x16x32_bf16 v[44:47], v[160:163], v[202:205], v[44:47]
	v_mfma_f32_16x16x32_bf16 v[28:31], v[160:163], v[210:213], v[28:31]
	v_mfma_f32_16x16x32_bf16 v[28:31], v[164:167], v[214:217], v[28:31]
	v_mfma_f32_16x16x32_bf16 v[20:23], v[172:175], v[214:217], v[20:23]
	v_mfma_f32_16x16x32_bf16 v[20:23], v[168:171], v[210:213], v[20:23]
	v_mfma_f32_16x16x32_bf16 v[4:7], v[168:171], v[218:221], v[4:7]
	v_mfma_f32_16x16x32_bf16 v[4:7], v[172:175], v[222:225], v[4:7]
	v_mfma_f32_16x16x32_bf16 v[12:15], v[164:167], v[222:225], v[12:15]
	v_mfma_f32_16x16x32_bf16 v[12:15], v[160:163], v[218:221], v[12:15]
	s_setprio 0
	s_setprio 1
	v_mfma_f32_16x16x32_bf16 v[56:59], v[176:179], v[194:197], v[56:59]
	v_mfma_f32_16x16x32_bf16 v[56:59], v[180:183], v[198:201], v[56:59]
	v_mfma_f32_16x16x32_bf16 v[48:51], v[190:193], v[198:201], v[48:51]
	v_mfma_f32_16x16x32_bf16 v[48:51], v[186:189], v[194:197], v[48:51]
	v_mfma_f32_16x16x32_bf16 v[32:35], v[186:189], v[202:205], v[32:35]
	v_mfma_f32_16x16x32_bf16 v[32:35], v[190:193], v[206:209], v[32:35]
	v_mfma_f32_16x16x32_bf16 v[40:43], v[180:183], v[206:209], v[40:43]
	v_mfma_f32_16x16x32_bf16 v[40:43], v[176:179], v[202:205], v[40:43]
	v_mfma_f32_16x16x32_bf16 v[24:27], v[176:179], v[210:213], v[24:27]
	v_mfma_f32_16x16x32_bf16 v[24:27], v[180:183], v[214:217], v[24:27]
	v_mfma_f32_16x16x32_bf16 v[16:19], v[190:193], v[214:217], v[16:19]
	v_mfma_f32_16x16x32_bf16 v[16:19], v[186:189], v[210:213], v[16:19]
	v_mfma_f32_16x16x32_bf16 v[0:3], v[186:189], v[218:221], v[0:3]
	v_mfma_f32_16x16x32_bf16 v[0:3], v[190:193], v[222:225], v[0:3]
	v_mfma_f32_16x16x32_bf16 v[8:11], v[180:183], v[222:225], v[8:11]
	v_mfma_f32_16x16x32_bf16 v[8:11], v[176:179], v[218:221], v[8:11]
	s_barrier
	s_setprio 0
	s_add_i32 s75, s75, 2
	s_add_u32 s71, s71, 0x100
	s_addc_u32 s74, s74, 0
	s_add_u32 s44, s44, 0x100
	s_addc_u32 s45, s45, 0
	s_branch .LBB0_76
.Lfa_0:
	s_add_u32 s48, s44, 0xfffc0080
	s_addc_u32 s49, s45, -1
	s_and_b64 s[46:47], s[46:47], exec
	s_cselect_b32 s49, s27, s49
	s_cselect_b32 s48, s68, s48
	s_cselect_b32 s47, s69, s74
	s_cselect_b32 s46, s70, s71
	v_lshl_add_u64 v[154:155], s[44:45], 0, v[138:139]
	s_add_i32 m0, s55, 0xc000
	s_nop 0
	global_load_lds_dwordx4 v[154:155], off
	v_lshl_add_u64 v[154:155], s[44:45], 0, v[136:137]
	s_add_i32 m0, s55, 0xe000
	s_nop 0
	global_load_lds_dwordx4 v[154:155], off
	v_add_u32_e32 v153, s64, v147
	ds_read_b128 v[160:163], v153
	v_xor_b32_e32 v253, 64, v153
	ds_read_b128 v[164:167], v253
	ds_read_b128 v[168:171], v153 offset:2048
	ds_read_b128 v[172:175], v253 offset:2048
	v_add_u32_e32 v153, s65, v147
	ds_read_b128 v[176:179], v153
	v_xor_b32_e32 v253, 64, v153
	ds_read_b128 v[180:183], v253
	ds_read_b128 v[186:189], v153 offset:2048
	ds_read_b128 v[190:193], v253 offset:2048
	ds_read_b128 v[194:197], v150
	v_xor_b32_e32 v253, 64, v150
	ds_read_b128 v[198:201], v253
	ds_read_b128 v[202:205], v150 offset:2048
	ds_read_b128 v[206:209], v253 offset:2048
	ds_read_b128 v[210:213], v150 offset:4096
	ds_read_b128 v[214:217], v253 offset:4096
	ds_read_b128 v[218:221], v150 offset:6144
	ds_read_b128 v[222:225], v253 offset:6144
	s_waitcnt vmcnt(8)
	s_waitcnt lgkmcnt(0)
	s_setprio 1
	s_barrier
	v_mfma_f32_16x16x32_bf16 v[124:127], v[160:163], v[194:197], 0
	v_mfma_f32_16x16x32_bf16 v[116:119], v[168:171], v[194:197], 0
	v_mfma_f32_16x16x32_bf16 v[108:111], v[160:163], v[202:205], 0
	v_mfma_f32_16x16x32_bf16 v[100:103], v[168:171], v[202:205], 0
	v_mfma_f32_16x16x32_bf16 v[92:95], v[160:163], v[210:213], 0
	v_mfma_f32_16x16x32_bf16 v[84:87], v[168:171], v[210:213], 0
	v_mfma_f32_16x16x32_bf16 v[76:79], v[160:163], v[218:221], 0
	v_mfma_f32_16x16x32_bf16 v[68:71], v[168:171], v[218:221], 0
	v_mfma_f32_16x16x32_bf16 v[124:127], v[164:167], v[198:201], v[124:127]
	v_mfma_f32_16x16x32_bf16 v[116:119], v[172:175], v[198:201], v[116:119]
	v_mfma_f32_16x16x32_bf16 v[108:111], v[164:167], v[206:209], v[108:111]
	v_mfma_f32_16x16x32_bf16 v[100:103], v[172:175], v[206:209], v[100:103]
	v_mfma_f32_16x16x32_bf16 v[92:95], v[164:167], v[214:217], v[92:95]
	v_mfma_f32_16x16x32_bf16 v[84:87], v[172:175], v[214:217], v[84:87]
	v_mfma_f32_16x16x32_bf16 v[76:79], v[164:167], v[222:225], v[76:79]
	v_mfma_f32_16x16x32_bf16 v[68:71], v[172:175], v[222:225], v[68:71]
	s_setprio 0
	s_setprio 1
	v_mfma_f32_16x16x32_bf16 v[120:123], v[176:179], v[194:197], 0
	v_mfma_f32_16x16x32_bf16 v[112:115], v[186:189], v[194:197], 0
	v_mfma_f32_16x16x32_bf16 v[104:107], v[176:179], v[202:205], 0
	v_mfma_f32_16x16x32_bf16 v[96:99], v[186:189], v[202:205], 0
	v_mfma_f32_16x16x32_bf16 v[88:91], v[176:179], v[210:213], 0
	v_mfma_f32_16x16x32_bf16 v[80:83], v[186:189], v[210:213], 0
	v_mfma_f32_16x16x32_bf16 v[72:75], v[176:179], v[218:221], 0
	v_mfma_f32_16x16x32_bf16 v[64:67], v[186:189], v[218:221], 0
	v_mfma_f32_16x16x32_bf16 v[120:123], v[180:183], v[198:201], v[120:123]
	v_mfma_f32_16x16x32_bf16 v[112:115], v[190:193], v[198:201], v[112:115]
	v_mfma_f32_16x16x32_bf16 v[104:107], v[180:183], v[206:209], v[104:107]
	v_mfma_f32_16x16x32_bf16 v[96:99], v[190:193], v[206:209], v[96:99]
	v_mfma_f32_16x16x32_bf16 v[88:91], v[180:183], v[214:217], v[88:91]
	v_mfma_f32_16x16x32_bf16 v[80:83], v[190:193], v[214:217], v[80:83]
	v_mfma_f32_16x16x32_bf16 v[72:75], v[180:183], v[222:225], v[72:75]
	v_mfma_f32_16x16x32_bf16 v[64:67], v[190:193], v[222:225], v[64:67]
	s_barrier
	s_setprio 0
	s_add_i32 s76, s64, s52
	v_lshl_add_u64 v[154:155], s[46:47], 0, v[132:133]
	s_mov_b32 m0, s76
	s_nop 0
	global_load_lds_dwordx4 v[154:155], off
	s_add_i32 m0, s76, 0x2000
	s_add_u32 s76, s46, 0x40000
	v_lshl_add_u64 v[226:227], s[46:47], 0, v[128:129]
	s_addc_u32 s77, s47, 0
	s_add_i32 s78, s65, s52
	global_load_lds_dwordx4 v[226:227], off
	v_lshl_add_u64 v[228:229], s[76:77], 0, v[132:133]
	s_mov_b32 m0, s78
	v_lshl_add_u64 v[230:231], s[48:49], 0, v[130:131]
	global_load_lds_dwordx4 v[228:229], off
	v_lshl_add_u64 v[228:229], s[76:77], 0, v[128:129]
	s_add_i32 m0, s78, 0x2000
	s_nop 0
	global_load_lds_dwordx4 v[228:229], off
	v_lshl_add_u64 v[228:229], s[48:49], 0, v[134:135]
	s_mov_b32 m0, s55
	s_nop 0
	global_load_lds_dwordx4 v[228:229], off
	s_mov_b32 m0, s56
	s_nop 0
	global_load_lds_dwordx4 v[230:231], off
	ds_read_b128 v[194:197], v150 offset:16384
	v_xor_b32_e32 v253, 64, v150
	ds_read_b128 v[198:201], v253 offset:16384
	ds_read_b128 v[202:205], v150 offset:18432
	ds_read_b128 v[206:209], v253 offset:18432
	ds_read_b128 v[210:213], v150 offset:20480
	ds_read_b128 v[214:217], v253 offset:20480
	ds_read_b128 v[218:221], v150 offset:22528
	ds_read_b128 v[222:225], v253 offset:22528
	s_waitcnt vmcnt(8)
	s_waitcnt lgkmcnt(0)
	s_setprio 1
	s_barrier
	v_mfma_f32_16x16x32_bf16 v[60:63], v[160:163], v[194:197], 0
	v_mfma_f32_16x16x32_bf16 v[52:55], v[168:171], v[194:197], 0
	v_mfma_f32_16x16x32_bf16 v[44:47], v[160:163], v[202:205], 0
	v_mfma_f32_16x16x32_bf16 v[36:39], v[168:171], v[202:205], 0
	v_mfma_f32_16x16x32_bf16 v[28:31], v[160:163], v[210:213], 0
	v_mfma_f32_16x16x32_bf16 v[20:23], v[168:171], v[210:213], 0
	v_mfma_f32_16x16x32_bf16 v[12:15], v[160:163], v[218:221], 0
	v_mfma_f32_16x16x32_bf16 v[4:7], v[168:171], v[218:221], 0
	v_mfma_f32_16x16x32_bf16 v[60:63], v[164:167], v[198:201], v[60:63]
	v_mfma_f32_16x16x32_bf16 v[52:55], v[172:175], v[198:201], v[52:55]
	v_mfma_f32_16x16x32_bf16 v[44:47], v[164:167], v[206:209], v[44:47]
	v_mfma_f32_16x16x32_bf16 v[36:39], v[172:175], v[206:209], v[36:39]
	v_mfma_f32_16x16x32_bf16 v[28:31], v[164:167], v[214:217], v[28:31]
	v_mfma_f32_16x16x32_bf16 v[20:23], v[172:175], v[214:217], v[20:23]
	v_mfma_f32_16x16x32_bf16 v[12:15], v[164:167], v[222:225], v[12:15]
	v_mfma_f32_16x16x32_bf16 v[4:7], v[172:175], v[222:225], v[4:7]
	s_setprio 0
	s_setprio 1
	v_mfma_f32_16x16x32_bf16 v[56:59], v[176:179], v[194:197], 0
	v_mfma_f32_16x16x32_bf16 v[48:51], v[186:189], v[194:197], 0
	v_mfma_f32_16x16x32_bf16 v[40:43], v[176:179], v[202:205], 0
	v_mfma_f32_16x16x32_bf16 v[32:35], v[186:189], v[202:205], 0
	v_mfma_f32_16x16x32_bf16 v[24:27], v[176:179], v[210:213], 0
	v_mfma_f32_16x16x32_bf16 v[16:19], v[186:189], v[210:213], 0
	v_mfma_f32_16x16x32_bf16 v[8:11], v[176:179], v[218:221], 0
	v_mfma_f32_16x16x32_bf16 v[0:3], v[186:189], v[218:221], 0
	v_mfma_f32_16x16x32_bf16 v[56:59], v[180:183], v[198:201], v[56:59]
	v_mfma_f32_16x16x32_bf16 v[48:51], v[190:193], v[198:201], v[48:51]
	v_mfma_f32_16x16x32_bf16 v[40:43], v[180:183], v[206:209], v[40:43]
	v_mfma_f32_16x16x32_bf16 v[32:35], v[190:193], v[206:209], v[32:35]
	v_mfma_f32_16x16x32_bf16 v[24:27], v[180:183], v[214:217], v[24:27]
	v_mfma_f32_16x16x32_bf16 v[16:19], v[190:193], v[214:217], v[16:19]
	v_mfma_f32_16x16x32_bf16 v[8:11], v[180:183], v[222:225], v[8:11]
	v_mfma_f32_16x16x32_bf16 v[0:3], v[190:193], v[222:225], v[0:3]
	s_barrier
	s_setprio 0
	s_add_i32 s76, 0, 0x18000
	s_add_i32 s77, 0, 0x1c000
	s_add_u32 s48, s48, 0x40000
	s_addc_u32 s49, s49, 0
	s_mov_b32 m0, s57
	v_lshl_add_u64 v[232:233], s[48:49], 0, v[134:135]
	global_load_lds_dwordx4 v[232:233], off
	v_lshl_add_u64 v[232:233], s[48:49], 0, v[130:131]
	s_mov_b32 m0, s58
	s_nop 0
	global_load_lds_dwordx4 v[232:233], off
	v_add_u32_e32 v153, s76, v147
	ds_read_b128 v[160:163], v153
	v_xor_b32_e32 v253, 64, v153
	ds_read_b128 v[164:167], v253
	ds_read_b128 v[168:171], v153 offset:2048
	ds_read_b128 v[172:175], v253 offset:2048
	v_add_u32_e32 v153, s77, v147
	ds_read_b128 v[176:179], v153
	v_xor_b32_e32 v253, 64, v153
	ds_read_b128 v[180:183], v253
	ds_read_b128 v[186:189], v153 offset:2048
	ds_read_b128 v[190:193], v253 offset:2048
	ds_read_b128 v[194:197], v150 offset:32768
	v_xor_b32_e32 v253, 64, v150
	ds_read_b128 v[198:201], v253 offset:32768
	ds_read_b128 v[202:205], v150 offset:34816
	ds_read_b128 v[206:209], v253 offset:34816
	ds_read_b128 v[210:213], v150 offset:36864
	ds_read_b128 v[214:217], v253 offset:36864
	ds_read_b128 v[218:221], v150 offset:38912
	ds_read_b128 v[222:225], v253 offset:38912
	s_waitcnt vmcnt(8)
	s_waitcnt lgkmcnt(0)
	s_setprio 1
	s_barrier
	v_mfma_f32_16x16x32_bf16 v[124:127], v[160:163], v[194:197], v[124:127]
	v_mfma_f32_16x16x32_bf16 v[124:127], v[164:167], v[198:201], v[124:127]
	v_mfma_f32_16x16x32_bf16 v[116:119], v[172:175], v[198:201], v[116:119]
	v_mfma_f32_16x16x32_bf16 v[116:119], v[168:171], v[194:197], v[116:119]
	v_mfma_f32_16x16x32_bf16 v[100:103], v[168:171], v[202:205], v[100:103]
	v_mfma_f32_16x16x32_bf16 v[100:103], v[172:175], v[206:209], v[100:103]
	v_mfma_f32_16x16x32_bf16 v[108:111], v[164:167], v[206:209], v[108:111]
	v_mfma_f32_16x16x32_bf16 v[108:111], v[160:163], v[202:205], v[108:111]
	v_mfma_f32_16x16x32_bf16 v[92:95], v[160:163], v[210:213], v[92:95]
	v_mfma_f32_16x16x32_bf16 v[92:95], v[164:167], v[214:217], v[92:95]
	v_mfma_f32_16x16x32_bf16 v[84:87], v[172:175], v[214:217], v[84:87]
	v_mfma_f32_16x16x32_bf16 v[84:87], v[168:171], v[210:213], v[84:87]
	v_mfma_f32_16x16x32_bf16 v[68:71], v[168:171], v[218:221], v[68:71]
	v_mfma_f32_16x16x32_bf16 v[68:71], v[172:175], v[222:225], v[68:71]
	v_mfma_f32_16x16x32_bf16 v[76:79], v[164:167], v[222:225], v[76:79]
	v_mfma_f32_16x16x32_bf16 v[76:79], v[160:163], v[218:221], v[76:79]
	s_setprio 0
	s_setprio 1
	v_mfma_f32_16x16x32_bf16 v[120:123], v[176:179], v[194:197], v[120:123]
	v_mfma_f32_16x16x32_bf16 v[120:123], v[180:183], v[198:201], v[120:123]
	v_mfma_f32_16x16x32_bf16 v[112:115], v[190:193], v[198:201], v[112:115]
	v_mfma_f32_16x16x32_bf16 v[112:115], v[186:189], v[194:197], v[112:115]
	v_mfma_f32_16x16x32_bf16 v[96:99], v[186:189], v[202:205], v[96:99]
	v_mfma_f32_16x16x32_bf16 v[96:99], v[190:193], v[206:209], v[96:99]
	v_mfma_f32_16x16x32_bf16 v[104:107], v[180:183], v[206:209], v[104:107]
	v_mfma_f32_16x16x32_bf16 v[104:107], v[176:179], v[202:205], v[104:107]
	v_mfma_f32_16x16x32_bf16 v[88:91], v[176:179], v[210:213], v[88:91]
	v_mfma_f32_16x16x32_bf16 v[88:91], v[180:183], v[214:217], v[88:91]
	v_mfma_f32_16x16x32_bf16 v[80:83], v[190:193], v[214:217], v[80:83]
	v_mfma_f32_16x16x32_bf16 v[80:83], v[186:189], v[210:213], v[80:83]
	v_mfma_f32_16x16x32_bf16 v[64:67], v[186:189], v[218:221], v[64:67]
	v_mfma_f32_16x16x32_bf16 v[64:67], v[190:193], v[222:225], v[64:67]
	v_mfma_f32_16x16x32_bf16 v[72:75], v[180:183], v[222:225], v[72:75]
	v_mfma_f32_16x16x32_bf16 v[72:75], v[176:179], v[218:221], v[72:75]
	s_barrier
	s_setprio 0
	s_add_i32 s48, s76, s52
	v_lshl_add_u64 v[154:155], v[154:155], 0, s[14:15]
	s_mov_b32 m0, s48
	s_nop 0
	global_load_lds_dwordx4 v[154:155], off
	s_add_i32 m0, s48, 0x2000
	s_add_u32 s46, s46, 0x40080
	v_lshl_add_u64 v[154:155], v[226:227], 0, s[14:15]
	s_addc_u32 s47, s47, 0
	s_add_i32 s48, s77, s52
	global_load_lds_dwordx4 v[154:155], off
	v_lshl_add_u64 v[154:155], s[46:47], 0, v[132:133]
	s_mov_b32 m0, s48
	s_nop 0
	global_load_lds_dwordx4 v[154:155], off
	v_lshl_add_u64 v[154:155], s[46:47], 0, v[128:129]
	s_add_i32 m0, s48, 0x2000
	s_nop 0
	global_load_lds_dwordx4 v[154:155], off
	v_lshl_add_u64 v[154:155], v[228:229], 0, s[14:15]
	s_mov_b32 m0, s60
	s_nop 0
	global_load_lds_dwordx4 v[154:155], off
	v_lshl_add_u64 v[154:155], v[230:231], 0, s[14:15]
	s_mov_b32 m0, s61
	s_nop 0
	global_load_lds_dwordx4 v[154:155], off
	ds_read_b128 v[194:197], v150 offset:49152
	v_xor_b32_e32 v253, 64, v150
	ds_read_b128 v[198:201], v253 offset:49152
	ds_read_b128 v[202:205], v150 offset:51200
	ds_read_b128 v[206:209], v253 offset:51200
	ds_read_b128 v[210:213], v150 offset:53248
	ds_read_b128 v[214:217], v253 offset:53248
	ds_read_b128 v[218:221], v150 offset:55296
	ds_read_b128 v[222:225], v253 offset:55296
	s_waitcnt vmcnt(8)
	s_waitcnt lgkmcnt(0)
	s_setprio 1
	s_barrier
	v_mfma_f32_16x16x32_bf16 v[60:63], v[160:163], v[194:197], v[60:63]
	v_mfma_f32_16x16x32_bf16 v[60:63], v[164:167], v[198:201], v[60:63]
	v_mfma_f32_16x16x32_bf16 v[52:55], v[172:175], v[198:201], v[52:55]
	v_mfma_f32_16x16x32_bf16 v[52:55], v[168:171], v[194:197], v[52:55]
	v_mfma_f32_16x16x32_bf16 v[36:39], v[168:171], v[202:205], v[36:39]
	v_mfma_f32_16x16x32_bf16 v[36:39], v[172:175], v[206:209], v[36:39]
	v_mfma_f32_16x16x32_bf16 v[44:47], v[164:167], v[206:209], v[44:47]
	v_mfma_f32_16x16x32_bf16 v[44:47], v[160:163], v[202:205], v[44:47]
	v_mfma_f32_16x16x32_bf16 v[28:31], v[160:163], v[210:213], v[28:31]
	v_mfma_f32_16x16x32_bf16 v[28:31], v[164:167], v[214:217], v[28:31]
	v_mfma_f32_16x16x32_bf16 v[20:23], v[172:175], v[214:217], v[20:23]
	v_mfma_f32_16x16x32_bf16 v[20:23], v[168:171], v[210:213], v[20:23]
	v_mfma_f32_16x16x32_bf16 v[4:7], v[168:171], v[218:221], v[4:7]
	v_mfma_f32_16x16x32_bf16 v[4:7], v[172:175], v[222:225], v[4:7]
	v_mfma_f32_16x16x32_bf16 v[12:15], v[164:167], v[222:225], v[12:15]
	v_mfma_f32_16x16x32_bf16 v[12:15], v[160:163], v[218:221], v[12:15]
	s_setprio 0
	s_setprio 1
	v_mfma_f32_16x16x32_bf16 v[56:59], v[176:179], v[194:197], v[56:59]
	v_mfma_f32_16x16x32_bf16 v[56:59], v[180:183], v[198:201], v[56:59]
	v_mfma_f32_16x16x32_bf16 v[48:51], v[190:193], v[198:201], v[48:51]
	v_mfma_f32_16x16x32_bf16 v[48:51], v[186:189], v[194:197], v[48:51]
	v_mfma_f32_16x16x32_bf16 v[32:35], v[186:189], v[202:205], v[32:35]
	v_mfma_f32_16x16x32_bf16 v[32:35], v[190:193], v[206:209], v[32:35]
	v_mfma_f32_16x16x32_bf16 v[40:43], v[180:183], v[206:209], v[40:43]
	v_mfma_f32_16x16x32_bf16 v[40:43], v[176:179], v[202:205], v[40:43]
	v_mfma_f32_16x16x32_bf16 v[24:27], v[176:179], v[210:213], v[24:27]
	v_mfma_f32_16x16x32_bf16 v[24:27], v[180:183], v[214:217], v[24:27]
	v_mfma_f32_16x16x32_bf16 v[16:19], v[190:193], v[214:217], v[16:19]
	v_mfma_f32_16x16x32_bf16 v[16:19], v[186:189], v[210:213], v[16:19]
	v_mfma_f32_16x16x32_bf16 v[0:3], v[186:189], v[218:221], v[0:3]
	v_mfma_f32_16x16x32_bf16 v[0:3], v[190:193], v[222:225], v[0:3]
	v_mfma_f32_16x16x32_bf16 v[8:11], v[180:183], v[222:225], v[8:11]
	v_mfma_f32_16x16x32_bf16 v[8:11], v[176:179], v[218:221], v[8:11]
	s_barrier
	s_setprio 0
	s_add_i32 s75, s75, 2
	s_add_u32 s71, s71, 0x100
	s_addc_u32 s74, s74, 0
	s_add_u32 s44, s44, 0x100
	s_addc_u32 s45, s45, 0
	s_branch .LBB0_76
.LBB0_75:
	s_add_u32 s48, s44, 0xfffc0080
	s_addc_u32 s49, s45, -1
	s_and_b64 s[46:47], s[46:47], exec
	s_cselect_b32 s49, s27, s49
	s_cselect_b32 s48, s68, s48
	s_cselect_b32 s47, s69, s74
	s_cselect_b32 s46, s70, s71
	v_lshl_add_u64 v[154:155], s[44:45], 0, v[138:139]
	s_add_i32 m0, s55, 0xc000
	s_nop 0
	global_load_lds_dwordx4 v[154:155], off
	v_lshl_add_u64 v[154:155], s[44:45], 0, v[136:137]
	s_add_i32 m0, s55, 0xe000
	s_nop 0
	global_load_lds_dwordx4 v[154:155], off
	v_add_u32_e32 v153, s64, v147
	ds_read_b128 v[160:163], v153
	v_xor_b32_e32 v253, 64, v153
	ds_read_b128 v[164:167], v253
	ds_read_b128 v[168:171], v153 offset:2048
	ds_read_b128 v[172:175], v253 offset:2048
	v_add_u32_e32 v153, s65, v147
	ds_read_b128 v[176:179], v153
	v_xor_b32_e32 v253, 64, v153
	ds_read_b128 v[180:183], v253
	ds_read_b128 v[186:189], v153 offset:2048
	ds_read_b128 v[190:193], v253 offset:2048
	ds_read_b128 v[194:197], v150
	v_xor_b32_e32 v253, 64, v150
	ds_read_b128 v[198:201], v253
	ds_read_b128 v[202:205], v150 offset:2048
	ds_read_b128 v[206:209], v253 offset:2048
	ds_read_b128 v[210:213], v150 offset:4096
	ds_read_b128 v[214:217], v253 offset:4096
	ds_read_b128 v[218:221], v150 offset:6144
	ds_read_b128 v[222:225], v253 offset:6144
	s_waitcnt vmcnt(8)
	s_waitcnt lgkmcnt(0)
	s_setprio 1
	s_barrier
	v_mfma_f32_16x16x32_bf16 v[124:127], v[160:163], v[194:197], v[124:127]
	v_mfma_f32_16x16x32_bf16 v[124:127], v[164:167], v[198:201], v[124:127]
	v_mfma_f32_16x16x32_bf16 v[116:119], v[172:175], v[198:201], v[116:119]
	v_mfma_f32_16x16x32_bf16 v[116:119], v[168:171], v[194:197], v[116:119]
	v_mfma_f32_16x16x32_bf16 v[100:103], v[168:171], v[202:205], v[100:103]
	v_mfma_f32_16x16x32_bf16 v[100:103], v[172:175], v[206:209], v[100:103]
	v_mfma_f32_16x16x32_bf16 v[108:111], v[164:167], v[206:209], v[108:111]
	v_mfma_f32_16x16x32_bf16 v[108:111], v[160:163], v[202:205], v[108:111]
	v_mfma_f32_16x16x32_bf16 v[92:95], v[160:163], v[210:213], v[92:95]
	v_mfma_f32_16x16x32_bf16 v[92:95], v[164:167], v[214:217], v[92:95]
	v_mfma_f32_16x16x32_bf16 v[84:87], v[172:175], v[214:217], v[84:87]
	v_mfma_f32_16x16x32_bf16 v[84:87], v[168:171], v[210:213], v[84:87]
	v_mfma_f32_16x16x32_bf16 v[68:71], v[168:171], v[218:221], v[68:71]
	v_mfma_f32_16x16x32_bf16 v[68:71], v[172:175], v[222:225], v[68:71]
	v_mfma_f32_16x16x32_bf16 v[76:79], v[164:167], v[222:225], v[76:79]
	v_mfma_f32_16x16x32_bf16 v[76:79], v[160:163], v[218:221], v[76:79]
	s_setprio 0
	s_setprio 1
	v_mfma_f32_16x16x32_bf16 v[120:123], v[176:179], v[194:197], v[120:123]
	v_mfma_f32_16x16x32_bf16 v[120:123], v[180:183], v[198:201], v[120:123]
	v_mfma_f32_16x16x32_bf16 v[112:115], v[190:193], v[198:201], v[112:115]
	v_mfma_f32_16x16x32_bf16 v[112:115], v[186:189], v[194:197], v[112:115]
	v_mfma_f32_16x16x32_bf16 v[96:99], v[186:189], v[202:205], v[96:99]
	v_mfma_f32_16x16x32_bf16 v[96:99], v[190:193], v[206:209], v[96:99]
	v_mfma_f32_16x16x32_bf16 v[104:107], v[180:183], v[206:209], v[104:107]
	v_mfma_f32_16x16x32_bf16 v[104:107], v[176:179], v[202:205], v[104:107]
	v_mfma_f32_16x16x32_bf16 v[88:91], v[176:179], v[210:213], v[88:91]
	v_mfma_f32_16x16x32_bf16 v[88:91], v[180:183], v[214:217], v[88:91]
	v_mfma_f32_16x16x32_bf16 v[80:83], v[190:193], v[214:217], v[80:83]
	v_mfma_f32_16x16x32_bf16 v[80:83], v[186:189], v[210:213], v[80:83]
	v_mfma_f32_16x16x32_bf16 v[64:67], v[186:189], v[218:221], v[64:67]
	v_mfma_f32_16x16x32_bf16 v[64:67], v[190:193], v[222:225], v[64:67]
	v_mfma_f32_16x16x32_bf16 v[72:75], v[180:183], v[222:225], v[72:75]
	v_mfma_f32_16x16x32_bf16 v[72:75], v[176:179], v[218:221], v[72:75]
	s_barrier
	s_setprio 0
	s_add_i32 s76, s64, s52
	v_lshl_add_u64 v[154:155], s[46:47], 0, v[132:133]
	s_mov_b32 m0, s76
	s_nop 0
	global_load_lds_dwordx4 v[154:155], off
	s_add_i32 m0, s76, 0x2000
	s_add_u32 s76, s46, 0x40000
	v_lshl_add_u64 v[226:227], s[46:47], 0, v[128:129]
	s_addc_u32 s77, s47, 0
	s_add_i32 s78, s65, s52
	global_load_lds_dwordx4 v[226:227], off
	v_lshl_add_u64 v[228:229], s[76:77], 0, v[132:133]
	s_mov_b32 m0, s78
	v_lshl_add_u64 v[230:231], s[48:49], 0, v[130:131]
	global_load_lds_dwordx4 v[228:229], off
	v_lshl_add_u64 v[228:229], s[76:77], 0, v[128:129]
	s_add_i32 m0, s78, 0x2000
	s_nop 0
	global_load_lds_dwordx4 v[228:229], off
	v_lshl_add_u64 v[228:229], s[48:49], 0, v[134:135]
	s_mov_b32 m0, s55
	s_nop 0
	global_load_lds_dwordx4 v[228:229], off
	s_mov_b32 m0, s56
	s_nop 0
	global_load_lds_dwordx4 v[230:231], off
	ds_read_b128 v[194:197], v150 offset:16384
	v_xor_b32_e32 v253, 64, v150
	ds_read_b128 v[198:201], v253 offset:16384
	ds_read_b128 v[202:205], v150 offset:18432
	ds_read_b128 v[206:209], v253 offset:18432
	ds_read_b128 v[210:213], v150 offset:20480
	ds_read_b128 v[214:217], v253 offset:20480
	ds_read_b128 v[218:221], v150 offset:22528
	ds_read_b128 v[222:225], v253 offset:22528
	s_waitcnt vmcnt(8)
	s_waitcnt lgkmcnt(0)
	s_setprio 1
	s_barrier
	v_mfma_f32_16x16x32_bf16 v[60:63], v[160:163], v[194:197], v[60:63]
	v_mfma_f32_16x16x32_bf16 v[60:63], v[164:167], v[198:201], v[60:63]
	v_mfma_f32_16x16x32_bf16 v[52:55], v[172:175], v[198:201], v[52:55]
	v_mfma_f32_16x16x32_bf16 v[52:55], v[168:171], v[194:197], v[52:55]
	v_mfma_f32_16x16x32_bf16 v[36:39], v[168:171], v[202:205], v[36:39]
	v_mfma_f32_16x16x32_bf16 v[36:39], v[172:175], v[206:209], v[36:39]
	v_mfma_f32_16x16x32_bf16 v[44:47], v[164:167], v[206:209], v[44:47]
	v_mfma_f32_16x16x32_bf16 v[44:47], v[160:163], v[202:205], v[44:47]
	v_mfma_f32_16x16x32_bf16 v[28:31], v[160:163], v[210:213], v[28:31]
	v_mfma_f32_16x16x32_bf16 v[28:31], v[164:167], v[214:217], v[28:31]
	v_mfma_f32_16x16x32_bf16 v[20:23], v[172:175], v[214:217], v[20:23]
	v_mfma_f32_16x16x32_bf16 v[20:23], v[168:171], v[210:213], v[20:23]
	v_mfma_f32_16x16x32_bf16 v[4:7], v[168:171], v[218:221], v[4:7]
	v_mfma_f32_16x16x32_bf16 v[4:7], v[172:175], v[222:225], v[4:7]
	v_mfma_f32_16x16x32_bf16 v[12:15], v[164:167], v[222:225], v[12:15]
	v_mfma_f32_16x16x32_bf16 v[12:15], v[160:163], v[218:221], v[12:15]
	s_setprio 0
	s_setprio 1
	v_mfma_f32_16x16x32_bf16 v[56:59], v[176:179], v[194:197], v[56:59]
	v_mfma_f32_16x16x32_bf16 v[56:59], v[180:183], v[198:201], v[56:59]
	v_mfma_f32_16x16x32_bf16 v[48:51], v[190:193], v[198:201], v[48:51]
	v_mfma_f32_16x16x32_bf16 v[48:51], v[186:189], v[194:197], v[48:51]
	v_mfma_f32_16x16x32_bf16 v[32:35], v[186:189], v[202:205], v[32:35]
	v_mfma_f32_16x16x32_bf16 v[32:35], v[190:193], v[206:209], v[32:35]
	v_mfma_f32_16x16x32_bf16 v[40:43], v[180:183], v[206:209], v[40:43]
	v_mfma_f32_16x16x32_bf16 v[40:43], v[176:179], v[202:205], v[40:43]
	v_mfma_f32_16x16x32_bf16 v[24:27], v[176:179], v[210:213], v[24:27]
	v_mfma_f32_16x16x32_bf16 v[24:27], v[180:183], v[214:217], v[24:27]
	v_mfma_f32_16x16x32_bf16 v[16:19], v[190:193], v[214:217], v[16:19]
	v_mfma_f32_16x16x32_bf16 v[16:19], v[186:189], v[210:213], v[16:19]
	v_mfma_f32_16x16x32_bf16 v[0:3], v[186:189], v[218:221], v[0:3]
	v_mfma_f32_16x16x32_bf16 v[0:3], v[190:193], v[222:225], v[0:3]
	v_mfma_f32_16x16x32_bf16 v[8:11], v[180:183], v[222:225], v[8:11]
	v_mfma_f32_16x16x32_bf16 v[8:11], v[176:179], v[218:221], v[8:11]
	s_barrier
	s_setprio 0
	s_add_i32 s76, 0, 0x18000
	s_add_i32 s77, 0, 0x1c000
	s_add_u32 s48, s48, 0x40000
	s_addc_u32 s49, s49, 0
	s_mov_b32 m0, s57
	v_lshl_add_u64 v[232:233], s[48:49], 0, v[134:135]
	global_load_lds_dwordx4 v[232:233], off
	v_lshl_add_u64 v[232:233], s[48:49], 0, v[130:131]
	s_mov_b32 m0, s58
	s_nop 0
	global_load_lds_dwordx4 v[232:233], off
	v_add_u32_e32 v153, s76, v147
	ds_read_b128 v[160:163], v153
	v_xor_b32_e32 v253, 64, v153
	ds_read_b128 v[164:167], v253
	ds_read_b128 v[168:171], v153 offset:2048
	ds_read_b128 v[172:175], v253 offset:2048
	v_add_u32_e32 v153, s77, v147
	ds_read_b128 v[176:179], v153
	v_xor_b32_e32 v253, 64, v153
	ds_read_b128 v[180:183], v253
	ds_read_b128 v[186:189], v153 offset:2048
	ds_read_b128 v[190:193], v253 offset:2048
	ds_read_b128 v[194:197], v150 offset:32768
	v_xor_b32_e32 v253, 64, v150
	ds_read_b128 v[198:201], v253 offset:32768
	ds_read_b128 v[202:205], v150 offset:34816
	ds_read_b128 v[206:209], v253 offset:34816
	ds_read_b128 v[210:213], v150 offset:36864
	ds_read_b128 v[214:217], v253 offset:36864
	ds_read_b128 v[218:221], v150 offset:38912
	ds_read_b128 v[222:225], v253 offset:38912
	s_waitcnt vmcnt(8)
	s_waitcnt lgkmcnt(0)
	s_setprio 1
	s_barrier
	v_mfma_f32_16x16x32_bf16 v[124:127], v[160:163], v[194:197], v[124:127]
	v_mfma_f32_16x16x32_bf16 v[124:127], v[164:167], v[198:201], v[124:127]
	v_mfma_f32_16x16x32_bf16 v[116:119], v[172:175], v[198:201], v[116:119]
	v_mfma_f32_16x16x32_bf16 v[116:119], v[168:171], v[194:197], v[116:119]
	v_mfma_f32_16x16x32_bf16 v[100:103], v[168:171], v[202:205], v[100:103]
	v_mfma_f32_16x16x32_bf16 v[100:103], v[172:175], v[206:209], v[100:103]
	v_mfma_f32_16x16x32_bf16 v[108:111], v[164:167], v[206:209], v[108:111]
	v_mfma_f32_16x16x32_bf16 v[108:111], v[160:163], v[202:205], v[108:111]
	v_mfma_f32_16x16x32_bf16 v[92:95], v[160:163], v[210:213], v[92:95]
	v_mfma_f32_16x16x32_bf16 v[92:95], v[164:167], v[214:217], v[92:95]
	v_mfma_f32_16x16x32_bf16 v[84:87], v[172:175], v[214:217], v[84:87]
	v_mfma_f32_16x16x32_bf16 v[84:87], v[168:171], v[210:213], v[84:87]
	v_mfma_f32_16x16x32_bf16 v[68:71], v[168:171], v[218:221], v[68:71]
	v_mfma_f32_16x16x32_bf16 v[68:71], v[172:175], v[222:225], v[68:71]
	v_mfma_f32_16x16x32_bf16 v[76:79], v[164:167], v[222:225], v[76:79]
	v_mfma_f32_16x16x32_bf16 v[76:79], v[160:163], v[218:221], v[76:79]
	s_setprio 0
	s_setprio 1
	v_mfma_f32_16x16x32_bf16 v[120:123], v[176:179], v[194:197], v[120:123]
	v_mfma_f32_16x16x32_bf16 v[120:123], v[180:183], v[198:201], v[120:123]
	v_mfma_f32_16x16x32_bf16 v[112:115], v[190:193], v[198:201], v[112:115]
	v_mfma_f32_16x16x32_bf16 v[112:115], v[186:189], v[194:197], v[112:115]
	v_mfma_f32_16x16x32_bf16 v[96:99], v[186:189], v[202:205], v[96:99]
	v_mfma_f32_16x16x32_bf16 v[96:99], v[190:193], v[206:209], v[96:99]
	v_mfma_f32_16x16x32_bf16 v[104:107], v[180:183], v[206:209], v[104:107]
	v_mfma_f32_16x16x32_bf16 v[104:107], v[176:179], v[202:205], v[104:107]
	v_mfma_f32_16x16x32_bf16 v[88:91], v[176:179], v[210:213], v[88:91]
	v_mfma_f32_16x16x32_bf16 v[88:91], v[180:183], v[214:217], v[88:91]
	v_mfma_f32_16x16x32_bf16 v[80:83], v[190:193], v[214:217], v[80:83]
	v_mfma_f32_16x16x32_bf16 v[80:83], v[186:189], v[210:213], v[80:83]
	v_mfma_f32_16x16x32_bf16 v[64:67], v[186:189], v[218:221], v[64:67]
	v_mfma_f32_16x16x32_bf16 v[64:67], v[190:193], v[222:225], v[64:67]
	v_mfma_f32_16x16x32_bf16 v[72:75], v[180:183], v[222:225], v[72:75]
	v_mfma_f32_16x16x32_bf16 v[72:75], v[176:179], v[218:221], v[72:75]
	s_barrier
	s_setprio 0
	s_add_i32 s48, s76, s52
	v_lshl_add_u64 v[154:155], v[154:155], 0, s[14:15]
	s_mov_b32 m0, s48
	s_nop 0
	global_load_lds_dwordx4 v[154:155], off
	s_add_i32 m0, s48, 0x2000
	s_add_u32 s46, s46, 0x40080
	v_lshl_add_u64 v[154:155], v[226:227], 0, s[14:15]
	s_addc_u32 s47, s47, 0
	s_add_i32 s48, s77, s52
	global_load_lds_dwordx4 v[154:155], off
	v_lshl_add_u64 v[154:155], s[46:47], 0, v[132:133]
	s_mov_b32 m0, s48
	s_nop 0
	global_load_lds_dwordx4 v[154:155], off
	v_lshl_add_u64 v[154:155], s[46:47], 0, v[128:129]
	s_add_i32 m0, s48, 0x2000
	s_nop 0
	global_load_lds_dwordx4 v[154:155], off
	v_lshl_add_u64 v[154:155], v[228:229], 0, s[14:15]
	s_mov_b32 m0, s60
	s_nop 0
	global_load_lds_dwordx4 v[154:155], off
	v_lshl_add_u64 v[154:155], v[230:231], 0, s[14:15]
	s_mov_b32 m0, s61
	s_nop 0
	global_load_lds_dwordx4 v[154:155], off
	ds_read_b128 v[194:197], v150 offset:49152
	v_xor_b32_e32 v253, 64, v150
	ds_read_b128 v[198:201], v253 offset:49152
	ds_read_b128 v[202:205], v150 offset:51200
	ds_read_b128 v[206:209], v253 offset:51200
	ds_read_b128 v[210:213], v150 offset:53248
	ds_read_b128 v[214:217], v253 offset:53248
	ds_read_b128 v[218:221], v150 offset:55296
	ds_read_b128 v[222:225], v253 offset:55296
	s_waitcnt vmcnt(8)
	s_waitcnt lgkmcnt(0)
	s_setprio 1
	s_barrier
	v_mfma_f32_16x16x32_bf16 v[60:63], v[160:163], v[194:197], v[60:63]
	v_mfma_f32_16x16x32_bf16 v[60:63], v[164:167], v[198:201], v[60:63]
	v_mfma_f32_16x16x32_bf16 v[52:55], v[172:175], v[198:201], v[52:55]
	v_mfma_f32_16x16x32_bf16 v[52:55], v[168:171], v[194:197], v[52:55]
	v_mfma_f32_16x16x32_bf16 v[36:39], v[168:171], v[202:205], v[36:39]
	v_mfma_f32_16x16x32_bf16 v[36:39], v[172:175], v[206:209], v[36:39]
	v_mfma_f32_16x16x32_bf16 v[44:47], v[164:167], v[206:209], v[44:47]
	v_mfma_f32_16x16x32_bf16 v[44:47], v[160:163], v[202:205], v[44:47]
	v_mfma_f32_16x16x32_bf16 v[28:31], v[160:163], v[210:213], v[28:31]
	v_mfma_f32_16x16x32_bf16 v[28:31], v[164:167], v[214:217], v[28:31]
	v_mfma_f32_16x16x32_bf16 v[20:23], v[172:175], v[214:217], v[20:23]
	v_mfma_f32_16x16x32_bf16 v[20:23], v[168:171], v[210:213], v[20:23]
	v_mfma_f32_16x16x32_bf16 v[4:7], v[168:171], v[218:221], v[4:7]
	v_mfma_f32_16x16x32_bf16 v[4:7], v[172:175], v[222:225], v[4:7]
	v_mfma_f32_16x16x32_bf16 v[12:15], v[164:167], v[222:225], v[12:15]
	v_mfma_f32_16x16x32_bf16 v[12:15], v[160:163], v[218:221], v[12:15]
	s_setprio 0
	s_setprio 1
	v_mfma_f32_16x16x32_bf16 v[56:59], v[176:179], v[194:197], v[56:59]
	v_mfma_f32_16x16x32_bf16 v[56:59], v[180:183], v[198:201], v[56:59]
	v_mfma_f32_16x16x32_bf16 v[48:51], v[190:193], v[198:201], v[48:51]
	v_mfma_f32_16x16x32_bf16 v[48:51], v[186:189], v[194:197], v[48:51]
	v_mfma_f32_16x16x32_bf16 v[32:35], v[186:189], v[202:205], v[32:35]
	v_mfma_f32_16x16x32_bf16 v[32:35], v[190:193], v[206:209], v[32:35]
	v_mfma_f32_16x16x32_bf16 v[40:43], v[180:183], v[206:209], v[40:43]
	v_mfma_f32_16x16x32_bf16 v[40:43], v[176:179], v[202:205], v[40:43]
	v_mfma_f32_16x16x32_bf16 v[24:27], v[176:179], v[210:213], v[24:27]
	v_mfma_f32_16x16x32_bf16 v[24:27], v[180:183], v[214:217], v[24:27]
	v_mfma_f32_16x16x32_bf16 v[16:19], v[190:193], v[214:217], v[16:19]
	v_mfma_f32_16x16x32_bf16 v[16:19], v[186:189], v[210:213], v[16:19]
	v_mfma_f32_16x16x32_bf16 v[0:3], v[186:189], v[218:221], v[0:3]
	v_mfma_f32_16x16x32_bf16 v[0:3], v[190:193], v[222:225], v[0:3]
	v_mfma_f32_16x16x32_bf16 v[8:11], v[180:183], v[222:225], v[8:11]
	v_mfma_f32_16x16x32_bf16 v[8:11], v[176:179], v[218:221], v[8:11]
	s_barrier
	s_setprio 0
	s_add_i32 s75, s75, 2
	s_add_u32 s71, s71, 0x100
	s_addc_u32 s74, s74, 0
	s_add_u32 s44, s44, 0x100
	s_addc_u32 s45, s45, 0
	s_cmp_gt_u32 s75, 13
	s_cbranch_scc1 .LBB0_78

.Llast_0:
	s_add_u32 s48, s44, 0xfffc0080
	s_addc_u32 s49, s45, -1
	s_and_b64 s[46:47], s[46:47], exec
	s_cselect_b32 s49, s27, s49
	s_cselect_b32 s48, s68, s48
	s_cselect_b32 s47, s69, s74
	s_cselect_b32 s46, s70, s71
	v_lshl_add_u64 v[154:155], s[44:45], 0, v[138:139]
	s_add_i32 m0, s55, 0xc000
	s_nop 0
	global_load_lds_dwordx4 v[154:155], off
	v_lshl_add_u64 v[154:155], s[44:45], 0, v[136:137]
	s_add_i32 m0, s55, 0xe000
	s_nop 0
	global_load_lds_dwordx4 v[154:155], off
	v_add_u32_e32 v153, s64, v147
	ds_read_b128 v[160:163], v153
	v_xor_b32_e32 v253, 64, v153
	ds_read_b128 v[164:167], v253
	ds_read_b128 v[168:171], v153 offset:2048
	ds_read_b128 v[172:175], v253 offset:2048
	v_add_u32_e32 v153, s65, v147
	ds_read_b128 v[176:179], v153
	v_xor_b32_e32 v253, 64, v153
	ds_read_b128 v[180:183], v253
	ds_read_b128 v[186:189], v153 offset:2048
	ds_read_b128 v[190:193], v253 offset:2048
	ds_read_b128 v[194:197], v150
	v_xor_b32_e32 v253, 64, v150
	ds_read_b128 v[198:201], v253
	ds_read_b128 v[202:205], v150 offset:2048
	ds_read_b128 v[206:209], v253 offset:2048
	ds_read_b128 v[210:213], v150 offset:4096
	ds_read_b128 v[214:217], v253 offset:4096
	ds_read_b128 v[218:221], v150 offset:6144
	ds_read_b128 v[222:225], v253 offset:6144
	s_waitcnt vmcnt(8)
	s_waitcnt lgkmcnt(0)
	s_setprio 1
	s_barrier
	v_mfma_f32_16x16x32_bf16 v[124:127], v[160:163], v[194:197], v[124:127]
	v_mfma_f32_16x16x32_bf16 v[124:127], v[164:167], v[198:201], v[124:127]
	v_mfma_f32_16x16x32_bf16 v[116:119], v[172:175], v[198:201], v[116:119]
	v_mfma_f32_16x16x32_bf16 v[116:119], v[168:171], v[194:197], v[116:119]
	v_mfma_f32_16x16x32_bf16 v[100:103], v[168:171], v[202:205], v[100:103]
	v_mfma_f32_16x16x32_bf16 v[100:103], v[172:175], v[206:209], v[100:103]
	v_mfma_f32_16x16x32_bf16 v[108:111], v[164:167], v[206:209], v[108:111]
	v_mfma_f32_16x16x32_bf16 v[108:111], v[160:163], v[202:205], v[108:111]
	v_mfma_f32_16x16x32_bf16 v[92:95], v[160:163], v[210:213], v[92:95]
	v_mfma_f32_16x16x32_bf16 v[92:95], v[164:167], v[214:217], v[92:95]
	v_mfma_f32_16x16x32_bf16 v[84:87], v[172:175], v[214:217], v[84:87]
	v_mfma_f32_16x16x32_bf16 v[84:87], v[168:171], v[210:213], v[84:87]
	v_mfma_f32_16x16x32_bf16 v[68:71], v[168:171], v[218:221], v[68:71]
	v_mfma_f32_16x16x32_bf16 v[68:71], v[172:175], v[222:225], v[68:71]
	v_mfma_f32_16x16x32_bf16 v[76:79], v[164:167], v[222:225], v[76:79]
	v_mfma_f32_16x16x32_bf16 v[76:79], v[160:163], v[218:221], v[76:79]
	s_setprio 0
	s_setprio 1
	v_mfma_f32_16x16x32_bf16 v[120:123], v[176:179], v[194:197], v[120:123]
	v_mfma_f32_16x16x32_bf16 v[120:123], v[180:183], v[198:201], v[120:123]
	v_mfma_f32_16x16x32_bf16 v[112:115], v[190:193], v[198:201], v[112:115]
	v_mfma_f32_16x16x32_bf16 v[112:115], v[186:189], v[194:197], v[112:115]
	v_mfma_f32_16x16x32_bf16 v[96:99], v[186:189], v[202:205], v[96:99]
	v_mfma_f32_16x16x32_bf16 v[96:99], v[190:193], v[206:209], v[96:99]
	v_mfma_f32_16x16x32_bf16 v[104:107], v[180:183], v[206:209], v[104:107]
	v_mfma_f32_16x16x32_bf16 v[104:107], v[176:179], v[202:205], v[104:107]
	v_mfma_f32_16x16x32_bf16 v[88:91], v[176:179], v[210:213], v[88:91]
	v_mfma_f32_16x16x32_bf16 v[88:91], v[180:183], v[214:217], v[88:91]
	v_mfma_f32_16x16x32_bf16 v[80:83], v[190:193], v[214:217], v[80:83]
	v_mfma_f32_16x16x32_bf16 v[80:83], v[186:189], v[210:213], v[80:83]
	v_mfma_f32_16x16x32_bf16 v[64:67], v[186:189], v[218:221], v[64:67]
	v_mfma_f32_16x16x32_bf16 v[64:67], v[190:193], v[222:225], v[64:67]
	v_mfma_f32_16x16x32_bf16 v[72:75], v[180:183], v[222:225], v[72:75]
	v_mfma_f32_16x16x32_bf16 v[72:75], v[176:179], v[218:221], v[72:75]
	s_barrier
	s_setprio 0
	s_add_i32 s76, s64, s52
	v_lshl_add_u64 v[154:155], s[46:47], 0, v[132:133]
	s_mov_b32 m0, s76
	s_nop 0
	global_load_lds_dwordx4 v[154:155], off
	s_add_i32 m0, s76, 0x2000
	s_add_u32 s76, s46, 0x40000
	v_lshl_add_u64 v[226:227], s[46:47], 0, v[128:129]
	s_addc_u32 s77, s47, 0
	s_add_i32 s78, s65, s52
	global_load_lds_dwordx4 v[226:227], off
	v_lshl_add_u64 v[228:229], s[76:77], 0, v[132:133]
	s_mov_b32 m0, s78
	v_lshl_add_u64 v[230:231], s[48:49], 0, v[130:131]
	global_load_lds_dwordx4 v[228:229], off
	v_lshl_add_u64 v[228:229], s[76:77], 0, v[128:129]
	s_add_i32 m0, s78, 0x2000
	s_nop 0
	global_load_lds_dwordx4 v[228:229], off
	v_lshl_add_u64 v[228:229], s[48:49], 0, v[134:135]
	s_mov_b32 m0, s55
	s_nop 0
	global_load_lds_dwordx4 v[228:229], off
	s_mov_b32 m0, s56
	s_nop 0
	global_load_lds_dwordx4 v[230:231], off
	ds_read_b128 v[194:197], v150 offset:16384
	v_xor_b32_e32 v253, 64, v150
	ds_read_b128 v[198:201], v253 offset:16384
	ds_read_b128 v[202:205], v150 offset:18432
	ds_read_b128 v[206:209], v253 offset:18432
	ds_read_b128 v[210:213], v150 offset:20480
	ds_read_b128 v[214:217], v253 offset:20480
	ds_read_b128 v[218:221], v150 offset:22528
	ds_read_b128 v[222:225], v253 offset:22528
	s_waitcnt vmcnt(8)
	s_waitcnt lgkmcnt(0)
	s_setprio 1
	s_barrier
	v_mfma_f32_16x16x32_bf16 v[60:63], v[160:163], v[194:197], v[60:63]
	v_mfma_f32_16x16x32_bf16 v[60:63], v[164:167], v[198:201], v[60:63]
	v_mfma_f32_16x16x32_bf16 v[52:55], v[172:175], v[198:201], v[52:55]
	v_mfma_f32_16x16x32_bf16 v[52:55], v[168:171], v[194:197], v[52:55]
	v_mfma_f32_16x16x32_bf16 v[36:39], v[168:171], v[202:205], v[36:39]
	v_mfma_f32_16x16x32_bf16 v[36:39], v[172:175], v[206:209], v[36:39]
	v_mfma_f32_16x16x32_bf16 v[44:47], v[164:167], v[206:209], v[44:47]
	v_mfma_f32_16x16x32_bf16 v[44:47], v[160:163], v[202:205], v[44:47]
	v_mfma_f32_16x16x32_bf16 v[28:31], v[160:163], v[210:213], v[28:31]
	v_mfma_f32_16x16x32_bf16 v[28:31], v[164:167], v[214:217], v[28:31]
	v_mfma_f32_16x16x32_bf16 v[20:23], v[172:175], v[214:217], v[20:23]
	v_mfma_f32_16x16x32_bf16 v[20:23], v[168:171], v[210:213], v[20:23]
	v_mfma_f32_16x16x32_bf16 v[4:7], v[168:171], v[218:221], v[4:7]
	v_mfma_f32_16x16x32_bf16 v[4:7], v[172:175], v[222:225], v[4:7]
	v_mfma_f32_16x16x32_bf16 v[12:15], v[164:167], v[222:225], v[12:15]
	v_mfma_f32_16x16x32_bf16 v[12:15], v[160:163], v[218:221], v[12:15]
	s_setprio 0
	s_setprio 1
	v_mfma_f32_16x16x32_bf16 v[56:59], v[176:179], v[194:197], v[56:59]
	v_mfma_f32_16x16x32_bf16 v[56:59], v[180:183], v[198:201], v[56:59]
	v_mfma_f32_16x16x32_bf16 v[48:51], v[190:193], v[198:201], v[48:51]
	v_mfma_f32_16x16x32_bf16 v[48:51], v[186:189], v[194:197], v[48:51]
	v_mfma_f32_16x16x32_bf16 v[32:35], v[186:189], v[202:205], v[32:35]
	v_mfma_f32_16x16x32_bf16 v[32:35], v[190:193], v[206:209], v[32:35]
	v_mfma_f32_16x16x32_bf16 v[40:43], v[180:183], v[206:209], v[40:43]
	v_mfma_f32_16x16x32_bf16 v[40:43], v[176:179], v[202:205], v[40:43]
	v_mfma_f32_16x16x32_bf16 v[24:27], v[176:179], v[210:213], v[24:27]
	v_mfma_f32_16x16x32_bf16 v[24:27], v[180:183], v[214:217], v[24:27]
	v_mfma_f32_16x16x32_bf16 v[16:19], v[190:193], v[214:217], v[16:19]
	v_mfma_f32_16x16x32_bf16 v[16:19], v[186:189], v[210:213], v[16:19]
	v_mfma_f32_16x16x32_bf16 v[0:3], v[186:189], v[218:221], v[0:3]
	v_mfma_f32_16x16x32_bf16 v[0:3], v[190:193], v[222:225], v[0:3]
	v_mfma_f32_16x16x32_bf16 v[8:11], v[180:183], v[222:225], v[8:11]
	v_mfma_f32_16x16x32_bf16 v[8:11], v[176:179], v[218:221], v[8:11]
	s_barrier
	s_setprio 0
	s_add_i32 s76, 0, 0x18000
	s_add_i32 s77, 0, 0x1c000
	s_add_u32 s48, s48, 0x40000
	s_addc_u32 s49, s49, 0
	s_mov_b32 m0, s57
	v_lshl_add_u64 v[232:233], s[48:49], 0, v[134:135]
	global_load_lds_dwordx4 v[232:233], off
	v_lshl_add_u64 v[232:233], s[48:49], 0, v[130:131]
	s_mov_b32 m0, s58
	s_nop 0
	global_load_lds_dwordx4 v[232:233], off
	v_add_u32_e32 v153, s76, v147
	ds_read_b128 v[160:163], v153
	v_xor_b32_e32 v253, 64, v153
	ds_read_b128 v[164:167], v253
	ds_read_b128 v[168:171], v153 offset:2048
	ds_read_b128 v[172:175], v253 offset:2048
	v_add_u32_e32 v153, s77, v147
	ds_read_b128 v[176:179], v153
	v_xor_b32_e32 v253, 64, v153
	ds_read_b128 v[180:183], v253
	ds_read_b128 v[186:189], v153 offset:2048
	ds_read_b128 v[190:193], v253 offset:2048
	ds_read_b128 v[194:197], v150 offset:32768
	v_xor_b32_e32 v253, 64, v150
	ds_read_b128 v[198:201], v253 offset:32768
	ds_read_b128 v[202:205], v150 offset:34816
	ds_read_b128 v[206:209], v253 offset:34816
	ds_read_b128 v[210:213], v150 offset:36864
	ds_read_b128 v[214:217], v253 offset:36864
	ds_read_b128 v[218:221], v150 offset:38912
	ds_read_b128 v[222:225], v253 offset:38912
	s_waitcnt vmcnt(8)
	s_waitcnt lgkmcnt(0)
	s_setprio 1
	s_barrier
	v_mfma_f32_16x16x32_bf16 v[124:127], v[160:163], v[194:197], v[124:127]
	v_mfma_f32_16x16x32_bf16 v[124:127], v[164:167], v[198:201], v[124:127]
	v_mfma_f32_16x16x32_bf16 v[116:119], v[172:175], v[198:201], v[116:119]
	v_mfma_f32_16x16x32_bf16 v[116:119], v[168:171], v[194:197], v[116:119]
	v_mfma_f32_16x16x32_bf16 v[100:103], v[168:171], v[202:205], v[100:103]
	v_mfma_f32_16x16x32_bf16 v[100:103], v[172:175], v[206:209], v[100:103]
	v_mfma_f32_16x16x32_bf16 v[108:111], v[164:167], v[206:209], v[108:111]
	v_mfma_f32_16x16x32_bf16 v[108:111], v[160:163], v[202:205], v[108:111]
	v_mfma_f32_16x16x32_bf16 v[92:95], v[160:163], v[210:213], v[92:95]
	v_mfma_f32_16x16x32_bf16 v[92:95], v[164:167], v[214:217], v[92:95]
	v_mfma_f32_16x16x32_bf16 v[84:87], v[172:175], v[214:217], v[84:87]
	v_mfma_f32_16x16x32_bf16 v[84:87], v[168:171], v[210:213], v[84:87]
	v_mfma_f32_16x16x32_bf16 v[68:71], v[168:171], v[218:221], v[68:71]
	v_mfma_f32_16x16x32_bf16 v[68:71], v[172:175], v[222:225], v[68:71]
	v_mfma_f32_16x16x32_bf16 v[76:79], v[164:167], v[222:225], v[76:79]
	v_mfma_f32_16x16x32_bf16 v[76:79], v[160:163], v[218:221], v[76:79]
	s_setprio 0
	s_setprio 1
	v_mfma_f32_16x16x32_bf16 v[120:123], v[176:179], v[194:197], v[120:123]
	v_mfma_f32_16x16x32_bf16 v[120:123], v[180:183], v[198:201], v[120:123]
	v_mfma_f32_16x16x32_bf16 v[112:115], v[190:193], v[198:201], v[112:115]
	v_mfma_f32_16x16x32_bf16 v[112:115], v[186:189], v[194:197], v[112:115]
	v_mfma_f32_16x16x32_bf16 v[96:99], v[186:189], v[202:205], v[96:99]
	v_mfma_f32_16x16x32_bf16 v[96:99], v[190:193], v[206:209], v[96:99]
	v_mfma_f32_16x16x32_bf16 v[104:107], v[180:183], v[206:209], v[104:107]
	v_mfma_f32_16x16x32_bf16 v[104:107], v[176:179], v[202:205], v[104:107]
	v_mfma_f32_16x16x32_bf16 v[88:91], v[176:179], v[210:213], v[88:91]
	v_mfma_f32_16x16x32_bf16 v[88:91], v[180:183], v[214:217], v[88:91]
	v_mfma_f32_16x16x32_bf16 v[80:83], v[190:193], v[214:217], v[80:83]
	v_mfma_f32_16x16x32_bf16 v[80:83], v[186:189], v[210:213], v[80:83]
	v_mfma_f32_16x16x32_bf16 v[64:67], v[186:189], v[218:221], v[64:67]
	v_mfma_f32_16x16x32_bf16 v[64:67], v[190:193], v[222:225], v[64:67]
	v_mfma_f32_16x16x32_bf16 v[72:75], v[180:183], v[222:225], v[72:75]
	v_mfma_f32_16x16x32_bf16 v[72:75], v[176:179], v[218:221], v[72:75]
	s_barrier
	s_setprio 0
	v_add_u32_e32 v234, 0x21000, v151
	ds_read_b128 v[236:239], v234
	ds_read_b128 v[240:243], v234 offset:256
	ds_read_b128 v[244:247], v234 offset:512
	ds_read_b128 v[248:251], v234 offset:768
	v_add_u32_e32 v235, s23, v146
	v_mul_u32_u24_e32 v235, 0x1600, v235
	v_lshl_or_b32 v234, s67, 7, v149
	v_lshl_add_u32 v235, v234, 1, v235
	s_add_i32 s48, s76, s52
	v_lshl_add_u64 v[154:155], v[154:155], 0, s[14:15]
	s_mov_b32 m0, s48
	ds_read_b128 v[194:197], v150 offset:49152
	v_xor_b32_e32 v253, 64, v150
	ds_read_b128 v[198:201], v253 offset:49152
	ds_read_b128 v[202:205], v150 offset:51200
	ds_read_b128 v[206:209], v253 offset:51200
	ds_read_b128 v[210:213], v150 offset:53248
	ds_read_b128 v[214:217], v253 offset:53248
	ds_read_b128 v[218:221], v150 offset:55296
	ds_read_b128 v[222:225], v253 offset:55296
	global_load_lds_dwordx4 v[154:155], off
	s_add_i32 m0, s48, 0x2000
	s_add_u32 s46, s46, 0x40080
	v_lshl_add_u64 v[154:155], v[226:227], 0, s[14:15]
	s_addc_u32 s47, s47, 0
	s_add_i32 s48, s77, s52
	global_load_lds_dwordx4 v[154:155], off
	v_lshl_add_u64 v[154:155], s[46:47], 0, v[132:133]
	s_mov_b32 m0, s48
	s_nop 0
	global_load_lds_dwordx4 v[154:155], off
	v_lshl_add_u64 v[154:155], s[46:47], 0, v[128:129]
	s_add_i32 m0, s48, 0x2000
	s_nop 0
	global_load_lds_dwordx4 v[154:155], off
	v_lshl_add_u64 v[154:155], v[228:229], 0, s[14:15]
	s_mov_b32 m0, s60
	s_nop 0
	global_load_lds_dwordx4 v[154:155], off
	v_lshl_add_u64 v[154:155], v[230:231], 0, s[14:15]
	s_mov_b32 m0, s61
	s_nop 0
	global_load_lds_dwordx4 v[154:155], off
	s_waitcnt lgkmcnt(8)
	v_add_f32_e32 v236, v236, v237
	v_add_f32_e32 v238, v238, v239
	v_add_f32_e32 v240, v240, v241
	v_add_f32_e32 v242, v242, v243
	v_add_f32_e32 v244, v244, v245
	v_add_f32_e32 v246, v246, v247
	v_add_f32_e32 v248, v248, v249
	v_add_f32_e32 v250, v250, v251
	v_add_f32_e32 v236, v236, v238
	v_add_f32_e32 v240, v240, v242
	v_add_f32_e32 v244, v244, v246
	v_add_f32_e32 v248, v248, v250
	v_fmamk_f32 v236, v236, 0x3a800000, v152
	v_fmamk_f32 v240, v240, 0x3a800000, v152
	v_fmamk_f32 v244, v244, 0x3a800000, v152
	v_fmamk_f32 v248, v248, 0x3a800000, v152
	v_rsq_f32_e32 v236, v236
	v_rsq_f32_e32 v240, v240
	v_rsq_f32_e32 v244, v244
	v_rsq_f32_e32 v248, v248
	v_mul_f32_e32 v252, 0xbfb8aa3b, v236
	v_mul_f32_e32 v254, v236, v236
	v_rcp_f32_e32 v254, v254
	v_pk_mul_f32 v[120:121], v[124:125], v[120:121]
	v_pk_mul_f32 v[122:123], v[126:127], v[122:123]
	v_pk_mul_f32 v[112:113], v[116:117], v[112:113]
	v_pk_mul_f32 v[114:115], v[118:119], v[114:115]
	v_pk_mul_f32 v[124:125], v[124:125], v[252:253] op_sel_hi:[1,0]
	v_pk_mul_f32 v[126:127], v[126:127], v[252:253] op_sel_hi:[1,0]
	v_pk_mul_f32 v[116:117], v[116:117], v[252:253] op_sel_hi:[1,0]
	v_pk_mul_f32 v[118:119], v[118:119], v[252:253] op_sel_hi:[1,0]
	v_exp_f32_e32 v124, v124
	v_exp_f32_e32 v125, v125
	v_exp_f32_e32 v126, v126
	v_exp_f32_e32 v127, v127
	v_exp_f32_e32 v116, v116
	v_exp_f32_e32 v117, v117
	v_exp_f32_e32 v118, v118
	v_exp_f32_e32 v119, v119
	v_pk_fma_f32 v[124:125], v[124:125], v[254:255], v[254:255] op_sel_hi:[1,0,0]
	v_pk_fma_f32 v[126:127], v[126:127], v[254:255], v[254:255] op_sel_hi:[1,0,0]
	v_pk_fma_f32 v[116:117], v[116:117], v[254:255], v[254:255] op_sel_hi:[1,0,0]
	v_pk_fma_f32 v[118:119], v[118:119], v[254:255], v[254:255] op_sel_hi:[1,0,0]
	v_rcp_f32_e32 v124, v124
	v_rcp_f32_e32 v125, v125
	v_rcp_f32_e32 v126, v126
	v_rcp_f32_e32 v127, v127
	v_rcp_f32_e32 v116, v116
	v_rcp_f32_e32 v117, v117
	v_rcp_f32_e32 v118, v118
	v_rcp_f32_e32 v119, v119
	v_pk_mul_f32 v[120:121], v[120:121], v[124:125]
	v_pk_mul_f32 v[122:123], v[122:123], v[126:127]
	v_pk_mul_f32 v[112:113], v[112:113], v[116:117]
	v_pk_mul_f32 v[114:115], v[114:115], v[118:119]
	v_cvt_pk_bf16_f32 v120, v120, v121
	v_cvt_pk_bf16_f32 v121, v122, v123
	v_cvt_pk_bf16_f32 v122, v112, v113
	v_cvt_pk_bf16_f32 v123, v114, v115
	global_store_dwordx4 v235, v[120:123], s[10:11]
	v_add_u32_e32 v234, 0x16000, v235
	v_mul_f32_e32 v252, 0xbfb8aa3b, v240
	v_mul_f32_e32 v254, v240, v240
	v_rcp_f32_e32 v254, v254
	v_pk_mul_f32 v[104:105], v[108:109], v[104:105]
	v_pk_mul_f32 v[106:107], v[110:111], v[106:107]
	v_pk_mul_f32 v[96:97], v[100:101], v[96:97]
	v_pk_mul_f32 v[98:99], v[102:103], v[98:99]
	v_pk_mul_f32 v[108:109], v[108:109], v[252:253] op_sel_hi:[1,0]
	v_pk_mul_f32 v[110:111], v[110:111], v[252:253] op_sel_hi:[1,0]
	v_pk_mul_f32 v[100:101], v[100:101], v[252:253] op_sel_hi:[1,0]
	v_pk_mul_f32 v[102:103], v[102:103], v[252:253] op_sel_hi:[1,0]
	v_exp_f32_e32 v108, v108
	v_exp_f32_e32 v109, v109
	v_exp_f32_e32 v110, v110
	v_exp_f32_e32 v111, v111
	v_exp_f32_e32 v100, v100
	v_exp_f32_e32 v101, v101
	v_exp_f32_e32 v102, v102
	v_exp_f32_e32 v103, v103
	v_pk_fma_f32 v[108:109], v[108:109], v[254:255], v[254:255] op_sel_hi:[1,0,0]
	v_pk_fma_f32 v[110:111], v[110:111], v[254:255], v[254:255] op_sel_hi:[1,0,0]
	v_pk_fma_f32 v[100:101], v[100:101], v[254:255], v[254:255] op_sel_hi:[1,0,0]
	v_pk_fma_f32 v[102:103], v[102:103], v[254:255], v[254:255] op_sel_hi:[1,0,0]
	v_rcp_f32_e32 v108, v108
	v_rcp_f32_e32 v109, v109
	v_rcp_f32_e32 v110, v110
	v_rcp_f32_e32 v111, v111
	v_rcp_f32_e32 v100, v100
	v_rcp_f32_e32 v101, v101
	v_rcp_f32_e32 v102, v102
	v_rcp_f32_e32 v103, v103
	v_pk_mul_f32 v[104:105], v[104:105], v[108:109]
	v_pk_mul_f32 v[106:107], v[106:107], v[110:111]
	v_pk_mul_f32 v[96:97], v[96:97], v[100:101]
	v_pk_mul_f32 v[98:99], v[98:99], v[102:103]
	v_cvt_pk_bf16_f32 v104, v104, v105
	v_cvt_pk_bf16_f32 v105, v106, v107
	v_cvt_pk_bf16_f32 v106, v96, v97
	v_cvt_pk_bf16_f32 v107, v98, v99
	global_store_dwordx4 v234, v[104:107], s[10:11]
	v_add_u32_e32 v235, 0x16000, v234
	v_mul_f32_e32 v252, 0xbfb8aa3b, v244
	v_mul_f32_e32 v254, v244, v244
	v_rcp_f32_e32 v254, v254
	v_pk_mul_f32 v[88:89], v[92:93], v[88:89]
	v_pk_mul_f32 v[90:91], v[94:95], v[90:91]
	v_pk_mul_f32 v[80:81], v[84:85], v[80:81]
	v_pk_mul_f32 v[82:83], v[86:87], v[82:83]
	v_pk_mul_f32 v[92:93], v[92:93], v[252:253] op_sel_hi:[1,0]
	v_pk_mul_f32 v[94:95], v[94:95], v[252:253] op_sel_hi:[1,0]
	v_pk_mul_f32 v[84:85], v[84:85], v[252:253] op_sel_hi:[1,0]
	v_pk_mul_f32 v[86:87], v[86:87], v[252:253] op_sel_hi:[1,0]
	v_exp_f32_e32 v92, v92
	v_exp_f32_e32 v93, v93
	v_exp_f32_e32 v94, v94
	v_exp_f32_e32 v95, v95
	v_exp_f32_e32 v84, v84
	v_exp_f32_e32 v85, v85
	v_exp_f32_e32 v86, v86
	v_exp_f32_e32 v87, v87
	v_pk_fma_f32 v[92:93], v[92:93], v[254:255], v[254:255] op_sel_hi:[1,0,0]
	v_pk_fma_f32 v[94:95], v[94:95], v[254:255], v[254:255] op_sel_hi:[1,0,0]
	v_pk_fma_f32 v[84:85], v[84:85], v[254:255], v[254:255] op_sel_hi:[1,0,0]
	v_pk_fma_f32 v[86:87], v[86:87], v[254:255], v[254:255] op_sel_hi:[1,0,0]
	v_rcp_f32_e32 v92, v92
	v_rcp_f32_e32 v93, v93
	v_rcp_f32_e32 v94, v94
	v_rcp_f32_e32 v95, v95
	v_rcp_f32_e32 v84, v84
	v_rcp_f32_e32 v85, v85
	v_rcp_f32_e32 v86, v86
	v_rcp_f32_e32 v87, v87
	v_pk_mul_f32 v[88:89], v[88:89], v[92:93]
	v_pk_mul_f32 v[90:91], v[90:91], v[94:95]
	v_pk_mul_f32 v[80:81], v[80:81], v[84:85]
	v_pk_mul_f32 v[82:83], v[82:83], v[86:87]
	v_cvt_pk_bf16_f32 v88, v88, v89
	v_cvt_pk_bf16_f32 v89, v90, v91
	v_cvt_pk_bf16_f32 v90, v80, v81
	v_cvt_pk_bf16_f32 v91, v82, v83
	global_store_dwordx4 v235, v[88:91], s[10:11]
	v_add_u32_e32 v234, 0x16000, v235
	v_mul_f32_e32 v252, 0xbfb8aa3b, v248
	v_mul_f32_e32 v254, v248, v248
	v_rcp_f32_e32 v254, v254
	v_pk_mul_f32 v[72:73], v[76:77], v[72:73]
	v_pk_mul_f32 v[74:75], v[78:79], v[74:75]
	v_pk_mul_f32 v[64:65], v[68:69], v[64:65]
	v_pk_mul_f32 v[66:67], v[70:71], v[66:67]
	v_pk_mul_f32 v[76:77], v[76:77], v[252:253] op_sel_hi:[1,0]
	v_pk_mul_f32 v[78:79], v[78:79], v[252:253] op_sel_hi:[1,0]
	v_pk_mul_f32 v[68:69], v[68:69], v[252:253] op_sel_hi:[1,0]
	v_pk_mul_f32 v[70:71], v[70:71], v[252:253] op_sel_hi:[1,0]
	v_exp_f32_e32 v76, v76
	v_exp_f32_e32 v77, v77
	v_exp_f32_e32 v78, v78
	v_exp_f32_e32 v79, v79
	v_exp_f32_e32 v68, v68
	v_exp_f32_e32 v69, v69
	v_exp_f32_e32 v70, v70
	v_exp_f32_e32 v71, v71
	v_pk_fma_f32 v[76:77], v[76:77], v[254:255], v[254:255] op_sel_hi:[1,0,0]
	v_pk_fma_f32 v[78:79], v[78:79], v[254:255], v[254:255] op_sel_hi:[1,0,0]
	v_pk_fma_f32 v[68:69], v[68:69], v[254:255], v[254:255] op_sel_hi:[1,0,0]
	v_pk_fma_f32 v[70:71], v[70:71], v[254:255], v[254:255] op_sel_hi:[1,0,0]
	v_rcp_f32_e32 v76, v76
	v_rcp_f32_e32 v77, v77
	v_rcp_f32_e32 v78, v78
	v_rcp_f32_e32 v79, v79
	v_rcp_f32_e32 v68, v68
	v_rcp_f32_e32 v69, v69
	v_rcp_f32_e32 v70, v70
	v_rcp_f32_e32 v71, v71
	v_pk_mul_f32 v[72:73], v[72:73], v[76:77]
	v_pk_mul_f32 v[74:75], v[74:75], v[78:79]
	v_pk_mul_f32 v[64:65], v[64:65], v[68:69]
	v_pk_mul_f32 v[66:67], v[66:67], v[70:71]
	v_cvt_pk_bf16_f32 v72, v72, v73
	v_cvt_pk_bf16_f32 v73, v74, v75
	v_cvt_pk_bf16_f32 v74, v64, v65
	v_cvt_pk_bf16_f32 v75, v66, v67
	global_store_dwordx4 v234, v[72:75], s[10:11]
	s_waitcnt vmcnt(12)
	s_waitcnt lgkmcnt(0)
	s_setprio 1
	s_barrier
	v_mfma_f32_16x16x32_bf16 v[60:63], v[160:163], v[194:197], v[60:63]
	v_mfma_f32_16x16x32_bf16 v[60:63], v[164:167], v[198:201], v[60:63]
	v_mfma_f32_16x16x32_bf16 v[52:55], v[172:175], v[198:201], v[52:55]
	v_mfma_f32_16x16x32_bf16 v[52:55], v[168:171], v[194:197], v[52:55]
	v_mfma_f32_16x16x32_bf16 v[36:39], v[168:171], v[202:205], v[36:39]
	v_mfma_f32_16x16x32_bf16 v[36:39], v[172:175], v[206:209], v[36:39]
	v_mfma_f32_16x16x32_bf16 v[44:47], v[164:167], v[206:209], v[44:47]
	v_mfma_f32_16x16x32_bf16 v[44:47], v[160:163], v[202:205], v[44:47]
	v_mfma_f32_16x16x32_bf16 v[28:31], v[160:163], v[210:213], v[28:31]
	v_mfma_f32_16x16x32_bf16 v[28:31], v[164:167], v[214:217], v[28:31]
	v_mfma_f32_16x16x32_bf16 v[20:23], v[172:175], v[214:217], v[20:23]
	v_mfma_f32_16x16x32_bf16 v[20:23], v[168:171], v[210:213], v[20:23]
	v_mfma_f32_16x16x32_bf16 v[4:7], v[168:171], v[218:221], v[4:7]
	v_mfma_f32_16x16x32_bf16 v[4:7], v[172:175], v[222:225], v[4:7]
	v_mfma_f32_16x16x32_bf16 v[12:15], v[164:167], v[222:225], v[12:15]
	v_mfma_f32_16x16x32_bf16 v[12:15], v[160:163], v[218:221], v[12:15]
	s_setprio 0
	s_setprio 1
	v_mfma_f32_16x16x32_bf16 v[56:59], v[176:179], v[194:197], v[56:59]
	v_mfma_f32_16x16x32_bf16 v[56:59], v[180:183], v[198:201], v[56:59]
	v_mfma_f32_16x16x32_bf16 v[48:51], v[190:193], v[198:201], v[48:51]
	v_mfma_f32_16x16x32_bf16 v[48:51], v[186:189], v[194:197], v[48:51]
	v_mfma_f32_16x16x32_bf16 v[32:35], v[186:189], v[202:205], v[32:35]
	v_mfma_f32_16x16x32_bf16 v[32:35], v[190:193], v[206:209], v[32:35]
	v_mfma_f32_16x16x32_bf16 v[40:43], v[180:183], v[206:209], v[40:43]
	v_mfma_f32_16x16x32_bf16 v[40:43], v[176:179], v[202:205], v[40:43]
	v_mfma_f32_16x16x32_bf16 v[24:27], v[176:179], v[210:213], v[24:27]
	v_mfma_f32_16x16x32_bf16 v[24:27], v[180:183], v[214:217], v[24:27]
	v_mfma_f32_16x16x32_bf16 v[16:19], v[190:193], v[214:217], v[16:19]
	v_mfma_f32_16x16x32_bf16 v[16:19], v[186:189], v[210:213], v[16:19]
	v_mfma_f32_16x16x32_bf16 v[0:3], v[186:189], v[218:221], v[0:3]
	v_mfma_f32_16x16x32_bf16 v[0:3], v[190:193], v[222:225], v[0:3]
	v_mfma_f32_16x16x32_bf16 v[8:11], v[180:183], v[222:225], v[8:11]
	v_mfma_f32_16x16x32_bf16 v[8:11], v[176:179], v[218:221], v[8:11]
	s_barrier
	s_setprio 0
	s_add_i32 s75, s75, 2
	s_add_u32 s71, s71, 0x100
	s_addc_u32 s74, s74, 0
	s_add_u32 s44, s44, 0x100
	s_addc_u32 s45, s45, 0

.LBB0_158:
	s_add_u32 s81, s56, 0x100
	s_addc_u32 s82, s57, 0
	s_mov_b32 s83, -2
	s_waitcnt lgkmcnt(0)
	s_cmp_eq_u32 s70, 1
	s_cbranch_scc1 .Lfa_1
	ds_read_b128 v[128:131], v189
	v_xor_b32_e32 v253, 64, v189
	ds_read_b128 v[132:135], v253
	ds_read_b128 v[136:139], v189 offset:2048
	ds_read_b128 v[140:143], v253 offset:2048
	ds_read_b128 v[144:147], v190
	v_xor_b32_e32 v253, 64, v190
	ds_read_b128 v[148:151], v253
	ds_read_b128 v[172:175], v190 offset:2048
	ds_read_b128 v[176:179], v253 offset:2048
	s_add_u32 s56, s54, 0x100
	s_addc_u32 s57, s55, 0
	s_cmp_eq_u32 s83, 40
	s_cselect_b32 s61, s15, s57
	s_cselect_b32 s60, s14, s56
	s_cselect_b32 s59, s53, s82
	s_cselect_b32 s58, s52, s81
	v_lshl_add_u64 v[222:223], s[54:55], 0, v[166:167]
	s_add_i32 m0, s66, 0xc000
	s_nop 0
	global_load_lds_dwordx4 v[222:223], off
	v_lshl_add_u64 v[222:223], s[54:55], 0, v[164:165]
	s_add_i32 m0, s66, 0xe000
	s_nop 0
	global_load_lds_dwordx4 v[222:223], off
	ds_read_b128 v[180:183], v191
	v_xor_b32_e32 v253, 64, v191
	ds_read_b128 v[194:197], v253
	ds_read_b128 v[198:201], v191 offset:2048
	ds_read_b128 v[202:205], v253 offset:2048
	ds_read_b128 v[206:209], v191 offset:4096
	ds_read_b128 v[210:213], v253 offset:4096
	ds_read_b128 v[214:217], v191 offset:6144
	ds_read_b128 v[218:221], v253 offset:6144
	s_waitcnt vmcnt(24)
	s_waitcnt lgkmcnt(0)
	s_setprio 1
	s_barrier
	v_mfma_f32_16x16x32_bf16 v[124:127], v[128:131], v[180:183], 0
	v_mfma_f32_16x16x32_bf16 v[120:123], v[136:139], v[180:183], 0
	v_mfma_f32_16x16x32_bf16 v[108:111], v[128:131], v[198:201], 0
	v_mfma_f32_16x16x32_bf16 v[104:107], v[136:139], v[198:201], 0
	v_mfma_f32_16x16x32_bf16 v[92:95], v[128:131], v[206:209], 0
	v_mfma_f32_16x16x32_bf16 v[88:91], v[136:139], v[206:209], 0
	v_mfma_f32_16x16x32_bf16 v[76:79], v[128:131], v[214:217], 0
	v_mfma_f32_16x16x32_bf16 v[72:75], v[136:139], v[214:217], 0
	v_mfma_f32_16x16x32_bf16 v[124:127], v[132:135], v[194:197], v[124:127]
	v_mfma_f32_16x16x32_bf16 v[120:123], v[140:143], v[194:197], v[120:123]
	v_mfma_f32_16x16x32_bf16 v[108:111], v[132:135], v[202:205], v[108:111]
	v_mfma_f32_16x16x32_bf16 v[104:107], v[140:143], v[202:205], v[104:107]
	v_mfma_f32_16x16x32_bf16 v[92:95], v[132:135], v[210:213], v[92:95]
	v_mfma_f32_16x16x32_bf16 v[88:91], v[140:143], v[210:213], v[88:91]
	v_mfma_f32_16x16x32_bf16 v[76:79], v[132:135], v[218:221], v[76:79]
	v_mfma_f32_16x16x32_bf16 v[72:75], v[140:143], v[218:221], v[72:75]
	s_setprio 0
	s_setprio 1
	v_mfma_f32_16x16x32_bf16 v[116:119], v[144:147], v[180:183], 0
	v_mfma_f32_16x16x32_bf16 v[112:115], v[172:175], v[180:183], 0
	v_mfma_f32_16x16x32_bf16 v[100:103], v[144:147], v[198:201], 0
	v_mfma_f32_16x16x32_bf16 v[96:99], v[172:175], v[198:201], 0
	v_mfma_f32_16x16x32_bf16 v[84:87], v[144:147], v[206:209], 0
	v_mfma_f32_16x16x32_bf16 v[80:83], v[172:175], v[206:209], 0
	v_mfma_f32_16x16x32_bf16 v[68:71], v[144:147], v[214:217], 0
	v_mfma_f32_16x16x32_bf16 v[64:67], v[172:175], v[214:217], 0
	v_mfma_f32_16x16x32_bf16 v[116:119], v[148:151], v[194:197], v[116:119]
	v_mfma_f32_16x16x32_bf16 v[112:115], v[176:179], v[194:197], v[112:115]
	v_mfma_f32_16x16x32_bf16 v[100:103], v[148:151], v[202:205], v[100:103]
	v_mfma_f32_16x16x32_bf16 v[96:99], v[176:179], v[202:205], v[96:99]
	v_mfma_f32_16x16x32_bf16 v[84:87], v[148:151], v[210:213], v[84:87]
	v_mfma_f32_16x16x32_bf16 v[80:83], v[176:179], v[210:213], v[80:83]
	v_mfma_f32_16x16x32_bf16 v[68:71], v[148:151], v[218:221], v[68:71]
	v_mfma_f32_16x16x32_bf16 v[64:67], v[176:179], v[218:221], v[64:67]
	s_barrier
	s_setprio 0
	s_add_i32 s54, s77, s65
	v_lshl_add_u64 v[222:223], s[58:59], 0, v[154:155]
	s_mov_b32 m0, s54
	s_nop 0
	global_load_lds_dwordx4 v[222:223], off
	s_add_i32 m0, s54, 0x2000
	s_add_u32 s54, s58, 0xb0000
	v_lshl_add_u64 v[224:225], s[58:59], 0, v[162:163]
	s_addc_u32 s55, s59, 0
	s_add_i32 s84, s78, s65
	global_load_lds_dwordx4 v[224:225], off
	v_lshl_add_u64 v[226:227], s[54:55], 0, v[154:155]
	s_mov_b32 m0, s84
	v_lshl_add_u64 v[228:229], s[60:61], 0, v[160:161]
	global_load_lds_dwordx4 v[226:227], off
	v_lshl_add_u64 v[226:227], s[54:55], 0, v[162:163]
	s_add_i32 m0, s84, 0x2000
	s_nop 0
	global_load_lds_dwordx4 v[226:227], off
	v_lshl_add_u64 v[226:227], s[60:61], 0, v[152:153]
	s_mov_b32 m0, s66
	s_nop 0
	global_load_lds_dwordx4 v[226:227], off
	s_mov_b32 m0, s67
	s_nop 0
	global_load_lds_dwordx4 v[228:229], off
	ds_read_b128 v[180:183], v191 offset:16384
	v_xor_b32_e32 v253, 64, v191
	ds_read_b128 v[194:197], v253 offset:16384
	ds_read_b128 v[198:201], v191 offset:18432
	ds_read_b128 v[202:205], v253 offset:18432
	ds_read_b128 v[206:209], v191 offset:20480
	ds_read_b128 v[210:213], v253 offset:20480
	ds_read_b128 v[214:217], v191 offset:22528
	ds_read_b128 v[218:221], v253 offset:22528
	s_waitcnt vmcnt(24)
	s_waitcnt lgkmcnt(0)
	s_setprio 1
	s_barrier
	v_mfma_f32_16x16x32_bf16 v[60:63], v[128:131], v[180:183], 0
	v_mfma_f32_16x16x32_bf16 v[56:59], v[136:139], v[180:183], 0
	v_mfma_f32_16x16x32_bf16 v[44:47], v[128:131], v[198:201], 0
	v_mfma_f32_16x16x32_bf16 v[40:43], v[136:139], v[198:201], 0
	v_mfma_f32_16x16x32_bf16 v[28:31], v[128:131], v[206:209], 0
	v_mfma_f32_16x16x32_bf16 v[24:27], v[136:139], v[206:209], 0
	v_mfma_f32_16x16x32_bf16 v[12:15], v[128:131], v[214:217], 0
	v_mfma_f32_16x16x32_bf16 v[8:11], v[136:139], v[214:217], 0
	v_mfma_f32_16x16x32_bf16 v[60:63], v[132:135], v[194:197], v[60:63]
	v_mfma_f32_16x16x32_bf16 v[56:59], v[140:143], v[194:197], v[56:59]
	v_mfma_f32_16x16x32_bf16 v[44:47], v[132:135], v[202:205], v[44:47]
	v_mfma_f32_16x16x32_bf16 v[40:43], v[140:143], v[202:205], v[40:43]
	v_mfma_f32_16x16x32_bf16 v[28:31], v[132:135], v[210:213], v[28:31]
	v_mfma_f32_16x16x32_bf16 v[24:27], v[140:143], v[210:213], v[24:27]
	v_mfma_f32_16x16x32_bf16 v[12:15], v[132:135], v[218:221], v[12:15]
	v_mfma_f32_16x16x32_bf16 v[8:11], v[140:143], v[218:221], v[8:11]
	s_setprio 0
	s_setprio 1
	v_mfma_f32_16x16x32_bf16 v[52:55], v[144:147], v[180:183], 0
	v_mfma_f32_16x16x32_bf16 v[48:51], v[172:175], v[180:183], 0
	v_mfma_f32_16x16x32_bf16 v[36:39], v[144:147], v[198:201], 0
	v_mfma_f32_16x16x32_bf16 v[32:35], v[172:175], v[198:201], 0
	v_mfma_f32_16x16x32_bf16 v[20:23], v[144:147], v[206:209], 0
	v_mfma_f32_16x16x32_bf16 v[16:19], v[172:175], v[206:209], 0
	v_mfma_f32_16x16x32_bf16 v[4:7], v[144:147], v[214:217], 0
	v_mfma_f32_16x16x32_bf16 v[0:3], v[172:175], v[214:217], 0
	v_mfma_f32_16x16x32_bf16 v[52:55], v[148:151], v[194:197], v[52:55]
	v_mfma_f32_16x16x32_bf16 v[48:51], v[176:179], v[194:197], v[48:51]
	v_mfma_f32_16x16x32_bf16 v[36:39], v[148:151], v[202:205], v[36:39]
	v_mfma_f32_16x16x32_bf16 v[32:35], v[176:179], v[202:205], v[32:35]
	v_mfma_f32_16x16x32_bf16 v[20:23], v[148:151], v[210:213], v[20:23]
	v_mfma_f32_16x16x32_bf16 v[16:19], v[176:179], v[210:213], v[16:19]
	v_mfma_f32_16x16x32_bf16 v[4:7], v[148:151], v[218:221], v[4:7]
	v_mfma_f32_16x16x32_bf16 v[0:3], v[176:179], v[218:221], v[0:3]
	s_barrier
	s_setprio 0
	s_add_i32 s84, 0, 0x18000
	s_add_i32 s85, 0, 0x1c000
	v_add_u32_e32 v140, s84, v186
	v_add_u32_e32 v176, s85, v186
	s_add_u32 s54, s60, 0xb0000
	s_addc_u32 s55, s61, 0
	s_mov_b32 m0, s68
	v_lshl_add_u64 v[230:231], s[54:55], 0, v[152:153]
	global_load_lds_dwordx4 v[230:231], off
	v_lshl_add_u64 v[230:231], s[54:55], 0, v[160:161]
	s_mov_b32 m0, s69
	s_nop 0
	global_load_lds_dwordx4 v[230:231], off
	ds_read_b128 v[128:131], v140
	v_xor_b32_e32 v253, 64, v140
	ds_read_b128 v[132:135], v253
	ds_read_b128 v[136:139], v140 offset:2048
	ds_read_b128 v[140:143], v253 offset:2048
	ds_read_b128 v[144:147], v176
	v_xor_b32_e32 v253, 64, v176
	ds_read_b128 v[148:151], v253
	ds_read_b128 v[172:175], v176 offset:2048
	ds_read_b128 v[176:179], v253 offset:2048
	ds_read_b128 v[180:183], v191 offset:32768
	v_xor_b32_e32 v253, 64, v191
	ds_read_b128 v[194:197], v253 offset:32768
	ds_read_b128 v[198:201], v191 offset:34816
	ds_read_b128 v[202:205], v253 offset:34816
	ds_read_b128 v[206:209], v191 offset:36864
	ds_read_b128 v[210:213], v253 offset:36864
	ds_read_b128 v[214:217], v191 offset:38912
	ds_read_b128 v[218:221], v253 offset:38912
	s_waitcnt vmcnt(8)
	s_waitcnt lgkmcnt(0)
	s_setprio 1
	s_barrier
	v_mfma_f32_16x16x32_bf16 v[124:127], v[128:131], v[180:183], v[124:127]
	v_mfma_f32_16x16x32_bf16 v[124:127], v[132:135], v[194:197], v[124:127]
	v_mfma_f32_16x16x32_bf16 v[120:123], v[140:143], v[194:197], v[120:123]
	v_mfma_f32_16x16x32_bf16 v[120:123], v[136:139], v[180:183], v[120:123]
	v_mfma_f32_16x16x32_bf16 v[104:107], v[136:139], v[198:201], v[104:107]
	v_mfma_f32_16x16x32_bf16 v[104:107], v[140:143], v[202:205], v[104:107]
	v_mfma_f32_16x16x32_bf16 v[108:111], v[132:135], v[202:205], v[108:111]
	v_mfma_f32_16x16x32_bf16 v[108:111], v[128:131], v[198:201], v[108:111]
	v_mfma_f32_16x16x32_bf16 v[92:95], v[128:131], v[206:209], v[92:95]
	v_mfma_f32_16x16x32_bf16 v[92:95], v[132:135], v[210:213], v[92:95]
	v_mfma_f32_16x16x32_bf16 v[88:91], v[140:143], v[210:213], v[88:91]
	v_mfma_f32_16x16x32_bf16 v[88:91], v[136:139], v[206:209], v[88:91]
	v_mfma_f32_16x16x32_bf16 v[72:75], v[136:139], v[214:217], v[72:75]
	v_mfma_f32_16x16x32_bf16 v[72:75], v[140:143], v[218:221], v[72:75]
	v_mfma_f32_16x16x32_bf16 v[76:79], v[132:135], v[218:221], v[76:79]
	v_mfma_f32_16x16x32_bf16 v[76:79], v[128:131], v[214:217], v[76:79]
	s_setprio 0
	s_setprio 1
	v_mfma_f32_16x16x32_bf16 v[116:119], v[144:147], v[180:183], v[116:119]
	v_mfma_f32_16x16x32_bf16 v[116:119], v[148:151], v[194:197], v[116:119]
	v_mfma_f32_16x16x32_bf16 v[112:115], v[176:179], v[194:197], v[112:115]
	v_mfma_f32_16x16x32_bf16 v[112:115], v[172:175], v[180:183], v[112:115]
	v_mfma_f32_16x16x32_bf16 v[96:99], v[172:175], v[198:201], v[96:99]
	v_mfma_f32_16x16x32_bf16 v[96:99], v[176:179], v[202:205], v[96:99]
	v_mfma_f32_16x16x32_bf16 v[100:103], v[148:151], v[202:205], v[100:103]
	v_mfma_f32_16x16x32_bf16 v[100:103], v[144:147], v[198:201], v[100:103]
	v_mfma_f32_16x16x32_bf16 v[84:87], v[144:147], v[206:209], v[84:87]
	v_mfma_f32_16x16x32_bf16 v[84:87], v[148:151], v[210:213], v[84:87]
	v_mfma_f32_16x16x32_bf16 v[80:83], v[176:179], v[210:213], v[80:83]
	v_mfma_f32_16x16x32_bf16 v[80:83], v[172:175], v[206:209], v[80:83]
	v_mfma_f32_16x16x32_bf16 v[64:67], v[172:175], v[214:217], v[64:67]
	v_mfma_f32_16x16x32_bf16 v[64:67], v[176:179], v[218:221], v[64:67]
	v_mfma_f32_16x16x32_bf16 v[68:71], v[148:151], v[218:221], v[68:71]
	v_mfma_f32_16x16x32_bf16 v[68:71], v[144:147], v[214:217], v[68:71]
	s_barrier
	s_setprio 0
	s_add_i32 s54, s84, s65
	v_lshl_add_u64 v[222:223], v[222:223], 0, s[28:29]
	s_mov_b32 m0, s54
	s_nop 0
	global_load_lds_dwordx4 v[222:223], off
	s_add_i32 m0, s54, 0x2000
	s_add_u32 s54, s58, 0xb0080
	v_lshl_add_u64 v[222:223], v[224:225], 0, s[28:29]
	s_addc_u32 s55, s59, 0
	s_add_i32 s58, s85, s65
	global_load_lds_dwordx4 v[222:223], off
	v_lshl_add_u64 v[222:223], s[54:55], 0, v[154:155]
	s_mov_b32 m0, s58
	s_nop 0
	global_load_lds_dwordx4 v[222:223], off
	v_lshl_add_u64 v[222:223], s[54:55], 0, v[162:163]
	s_add_i32 m0, s58, 0x2000
	s_nop 0
	global_load_lds_dwordx4 v[222:223], off
	v_lshl_add_u64 v[222:223], v[226:227], 0, s[28:29]
	s_mov_b32 m0, s3
	s_nop 0
	global_load_lds_dwordx4 v[222:223], off
	v_lshl_add_u64 v[222:223], v[228:229], 0, s[28:29]
	s_mov_b32 m0, s71
	s_nop 0
	global_load_lds_dwordx4 v[222:223], off
	ds_read_b128 v[180:183], v191 offset:49152
	v_xor_b32_e32 v253, 64, v191
	ds_read_b128 v[194:197], v253 offset:49152
	ds_read_b128 v[198:201], v191 offset:51200
	ds_read_b128 v[202:205], v253 offset:51200
	ds_read_b128 v[206:209], v191 offset:53248
	ds_read_b128 v[210:213], v253 offset:53248
	ds_read_b128 v[214:217], v191 offset:55296
	ds_read_b128 v[218:221], v253 offset:55296
	s_waitcnt vmcnt(8)
	s_waitcnt lgkmcnt(0)
	s_setprio 1
	s_barrier
	v_mfma_f32_16x16x32_bf16 v[60:63], v[128:131], v[180:183], v[60:63]
	v_mfma_f32_16x16x32_bf16 v[60:63], v[132:135], v[194:197], v[60:63]
	v_mfma_f32_16x16x32_bf16 v[56:59], v[140:143], v[194:197], v[56:59]
	v_mfma_f32_16x16x32_bf16 v[56:59], v[136:139], v[180:183], v[56:59]
	v_mfma_f32_16x16x32_bf16 v[40:43], v[136:139], v[198:201], v[40:43]
	v_mfma_f32_16x16x32_bf16 v[40:43], v[140:143], v[202:205], v[40:43]
	v_mfma_f32_16x16x32_bf16 v[44:47], v[132:135], v[202:205], v[44:47]
	v_mfma_f32_16x16x32_bf16 v[44:47], v[128:131], v[198:201], v[44:47]
	v_mfma_f32_16x16x32_bf16 v[28:31], v[128:131], v[206:209], v[28:31]
	v_mfma_f32_16x16x32_bf16 v[28:31], v[132:135], v[210:213], v[28:31]
	v_mfma_f32_16x16x32_bf16 v[24:27], v[140:143], v[210:213], v[24:27]
	v_mfma_f32_16x16x32_bf16 v[24:27], v[136:139], v[206:209], v[24:27]
	v_mfma_f32_16x16x32_bf16 v[8:11], v[136:139], v[214:217], v[8:11]
	v_mfma_f32_16x16x32_bf16 v[8:11], v[140:143], v[218:221], v[8:11]
	v_mfma_f32_16x16x32_bf16 v[12:15], v[132:135], v[218:221], v[12:15]
	v_mfma_f32_16x16x32_bf16 v[12:15], v[128:131], v[214:217], v[12:15]
	s_setprio 0
	s_setprio 1
	v_mfma_f32_16x16x32_bf16 v[52:55], v[144:147], v[180:183], v[52:55]
	v_mfma_f32_16x16x32_bf16 v[52:55], v[148:151], v[194:197], v[52:55]
	v_mfma_f32_16x16x32_bf16 v[48:51], v[176:179], v[194:197], v[48:51]
	v_mfma_f32_16x16x32_bf16 v[48:51], v[172:175], v[180:183], v[48:51]
	v_mfma_f32_16x16x32_bf16 v[32:35], v[172:175], v[198:201], v[32:35]
	v_mfma_f32_16x16x32_bf16 v[32:35], v[176:179], v[202:205], v[32:35]
	v_mfma_f32_16x16x32_bf16 v[36:39], v[148:151], v[202:205], v[36:39]
	v_mfma_f32_16x16x32_bf16 v[36:39], v[144:147], v[198:201], v[36:39]
	v_mfma_f32_16x16x32_bf16 v[20:23], v[144:147], v[206:209], v[20:23]
	v_mfma_f32_16x16x32_bf16 v[20:23], v[148:151], v[210:213], v[20:23]
	v_mfma_f32_16x16x32_bf16 v[16:19], v[176:179], v[210:213], v[16:19]
	v_mfma_f32_16x16x32_bf16 v[16:19], v[172:175], v[206:209], v[16:19]
	v_mfma_f32_16x16x32_bf16 v[0:3], v[172:175], v[214:217], v[0:3]
	v_mfma_f32_16x16x32_bf16 v[0:3], v[176:179], v[218:221], v[0:3]
	v_mfma_f32_16x16x32_bf16 v[4:7], v[148:151], v[218:221], v[4:7]
	v_mfma_f32_16x16x32_bf16 v[4:7], v[144:147], v[214:217], v[4:7]
	s_barrier
	s_setprio 0
	s_add_i32 s83, s83, 2
	s_add_u32 s81, s81, 0x100
	s_addc_u32 s82, s82, 0
	s_cmp_gt_u32 s83, 41
	s_mov_b64 s[54:55], s[56:57]
	s_branch .LBB0_159
.Lfa_1:
	ds_read_b128 v[128:131], v189
	v_xor_b32_e32 v253, 64, v189
	ds_read_b128 v[132:135], v253
	ds_read_b128 v[136:139], v189 offset:2048
	ds_read_b128 v[140:143], v253 offset:2048
	ds_read_b128 v[144:147], v190
	v_xor_b32_e32 v253, 64, v190
	ds_read_b128 v[148:151], v253
	ds_read_b128 v[172:175], v190 offset:2048
	ds_read_b128 v[176:179], v253 offset:2048
	s_add_u32 s56, s54, 0x100
	s_addc_u32 s57, s55, 0
	s_cmp_eq_u32 s83, 40
	s_cselect_b32 s61, s15, s57
	s_cselect_b32 s60, s14, s56
	s_cselect_b32 s59, s53, s82
	s_cselect_b32 s58, s52, s81
	v_lshl_add_u64 v[222:223], s[54:55], 0, v[166:167]
	s_add_i32 m0, s66, 0xc000
	s_nop 0
	global_load_lds_dwordx4 v[222:223], off
	v_lshl_add_u64 v[222:223], s[54:55], 0, v[164:165]
	s_add_i32 m0, s66, 0xe000
	s_nop 0
	global_load_lds_dwordx4 v[222:223], off
	ds_read_b128 v[180:183], v191
	v_xor_b32_e32 v253, 64, v191
	ds_read_b128 v[194:197], v253
	ds_read_b128 v[198:201], v191 offset:2048
	ds_read_b128 v[202:205], v253 offset:2048
	ds_read_b128 v[206:209], v191 offset:4096
	ds_read_b128 v[210:213], v253 offset:4096
	ds_read_b128 v[214:217], v191 offset:6144
	ds_read_b128 v[218:221], v253 offset:6144
	s_waitcnt vmcnt(8)
	s_waitcnt lgkmcnt(0)
	s_setprio 1
	s_barrier
	v_mfma_f32_16x16x32_bf16 v[124:127], v[128:131], v[180:183], 0
	v_mfma_f32_16x16x32_bf16 v[120:123], v[136:139], v[180:183], 0
	v_mfma_f32_16x16x32_bf16 v[108:111], v[128:131], v[198:201], 0
	v_mfma_f32_16x16x32_bf16 v[104:107], v[136:139], v[198:201], 0
	v_mfma_f32_16x16x32_bf16 v[92:95], v[128:131], v[206:209], 0
	v_mfma_f32_16x16x32_bf16 v[88:91], v[136:139], v[206:209], 0
	v_mfma_f32_16x16x32_bf16 v[76:79], v[128:131], v[214:217], 0
	v_mfma_f32_16x16x32_bf16 v[72:75], v[136:139], v[214:217], 0
	v_mfma_f32_16x16x32_bf16 v[124:127], v[132:135], v[194:197], v[124:127]
	v_mfma_f32_16x16x32_bf16 v[120:123], v[140:143], v[194:197], v[120:123]
	v_mfma_f32_16x16x32_bf16 v[108:111], v[132:135], v[202:205], v[108:111]
	v_mfma_f32_16x16x32_bf16 v[104:107], v[140:143], v[202:205], v[104:107]
	v_mfma_f32_16x16x32_bf16 v[92:95], v[132:135], v[210:213], v[92:95]
	v_mfma_f32_16x16x32_bf16 v[88:91], v[140:143], v[210:213], v[88:91]
	v_mfma_f32_16x16x32_bf16 v[76:79], v[132:135], v[218:221], v[76:79]
	v_mfma_f32_16x16x32_bf16 v[72:75], v[140:143], v[218:221], v[72:75]
	s_setprio 0
	s_setprio 1
	v_mfma_f32_16x16x32_bf16 v[116:119], v[144:147], v[180:183], 0
	v_mfma_f32_16x16x32_bf16 v[112:115], v[172:175], v[180:183], 0
	v_mfma_f32_16x16x32_bf16 v[100:103], v[144:147], v[198:201], 0
	v_mfma_f32_16x16x32_bf16 v[96:99], v[172:175], v[198:201], 0
	v_mfma_f32_16x16x32_bf16 v[84:87], v[144:147], v[206:209], 0
	v_mfma_f32_16x16x32_bf16 v[80:83], v[172:175], v[206:209], 0
	v_mfma_f32_16x16x32_bf16 v[68:71], v[144:147], v[214:217], 0
	v_mfma_f32_16x16x32_bf16 v[64:67], v[172:175], v[214:217], 0
	v_mfma_f32_16x16x32_bf16 v[116:119], v[148:151], v[194:197], v[116:119]
	v_mfma_f32_16x16x32_bf16 v[112:115], v[176:179], v[194:197], v[112:115]
	v_mfma_f32_16x16x32_bf16 v[100:103], v[148:151], v[202:205], v[100:103]
	v_mfma_f32_16x16x32_bf16 v[96:99], v[176:179], v[202:205], v[96:99]
	v_mfma_f32_16x16x32_bf16 v[84:87], v[148:151], v[210:213], v[84:87]
	v_mfma_f32_16x16x32_bf16 v[80:83], v[176:179], v[210:213], v[80:83]
	v_mfma_f32_16x16x32_bf16 v[68:71], v[148:151], v[218:221], v[68:71]
	v_mfma_f32_16x16x32_bf16 v[64:67], v[176:179], v[218:221], v[64:67]
	s_barrier
	s_setprio 0
	s_add_i32 s54, s77, s65
	v_lshl_add_u64 v[222:223], s[58:59], 0, v[154:155]
	s_mov_b32 m0, s54
	s_nop 0
	global_load_lds_dwordx4 v[222:223], off
	s_add_i32 m0, s54, 0x2000
	s_add_u32 s54, s58, 0xb0000
	v_lshl_add_u64 v[224:225], s[58:59], 0, v[162:163]
	s_addc_u32 s55, s59, 0
	s_add_i32 s84, s78, s65
	global_load_lds_dwordx4 v[224:225], off
	v_lshl_add_u64 v[226:227], s[54:55], 0, v[154:155]
	s_mov_b32 m0, s84
	v_lshl_add_u64 v[228:229], s[60:61], 0, v[160:161]
	global_load_lds_dwordx4 v[226:227], off
	v_lshl_add_u64 v[226:227], s[54:55], 0, v[162:163]
	s_add_i32 m0, s84, 0x2000
	s_nop 0
	global_load_lds_dwordx4 v[226:227], off
	v_lshl_add_u64 v[226:227], s[60:61], 0, v[152:153]
	s_mov_b32 m0, s66
	s_nop 0
	global_load_lds_dwordx4 v[226:227], off
	s_mov_b32 m0, s67
	s_nop 0
	global_load_lds_dwordx4 v[228:229], off
	ds_read_b128 v[180:183], v191 offset:16384
	v_xor_b32_e32 v253, 64, v191
	ds_read_b128 v[194:197], v253 offset:16384
	ds_read_b128 v[198:201], v191 offset:18432
	ds_read_b128 v[202:205], v253 offset:18432
	ds_read_b128 v[206:209], v191 offset:20480
	ds_read_b128 v[210:213], v253 offset:20480
	ds_read_b128 v[214:217], v191 offset:22528
	ds_read_b128 v[218:221], v253 offset:22528
	s_waitcnt vmcnt(8)
	s_waitcnt lgkmcnt(0)
	s_setprio 1
	s_barrier
	v_mfma_f32_16x16x32_bf16 v[60:63], v[128:131], v[180:183], 0
	v_mfma_f32_16x16x32_bf16 v[56:59], v[136:139], v[180:183], 0
	v_mfma_f32_16x16x32_bf16 v[44:47], v[128:131], v[198:201], 0
	v_mfma_f32_16x16x32_bf16 v[40:43], v[136:139], v[198:201], 0
	v_mfma_f32_16x16x32_bf16 v[28:31], v[128:131], v[206:209], 0
	v_mfma_f32_16x16x32_bf16 v[24:27], v[136:139], v[206:209], 0
	v_mfma_f32_16x16x32_bf16 v[12:15], v[128:131], v[214:217], 0
	v_mfma_f32_16x16x32_bf16 v[8:11], v[136:139], v[214:217], 0
	v_mfma_f32_16x16x32_bf16 v[60:63], v[132:135], v[194:197], v[60:63]
	v_mfma_f32_16x16x32_bf16 v[56:59], v[140:143], v[194:197], v[56:59]
	v_mfma_f32_16x16x32_bf16 v[44:47], v[132:135], v[202:205], v[44:47]
	v_mfma_f32_16x16x32_bf16 v[40:43], v[140:143], v[202:205], v[40:43]
	v_mfma_f32_16x16x32_bf16 v[28:31], v[132:135], v[210:213], v[28:31]
	v_mfma_f32_16x16x32_bf16 v[24:27], v[140:143], v[210:213], v[24:27]
	v_mfma_f32_16x16x32_bf16 v[12:15], v[132:135], v[218:221], v[12:15]
	v_mfma_f32_16x16x32_bf16 v[8:11], v[140:143], v[218:221], v[8:11]
	s_setprio 0
	s_setprio 1
	v_mfma_f32_16x16x32_bf16 v[52:55], v[144:147], v[180:183], 0
	v_mfma_f32_16x16x32_bf16 v[48:51], v[172:175], v[180:183], 0
	v_mfma_f32_16x16x32_bf16 v[36:39], v[144:147], v[198:201], 0
	v_mfma_f32_16x16x32_bf16 v[32:35], v[172:175], v[198:201], 0
	v_mfma_f32_16x16x32_bf16 v[20:23], v[144:147], v[206:209], 0
	v_mfma_f32_16x16x32_bf16 v[16:19], v[172:175], v[206:209], 0
	v_mfma_f32_16x16x32_bf16 v[4:7], v[144:147], v[214:217], 0
	v_mfma_f32_16x16x32_bf16 v[0:3], v[172:175], v[214:217], 0
	v_mfma_f32_16x16x32_bf16 v[52:55], v[148:151], v[194:197], v[52:55]
	v_mfma_f32_16x16x32_bf16 v[48:51], v[176:179], v[194:197], v[48:51]
	v_mfma_f32_16x16x32_bf16 v[36:39], v[148:151], v[202:205], v[36:39]
	v_mfma_f32_16x16x32_bf16 v[32:35], v[176:179], v[202:205], v[32:35]
	v_mfma_f32_16x16x32_bf16 v[20:23], v[148:151], v[210:213], v[20:23]
	v_mfma_f32_16x16x32_bf16 v[16:19], v[176:179], v[210:213], v[16:19]
	v_mfma_f32_16x16x32_bf16 v[4:7], v[148:151], v[218:221], v[4:7]
	v_mfma_f32_16x16x32_bf16 v[0:3], v[176:179], v[218:221], v[0:3]
	s_barrier
	s_setprio 0
	s_add_i32 s84, 0, 0x18000
	s_add_i32 s85, 0, 0x1c000
	v_add_u32_e32 v140, s84, v186
	v_add_u32_e32 v176, s85, v186
	s_add_u32 s54, s60, 0xb0000
	s_addc_u32 s55, s61, 0
	s_mov_b32 m0, s68
	v_lshl_add_u64 v[230:231], s[54:55], 0, v[152:153]
	global_load_lds_dwordx4 v[230:231], off
	v_lshl_add_u64 v[230:231], s[54:55], 0, v[160:161]
	s_mov_b32 m0, s69
	s_nop 0
	global_load_lds_dwordx4 v[230:231], off
	ds_read_b128 v[128:131], v140
	v_xor_b32_e32 v253, 64, v140
	ds_read_b128 v[132:135], v253
	ds_read_b128 v[136:139], v140 offset:2048
	ds_read_b128 v[140:143], v253 offset:2048
	ds_read_b128 v[144:147], v176
	v_xor_b32_e32 v253, 64, v176
	ds_read_b128 v[148:151], v253
	ds_read_b128 v[172:175], v176 offset:2048
	ds_read_b128 v[176:179], v253 offset:2048
	ds_read_b128 v[180:183], v191 offset:32768
	v_xor_b32_e32 v253, 64, v191
	ds_read_b128 v[194:197], v253 offset:32768
	ds_read_b128 v[198:201], v191 offset:34816
	ds_read_b128 v[202:205], v253 offset:34816
	ds_read_b128 v[206:209], v191 offset:36864
	ds_read_b128 v[210:213], v253 offset:36864
	ds_read_b128 v[214:217], v191 offset:38912
	ds_read_b128 v[218:221], v253 offset:38912
	s_waitcnt vmcnt(8)
	s_waitcnt lgkmcnt(0)
	s_setprio 1
	s_barrier
	v_mfma_f32_16x16x32_bf16 v[124:127], v[128:131], v[180:183], v[124:127]
	v_mfma_f32_16x16x32_bf16 v[124:127], v[132:135], v[194:197], v[124:127]
	v_mfma_f32_16x16x32_bf16 v[120:123], v[140:143], v[194:197], v[120:123]
	v_mfma_f32_16x16x32_bf16 v[120:123], v[136:139], v[180:183], v[120:123]
	v_mfma_f32_16x16x32_bf16 v[104:107], v[136:139], v[198:201], v[104:107]
	v_mfma_f32_16x16x32_bf16 v[104:107], v[140:143], v[202:205], v[104:107]
	v_mfma_f32_16x16x32_bf16 v[108:111], v[132:135], v[202:205], v[108:111]
	v_mfma_f32_16x16x32_bf16 v[108:111], v[128:131], v[198:201], v[108:111]
	v_mfma_f32_16x16x32_bf16 v[92:95], v[128:131], v[206:209], v[92:95]
	v_mfma_f32_16x16x32_bf16 v[92:95], v[132:135], v[210:213], v[92:95]
	v_mfma_f32_16x16x32_bf16 v[88:91], v[140:143], v[210:213], v[88:91]
	v_mfma_f32_16x16x32_bf16 v[88:91], v[136:139], v[206:209], v[88:91]
	v_mfma_f32_16x16x32_bf16 v[72:75], v[136:139], v[214:217], v[72:75]
	v_mfma_f32_16x16x32_bf16 v[72:75], v[140:143], v[218:221], v[72:75]
	v_mfma_f32_16x16x32_bf16 v[76:79], v[132:135], v[218:221], v[76:79]
	v_mfma_f32_16x16x32_bf16 v[76:79], v[128:131], v[214:217], v[76:79]
	s_setprio 0
	s_setprio 1
	v_mfma_f32_16x16x32_bf16 v[116:119], v[144:147], v[180:183], v[116:119]
	v_mfma_f32_16x16x32_bf16 v[116:119], v[148:151], v[194:197], v[116:119]
	v_mfma_f32_16x16x32_bf16 v[112:115], v[176:179], v[194:197], v[112:115]
	v_mfma_f32_16x16x32_bf16 v[112:115], v[172:175], v[180:183], v[112:115]
	v_mfma_f32_16x16x32_bf16 v[96:99], v[172:175], v[198:201], v[96:99]
	v_mfma_f32_16x16x32_bf16 v[96:99], v[176:179], v[202:205], v[96:99]
	v_mfma_f32_16x16x32_bf16 v[100:103], v[148:151], v[202:205], v[100:103]
	v_mfma_f32_16x16x32_bf16 v[100:103], v[144:147], v[198:201], v[100:103]
	v_mfma_f32_16x16x32_bf16 v[84:87], v[144:147], v[206:209], v[84:87]
	v_mfma_f32_16x16x32_bf16 v[84:87], v[148:151], v[210:213], v[84:87]
	v_mfma_f32_16x16x32_bf16 v[80:83], v[176:179], v[210:213], v[80:83]
	v_mfma_f32_16x16x32_bf16 v[80:83], v[172:175], v[206:209], v[80:83]
	v_mfma_f32_16x16x32_bf16 v[64:67], v[172:175], v[214:217], v[64:67]
	v_mfma_f32_16x16x32_bf16 v[64:67], v[176:179], v[218:221], v[64:67]
	v_mfma_f32_16x16x32_bf16 v[68:71], v[148:151], v[218:221], v[68:71]
	v_mfma_f32_16x16x32_bf16 v[68:71], v[144:147], v[214:217], v[68:71]
	s_barrier
	s_setprio 0
	s_add_i32 s54, s84, s65
	v_lshl_add_u64 v[222:223], v[222:223], 0, s[28:29]
	s_mov_b32 m0, s54
	s_nop 0
	global_load_lds_dwordx4 v[222:223], off
	s_add_i32 m0, s54, 0x2000
	s_add_u32 s54, s58, 0xb0080
	v_lshl_add_u64 v[222:223], v[224:225], 0, s[28:29]
	s_addc_u32 s55, s59, 0
	s_add_i32 s58, s85, s65
	global_load_lds_dwordx4 v[222:223], off
	v_lshl_add_u64 v[222:223], s[54:55], 0, v[154:155]
	s_mov_b32 m0, s58
	s_nop 0
	global_load_lds_dwordx4 v[222:223], off
	v_lshl_add_u64 v[222:223], s[54:55], 0, v[162:163]
	s_add_i32 m0, s58, 0x2000
	s_nop 0
	global_load_lds_dwordx4 v[222:223], off
	v_lshl_add_u64 v[222:223], v[226:227], 0, s[28:29]
	s_mov_b32 m0, s3
	s_nop 0
	global_load_lds_dwordx4 v[222:223], off
	v_lshl_add_u64 v[222:223], v[228:229], 0, s[28:29]
	s_mov_b32 m0, s71
	s_nop 0
	global_load_lds_dwordx4 v[222:223], off
	ds_read_b128 v[180:183], v191 offset:49152
	v_xor_b32_e32 v253, 64, v191
	ds_read_b128 v[194:197], v253 offset:49152
	ds_read_b128 v[198:201], v191 offset:51200
	ds_read_b128 v[202:205], v253 offset:51200
	ds_read_b128 v[206:209], v191 offset:53248
	ds_read_b128 v[210:213], v253 offset:53248
	ds_read_b128 v[214:217], v191 offset:55296
	ds_read_b128 v[218:221], v253 offset:55296
	s_waitcnt vmcnt(8)
	s_waitcnt lgkmcnt(0)
	s_setprio 1
	s_barrier
	v_mfma_f32_16x16x32_bf16 v[60:63], v[128:131], v[180:183], v[60:63]
	v_mfma_f32_16x16x32_bf16 v[60:63], v[132:135], v[194:197], v[60:63]
	v_mfma_f32_16x16x32_bf16 v[56:59], v[140:143], v[194:197], v[56:59]
	v_mfma_f32_16x16x32_bf16 v[56:59], v[136:139], v[180:183], v[56:59]
	v_mfma_f32_16x16x32_bf16 v[40:43], v[136:139], v[198:201], v[40:43]
	v_mfma_f32_16x16x32_bf16 v[40:43], v[140:143], v[202:205], v[40:43]
	v_mfma_f32_16x16x32_bf16 v[44:47], v[132:135], v[202:205], v[44:47]
	v_mfma_f32_16x16x32_bf16 v[44:47], v[128:131], v[198:201], v[44:47]
	v_mfma_f32_16x16x32_bf16 v[28:31], v[128:131], v[206:209], v[28:31]
	v_mfma_f32_16x16x32_bf16 v[28:31], v[132:135], v[210:213], v[28:31]
	v_mfma_f32_16x16x32_bf16 v[24:27], v[140:143], v[210:213], v[24:27]
	v_mfma_f32_16x16x32_bf16 v[24:27], v[136:139], v[206:209], v[24:27]
	v_mfma_f32_16x16x32_bf16 v[8:11], v[136:139], v[214:217], v[8:11]
	v_mfma_f32_16x16x32_bf16 v[8:11], v[140:143], v[218:221], v[8:11]
	v_mfma_f32_16x16x32_bf16 v[12:15], v[132:135], v[218:221], v[12:15]
	v_mfma_f32_16x16x32_bf16 v[12:15], v[128:131], v[214:217], v[12:15]
	s_setprio 0
	s_setprio 1
	v_mfma_f32_16x16x32_bf16 v[52:55], v[144:147], v[180:183], v[52:55]
	v_mfma_f32_16x16x32_bf16 v[52:55], v[148:151], v[194:197], v[52:55]
	v_mfma_f32_16x16x32_bf16 v[48:51], v[176:179], v[194:197], v[48:51]
	v_mfma_f32_16x16x32_bf16 v[48:51], v[172:175], v[180:183], v[48:51]
	v_mfma_f32_16x16x32_bf16 v[32:35], v[172:175], v[198:201], v[32:35]
	v_mfma_f32_16x16x32_bf16 v[32:35], v[176:179], v[202:205], v[32:35]
	v_mfma_f32_16x16x32_bf16 v[36:39], v[148:151], v[202:205], v[36:39]
	v_mfma_f32_16x16x32_bf16 v[36:39], v[144:147], v[198:201], v[36:39]
	v_mfma_f32_16x16x32_bf16 v[20:23], v[144:147], v[206:209], v[20:23]
	v_mfma_f32_16x16x32_bf16 v[20:23], v[148:151], v[210:213], v[20:23]
	v_mfma_f32_16x16x32_bf16 v[16:19], v[176:179], v[210:213], v[16:19]
	v_mfma_f32_16x16x32_bf16 v[16:19], v[172:175], v[206:209], v[16:19]
	v_mfma_f32_16x16x32_bf16 v[0:3], v[172:175], v[214:217], v[0:3]
	v_mfma_f32_16x16x32_bf16 v[0:3], v[176:179], v[218:221], v[0:3]
	v_mfma_f32_16x16x32_bf16 v[4:7], v[148:151], v[218:221], v[4:7]
	v_mfma_f32_16x16x32_bf16 v[4:7], v[144:147], v[214:217], v[4:7]
	s_barrier
	s_setprio 0
	s_add_i32 s83, s83, 2
	s_add_u32 s81, s81, 0x100
	s_addc_u32 s82, s82, 0
	s_cmp_gt_u32 s83, 41
	s_mov_b64 s[54:55], s[56:57]
.LBB0_159:
	ds_read_b128 v[128:131], v189
	v_xor_b32_e32 v253, 64, v189
	ds_read_b128 v[132:135], v253
	ds_read_b128 v[136:139], v189 offset:2048
	ds_read_b128 v[140:143], v253 offset:2048
	ds_read_b128 v[144:147], v190
	v_xor_b32_e32 v253, 64, v190
	ds_read_b128 v[148:151], v253
	ds_read_b128 v[172:175], v190 offset:2048
	ds_read_b128 v[176:179], v253 offset:2048
	s_add_u32 s56, s54, 0x100
	s_addc_u32 s57, s55, 0
	s_cmp_eq_u32 s83, 40
	s_cselect_b32 s61, s15, s57
	s_cselect_b32 s60, s14, s56
	s_cselect_b32 s59, s53, s82
	s_cselect_b32 s58, s52, s81
	v_lshl_add_u64 v[222:223], s[54:55], 0, v[166:167]
	s_add_i32 m0, s66, 0xc000
	s_nop 0
	global_load_lds_dwordx4 v[222:223], off
	v_lshl_add_u64 v[222:223], s[54:55], 0, v[164:165]
	s_add_i32 m0, s66, 0xe000
	s_nop 0
	global_load_lds_dwordx4 v[222:223], off
	ds_read_b128 v[180:183], v191
	v_xor_b32_e32 v253, 64, v191
	ds_read_b128 v[194:197], v253
	ds_read_b128 v[198:201], v191 offset:2048
	ds_read_b128 v[202:205], v253 offset:2048
	ds_read_b128 v[206:209], v191 offset:4096
	ds_read_b128 v[210:213], v253 offset:4096
	ds_read_b128 v[214:217], v191 offset:6144
	ds_read_b128 v[218:221], v253 offset:6144
	s_waitcnt vmcnt(8)
	s_waitcnt lgkmcnt(0)
	s_setprio 1
	s_barrier
	v_mfma_f32_16x16x32_bf16 v[124:127], v[128:131], v[180:183], v[124:127]
	v_mfma_f32_16x16x32_bf16 v[124:127], v[132:135], v[194:197], v[124:127]
	v_mfma_f32_16x16x32_bf16 v[120:123], v[140:143], v[194:197], v[120:123]
	v_mfma_f32_16x16x32_bf16 v[120:123], v[136:139], v[180:183], v[120:123]
	v_mfma_f32_16x16x32_bf16 v[104:107], v[136:139], v[198:201], v[104:107]
	v_mfma_f32_16x16x32_bf16 v[104:107], v[140:143], v[202:205], v[104:107]
	v_mfma_f32_16x16x32_bf16 v[108:111], v[132:135], v[202:205], v[108:111]
	v_mfma_f32_16x16x32_bf16 v[108:111], v[128:131], v[198:201], v[108:111]
	v_mfma_f32_16x16x32_bf16 v[92:95], v[128:131], v[206:209], v[92:95]
	v_mfma_f32_16x16x32_bf16 v[92:95], v[132:135], v[210:213], v[92:95]
	v_mfma_f32_16x16x32_bf16 v[88:91], v[140:143], v[210:213], v[88:91]
	v_mfma_f32_16x16x32_bf16 v[88:91], v[136:139], v[206:209], v[88:91]
	v_mfma_f32_16x16x32_bf16 v[72:75], v[136:139], v[214:217], v[72:75]
	v_mfma_f32_16x16x32_bf16 v[72:75], v[140:143], v[218:221], v[72:75]
	v_mfma_f32_16x16x32_bf16 v[76:79], v[132:135], v[218:221], v[76:79]
	v_mfma_f32_16x16x32_bf16 v[76:79], v[128:131], v[214:217], v[76:79]
	s_setprio 0
	s_setprio 1
	v_mfma_f32_16x16x32_bf16 v[116:119], v[144:147], v[180:183], v[116:119]
	v_mfma_f32_16x16x32_bf16 v[116:119], v[148:151], v[194:197], v[116:119]
	v_mfma_f32_16x16x32_bf16 v[112:115], v[176:179], v[194:197], v[112:115]
	v_mfma_f32_16x16x32_bf16 v[112:115], v[172:175], v[180:183], v[112:115]
	v_mfma_f32_16x16x32_bf16 v[96:99], v[172:175], v[198:201], v[96:99]
	v_mfma_f32_16x16x32_bf16 v[96:99], v[176:179], v[202:205], v[96:99]
	v_mfma_f32_16x16x32_bf16 v[100:103], v[148:151], v[202:205], v[100:103]
	v_mfma_f32_16x16x32_bf16 v[100:103], v[144:147], v[198:201], v[100:103]
	v_mfma_f32_16x16x32_bf16 v[84:87], v[144:147], v[206:209], v[84:87]
	v_mfma_f32_16x16x32_bf16 v[84:87], v[148:151], v[210:213], v[84:87]
	v_mfma_f32_16x16x32_bf16 v[80:83], v[176:179], v[210:213], v[80:83]
	v_mfma_f32_16x16x32_bf16 v[80:83], v[172:175], v[206:209], v[80:83]
	v_mfma_f32_16x16x32_bf16 v[64:67], v[172:175], v[214:217], v[64:67]
	v_mfma_f32_16x16x32_bf16 v[64:67], v[176:179], v[218:221], v[64:67]
	v_mfma_f32_16x16x32_bf16 v[68:71], v[148:151], v[218:221], v[68:71]
	v_mfma_f32_16x16x32_bf16 v[68:71], v[144:147], v[214:217], v[68:71]
	s_barrier
	s_setprio 0
	s_add_i32 s54, s77, s65
	v_lshl_add_u64 v[222:223], s[58:59], 0, v[154:155]
	s_mov_b32 m0, s54
	s_nop 0
	global_load_lds_dwordx4 v[222:223], off
	s_add_i32 m0, s54, 0x2000
	s_add_u32 s54, s58, 0xb0000
	v_lshl_add_u64 v[224:225], s[58:59], 0, v[162:163]
	s_addc_u32 s55, s59, 0
	s_add_i32 s84, s78, s65
	global_load_lds_dwordx4 v[224:225], off
	v_lshl_add_u64 v[226:227], s[54:55], 0, v[154:155]
	s_mov_b32 m0, s84
	v_lshl_add_u64 v[228:229], s[60:61], 0, v[160:161]
	global_load_lds_dwordx4 v[226:227], off
	v_lshl_add_u64 v[226:227], s[54:55], 0, v[162:163]
	s_add_i32 m0, s84, 0x2000
	s_nop 0
	global_load_lds_dwordx4 v[226:227], off
	v_lshl_add_u64 v[226:227], s[60:61], 0, v[152:153]
	s_mov_b32 m0, s66
	s_nop 0
	global_load_lds_dwordx4 v[226:227], off
	s_mov_b32 m0, s67
	s_nop 0
	global_load_lds_dwordx4 v[228:229], off
	ds_read_b128 v[180:183], v191 offset:16384
	v_xor_b32_e32 v253, 64, v191
	ds_read_b128 v[194:197], v253 offset:16384
	ds_read_b128 v[198:201], v191 offset:18432
	ds_read_b128 v[202:205], v253 offset:18432
	ds_read_b128 v[206:209], v191 offset:20480
	ds_read_b128 v[210:213], v253 offset:20480
	ds_read_b128 v[214:217], v191 offset:22528
	ds_read_b128 v[218:221], v253 offset:22528
	s_waitcnt vmcnt(8)
	s_waitcnt lgkmcnt(0)
	s_setprio 1
	s_barrier
	v_mfma_f32_16x16x32_bf16 v[60:63], v[128:131], v[180:183], v[60:63]
	v_mfma_f32_16x16x32_bf16 v[60:63], v[132:135], v[194:197], v[60:63]
	v_mfma_f32_16x16x32_bf16 v[56:59], v[140:143], v[194:197], v[56:59]
	v_mfma_f32_16x16x32_bf16 v[56:59], v[136:139], v[180:183], v[56:59]
	v_mfma_f32_16x16x32_bf16 v[40:43], v[136:139], v[198:201], v[40:43]
	v_mfma_f32_16x16x32_bf16 v[40:43], v[140:143], v[202:205], v[40:43]
	v_mfma_f32_16x16x32_bf16 v[44:47], v[132:135], v[202:205], v[44:47]
	v_mfma_f32_16x16x32_bf16 v[44:47], v[128:131], v[198:201], v[44:47]
	v_mfma_f32_16x16x32_bf16 v[28:31], v[128:131], v[206:209], v[28:31]
	v_mfma_f32_16x16x32_bf16 v[28:31], v[132:135], v[210:213], v[28:31]
	v_mfma_f32_16x16x32_bf16 v[24:27], v[140:143], v[210:213], v[24:27]
	v_mfma_f32_16x16x32_bf16 v[24:27], v[136:139], v[206:209], v[24:27]
	v_mfma_f32_16x16x32_bf16 v[8:11], v[136:139], v[214:217], v[8:11]
	v_mfma_f32_16x16x32_bf16 v[8:11], v[140:143], v[218:221], v[8:11]
	v_mfma_f32_16x16x32_bf16 v[12:15], v[132:135], v[218:221], v[12:15]
	v_mfma_f32_16x16x32_bf16 v[12:15], v[128:131], v[214:217], v[12:15]
	s_setprio 0
	s_setprio 1
	v_mfma_f32_16x16x32_bf16 v[52:55], v[144:147], v[180:183], v[52:55]
	v_mfma_f32_16x16x32_bf16 v[52:55], v[148:151], v[194:197], v[52:55]
	v_mfma_f32_16x16x32_bf16 v[48:51], v[176:179], v[194:197], v[48:51]
	v_mfma_f32_16x16x32_bf16 v[48:51], v[172:175], v[180:183], v[48:51]
	v_mfma_f32_16x16x32_bf16 v[32:35], v[172:175], v[198:201], v[32:35]
	v_mfma_f32_16x16x32_bf16 v[32:35], v[176:179], v[202:205], v[32:35]
	v_mfma_f32_16x16x32_bf16 v[36:39], v[148:151], v[202:205], v[36:39]
	v_mfma_f32_16x16x32_bf16 v[36:39], v[144:147], v[198:201], v[36:39]
	v_mfma_f32_16x16x32_bf16 v[20:23], v[144:147], v[206:209], v[20:23]
	v_mfma_f32_16x16x32_bf16 v[20:23], v[148:151], v[210:213], v[20:23]
	v_mfma_f32_16x16x32_bf16 v[16:19], v[176:179], v[210:213], v[16:19]
	v_mfma_f32_16x16x32_bf16 v[16:19], v[172:175], v[206:209], v[16:19]
	v_mfma_f32_16x16x32_bf16 v[0:3], v[172:175], v[214:217], v[0:3]
	v_mfma_f32_16x16x32_bf16 v[0:3], v[176:179], v[218:221], v[0:3]
	v_mfma_f32_16x16x32_bf16 v[4:7], v[148:151], v[218:221], v[4:7]
	v_mfma_f32_16x16x32_bf16 v[4:7], v[144:147], v[214:217], v[4:7]
	s_barrier
	s_setprio 0
	s_add_i32 s84, 0, 0x18000
	s_add_i32 s85, 0, 0x1c000
	v_add_u32_e32 v140, s84, v186
	v_add_u32_e32 v176, s85, v186
	s_add_u32 s54, s60, 0xb0000
	s_addc_u32 s55, s61, 0
	s_mov_b32 m0, s68
	v_lshl_add_u64 v[230:231], s[54:55], 0, v[152:153]
	global_load_lds_dwordx4 v[230:231], off
	v_lshl_add_u64 v[230:231], s[54:55], 0, v[160:161]
	s_mov_b32 m0, s69
	s_nop 0
	global_load_lds_dwordx4 v[230:231], off
	ds_read_b128 v[128:131], v140
	v_xor_b32_e32 v253, 64, v140
	ds_read_b128 v[132:135], v253
	ds_read_b128 v[136:139], v140 offset:2048
	ds_read_b128 v[140:143], v253 offset:2048
	ds_read_b128 v[144:147], v176
	v_xor_b32_e32 v253, 64, v176
	ds_read_b128 v[148:151], v253
	ds_read_b128 v[172:175], v176 offset:2048
	ds_read_b128 v[176:179], v253 offset:2048
	ds_read_b128 v[180:183], v191 offset:32768
	v_xor_b32_e32 v253, 64, v191
	ds_read_b128 v[194:197], v253 offset:32768
	ds_read_b128 v[198:201], v191 offset:34816
	ds_read_b128 v[202:205], v253 offset:34816
	ds_read_b128 v[206:209], v191 offset:36864
	ds_read_b128 v[210:213], v253 offset:36864
	ds_read_b128 v[214:217], v191 offset:38912
	ds_read_b128 v[218:221], v253 offset:38912
	s_waitcnt vmcnt(8)
	s_waitcnt lgkmcnt(0)
	s_setprio 1
	s_barrier
	v_mfma_f32_16x16x32_bf16 v[124:127], v[128:131], v[180:183], v[124:127]
	v_mfma_f32_16x16x32_bf16 v[124:127], v[132:135], v[194:197], v[124:127]
	v_mfma_f32_16x16x32_bf16 v[120:123], v[140:143], v[194:197], v[120:123]
	v_mfma_f32_16x16x32_bf16 v[120:123], v[136:139], v[180:183], v[120:123]
	v_mfma_f32_16x16x32_bf16 v[104:107], v[136:139], v[198:201], v[104:107]
	v_mfma_f32_16x16x32_bf16 v[104:107], v[140:143], v[202:205], v[104:107]
	v_mfma_f32_16x16x32_bf16 v[108:111], v[132:135], v[202:205], v[108:111]
	v_mfma_f32_16x16x32_bf16 v[108:111], v[128:131], v[198:201], v[108:111]
	v_mfma_f32_16x16x32_bf16 v[92:95], v[128:131], v[206:209], v[92:95]
	v_mfma_f32_16x16x32_bf16 v[92:95], v[132:135], v[210:213], v[92:95]
	v_mfma_f32_16x16x32_bf16 v[88:91], v[140:143], v[210:213], v[88:91]
	v_mfma_f32_16x16x32_bf16 v[88:91], v[136:139], v[206:209], v[88:91]
	v_mfma_f32_16x16x32_bf16 v[72:75], v[136:139], v[214:217], v[72:75]
	v_mfma_f32_16x16x32_bf16 v[72:75], v[140:143], v[218:221], v[72:75]
	v_mfma_f32_16x16x32_bf16 v[76:79], v[132:135], v[218:221], v[76:79]
	v_mfma_f32_16x16x32_bf16 v[76:79], v[128:131], v[214:217], v[76:79]
	s_setprio 0
	s_setprio 1
	v_mfma_f32_16x16x32_bf16 v[116:119], v[144:147], v[180:183], v[116:119]
	v_mfma_f32_16x16x32_bf16 v[116:119], v[148:151], v[194:197], v[116:119]
	v_mfma_f32_16x16x32_bf16 v[112:115], v[176:179], v[194:197], v[112:115]
	v_mfma_f32_16x16x32_bf16 v[112:115], v[172:175], v[180:183], v[112:115]
	v_mfma_f32_16x16x32_bf16 v[96:99], v[172:175], v[198:201], v[96:99]
	v_mfma_f32_16x16x32_bf16 v[96:99], v[176:179], v[202:205], v[96:99]
	v_mfma_f32_16x16x32_bf16 v[100:103], v[148:151], v[202:205], v[100:103]
	v_mfma_f32_16x16x32_bf16 v[100:103], v[144:147], v[198:201], v[100:103]
	v_mfma_f32_16x16x32_bf16 v[84:87], v[144:147], v[206:209], v[84:87]
	v_mfma_f32_16x16x32_bf16 v[84:87], v[148:151], v[210:213], v[84:87]
	v_mfma_f32_16x16x32_bf16 v[80:83], v[176:179], v[210:213], v[80:83]
	v_mfma_f32_16x16x32_bf16 v[80:83], v[172:175], v[206:209], v[80:83]
	v_mfma_f32_16x16x32_bf16 v[64:67], v[172:175], v[214:217], v[64:67]
	v_mfma_f32_16x16x32_bf16 v[64:67], v[176:179], v[218:221], v[64:67]
	v_mfma_f32_16x16x32_bf16 v[68:71], v[148:151], v[218:221], v[68:71]
	v_mfma_f32_16x16x32_bf16 v[68:71], v[144:147], v[214:217], v[68:71]
	s_barrier
	s_setprio 0
	s_add_i32 s54, s84, s65
	v_lshl_add_u64 v[222:223], v[222:223], 0, s[28:29]
	s_mov_b32 m0, s54
	s_nop 0
	global_load_lds_dwordx4 v[222:223], off
	s_add_i32 m0, s54, 0x2000
	s_add_u32 s54, s58, 0xb0080
	v_lshl_add_u64 v[222:223], v[224:225], 0, s[28:29]
	s_addc_u32 s55, s59, 0
	s_add_i32 s58, s85, s65
	global_load_lds_dwordx4 v[222:223], off
	v_lshl_add_u64 v[222:223], s[54:55], 0, v[154:155]
	s_mov_b32 m0, s58
	s_nop 0
	global_load_lds_dwordx4 v[222:223], off
	v_lshl_add_u64 v[222:223], s[54:55], 0, v[162:163]
	s_add_i32 m0, s58, 0x2000
	s_nop 0
	global_load_lds_dwordx4 v[222:223], off
	v_lshl_add_u64 v[222:223], v[226:227], 0, s[28:29]
	s_mov_b32 m0, s3
	s_nop 0
	global_load_lds_dwordx4 v[222:223], off
	v_lshl_add_u64 v[222:223], v[228:229], 0, s[28:29]
	s_mov_b32 m0, s71
	s_nop 0
	global_load_lds_dwordx4 v[222:223], off
	ds_read_b128 v[180:183], v191 offset:49152
	v_xor_b32_e32 v253, 64, v191
	ds_read_b128 v[194:197], v253 offset:49152
	ds_read_b128 v[198:201], v191 offset:51200
	ds_read_b128 v[202:205], v253 offset:51200
	ds_read_b128 v[206:209], v191 offset:53248
	ds_read_b128 v[210:213], v253 offset:53248
	ds_read_b128 v[214:217], v191 offset:55296
	ds_read_b128 v[218:221], v253 offset:55296
	s_waitcnt vmcnt(8)
	s_waitcnt lgkmcnt(0)
	s_setprio 1
	s_barrier
	v_mfma_f32_16x16x32_bf16 v[60:63], v[128:131], v[180:183], v[60:63]
	v_mfma_f32_16x16x32_bf16 v[60:63], v[132:135], v[194:197], v[60:63]
	v_mfma_f32_16x16x32_bf16 v[56:59], v[140:143], v[194:197], v[56:59]
	v_mfma_f32_16x16x32_bf16 v[56:59], v[136:139], v[180:183], v[56:59]
	v_mfma_f32_16x16x32_bf16 v[40:43], v[136:139], v[198:201], v[40:43]
	v_mfma_f32_16x16x32_bf16 v[40:43], v[140:143], v[202:205], v[40:43]
	v_mfma_f32_16x16x32_bf16 v[44:47], v[132:135], v[202:205], v[44:47]
	v_mfma_f32_16x16x32_bf16 v[44:47], v[128:131], v[198:201], v[44:47]
	v_mfma_f32_16x16x32_bf16 v[28:31], v[128:131], v[206:209], v[28:31]
	v_mfma_f32_16x16x32_bf16 v[28:31], v[132:135], v[210:213], v[28:31]
	v_mfma_f32_16x16x32_bf16 v[24:27], v[140:143], v[210:213], v[24:27]
	v_mfma_f32_16x16x32_bf16 v[24:27], v[136:139], v[206:209], v[24:27]
	v_mfma_f32_16x16x32_bf16 v[8:11], v[136:139], v[214:217], v[8:11]
	v_mfma_f32_16x16x32_bf16 v[8:11], v[140:143], v[218:221], v[8:11]
	v_mfma_f32_16x16x32_bf16 v[12:15], v[132:135], v[218:221], v[12:15]
	v_mfma_f32_16x16x32_bf16 v[12:15], v[128:131], v[214:217], v[12:15]
	s_setprio 0
	s_setprio 1
	v_mfma_f32_16x16x32_bf16 v[52:55], v[144:147], v[180:183], v[52:55]
	v_mfma_f32_16x16x32_bf16 v[52:55], v[148:151], v[194:197], v[52:55]
	v_mfma_f32_16x16x32_bf16 v[48:51], v[176:179], v[194:197], v[48:51]
	v_mfma_f32_16x16x32_bf16 v[48:51], v[172:175], v[180:183], v[48:51]
	v_mfma_f32_16x16x32_bf16 v[32:35], v[172:175], v[198:201], v[32:35]
	v_mfma_f32_16x16x32_bf16 v[32:35], v[176:179], v[202:205], v[32:35]
	v_mfma_f32_16x16x32_bf16 v[36:39], v[148:151], v[202:205], v[36:39]
	v_mfma_f32_16x16x32_bf16 v[36:39], v[144:147], v[198:201], v[36:39]
	v_mfma_f32_16x16x32_bf16 v[20:23], v[144:147], v[206:209], v[20:23]
	v_mfma_f32_16x16x32_bf16 v[20:23], v[148:151], v[210:213], v[20:23]
	v_mfma_f32_16x16x32_bf16 v[16:19], v[176:179], v[210:213], v[16:19]
	v_mfma_f32_16x16x32_bf16 v[16:19], v[172:175], v[206:209], v[16:19]
	v_mfma_f32_16x16x32_bf16 v[0:3], v[172:175], v[214:217], v[0:3]
	v_mfma_f32_16x16x32_bf16 v[0:3], v[176:179], v[218:221], v[0:3]
	v_mfma_f32_16x16x32_bf16 v[4:7], v[148:151], v[218:221], v[4:7]
	v_mfma_f32_16x16x32_bf16 v[4:7], v[144:147], v[214:217], v[4:7]
	s_barrier
	s_setprio 0
	s_add_i32 s83, s83, 2
	s_add_u32 s81, s81, 0x100
	s_addc_u32 s82, s82, 0
	s_cmp_gt_u32 s83, 41
	s_mov_b64 s[54:55], s[56:57]
	s_cbranch_scc0 .LBB0_159
	s_and_b64 vcc, exec, s[30:31]
	s_cbranch_vccz .LBB0_162
	s_barrier

.LBB0_254:
	s_ashr_i32 s61, s60, 31
	s_lshl_b64 s[62:63], s[60:61], 19
	s_add_u32 s62, s35, s62
	s_addc_u32 s63, s47, s63
	s_and_b64 s[64:65], s[12:13], exec
	s_cselect_b32 s3, s63, s69
	s_cselect_b32 s61, s62, s68
	s_ashr_i32 s59, s58, 31
	s_lshl_b64 s[64:65], s[58:59], 19
	s_add_u32 s64, s49, s64
	s_addc_u32 s65, s70, s65
	s_and_b64 s[92:93], s[12:13], exec
	s_cselect_b32 s91, s65, s67
	s_cselect_b32 s92, s64, s66
	s_lshl_b32 s59, s14, 8
	v_add_u32_e32 v0, s59, v182
	s_add_u32 s93, s66, 0x100
	s_waitcnt lgkmcnt(0)
	v_ashrrev_i32_e32 v1, 31, v0
	s_addc_u32 s94, s67, 0
	v_lshl_add_u64 v[72:73], v[0:1], 4, s[26:27]
	s_add_u32 s14, s68, 0x40080
	s_addc_u32 s15, s69, 0
	s_mov_b32 s95, -2
	s_mov_b64 s[66:67], 0
	s_cmp_eq_u32 s90, 1
	s_cbranch_scc1 .Lfa_2
	v_add_u32_e32 v74, s83, v181
	ds_read_b128 v[88:91], v74
	v_xor_b32_e32 v253, 64, v74
	ds_read_b128 v[108:111], v253
	ds_read_b128 v[128:131], v74 offset:2048
	ds_read_b128 v[144:147], v253 offset:2048
	v_add_u32_e32 v74, s84, v181
	ds_read_b128 v[148:151], v74
	v_xor_b32_e32 v253, 64, v74
	ds_read_b128 v[152:155], v253
	ds_read_b128 v[176:179], v74 offset:2048
	ds_read_b128 v[190:193], v253 offset:2048
	s_add_u32 s68, s14, 0xfffc0080
	s_addc_u32 s69, s15, -1
	s_and_b64 s[66:67], s[66:67], exec
	s_cselect_b32 s69, s3, s69
	s_cselect_b32 s68, s61, s68
	s_cselect_b32 s67, s91, s94
	s_cselect_b32 s66, s92, s93
	v_lshl_add_u64 v[74:75], s[14:15], 0, v[170:171]
	s_add_i32 m0, s74, 0xc000
	ds_read_b128 v[194:197], v187
	v_xor_b32_e32 v253, 64, v187
	ds_read_b128 v[198:201], v253
	ds_read_b128 v[202:205], v187 offset:2048
	ds_read_b128 v[206:209], v253 offset:2048
	ds_read_b128 v[210:213], v187 offset:4096
	ds_read_b128 v[214:217], v253 offset:4096
	ds_read_b128 v[218:221], v187 offset:6144
	ds_read_b128 v[222:225], v253 offset:6144
	global_load_lds_dwordx4 v[74:75], off
	v_lshl_add_u64 v[74:75], s[14:15], 0, v[168:169]
	s_add_i32 m0, s74, 0xe000
	s_nop 0
	global_load_lds_dwordx4 v[74:75], off
	s_waitcnt vmcnt(24)
	s_waitcnt lgkmcnt(0)
	s_setprio 1
	s_barrier
	v_mfma_f32_16x16x32_bf16 v[140:143], v[88:91], v[194:197], 0
	v_mfma_f32_16x16x32_bf16 v[136:139], v[128:131], v[194:197], 0
	v_mfma_f32_16x16x32_bf16 v[120:123], v[88:91], v[202:205], 0
	v_mfma_f32_16x16x32_bf16 v[116:119], v[128:131], v[202:205], 0
	v_mfma_f32_16x16x32_bf16 v[100:103], v[88:91], v[210:213], 0
	v_mfma_f32_16x16x32_bf16 v[96:99], v[128:131], v[210:213], 0
	v_mfma_f32_16x16x32_bf16 v[80:83], v[88:91], v[218:221], 0
	v_mfma_f32_16x16x32_bf16 v[74:77], v[128:131], v[218:221], 0
	v_mfma_f32_16x16x32_bf16 v[140:143], v[108:111], v[198:201], v[140:143]
	v_mfma_f32_16x16x32_bf16 v[136:139], v[144:147], v[198:201], v[136:139]
	v_mfma_f32_16x16x32_bf16 v[120:123], v[108:111], v[206:209], v[120:123]
	v_mfma_f32_16x16x32_bf16 v[116:119], v[144:147], v[206:209], v[116:119]
	v_mfma_f32_16x16x32_bf16 v[100:103], v[108:111], v[214:217], v[100:103]
	v_mfma_f32_16x16x32_bf16 v[96:99], v[144:147], v[214:217], v[96:99]
	v_mfma_f32_16x16x32_bf16 v[80:83], v[108:111], v[222:225], v[80:83]
	v_mfma_f32_16x16x32_bf16 v[74:77], v[144:147], v[222:225], v[74:77]
	s_setprio 0
	s_setprio 1
	v_mfma_f32_16x16x32_bf16 v[132:135], v[148:151], v[194:197], 0
	v_mfma_f32_16x16x32_bf16 v[124:127], v[176:179], v[194:197], 0
	v_mfma_f32_16x16x32_bf16 v[112:115], v[148:151], v[202:205], 0
	v_mfma_f32_16x16x32_bf16 v[104:107], v[176:179], v[202:205], 0
	v_mfma_f32_16x16x32_bf16 v[92:95], v[148:151], v[210:213], 0
	v_mfma_f32_16x16x32_bf16 v[84:87], v[176:179], v[210:213], 0
	v_mfma_f32_16x16x32_bf16 v[68:71], v[148:151], v[218:221], 0
	v_mfma_f32_16x16x32_bf16 v[64:67], v[176:179], v[218:221], 0
	v_mfma_f32_16x16x32_bf16 v[132:135], v[152:155], v[198:201], v[132:135]
	v_mfma_f32_16x16x32_bf16 v[124:127], v[190:193], v[198:201], v[124:127]
	v_mfma_f32_16x16x32_bf16 v[112:115], v[152:155], v[206:209], v[112:115]
	v_mfma_f32_16x16x32_bf16 v[104:107], v[190:193], v[206:209], v[104:107]
	v_mfma_f32_16x16x32_bf16 v[92:95], v[152:155], v[214:217], v[92:95]
	v_mfma_f32_16x16x32_bf16 v[84:87], v[190:193], v[214:217], v[84:87]
	v_mfma_f32_16x16x32_bf16 v[68:71], v[152:155], v[222:225], v[68:71]
	v_mfma_f32_16x16x32_bf16 v[64:67], v[190:193], v[222:225], v[64:67]
	s_barrier
	s_setprio 0
	s_add_i32 s96, s83, s71
	v_lshl_add_u64 v[226:227], s[66:67], 0, v[162:163]
	s_mov_b32 m0, s96
	s_nop 0
	global_load_lds_dwordx4 v[226:227], off
	s_add_i32 m0, s96, 0x2000
	s_add_u32 s96, s66, 0x40000
	v_lshl_add_u64 v[228:229], s[66:67], 0, v[166:167]
	s_addc_u32 s97, s67, 0
	s_add_i32 vcc_lo, s84, s71
	global_load_lds_dwordx4 v[228:229], off
	v_lshl_add_u64 v[78:79], s[96:97], 0, v[162:163]
	s_mov_b32 m0, vcc_lo
	v_lshl_add_u64 v[230:231], s[68:69], 0, v[160:161]
	global_load_lds_dwordx4 v[78:79], off
	v_lshl_add_u64 v[78:79], s[96:97], 0, v[166:167]
	s_add_i32 m0, vcc_lo, 0x2000
	v_lshl_add_u64 v[232:233], s[68:69], 0, v[164:165]
	global_load_lds_dwordx4 v[78:79], off
	s_mov_b32 m0, s74
	s_nop 0
	global_load_lds_dwordx4 v[230:231], off
	s_mov_b32 m0, s75
	s_nop 0
	global_load_lds_dwordx4 v[232:233], off
	ds_read_b128 v[194:197], v187 offset:16384
	v_xor_b32_e32 v253, 64, v187
	ds_read_b128 v[198:201], v253 offset:16384
	ds_read_b128 v[202:205], v187 offset:18432
	ds_read_b128 v[206:209], v253 offset:18432
	ds_read_b128 v[210:213], v187 offset:20480
	ds_read_b128 v[214:217], v253 offset:20480
	ds_read_b128 v[218:221], v187 offset:22528
	ds_read_b128 v[222:225], v253 offset:22528
	s_waitcnt vmcnt(24)
	s_waitcnt lgkmcnt(0)
	s_setprio 1
	s_barrier
	v_mfma_f32_16x16x32_bf16 v[60:63], v[88:91], v[194:197], 0
	v_mfma_f32_16x16x32_bf16 v[56:59], v[128:131], v[194:197], 0
	v_mfma_f32_16x16x32_bf16 v[44:47], v[88:91], v[202:205], 0
	v_mfma_f32_16x16x32_bf16 v[40:43], v[128:131], v[202:205], 0
	v_mfma_f32_16x16x32_bf16 v[28:31], v[88:91], v[210:213], 0
	v_mfma_f32_16x16x32_bf16 v[24:27], v[128:131], v[210:213], 0
	v_mfma_f32_16x16x32_bf16 v[12:15], v[88:91], v[218:221], 0
	v_mfma_f32_16x16x32_bf16 v[8:11], v[128:131], v[218:221], 0
	v_mfma_f32_16x16x32_bf16 v[60:63], v[108:111], v[198:201], v[60:63]
	v_mfma_f32_16x16x32_bf16 v[56:59], v[144:147], v[198:201], v[56:59]
	v_mfma_f32_16x16x32_bf16 v[44:47], v[108:111], v[206:209], v[44:47]
	v_mfma_f32_16x16x32_bf16 v[40:43], v[144:147], v[206:209], v[40:43]
	v_mfma_f32_16x16x32_bf16 v[28:31], v[108:111], v[214:217], v[28:31]
	v_mfma_f32_16x16x32_bf16 v[24:27], v[144:147], v[214:217], v[24:27]
	v_mfma_f32_16x16x32_bf16 v[12:15], v[108:111], v[222:225], v[12:15]
	v_mfma_f32_16x16x32_bf16 v[8:11], v[144:147], v[222:225], v[8:11]
	s_setprio 0
	s_setprio 1
	v_mfma_f32_16x16x32_bf16 v[52:55], v[148:151], v[194:197], 0
	v_mfma_f32_16x16x32_bf16 v[48:51], v[176:179], v[194:197], 0
	v_mfma_f32_16x16x32_bf16 v[36:39], v[148:151], v[202:205], 0
	v_mfma_f32_16x16x32_bf16 v[32:35], v[176:179], v[202:205], 0
	v_mfma_f32_16x16x32_bf16 v[20:23], v[148:151], v[210:213], 0
	v_mfma_f32_16x16x32_bf16 v[16:19], v[176:179], v[210:213], 0
	v_mfma_f32_16x16x32_bf16 v[4:7], v[148:151], v[218:221], 0
	v_mfma_f32_16x16x32_bf16 v[0:3], v[176:179], v[218:221], 0
	v_mfma_f32_16x16x32_bf16 v[52:55], v[152:155], v[198:201], v[52:55]
	v_mfma_f32_16x16x32_bf16 v[48:51], v[190:193], v[198:201], v[48:51]
	v_mfma_f32_16x16x32_bf16 v[36:39], v[152:155], v[206:209], v[36:39]
	v_mfma_f32_16x16x32_bf16 v[32:35], v[190:193], v[206:209], v[32:35]
	v_mfma_f32_16x16x32_bf16 v[20:23], v[152:155], v[214:217], v[20:23]
	v_mfma_f32_16x16x32_bf16 v[16:19], v[190:193], v[214:217], v[16:19]
	v_mfma_f32_16x16x32_bf16 v[4:7], v[152:155], v[222:225], v[4:7]
	v_mfma_f32_16x16x32_bf16 v[0:3], v[190:193], v[222:225], v[0:3]
	s_barrier
	s_setprio 0
	s_add_i32 s96, 0, 0x18000
	v_add_u32_e32 v78, s96, v181
	s_add_i32 s97, 0, 0x1c000
	ds_read_b128 v[88:91], v78
	v_xor_b32_e32 v253, 64, v78
	ds_read_b128 v[108:111], v253
	ds_read_b128 v[128:131], v78 offset:2048
	ds_read_b128 v[144:147], v253 offset:2048
	v_add_u32_e32 v78, s97, v181
	ds_read_b128 v[148:151], v78
	v_xor_b32_e32 v253, 64, v78
	ds_read_b128 v[152:155], v253
	ds_read_b128 v[176:179], v78 offset:2048
	ds_read_b128 v[190:193], v253 offset:2048
	s_add_u32 s68, s68, 0x40000
	s_addc_u32 s69, s69, 0
	s_mov_b32 m0, s76
	v_lshl_add_u64 v[78:79], s[68:69], 0, v[160:161]
	ds_read_b128 v[194:197], v187 offset:32768
	v_xor_b32_e32 v253, 64, v187
	ds_read_b128 v[198:201], v253 offset:32768
	ds_read_b128 v[202:205], v187 offset:34816
	ds_read_b128 v[206:209], v253 offset:34816
	ds_read_b128 v[210:213], v187 offset:36864
	ds_read_b128 v[214:217], v253 offset:36864
	ds_read_b128 v[218:221], v187 offset:38912
	ds_read_b128 v[222:225], v253 offset:38912
	global_load_lds_dwordx4 v[78:79], off
	v_lshl_add_u64 v[78:79], s[68:69], 0, v[164:165]
	s_mov_b32 m0, s77
	s_nop 0
	global_load_lds_dwordx4 v[78:79], off
	s_waitcnt vmcnt(8)
	s_waitcnt lgkmcnt(0)
	s_setprio 1
	s_barrier
	v_mfma_f32_16x16x32_bf16 v[140:143], v[88:91], v[194:197], v[140:143]
	v_mfma_f32_16x16x32_bf16 v[136:139], v[128:131], v[194:197], v[136:139]
	v_mfma_f32_16x16x32_bf16 v[120:123], v[88:91], v[202:205], v[120:123]
	v_mfma_f32_16x16x32_bf16 v[116:119], v[128:131], v[202:205], v[116:119]
	v_mfma_f32_16x16x32_bf16 v[100:103], v[88:91], v[210:213], v[100:103]
	v_mfma_f32_16x16x32_bf16 v[96:99], v[128:131], v[210:213], v[96:99]
	v_mfma_f32_16x16x32_bf16 v[78:81], v[88:91], v[218:221], v[80:83]
	v_mfma_f32_16x16x32_bf16 v[74:77], v[128:131], v[218:221], v[74:77]
	v_mfma_f32_16x16x32_bf16 v[140:143], v[108:111], v[198:201], v[140:143]
	v_mfma_f32_16x16x32_bf16 v[136:139], v[144:147], v[198:201], v[136:139]
	v_mfma_f32_16x16x32_bf16 v[120:123], v[108:111], v[206:209], v[120:123]
	v_mfma_f32_16x16x32_bf16 v[116:119], v[144:147], v[206:209], v[116:119]
	v_mfma_f32_16x16x32_bf16 v[100:103], v[108:111], v[214:217], v[100:103]
	v_mfma_f32_16x16x32_bf16 v[96:99], v[144:147], v[214:217], v[96:99]
	v_mfma_f32_16x16x32_bf16 v[80:83], v[108:111], v[222:225], v[78:81]
	v_mfma_f32_16x16x32_bf16 v[76:79], v[144:147], v[222:225], v[74:77]
	s_setprio 0
	s_setprio 1
	v_mfma_f32_16x16x32_bf16 v[132:135], v[148:151], v[194:197], v[132:135]
	v_mfma_f32_16x16x32_bf16 v[132:135], v[152:155], v[198:201], v[132:135]
	v_mfma_f32_16x16x32_bf16 v[124:127], v[190:193], v[198:201], v[124:127]
	v_mfma_f32_16x16x32_bf16 v[124:127], v[176:179], v[194:197], v[124:127]
	v_mfma_f32_16x16x32_bf16 v[104:107], v[176:179], v[202:205], v[104:107]
	v_mfma_f32_16x16x32_bf16 v[104:107], v[190:193], v[206:209], v[104:107]
	v_mfma_f32_16x16x32_bf16 v[112:115], v[152:155], v[206:209], v[112:115]
	v_mfma_f32_16x16x32_bf16 v[112:115], v[148:151], v[202:205], v[112:115]
	v_mfma_f32_16x16x32_bf16 v[92:95], v[148:151], v[210:213], v[92:95]
	v_mfma_f32_16x16x32_bf16 v[92:95], v[152:155], v[214:217], v[92:95]
	v_mfma_f32_16x16x32_bf16 v[84:87], v[190:193], v[214:217], v[84:87]
	v_mfma_f32_16x16x32_bf16 v[84:87], v[176:179], v[210:213], v[84:87]
	v_mfma_f32_16x16x32_bf16 v[64:67], v[176:179], v[218:221], v[64:67]
	v_mfma_f32_16x16x32_bf16 v[64:67], v[190:193], v[222:225], v[64:67]
	v_mfma_f32_16x16x32_bf16 v[68:71], v[152:155], v[222:225], v[68:71]
	v_mfma_f32_16x16x32_bf16 v[68:71], v[148:151], v[218:221], v[68:71]
	s_barrier
	s_setprio 0
	s_add_i32 s68, s96, s71
	v_lshl_add_u64 v[74:75], v[226:227], 0, s[28:29]
	s_mov_b32 m0, s68
	s_nop 0
	global_load_lds_dwordx4 v[74:75], off
	s_add_i32 m0, s68, 0x2000
	s_add_u32 s66, s66, 0x40080
	v_lshl_add_u64 v[74:75], v[228:229], 0, s[28:29]
	s_addc_u32 s67, s67, 0
	s_add_i32 s68, s97, s71
	global_load_lds_dwordx4 v[74:75], off
	v_lshl_add_u64 v[74:75], s[66:67], 0, v[162:163]
	s_mov_b32 m0, s68
	s_nop 0
	global_load_lds_dwordx4 v[74:75], off
	v_lshl_add_u64 v[74:75], s[66:67], 0, v[166:167]
	s_add_i32 m0, s68, 0x2000
	s_nop 0
	global_load_lds_dwordx4 v[74:75], off
	v_lshl_add_u64 v[74:75], v[230:231], 0, s[28:29]
	s_mov_b32 m0, s78
	s_nop 0
	global_load_lds_dwordx4 v[74:75], off
	v_lshl_add_u64 v[74:75], v[232:233], 0, s[28:29]
	s_mov_b32 m0, s79
	s_nop 0
	global_load_lds_dwordx4 v[74:75], off
	ds_read_b128 v[194:197], v187 offset:49152
	v_xor_b32_e32 v253, 64, v187
	ds_read_b128 v[198:201], v253 offset:49152
	ds_read_b128 v[202:205], v187 offset:51200
	ds_read_b128 v[206:209], v253 offset:51200
	ds_read_b128 v[210:213], v187 offset:53248
	ds_read_b128 v[214:217], v253 offset:53248
	ds_read_b128 v[218:221], v187 offset:55296
	ds_read_b128 v[222:225], v253 offset:55296
	s_waitcnt vmcnt(8)
	s_waitcnt lgkmcnt(0)
	s_setprio 1
	s_barrier
	v_mfma_f32_16x16x32_bf16 v[60:63], v[88:91], v[194:197], v[60:63]
	v_mfma_f32_16x16x32_bf16 v[60:63], v[108:111], v[198:201], v[60:63]
	v_mfma_f32_16x16x32_bf16 v[56:59], v[144:147], v[198:201], v[56:59]
	v_mfma_f32_16x16x32_bf16 v[56:59], v[128:131], v[194:197], v[56:59]
	v_mfma_f32_16x16x32_bf16 v[40:43], v[128:131], v[202:205], v[40:43]
	v_mfma_f32_16x16x32_bf16 v[40:43], v[144:147], v[206:209], v[40:43]
	v_mfma_f32_16x16x32_bf16 v[44:47], v[108:111], v[206:209], v[44:47]
	v_mfma_f32_16x16x32_bf16 v[44:47], v[88:91], v[202:205], v[44:47]
	v_mfma_f32_16x16x32_bf16 v[28:31], v[88:91], v[210:213], v[28:31]
	v_mfma_f32_16x16x32_bf16 v[28:31], v[108:111], v[214:217], v[28:31]
	v_mfma_f32_16x16x32_bf16 v[24:27], v[144:147], v[214:217], v[24:27]
	v_mfma_f32_16x16x32_bf16 v[24:27], v[128:131], v[210:213], v[24:27]
	v_mfma_f32_16x16x32_bf16 v[8:11], v[128:131], v[218:221], v[8:11]
	v_mfma_f32_16x16x32_bf16 v[8:11], v[144:147], v[222:225], v[8:11]
	v_mfma_f32_16x16x32_bf16 v[12:15], v[108:111], v[222:225], v[12:15]
	v_mfma_f32_16x16x32_bf16 v[12:15], v[88:91], v[218:221], v[12:15]
	s_setprio 0
	s_setprio 1
	v_mfma_f32_16x16x32_bf16 v[52:55], v[148:151], v[194:197], v[52:55]
	v_mfma_f32_16x16x32_bf16 v[52:55], v[152:155], v[198:201], v[52:55]
	v_mfma_f32_16x16x32_bf16 v[48:51], v[190:193], v[198:201], v[48:51]
	v_mfma_f32_16x16x32_bf16 v[48:51], v[176:179], v[194:197], v[48:51]
	v_mfma_f32_16x16x32_bf16 v[32:35], v[176:179], v[202:205], v[32:35]
	v_mfma_f32_16x16x32_bf16 v[32:35], v[190:193], v[206:209], v[32:35]
	v_mfma_f32_16x16x32_bf16 v[36:39], v[152:155], v[206:209], v[36:39]
	v_mfma_f32_16x16x32_bf16 v[36:39], v[148:151], v[202:205], v[36:39]
	v_mfma_f32_16x16x32_bf16 v[20:23], v[148:151], v[210:213], v[20:23]
	v_mfma_f32_16x16x32_bf16 v[20:23], v[152:155], v[214:217], v[20:23]
	v_mfma_f32_16x16x32_bf16 v[16:19], v[190:193], v[214:217], v[16:19]
	v_mfma_f32_16x16x32_bf16 v[16:19], v[176:179], v[210:213], v[16:19]
	v_mfma_f32_16x16x32_bf16 v[0:3], v[176:179], v[218:221], v[0:3]
	v_mfma_f32_16x16x32_bf16 v[0:3], v[190:193], v[222:225], v[0:3]
	v_mfma_f32_16x16x32_bf16 v[4:7], v[152:155], v[222:225], v[4:7]
	v_mfma_f32_16x16x32_bf16 v[4:7], v[148:151], v[218:221], v[4:7]
	s_barrier
	s_setprio 0
	s_add_i32 s95, s95, 2
	s_add_u32 s93, s93, 0x100
	s_addc_u32 s94, s94, 0
	s_add_u32 s14, s14, 0x100
	s_addc_u32 s15, s15, 0
	s_branch .LBB0_256
.Lfa_2:
	v_add_u32_e32 v74, s83, v181
	ds_read_b128 v[88:91], v74
	v_xor_b32_e32 v253, 64, v74
	ds_read_b128 v[108:111], v253
	ds_read_b128 v[128:131], v74 offset:2048
	ds_read_b128 v[144:147], v253 offset:2048
	v_add_u32_e32 v74, s84, v181
	ds_read_b128 v[148:151], v74
	v_xor_b32_e32 v253, 64, v74
	ds_read_b128 v[152:155], v253
	ds_read_b128 v[176:179], v74 offset:2048
	ds_read_b128 v[190:193], v253 offset:2048
	s_add_u32 s68, s14, 0xfffc0080
	s_addc_u32 s69, s15, -1
	s_and_b64 s[66:67], s[66:67], exec
	s_cselect_b32 s69, s3, s69
	s_cselect_b32 s68, s61, s68
	s_cselect_b32 s67, s91, s94
	s_cselect_b32 s66, s92, s93
	v_lshl_add_u64 v[74:75], s[14:15], 0, v[170:171]
	s_add_i32 m0, s74, 0xc000
	ds_read_b128 v[194:197], v187
	v_xor_b32_e32 v253, 64, v187
	ds_read_b128 v[198:201], v253
	ds_read_b128 v[202:205], v187 offset:2048
	ds_read_b128 v[206:209], v253 offset:2048
	ds_read_b128 v[210:213], v187 offset:4096
	ds_read_b128 v[214:217], v253 offset:4096
	ds_read_b128 v[218:221], v187 offset:6144
	ds_read_b128 v[222:225], v253 offset:6144
	global_load_lds_dwordx4 v[74:75], off
	v_lshl_add_u64 v[74:75], s[14:15], 0, v[168:169]
	s_add_i32 m0, s74, 0xe000
	s_nop 0
	global_load_lds_dwordx4 v[74:75], off
	s_waitcnt vmcnt(8)
	s_waitcnt lgkmcnt(0)
	s_setprio 1
	s_barrier
	v_mfma_f32_16x16x32_bf16 v[140:143], v[88:91], v[194:197], 0
	v_mfma_f32_16x16x32_bf16 v[136:139], v[128:131], v[194:197], 0
	v_mfma_f32_16x16x32_bf16 v[120:123], v[88:91], v[202:205], 0
	v_mfma_f32_16x16x32_bf16 v[116:119], v[128:131], v[202:205], 0
	v_mfma_f32_16x16x32_bf16 v[100:103], v[88:91], v[210:213], 0
	v_mfma_f32_16x16x32_bf16 v[96:99], v[128:131], v[210:213], 0
	v_mfma_f32_16x16x32_bf16 v[80:83], v[88:91], v[218:221], 0
	v_mfma_f32_16x16x32_bf16 v[74:77], v[128:131], v[218:221], 0
	v_mfma_f32_16x16x32_bf16 v[140:143], v[108:111], v[198:201], v[140:143]
	v_mfma_f32_16x16x32_bf16 v[136:139], v[144:147], v[198:201], v[136:139]
	v_mfma_f32_16x16x32_bf16 v[120:123], v[108:111], v[206:209], v[120:123]
	v_mfma_f32_16x16x32_bf16 v[116:119], v[144:147], v[206:209], v[116:119]
	v_mfma_f32_16x16x32_bf16 v[100:103], v[108:111], v[214:217], v[100:103]
	v_mfma_f32_16x16x32_bf16 v[96:99], v[144:147], v[214:217], v[96:99]
	v_mfma_f32_16x16x32_bf16 v[80:83], v[108:111], v[222:225], v[80:83]
	v_mfma_f32_16x16x32_bf16 v[74:77], v[144:147], v[222:225], v[74:77]
	s_setprio 0
	s_setprio 1
	v_mfma_f32_16x16x32_bf16 v[132:135], v[148:151], v[194:197], 0
	v_mfma_f32_16x16x32_bf16 v[124:127], v[176:179], v[194:197], 0
	v_mfma_f32_16x16x32_bf16 v[112:115], v[148:151], v[202:205], 0
	v_mfma_f32_16x16x32_bf16 v[104:107], v[176:179], v[202:205], 0
	v_mfma_f32_16x16x32_bf16 v[92:95], v[148:151], v[210:213], 0
	v_mfma_f32_16x16x32_bf16 v[84:87], v[176:179], v[210:213], 0
	v_mfma_f32_16x16x32_bf16 v[68:71], v[148:151], v[218:221], 0
	v_mfma_f32_16x16x32_bf16 v[64:67], v[176:179], v[218:221], 0
	v_mfma_f32_16x16x32_bf16 v[132:135], v[152:155], v[198:201], v[132:135]
	v_mfma_f32_16x16x32_bf16 v[124:127], v[190:193], v[198:201], v[124:127]
	v_mfma_f32_16x16x32_bf16 v[112:115], v[152:155], v[206:209], v[112:115]
	v_mfma_f32_16x16x32_bf16 v[104:107], v[190:193], v[206:209], v[104:107]
	v_mfma_f32_16x16x32_bf16 v[92:95], v[152:155], v[214:217], v[92:95]
	v_mfma_f32_16x16x32_bf16 v[84:87], v[190:193], v[214:217], v[84:87]
	v_mfma_f32_16x16x32_bf16 v[68:71], v[152:155], v[222:225], v[68:71]
	v_mfma_f32_16x16x32_bf16 v[64:67], v[190:193], v[222:225], v[64:67]
	s_barrier
	s_setprio 0
	s_add_i32 s96, s83, s71
	v_lshl_add_u64 v[226:227], s[66:67], 0, v[162:163]
	s_mov_b32 m0, s96
	s_nop 0
	global_load_lds_dwordx4 v[226:227], off
	s_add_i32 m0, s96, 0x2000
	s_add_u32 s96, s66, 0x40000
	v_lshl_add_u64 v[228:229], s[66:67], 0, v[166:167]
	s_addc_u32 s97, s67, 0
	s_add_i32 vcc_lo, s84, s71
	global_load_lds_dwordx4 v[228:229], off
	v_lshl_add_u64 v[78:79], s[96:97], 0, v[162:163]
	s_mov_b32 m0, vcc_lo
	v_lshl_add_u64 v[230:231], s[68:69], 0, v[160:161]
	global_load_lds_dwordx4 v[78:79], off
	v_lshl_add_u64 v[78:79], s[96:97], 0, v[166:167]
	s_add_i32 m0, vcc_lo, 0x2000
	v_lshl_add_u64 v[232:233], s[68:69], 0, v[164:165]
	global_load_lds_dwordx4 v[78:79], off
	s_mov_b32 m0, s74
	s_nop 0
	global_load_lds_dwordx4 v[230:231], off
	s_mov_b32 m0, s75
	s_nop 0
	global_load_lds_dwordx4 v[232:233], off
	ds_read_b128 v[194:197], v187 offset:16384
	v_xor_b32_e32 v253, 64, v187
	ds_read_b128 v[198:201], v253 offset:16384
	ds_read_b128 v[202:205], v187 offset:18432
	ds_read_b128 v[206:209], v253 offset:18432
	ds_read_b128 v[210:213], v187 offset:20480
	ds_read_b128 v[214:217], v253 offset:20480
	ds_read_b128 v[218:221], v187 offset:22528
	ds_read_b128 v[222:225], v253 offset:22528
	s_waitcnt vmcnt(8)
	s_waitcnt lgkmcnt(0)
	s_setprio 1
	s_barrier
	v_mfma_f32_16x16x32_bf16 v[60:63], v[88:91], v[194:197], 0
	v_mfma_f32_16x16x32_bf16 v[56:59], v[128:131], v[194:197], 0
	v_mfma_f32_16x16x32_bf16 v[44:47], v[88:91], v[202:205], 0
	v_mfma_f32_16x16x32_bf16 v[40:43], v[128:131], v[202:205], 0
	v_mfma_f32_16x16x32_bf16 v[28:31], v[88:91], v[210:213], 0
	v_mfma_f32_16x16x32_bf16 v[24:27], v[128:131], v[210:213], 0
	v_mfma_f32_16x16x32_bf16 v[12:15], v[88:91], v[218:221], 0
	v_mfma_f32_16x16x32_bf16 v[8:11], v[128:131], v[218:221], 0
	v_mfma_f32_16x16x32_bf16 v[60:63], v[108:111], v[198:201], v[60:63]
	v_mfma_f32_16x16x32_bf16 v[56:59], v[144:147], v[198:201], v[56:59]
	v_mfma_f32_16x16x32_bf16 v[44:47], v[108:111], v[206:209], v[44:47]
	v_mfma_f32_16x16x32_bf16 v[40:43], v[144:147], v[206:209], v[40:43]
	v_mfma_f32_16x16x32_bf16 v[28:31], v[108:111], v[214:217], v[28:31]
	v_mfma_f32_16x16x32_bf16 v[24:27], v[144:147], v[214:217], v[24:27]
	v_mfma_f32_16x16x32_bf16 v[12:15], v[108:111], v[222:225], v[12:15]
	v_mfma_f32_16x16x32_bf16 v[8:11], v[144:147], v[222:225], v[8:11]
	s_setprio 0
	s_setprio 1
	v_mfma_f32_16x16x32_bf16 v[52:55], v[148:151], v[194:197], 0
	v_mfma_f32_16x16x32_bf16 v[48:51], v[176:179], v[194:197], 0
	v_mfma_f32_16x16x32_bf16 v[36:39], v[148:151], v[202:205], 0
	v_mfma_f32_16x16x32_bf16 v[32:35], v[176:179], v[202:205], 0
	v_mfma_f32_16x16x32_bf16 v[20:23], v[148:151], v[210:213], 0
	v_mfma_f32_16x16x32_bf16 v[16:19], v[176:179], v[210:213], 0
	v_mfma_f32_16x16x32_bf16 v[4:7], v[148:151], v[218:221], 0
	v_mfma_f32_16x16x32_bf16 v[0:3], v[176:179], v[218:221], 0
	v_mfma_f32_16x16x32_bf16 v[52:55], v[152:155], v[198:201], v[52:55]
	v_mfma_f32_16x16x32_bf16 v[48:51], v[190:193], v[198:201], v[48:51]
	v_mfma_f32_16x16x32_bf16 v[36:39], v[152:155], v[206:209], v[36:39]
	v_mfma_f32_16x16x32_bf16 v[32:35], v[190:193], v[206:209], v[32:35]
	v_mfma_f32_16x16x32_bf16 v[20:23], v[152:155], v[214:217], v[20:23]
	v_mfma_f32_16x16x32_bf16 v[16:19], v[190:193], v[214:217], v[16:19]
	v_mfma_f32_16x16x32_bf16 v[4:7], v[152:155], v[222:225], v[4:7]
	v_mfma_f32_16x16x32_bf16 v[0:3], v[190:193], v[222:225], v[0:3]
	s_barrier
	s_setprio 0
	s_add_i32 s96, 0, 0x18000
	v_add_u32_e32 v78, s96, v181
	s_add_i32 s97, 0, 0x1c000
	ds_read_b128 v[88:91], v78
	v_xor_b32_e32 v253, 64, v78
	ds_read_b128 v[108:111], v253
	ds_read_b128 v[128:131], v78 offset:2048
	ds_read_b128 v[144:147], v253 offset:2048
	v_add_u32_e32 v78, s97, v181
	ds_read_b128 v[148:151], v78
	v_xor_b32_e32 v253, 64, v78
	ds_read_b128 v[152:155], v253
	ds_read_b128 v[176:179], v78 offset:2048
	ds_read_b128 v[190:193], v253 offset:2048
	s_add_u32 s68, s68, 0x40000
	s_addc_u32 s69, s69, 0
	s_mov_b32 m0, s76
	v_lshl_add_u64 v[78:79], s[68:69], 0, v[160:161]
	ds_read_b128 v[194:197], v187 offset:32768
	v_xor_b32_e32 v253, 64, v187
	ds_read_b128 v[198:201], v253 offset:32768
	ds_read_b128 v[202:205], v187 offset:34816
	ds_read_b128 v[206:209], v253 offset:34816
	ds_read_b128 v[210:213], v187 offset:36864
	ds_read_b128 v[214:217], v253 offset:36864
	ds_read_b128 v[218:221], v187 offset:38912
	ds_read_b128 v[222:225], v253 offset:38912
	global_load_lds_dwordx4 v[78:79], off
	v_lshl_add_u64 v[78:79], s[68:69], 0, v[164:165]
	s_mov_b32 m0, s77
	s_nop 0
	global_load_lds_dwordx4 v[78:79], off
	s_waitcnt vmcnt(8)
	s_waitcnt lgkmcnt(0)
	s_setprio 1
	s_barrier
	v_mfma_f32_16x16x32_bf16 v[140:143], v[88:91], v[194:197], v[140:143]
	v_mfma_f32_16x16x32_bf16 v[136:139], v[128:131], v[194:197], v[136:139]
	v_mfma_f32_16x16x32_bf16 v[120:123], v[88:91], v[202:205], v[120:123]
	v_mfma_f32_16x16x32_bf16 v[116:119], v[128:131], v[202:205], v[116:119]
	v_mfma_f32_16x16x32_bf16 v[100:103], v[88:91], v[210:213], v[100:103]
	v_mfma_f32_16x16x32_bf16 v[96:99], v[128:131], v[210:213], v[96:99]
	v_mfma_f32_16x16x32_bf16 v[78:81], v[88:91], v[218:221], v[80:83]
	v_mfma_f32_16x16x32_bf16 v[74:77], v[128:131], v[218:221], v[74:77]
	v_mfma_f32_16x16x32_bf16 v[140:143], v[108:111], v[198:201], v[140:143]
	v_mfma_f32_16x16x32_bf16 v[136:139], v[144:147], v[198:201], v[136:139]
	v_mfma_f32_16x16x32_bf16 v[120:123], v[108:111], v[206:209], v[120:123]
	v_mfma_f32_16x16x32_bf16 v[116:119], v[144:147], v[206:209], v[116:119]
	v_mfma_f32_16x16x32_bf16 v[100:103], v[108:111], v[214:217], v[100:103]
	v_mfma_f32_16x16x32_bf16 v[96:99], v[144:147], v[214:217], v[96:99]
	v_mfma_f32_16x16x32_bf16 v[80:83], v[108:111], v[222:225], v[78:81]
	v_mfma_f32_16x16x32_bf16 v[76:79], v[144:147], v[222:225], v[74:77]
	s_setprio 0
	s_setprio 1
	v_mfma_f32_16x16x32_bf16 v[132:135], v[148:151], v[194:197], v[132:135]
	v_mfma_f32_16x16x32_bf16 v[132:135], v[152:155], v[198:201], v[132:135]
	v_mfma_f32_16x16x32_bf16 v[124:127], v[190:193], v[198:201], v[124:127]
	v_mfma_f32_16x16x32_bf16 v[124:127], v[176:179], v[194:197], v[124:127]
	v_mfma_f32_16x16x32_bf16 v[104:107], v[176:179], v[202:205], v[104:107]
	v_mfma_f32_16x16x32_bf16 v[104:107], v[190:193], v[206:209], v[104:107]
	v_mfma_f32_16x16x32_bf16 v[112:115], v[152:155], v[206:209], v[112:115]
	v_mfma_f32_16x16x32_bf16 v[112:115], v[148:151], v[202:205], v[112:115]
	v_mfma_f32_16x16x32_bf16 v[92:95], v[148:151], v[210:213], v[92:95]
	v_mfma_f32_16x16x32_bf16 v[92:95], v[152:155], v[214:217], v[92:95]
	v_mfma_f32_16x16x32_bf16 v[84:87], v[190:193], v[214:217], v[84:87]
	v_mfma_f32_16x16x32_bf16 v[84:87], v[176:179], v[210:213], v[84:87]
	v_mfma_f32_16x16x32_bf16 v[64:67], v[176:179], v[218:221], v[64:67]
	v_mfma_f32_16x16x32_bf16 v[64:67], v[190:193], v[222:225], v[64:67]
	v_mfma_f32_16x16x32_bf16 v[68:71], v[152:155], v[222:225], v[68:71]
	v_mfma_f32_16x16x32_bf16 v[68:71], v[148:151], v[218:221], v[68:71]
	s_barrier
	s_setprio 0
	s_add_i32 s68, s96, s71
	v_lshl_add_u64 v[74:75], v[226:227], 0, s[28:29]
	s_mov_b32 m0, s68
	s_nop 0
	global_load_lds_dwordx4 v[74:75], off
	s_add_i32 m0, s68, 0x2000
	s_add_u32 s66, s66, 0x40080
	v_lshl_add_u64 v[74:75], v[228:229], 0, s[28:29]
	s_addc_u32 s67, s67, 0
	s_add_i32 s68, s97, s71
	global_load_lds_dwordx4 v[74:75], off
	v_lshl_add_u64 v[74:75], s[66:67], 0, v[162:163]
	s_mov_b32 m0, s68
	s_nop 0
	global_load_lds_dwordx4 v[74:75], off
	v_lshl_add_u64 v[74:75], s[66:67], 0, v[166:167]
	s_add_i32 m0, s68, 0x2000
	s_nop 0
	global_load_lds_dwordx4 v[74:75], off
	v_lshl_add_u64 v[74:75], v[230:231], 0, s[28:29]
	s_mov_b32 m0, s78
	s_nop 0
	global_load_lds_dwordx4 v[74:75], off
	v_lshl_add_u64 v[74:75], v[232:233], 0, s[28:29]
	s_mov_b32 m0, s79
	s_nop 0
	global_load_lds_dwordx4 v[74:75], off
	ds_read_b128 v[194:197], v187 offset:49152
	v_xor_b32_e32 v253, 64, v187
	ds_read_b128 v[198:201], v253 offset:49152
	ds_read_b128 v[202:205], v187 offset:51200
	ds_read_b128 v[206:209], v253 offset:51200
	ds_read_b128 v[210:213], v187 offset:53248
	ds_read_b128 v[214:217], v253 offset:53248
	ds_read_b128 v[218:221], v187 offset:55296
	ds_read_b128 v[222:225], v253 offset:55296
	s_waitcnt vmcnt(8)
	s_waitcnt lgkmcnt(0)
	s_setprio 1
	s_barrier
	v_mfma_f32_16x16x32_bf16 v[60:63], v[88:91], v[194:197], v[60:63]
	v_mfma_f32_16x16x32_bf16 v[60:63], v[108:111], v[198:201], v[60:63]
	v_mfma_f32_16x16x32_bf16 v[56:59], v[144:147], v[198:201], v[56:59]
	v_mfma_f32_16x16x32_bf16 v[56:59], v[128:131], v[194:197], v[56:59]
	v_mfma_f32_16x16x32_bf16 v[40:43], v[128:131], v[202:205], v[40:43]
	v_mfma_f32_16x16x32_bf16 v[40:43], v[144:147], v[206:209], v[40:43]
	v_mfma_f32_16x16x32_bf16 v[44:47], v[108:111], v[206:209], v[44:47]
	v_mfma_f32_16x16x32_bf16 v[44:47], v[88:91], v[202:205], v[44:47]
	v_mfma_f32_16x16x32_bf16 v[28:31], v[88:91], v[210:213], v[28:31]
	v_mfma_f32_16x16x32_bf16 v[28:31], v[108:111], v[214:217], v[28:31]
	v_mfma_f32_16x16x32_bf16 v[24:27], v[144:147], v[214:217], v[24:27]
	v_mfma_f32_16x16x32_bf16 v[24:27], v[128:131], v[210:213], v[24:27]
	v_mfma_f32_16x16x32_bf16 v[8:11], v[128:131], v[218:221], v[8:11]
	v_mfma_f32_16x16x32_bf16 v[8:11], v[144:147], v[222:225], v[8:11]
	v_mfma_f32_16x16x32_bf16 v[12:15], v[108:111], v[222:225], v[12:15]
	v_mfma_f32_16x16x32_bf16 v[12:15], v[88:91], v[218:221], v[12:15]
	s_setprio 0
	s_setprio 1
	v_mfma_f32_16x16x32_bf16 v[52:55], v[148:151], v[194:197], v[52:55]
	v_mfma_f32_16x16x32_bf16 v[52:55], v[152:155], v[198:201], v[52:55]
	v_mfma_f32_16x16x32_bf16 v[48:51], v[190:193], v[198:201], v[48:51]
	v_mfma_f32_16x16x32_bf16 v[48:51], v[176:179], v[194:197], v[48:51]
	v_mfma_f32_16x16x32_bf16 v[32:35], v[176:179], v[202:205], v[32:35]
	v_mfma_f32_16x16x32_bf16 v[32:35], v[190:193], v[206:209], v[32:35]
	v_mfma_f32_16x16x32_bf16 v[36:39], v[152:155], v[206:209], v[36:39]
	v_mfma_f32_16x16x32_bf16 v[36:39], v[148:151], v[202:205], v[36:39]
	v_mfma_f32_16x16x32_bf16 v[20:23], v[148:151], v[210:213], v[20:23]
	v_mfma_f32_16x16x32_bf16 v[20:23], v[152:155], v[214:217], v[20:23]
	v_mfma_f32_16x16x32_bf16 v[16:19], v[190:193], v[214:217], v[16:19]
	v_mfma_f32_16x16x32_bf16 v[16:19], v[176:179], v[210:213], v[16:19]
	v_mfma_f32_16x16x32_bf16 v[0:3], v[176:179], v[218:221], v[0:3]
	v_mfma_f32_16x16x32_bf16 v[0:3], v[190:193], v[222:225], v[0:3]
	v_mfma_f32_16x16x32_bf16 v[4:7], v[152:155], v[222:225], v[4:7]
	v_mfma_f32_16x16x32_bf16 v[4:7], v[148:151], v[218:221], v[4:7]
	s_barrier
	s_setprio 0
	s_add_i32 s95, s95, 2
	s_add_u32 s93, s93, 0x100
	s_addc_u32 s94, s94, 0
	s_add_u32 s14, s14, 0x100
	s_addc_u32 s15, s15, 0
	s_branch .LBB0_256
.LBB0_255:
	v_add_u32_e32 v74, s83, v181
	ds_read_b128 v[88:91], v74
	v_xor_b32_e32 v253, 64, v74
	ds_read_b128 v[108:111], v253
	ds_read_b128 v[128:131], v74 offset:2048
	ds_read_b128 v[144:147], v253 offset:2048
	v_add_u32_e32 v74, s84, v181
	ds_read_b128 v[148:151], v74
	v_xor_b32_e32 v253, 64, v74
	ds_read_b128 v[152:155], v253
	ds_read_b128 v[176:179], v74 offset:2048
	ds_read_b128 v[190:193], v253 offset:2048
	s_add_u32 s68, s14, 0xfffc0080
	s_addc_u32 s69, s15, -1
	s_and_b64 s[66:67], s[66:67], exec
	s_cselect_b32 s69, s3, s69
	s_cselect_b32 s68, s61, s68
	s_cselect_b32 s67, s91, s94
	s_cselect_b32 s66, s92, s93
	v_lshl_add_u64 v[74:75], s[14:15], 0, v[170:171]
	s_add_i32 m0, s74, 0xc000
	ds_read_b128 v[194:197], v187
	v_xor_b32_e32 v253, 64, v187
	ds_read_b128 v[198:201], v253
	ds_read_b128 v[202:205], v187 offset:2048
	ds_read_b128 v[206:209], v253 offset:2048
	ds_read_b128 v[210:213], v187 offset:4096
	ds_read_b128 v[214:217], v253 offset:4096
	ds_read_b128 v[218:221], v187 offset:6144
	ds_read_b128 v[222:225], v253 offset:6144
	global_load_lds_dwordx4 v[74:75], off
	v_lshl_add_u64 v[74:75], s[14:15], 0, v[168:169]
	s_add_i32 m0, s74, 0xe000
	s_nop 0
	global_load_lds_dwordx4 v[74:75], off
	s_waitcnt vmcnt(8)
	s_waitcnt lgkmcnt(0)
	s_setprio 1
	s_barrier
	v_mfma_f32_16x16x32_bf16 v[140:143], v[88:91], v[194:197], v[140:143]
	v_mfma_f32_16x16x32_bf16 v[136:139], v[128:131], v[194:197], v[136:139]
	v_mfma_f32_16x16x32_bf16 v[120:123], v[88:91], v[202:205], v[120:123]
	v_mfma_f32_16x16x32_bf16 v[116:119], v[128:131], v[202:205], v[116:119]
	v_mfma_f32_16x16x32_bf16 v[100:103], v[88:91], v[210:213], v[100:103]
	v_mfma_f32_16x16x32_bf16 v[96:99], v[128:131], v[210:213], v[96:99]
	v_mfma_f32_16x16x32_bf16 v[80:83], v[88:91], v[218:221], v[80:83]
	v_mfma_f32_16x16x32_bf16 v[74:77], v[128:131], v[218:221], v[76:79]
	v_mfma_f32_16x16x32_bf16 v[140:143], v[108:111], v[198:201], v[140:143]
	v_mfma_f32_16x16x32_bf16 v[136:139], v[144:147], v[198:201], v[136:139]
	v_mfma_f32_16x16x32_bf16 v[120:123], v[108:111], v[206:209], v[120:123]
	v_mfma_f32_16x16x32_bf16 v[116:119], v[144:147], v[206:209], v[116:119]
	v_mfma_f32_16x16x32_bf16 v[100:103], v[108:111], v[214:217], v[100:103]
	v_mfma_f32_16x16x32_bf16 v[96:99], v[144:147], v[214:217], v[96:99]
	v_mfma_f32_16x16x32_bf16 v[80:83], v[108:111], v[222:225], v[80:83]
	v_mfma_f32_16x16x32_bf16 v[74:77], v[144:147], v[222:225], v[74:77]
	s_setprio 0
	s_setprio 1
	v_mfma_f32_16x16x32_bf16 v[132:135], v[148:151], v[194:197], v[132:135]
	v_mfma_f32_16x16x32_bf16 v[132:135], v[152:155], v[198:201], v[132:135]
	v_mfma_f32_16x16x32_bf16 v[124:127], v[190:193], v[198:201], v[124:127]
	v_mfma_f32_16x16x32_bf16 v[124:127], v[176:179], v[194:197], v[124:127]
	v_mfma_f32_16x16x32_bf16 v[104:107], v[176:179], v[202:205], v[104:107]
	v_mfma_f32_16x16x32_bf16 v[104:107], v[190:193], v[206:209], v[104:107]
	v_mfma_f32_16x16x32_bf16 v[112:115], v[152:155], v[206:209], v[112:115]
	v_mfma_f32_16x16x32_bf16 v[112:115], v[148:151], v[202:205], v[112:115]
	v_mfma_f32_16x16x32_bf16 v[92:95], v[148:151], v[210:213], v[92:95]
	v_mfma_f32_16x16x32_bf16 v[92:95], v[152:155], v[214:217], v[92:95]
	v_mfma_f32_16x16x32_bf16 v[84:87], v[190:193], v[214:217], v[84:87]
	v_mfma_f32_16x16x32_bf16 v[84:87], v[176:179], v[210:213], v[84:87]
	v_mfma_f32_16x16x32_bf16 v[64:67], v[176:179], v[218:221], v[64:67]
	v_mfma_f32_16x16x32_bf16 v[64:67], v[190:193], v[222:225], v[64:67]
	v_mfma_f32_16x16x32_bf16 v[68:71], v[152:155], v[222:225], v[68:71]
	v_mfma_f32_16x16x32_bf16 v[68:71], v[148:151], v[218:221], v[68:71]
	s_barrier
	s_setprio 0
	s_add_i32 s96, s83, s71
	v_lshl_add_u64 v[226:227], s[66:67], 0, v[162:163]
	s_mov_b32 m0, s96
	s_nop 0
	global_load_lds_dwordx4 v[226:227], off
	s_add_i32 m0, s96, 0x2000
	s_add_u32 s96, s66, 0x40000
	v_lshl_add_u64 v[228:229], s[66:67], 0, v[166:167]
	s_addc_u32 s97, s67, 0
	s_add_i32 vcc_lo, s84, s71
	global_load_lds_dwordx4 v[228:229], off
	v_lshl_add_u64 v[78:79], s[96:97], 0, v[162:163]
	s_mov_b32 m0, vcc_lo
	v_lshl_add_u64 v[230:231], s[68:69], 0, v[160:161]
	global_load_lds_dwordx4 v[78:79], off
	v_lshl_add_u64 v[78:79], s[96:97], 0, v[166:167]
	s_add_i32 m0, vcc_lo, 0x2000
	v_lshl_add_u64 v[232:233], s[68:69], 0, v[164:165]
	global_load_lds_dwordx4 v[78:79], off
	s_mov_b32 m0, s74
	s_nop 0
	global_load_lds_dwordx4 v[230:231], off
	s_mov_b32 m0, s75
	s_nop 0
	global_load_lds_dwordx4 v[232:233], off
	ds_read_b128 v[194:197], v187 offset:16384
	v_xor_b32_e32 v253, 64, v187
	ds_read_b128 v[198:201], v253 offset:16384
	ds_read_b128 v[202:205], v187 offset:18432
	ds_read_b128 v[206:209], v253 offset:18432
	ds_read_b128 v[210:213], v187 offset:20480
	ds_read_b128 v[214:217], v253 offset:20480
	ds_read_b128 v[218:221], v187 offset:22528
	ds_read_b128 v[222:225], v253 offset:22528
	s_waitcnt vmcnt(8)
	s_waitcnt lgkmcnt(0)
	s_setprio 1
	s_barrier
	v_mfma_f32_16x16x32_bf16 v[60:63], v[88:91], v[194:197], v[60:63]
	v_mfma_f32_16x16x32_bf16 v[60:63], v[108:111], v[198:201], v[60:63]
	v_mfma_f32_16x16x32_bf16 v[56:59], v[144:147], v[198:201], v[56:59]
	v_mfma_f32_16x16x32_bf16 v[56:59], v[128:131], v[194:197], v[56:59]
	v_mfma_f32_16x16x32_bf16 v[40:43], v[128:131], v[202:205], v[40:43]
	v_mfma_f32_16x16x32_bf16 v[40:43], v[144:147], v[206:209], v[40:43]
	v_mfma_f32_16x16x32_bf16 v[44:47], v[108:111], v[206:209], v[44:47]
	v_mfma_f32_16x16x32_bf16 v[44:47], v[88:91], v[202:205], v[44:47]
	v_mfma_f32_16x16x32_bf16 v[28:31], v[88:91], v[210:213], v[28:31]
	v_mfma_f32_16x16x32_bf16 v[28:31], v[108:111], v[214:217], v[28:31]
	v_mfma_f32_16x16x32_bf16 v[24:27], v[144:147], v[214:217], v[24:27]
	v_mfma_f32_16x16x32_bf16 v[24:27], v[128:131], v[210:213], v[24:27]
	v_mfma_f32_16x16x32_bf16 v[8:11], v[128:131], v[218:221], v[8:11]
	v_mfma_f32_16x16x32_bf16 v[8:11], v[144:147], v[222:225], v[8:11]
	v_mfma_f32_16x16x32_bf16 v[12:15], v[108:111], v[222:225], v[12:15]
	v_mfma_f32_16x16x32_bf16 v[12:15], v[88:91], v[218:221], v[12:15]
	s_setprio 0
	s_setprio 1
	v_mfma_f32_16x16x32_bf16 v[52:55], v[148:151], v[194:197], v[52:55]
	v_mfma_f32_16x16x32_bf16 v[52:55], v[152:155], v[198:201], v[52:55]
	v_mfma_f32_16x16x32_bf16 v[48:51], v[190:193], v[198:201], v[48:51]
	v_mfma_f32_16x16x32_bf16 v[48:51], v[176:179], v[194:197], v[48:51]
	v_mfma_f32_16x16x32_bf16 v[32:35], v[176:179], v[202:205], v[32:35]
	v_mfma_f32_16x16x32_bf16 v[32:35], v[190:193], v[206:209], v[32:35]
	v_mfma_f32_16x16x32_bf16 v[36:39], v[152:155], v[206:209], v[36:39]
	v_mfma_f32_16x16x32_bf16 v[36:39], v[148:151], v[202:205], v[36:39]
	v_mfma_f32_16x16x32_bf16 v[20:23], v[148:151], v[210:213], v[20:23]
	v_mfma_f32_16x16x32_bf16 v[20:23], v[152:155], v[214:217], v[20:23]
	v_mfma_f32_16x16x32_bf16 v[16:19], v[190:193], v[214:217], v[16:19]
	v_mfma_f32_16x16x32_bf16 v[16:19], v[176:179], v[210:213], v[16:19]
	v_mfma_f32_16x16x32_bf16 v[0:3], v[176:179], v[218:221], v[0:3]
	v_mfma_f32_16x16x32_bf16 v[0:3], v[190:193], v[222:225], v[0:3]
	v_mfma_f32_16x16x32_bf16 v[4:7], v[152:155], v[222:225], v[4:7]
	v_mfma_f32_16x16x32_bf16 v[4:7], v[148:151], v[218:221], v[4:7]
	s_barrier
	s_setprio 0
	s_add_i32 s96, 0, 0x18000
	v_add_u32_e32 v78, s96, v181
	s_add_i32 s97, 0, 0x1c000
	ds_read_b128 v[88:91], v78
	v_xor_b32_e32 v253, 64, v78
	ds_read_b128 v[108:111], v253
	ds_read_b128 v[128:131], v78 offset:2048
	ds_read_b128 v[144:147], v253 offset:2048
	v_add_u32_e32 v78, s97, v181
	ds_read_b128 v[148:151], v78
	v_xor_b32_e32 v253, 64, v78
	ds_read_b128 v[152:155], v253
	ds_read_b128 v[176:179], v78 offset:2048
	ds_read_b128 v[190:193], v253 offset:2048
	s_add_u32 s68, s68, 0x40000
	s_addc_u32 s69, s69, 0
	s_mov_b32 m0, s76
	v_lshl_add_u64 v[78:79], s[68:69], 0, v[160:161]
	ds_read_b128 v[194:197], v187 offset:32768
	v_xor_b32_e32 v253, 64, v187
	ds_read_b128 v[198:201], v253 offset:32768
	ds_read_b128 v[202:205], v187 offset:34816
	ds_read_b128 v[206:209], v253 offset:34816
	ds_read_b128 v[210:213], v187 offset:36864
	ds_read_b128 v[214:217], v253 offset:36864
	ds_read_b128 v[218:221], v187 offset:38912
	ds_read_b128 v[222:225], v253 offset:38912
	global_load_lds_dwordx4 v[78:79], off
	v_lshl_add_u64 v[78:79], s[68:69], 0, v[164:165]
	s_mov_b32 m0, s77
	s_nop 0
	global_load_lds_dwordx4 v[78:79], off
	s_waitcnt vmcnt(8)
	s_waitcnt lgkmcnt(0)
	s_setprio 1
	s_barrier
	v_mfma_f32_16x16x32_bf16 v[140:143], v[88:91], v[194:197], v[140:143]
	v_mfma_f32_16x16x32_bf16 v[136:139], v[128:131], v[194:197], v[136:139]
	v_mfma_f32_16x16x32_bf16 v[120:123], v[88:91], v[202:205], v[120:123]
	v_mfma_f32_16x16x32_bf16 v[116:119], v[128:131], v[202:205], v[116:119]
	v_mfma_f32_16x16x32_bf16 v[100:103], v[88:91], v[210:213], v[100:103]
	v_mfma_f32_16x16x32_bf16 v[96:99], v[128:131], v[210:213], v[96:99]
	v_mfma_f32_16x16x32_bf16 v[78:81], v[88:91], v[218:221], v[80:83]
	v_mfma_f32_16x16x32_bf16 v[74:77], v[128:131], v[218:221], v[74:77]
	v_mfma_f32_16x16x32_bf16 v[140:143], v[108:111], v[198:201], v[140:143]
	v_mfma_f32_16x16x32_bf16 v[136:139], v[144:147], v[198:201], v[136:139]
	v_mfma_f32_16x16x32_bf16 v[120:123], v[108:111], v[206:209], v[120:123]
	v_mfma_f32_16x16x32_bf16 v[116:119], v[144:147], v[206:209], v[116:119]
	v_mfma_f32_16x16x32_bf16 v[100:103], v[108:111], v[214:217], v[100:103]
	v_mfma_f32_16x16x32_bf16 v[96:99], v[144:147], v[214:217], v[96:99]
	v_mfma_f32_16x16x32_bf16 v[80:83], v[108:111], v[222:225], v[78:81]
	v_mfma_f32_16x16x32_bf16 v[76:79], v[144:147], v[222:225], v[74:77]
	s_setprio 0
	s_setprio 1
	v_mfma_f32_16x16x32_bf16 v[132:135], v[148:151], v[194:197], v[132:135]
	v_mfma_f32_16x16x32_bf16 v[132:135], v[152:155], v[198:201], v[132:135]
	v_mfma_f32_16x16x32_bf16 v[124:127], v[190:193], v[198:201], v[124:127]
	v_mfma_f32_16x16x32_bf16 v[124:127], v[176:179], v[194:197], v[124:127]
	v_mfma_f32_16x16x32_bf16 v[104:107], v[176:179], v[202:205], v[104:107]
	v_mfma_f32_16x16x32_bf16 v[104:107], v[190:193], v[206:209], v[104:107]
	v_mfma_f32_16x16x32_bf16 v[112:115], v[152:155], v[206:209], v[112:115]
	v_mfma_f32_16x16x32_bf16 v[112:115], v[148:151], v[202:205], v[112:115]
	v_mfma_f32_16x16x32_bf16 v[92:95], v[148:151], v[210:213], v[92:95]
	v_mfma_f32_16x16x32_bf16 v[92:95], v[152:155], v[214:217], v[92:95]
	v_mfma_f32_16x16x32_bf16 v[84:87], v[190:193], v[214:217], v[84:87]
	v_mfma_f32_16x16x32_bf16 v[84:87], v[176:179], v[210:213], v[84:87]
	v_mfma_f32_16x16x32_bf16 v[64:67], v[176:179], v[218:221], v[64:67]
	v_mfma_f32_16x16x32_bf16 v[64:67], v[190:193], v[222:225], v[64:67]
	v_mfma_f32_16x16x32_bf16 v[68:71], v[152:155], v[222:225], v[68:71]
	v_mfma_f32_16x16x32_bf16 v[68:71], v[148:151], v[218:221], v[68:71]
	s_barrier
	s_setprio 0
	s_add_i32 s68, s96, s71
	v_lshl_add_u64 v[74:75], v[226:227], 0, s[28:29]
	s_mov_b32 m0, s68
	s_nop 0
	global_load_lds_dwordx4 v[74:75], off
	s_add_i32 m0, s68, 0x2000
	s_add_u32 s66, s66, 0x40080
	v_lshl_add_u64 v[74:75], v[228:229], 0, s[28:29]
	s_addc_u32 s67, s67, 0
	s_add_i32 s68, s97, s71
	global_load_lds_dwordx4 v[74:75], off
	v_lshl_add_u64 v[74:75], s[66:67], 0, v[162:163]
	s_mov_b32 m0, s68
	s_nop 0
	global_load_lds_dwordx4 v[74:75], off
	v_lshl_add_u64 v[74:75], s[66:67], 0, v[166:167]
	s_add_i32 m0, s68, 0x2000
	s_nop 0
	global_load_lds_dwordx4 v[74:75], off
	v_lshl_add_u64 v[74:75], v[230:231], 0, s[28:29]
	s_mov_b32 m0, s78
	s_nop 0
	global_load_lds_dwordx4 v[74:75], off
	v_lshl_add_u64 v[74:75], v[232:233], 0, s[28:29]
	s_mov_b32 m0, s79
	s_nop 0
	global_load_lds_dwordx4 v[74:75], off
	ds_read_b128 v[194:197], v187 offset:49152
	v_xor_b32_e32 v253, 64, v187
	ds_read_b128 v[198:201], v253 offset:49152
	ds_read_b128 v[202:205], v187 offset:51200
	ds_read_b128 v[206:209], v253 offset:51200
	ds_read_b128 v[210:213], v187 offset:53248
	ds_read_b128 v[214:217], v253 offset:53248
	ds_read_b128 v[218:221], v187 offset:55296
	ds_read_b128 v[222:225], v253 offset:55296
	s_waitcnt vmcnt(8)
	s_waitcnt lgkmcnt(0)
	s_setprio 1
	s_barrier
	v_mfma_f32_16x16x32_bf16 v[60:63], v[88:91], v[194:197], v[60:63]
	v_mfma_f32_16x16x32_bf16 v[60:63], v[108:111], v[198:201], v[60:63]
	v_mfma_f32_16x16x32_bf16 v[56:59], v[144:147], v[198:201], v[56:59]
	v_mfma_f32_16x16x32_bf16 v[56:59], v[128:131], v[194:197], v[56:59]
	v_mfma_f32_16x16x32_bf16 v[40:43], v[128:131], v[202:205], v[40:43]
	v_mfma_f32_16x16x32_bf16 v[40:43], v[144:147], v[206:209], v[40:43]
	v_mfma_f32_16x16x32_bf16 v[44:47], v[108:111], v[206:209], v[44:47]
	v_mfma_f32_16x16x32_bf16 v[44:47], v[88:91], v[202:205], v[44:47]
	v_mfma_f32_16x16x32_bf16 v[28:31], v[88:91], v[210:213], v[28:31]
	v_mfma_f32_16x16x32_bf16 v[28:31], v[108:111], v[214:217], v[28:31]
	v_mfma_f32_16x16x32_bf16 v[24:27], v[144:147], v[214:217], v[24:27]
	v_mfma_f32_16x16x32_bf16 v[24:27], v[128:131], v[210:213], v[24:27]
	v_mfma_f32_16x16x32_bf16 v[8:11], v[128:131], v[218:221], v[8:11]
	v_mfma_f32_16x16x32_bf16 v[8:11], v[144:147], v[222:225], v[8:11]
	v_mfma_f32_16x16x32_bf16 v[12:15], v[108:111], v[222:225], v[12:15]
	v_mfma_f32_16x16x32_bf16 v[12:15], v[88:91], v[218:221], v[12:15]
	s_setprio 0
	s_setprio 1
	v_mfma_f32_16x16x32_bf16 v[52:55], v[148:151], v[194:197], v[52:55]
	v_mfma_f32_16x16x32_bf16 v[52:55], v[152:155], v[198:201], v[52:55]
	v_mfma_f32_16x16x32_bf16 v[48:51], v[190:193], v[198:201], v[48:51]
	v_mfma_f32_16x16x32_bf16 v[48:51], v[176:179], v[194:197], v[48:51]
	v_mfma_f32_16x16x32_bf16 v[32:35], v[176:179], v[202:205], v[32:35]
	v_mfma_f32_16x16x32_bf16 v[32:35], v[190:193], v[206:209], v[32:35]
	v_mfma_f32_16x16x32_bf16 v[36:39], v[152:155], v[206:209], v[36:39]
	v_mfma_f32_16x16x32_bf16 v[36:39], v[148:151], v[202:205], v[36:39]
	v_mfma_f32_16x16x32_bf16 v[20:23], v[148:151], v[210:213], v[20:23]
	v_mfma_f32_16x16x32_bf16 v[20:23], v[152:155], v[214:217], v[20:23]
	v_mfma_f32_16x16x32_bf16 v[16:19], v[190:193], v[214:217], v[16:19]
	v_mfma_f32_16x16x32_bf16 v[16:19], v[176:179], v[210:213], v[16:19]
	v_mfma_f32_16x16x32_bf16 v[0:3], v[176:179], v[218:221], v[0:3]
	v_mfma_f32_16x16x32_bf16 v[0:3], v[190:193], v[222:225], v[0:3]
	v_mfma_f32_16x16x32_bf16 v[4:7], v[152:155], v[222:225], v[4:7]
	v_mfma_f32_16x16x32_bf16 v[4:7], v[148:151], v[218:221], v[4:7]
	s_barrier
	s_setprio 0
	s_add_i32 s95, s95, 2
	s_add_u32 s93, s93, 0x100
	s_addc_u32 s94, s94, 0
	s_add_u32 s14, s14, 0x100
	s_addc_u32 s15, s15, 0
	s_cmp_gt_u32 s95, 13
	s_cbranch_scc1 .LBB0_258

.LBB0_439:
	s_ashr_i32 s53, s52, 31
	s_lshl_b64 s[54:55], s[52:53], 20
	s_add_u32 s54, s35, s54
	s_addc_u32 s55, s66, s55
	s_and_b64 s[56:57], s[12:13], exec
	s_cselect_b32 s15, s55, s63
	s_cselect_b32 s53, s54, s62
	s_ashr_i32 s51, s50, 31
	s_lshl_b64 s[56:57], s[50:51], 20
	s_add_u32 s56, s67, s56
	s_addc_u32 s57, s68, s57
	s_and_b64 s[64:65], s[12:13], exec
	s_cselect_b32 s51, s57, s61
	s_cselect_b32 s59, s56, s60
	s_add_u32 s81, s60, 0x100
	s_addc_u32 s82, s61, 0
	s_add_u32 s60, s62, 0x80080
	s_addc_u32 s61, s63, 0
	s_mov_b32 s83, -2
	s_waitcnt lgkmcnt(0)
	s_cmp_eq_u32 s74, 1
	s_cbranch_scc1 .Lfa_3
	ds_read_b128 v[128:131], v189
	v_xor_b32_e32 v253, 64, v189
	ds_read_b128 v[132:135], v253
	ds_read_b128 v[136:139], v189 offset:2048
	ds_read_b128 v[140:143], v253 offset:2048
	ds_read_b128 v[144:147], v190
	v_xor_b32_e32 v253, 64, v190
	ds_read_b128 v[148:151], v253
	ds_read_b128 v[172:175], v190 offset:2048
	ds_read_b128 v[176:179], v253 offset:2048
	s_add_u32 s62, s60, 0xfff80080
	s_addc_u32 s63, s61, -1
	s_cmp_eq_u32 s83, 28
	s_cselect_b32 s65, s15, s63
	s_cselect_b32 s64, s53, s62
	s_cselect_b32 s63, s51, s82
	s_cselect_b32 s62, s59, s81
	v_lshl_add_u64 v[222:223], s[60:61], 0, v[166:167]
	s_add_i32 m0, s70, 0xc000
	s_nop 0
	global_load_lds_dwordx4 v[222:223], off
	v_lshl_add_u64 v[222:223], s[60:61], 0, v[164:165]
	s_add_i32 m0, s70, 0xe000
	s_nop 0
	global_load_lds_dwordx4 v[222:223], off
	ds_read_b128 v[180:183], v191
	v_xor_b32_e32 v253, 64, v191
	ds_read_b128 v[194:197], v253
	ds_read_b128 v[198:201], v191 offset:2048
	ds_read_b128 v[202:205], v253 offset:2048
	ds_read_b128 v[206:209], v191 offset:4096
	ds_read_b128 v[210:213], v253 offset:4096
	ds_read_b128 v[214:217], v191 offset:6144
	ds_read_b128 v[218:221], v253 offset:6144
	s_waitcnt vmcnt(24)
	s_waitcnt lgkmcnt(0)
	s_setprio 1
	s_barrier
	v_mfma_f32_16x16x32_bf16 v[124:127], v[128:131], v[180:183], 0
	v_mfma_f32_16x16x32_bf16 v[120:123], v[136:139], v[180:183], 0
	v_mfma_f32_16x16x32_bf16 v[108:111], v[128:131], v[198:201], 0
	v_mfma_f32_16x16x32_bf16 v[104:107], v[136:139], v[198:201], 0
	v_mfma_f32_16x16x32_bf16 v[92:95], v[128:131], v[206:209], 0
	v_mfma_f32_16x16x32_bf16 v[88:91], v[136:139], v[206:209], 0
	v_mfma_f32_16x16x32_bf16 v[76:79], v[128:131], v[214:217], 0
	v_mfma_f32_16x16x32_bf16 v[72:75], v[136:139], v[214:217], 0
	v_mfma_f32_16x16x32_bf16 v[124:127], v[132:135], v[194:197], v[124:127]
	v_mfma_f32_16x16x32_bf16 v[120:123], v[140:143], v[194:197], v[120:123]
	v_mfma_f32_16x16x32_bf16 v[108:111], v[132:135], v[202:205], v[108:111]
	v_mfma_f32_16x16x32_bf16 v[104:107], v[140:143], v[202:205], v[104:107]
	v_mfma_f32_16x16x32_bf16 v[92:95], v[132:135], v[210:213], v[92:95]
	v_mfma_f32_16x16x32_bf16 v[88:91], v[140:143], v[210:213], v[88:91]
	v_mfma_f32_16x16x32_bf16 v[76:79], v[132:135], v[218:221], v[76:79]
	v_mfma_f32_16x16x32_bf16 v[72:75], v[140:143], v[218:221], v[72:75]
	s_setprio 0
	s_setprio 1
	v_mfma_f32_16x16x32_bf16 v[116:119], v[144:147], v[180:183], 0
	v_mfma_f32_16x16x32_bf16 v[112:115], v[172:175], v[180:183], 0
	v_mfma_f32_16x16x32_bf16 v[100:103], v[144:147], v[198:201], 0
	v_mfma_f32_16x16x32_bf16 v[96:99], v[172:175], v[198:201], 0
	v_mfma_f32_16x16x32_bf16 v[84:87], v[144:147], v[206:209], 0
	v_mfma_f32_16x16x32_bf16 v[80:83], v[172:175], v[206:209], 0
	v_mfma_f32_16x16x32_bf16 v[68:71], v[144:147], v[214:217], 0
	v_mfma_f32_16x16x32_bf16 v[64:67], v[172:175], v[214:217], 0
	v_mfma_f32_16x16x32_bf16 v[116:119], v[148:151], v[194:197], v[116:119]
	v_mfma_f32_16x16x32_bf16 v[112:115], v[176:179], v[194:197], v[112:115]
	v_mfma_f32_16x16x32_bf16 v[100:103], v[148:151], v[202:205], v[100:103]
	v_mfma_f32_16x16x32_bf16 v[96:99], v[176:179], v[202:205], v[96:99]
	v_mfma_f32_16x16x32_bf16 v[84:87], v[148:151], v[210:213], v[84:87]
	v_mfma_f32_16x16x32_bf16 v[80:83], v[176:179], v[210:213], v[80:83]
	v_mfma_f32_16x16x32_bf16 v[68:71], v[148:151], v[218:221], v[68:71]
	v_mfma_f32_16x16x32_bf16 v[64:67], v[176:179], v[218:221], v[64:67]
	s_barrier
	s_setprio 0
	s_add_i32 s84, s79, s69
	v_lshl_add_u64 v[222:223], s[62:63], 0, v[154:155]
	s_mov_b32 m0, s84
	s_nop 0
	global_load_lds_dwordx4 v[222:223], off
	s_add_i32 m0, s84, 0x2000
	s_add_u32 s84, s62, 0x80000
	v_lshl_add_u64 v[224:225], s[62:63], 0, v[162:163]
	s_addc_u32 s85, s63, 0
	s_add_i32 s86, s80, s69
	global_load_lds_dwordx4 v[224:225], off
	v_lshl_add_u64 v[226:227], s[84:85], 0, v[154:155]
	s_mov_b32 m0, s86
	v_lshl_add_u64 v[228:229], s[64:65], 0, v[160:161]
	global_load_lds_dwordx4 v[226:227], off
	v_lshl_add_u64 v[226:227], s[84:85], 0, v[162:163]
	s_add_i32 m0, s86, 0x2000
	s_nop 0
	global_load_lds_dwordx4 v[226:227], off
	v_lshl_add_u64 v[226:227], s[64:65], 0, v[152:153]
	s_mov_b32 m0, s70
	s_nop 0
	global_load_lds_dwordx4 v[226:227], off
	s_mov_b32 m0, s71
	s_nop 0
	global_load_lds_dwordx4 v[228:229], off
	ds_read_b128 v[180:183], v191 offset:16384
	v_xor_b32_e32 v253, 64, v191
	ds_read_b128 v[194:197], v253 offset:16384
	ds_read_b128 v[198:201], v191 offset:18432
	ds_read_b128 v[202:205], v253 offset:18432
	ds_read_b128 v[206:209], v191 offset:20480
	ds_read_b128 v[210:213], v253 offset:20480
	ds_read_b128 v[214:217], v191 offset:22528
	ds_read_b128 v[218:221], v253 offset:22528
	s_waitcnt vmcnt(24)
	s_waitcnt lgkmcnt(0)
	s_setprio 1
	s_barrier
	v_mfma_f32_16x16x32_bf16 v[60:63], v[128:131], v[180:183], 0
	v_mfma_f32_16x16x32_bf16 v[56:59], v[136:139], v[180:183], 0
	v_mfma_f32_16x16x32_bf16 v[44:47], v[128:131], v[198:201], 0
	v_mfma_f32_16x16x32_bf16 v[40:43], v[136:139], v[198:201], 0
	v_mfma_f32_16x16x32_bf16 v[28:31], v[128:131], v[206:209], 0
	v_mfma_f32_16x16x32_bf16 v[24:27], v[136:139], v[206:209], 0
	v_mfma_f32_16x16x32_bf16 v[12:15], v[128:131], v[214:217], 0
	v_mfma_f32_16x16x32_bf16 v[8:11], v[136:139], v[214:217], 0
	v_mfma_f32_16x16x32_bf16 v[60:63], v[132:135], v[194:197], v[60:63]
	v_mfma_f32_16x16x32_bf16 v[56:59], v[140:143], v[194:197], v[56:59]
	v_mfma_f32_16x16x32_bf16 v[44:47], v[132:135], v[202:205], v[44:47]
	v_mfma_f32_16x16x32_bf16 v[40:43], v[140:143], v[202:205], v[40:43]
	v_mfma_f32_16x16x32_bf16 v[28:31], v[132:135], v[210:213], v[28:31]
	v_mfma_f32_16x16x32_bf16 v[24:27], v[140:143], v[210:213], v[24:27]
	v_mfma_f32_16x16x32_bf16 v[12:15], v[132:135], v[218:221], v[12:15]
	v_mfma_f32_16x16x32_bf16 v[8:11], v[140:143], v[218:221], v[8:11]
	s_setprio 0
	s_setprio 1
	v_mfma_f32_16x16x32_bf16 v[52:55], v[144:147], v[180:183], 0
	v_mfma_f32_16x16x32_bf16 v[48:51], v[172:175], v[180:183], 0
	v_mfma_f32_16x16x32_bf16 v[36:39], v[144:147], v[198:201], 0
	v_mfma_f32_16x16x32_bf16 v[32:35], v[172:175], v[198:201], 0
	v_mfma_f32_16x16x32_bf16 v[20:23], v[144:147], v[206:209], 0
	v_mfma_f32_16x16x32_bf16 v[16:19], v[172:175], v[206:209], 0
	v_mfma_f32_16x16x32_bf16 v[4:7], v[144:147], v[214:217], 0
	v_mfma_f32_16x16x32_bf16 v[0:3], v[172:175], v[214:217], 0
	v_mfma_f32_16x16x32_bf16 v[52:55], v[148:151], v[194:197], v[52:55]
	v_mfma_f32_16x16x32_bf16 v[48:51], v[176:179], v[194:197], v[48:51]
	v_mfma_f32_16x16x32_bf16 v[36:39], v[148:151], v[202:205], v[36:39]
	v_mfma_f32_16x16x32_bf16 v[32:35], v[176:179], v[202:205], v[32:35]
	v_mfma_f32_16x16x32_bf16 v[20:23], v[148:151], v[210:213], v[20:23]
	v_mfma_f32_16x16x32_bf16 v[16:19], v[176:179], v[210:213], v[16:19]
	v_mfma_f32_16x16x32_bf16 v[4:7], v[148:151], v[218:221], v[4:7]
	v_mfma_f32_16x16x32_bf16 v[0:3], v[176:179], v[218:221], v[0:3]
	s_barrier
	s_setprio 0
	s_add_i32 s84, 0, 0x18000
	s_add_i32 s85, 0, 0x1c000
	v_add_u32_e32 v140, s84, v186
	v_add_u32_e32 v176, s85, v186
	s_add_u32 s64, s64, 0x80000
	s_addc_u32 s65, s65, 0
	s_mov_b32 m0, s72
	v_lshl_add_u64 v[230:231], s[64:65], 0, v[152:153]
	global_load_lds_dwordx4 v[230:231], off
	v_lshl_add_u64 v[230:231], s[64:65], 0, v[160:161]
	s_mov_b32 m0, s73
	s_nop 0
	global_load_lds_dwordx4 v[230:231], off
	ds_read_b128 v[128:131], v140
	v_xor_b32_e32 v253, 64, v140
	ds_read_b128 v[132:135], v253
	ds_read_b128 v[136:139], v140 offset:2048
	ds_read_b128 v[140:143], v253 offset:2048
	ds_read_b128 v[144:147], v176
	v_xor_b32_e32 v253, 64, v176
	ds_read_b128 v[148:151], v253
	ds_read_b128 v[172:175], v176 offset:2048
	ds_read_b128 v[176:179], v253 offset:2048
	ds_read_b128 v[180:183], v191 offset:32768
	v_xor_b32_e32 v253, 64, v191
	ds_read_b128 v[194:197], v253 offset:32768
	ds_read_b128 v[198:201], v191 offset:34816
	ds_read_b128 v[202:205], v253 offset:34816
	ds_read_b128 v[206:209], v191 offset:36864
	ds_read_b128 v[210:213], v253 offset:36864
	ds_read_b128 v[214:217], v191 offset:38912
	ds_read_b128 v[218:221], v253 offset:38912
	s_waitcnt vmcnt(8)
	s_waitcnt lgkmcnt(0)
	s_setprio 1
	s_barrier
	v_mfma_f32_16x16x32_bf16 v[124:127], v[128:131], v[180:183], v[124:127]
	v_mfma_f32_16x16x32_bf16 v[124:127], v[132:135], v[194:197], v[124:127]
	v_mfma_f32_16x16x32_bf16 v[120:123], v[140:143], v[194:197], v[120:123]
	v_mfma_f32_16x16x32_bf16 v[120:123], v[136:139], v[180:183], v[120:123]
	v_mfma_f32_16x16x32_bf16 v[104:107], v[136:139], v[198:201], v[104:107]
	v_mfma_f32_16x16x32_bf16 v[104:107], v[140:143], v[202:205], v[104:107]
	v_mfma_f32_16x16x32_bf16 v[108:111], v[132:135], v[202:205], v[108:111]
	v_mfma_f32_16x16x32_bf16 v[108:111], v[128:131], v[198:201], v[108:111]
	v_mfma_f32_16x16x32_bf16 v[92:95], v[128:131], v[206:209], v[92:95]
	v_mfma_f32_16x16x32_bf16 v[92:95], v[132:135], v[210:213], v[92:95]
	v_mfma_f32_16x16x32_bf16 v[88:91], v[140:143], v[210:213], v[88:91]
	v_mfma_f32_16x16x32_bf16 v[88:91], v[136:139], v[206:209], v[88:91]
	v_mfma_f32_16x16x32_bf16 v[72:75], v[136:139], v[214:217], v[72:75]
	v_mfma_f32_16x16x32_bf16 v[72:75], v[140:143], v[218:221], v[72:75]
	v_mfma_f32_16x16x32_bf16 v[76:79], v[132:135], v[218:221], v[76:79]
	v_mfma_f32_16x16x32_bf16 v[76:79], v[128:131], v[214:217], v[76:79]
	s_setprio 0
	s_setprio 1
	v_mfma_f32_16x16x32_bf16 v[116:119], v[144:147], v[180:183], v[116:119]
	v_mfma_f32_16x16x32_bf16 v[116:119], v[148:151], v[194:197], v[116:119]
	v_mfma_f32_16x16x32_bf16 v[112:115], v[176:179], v[194:197], v[112:115]
	v_mfma_f32_16x16x32_bf16 v[112:115], v[172:175], v[180:183], v[112:115]
	v_mfma_f32_16x16x32_bf16 v[96:99], v[172:175], v[198:201], v[96:99]
	v_mfma_f32_16x16x32_bf16 v[96:99], v[176:179], v[202:205], v[96:99]
	v_mfma_f32_16x16x32_bf16 v[100:103], v[148:151], v[202:205], v[100:103]
	v_mfma_f32_16x16x32_bf16 v[100:103], v[144:147], v[198:201], v[100:103]
	v_mfma_f32_16x16x32_bf16 v[84:87], v[144:147], v[206:209], v[84:87]
	v_mfma_f32_16x16x32_bf16 v[84:87], v[148:151], v[210:213], v[84:87]
	v_mfma_f32_16x16x32_bf16 v[80:83], v[176:179], v[210:213], v[80:83]
	v_mfma_f32_16x16x32_bf16 v[80:83], v[172:175], v[206:209], v[80:83]
	v_mfma_f32_16x16x32_bf16 v[64:67], v[172:175], v[214:217], v[64:67]
	v_mfma_f32_16x16x32_bf16 v[64:67], v[176:179], v[218:221], v[64:67]
	v_mfma_f32_16x16x32_bf16 v[68:71], v[148:151], v[218:221], v[68:71]
	v_mfma_f32_16x16x32_bf16 v[68:71], v[144:147], v[214:217], v[68:71]
	s_barrier
	s_setprio 0
	s_add_i32 s64, s84, s69
	v_lshl_add_u64 v[222:223], v[222:223], 0, s[26:27]
	s_mov_b32 m0, s64
	s_nop 0
	global_load_lds_dwordx4 v[222:223], off
	s_add_i32 m0, s64, 0x2000
	s_add_u32 s62, s62, 0x80080
	v_lshl_add_u64 v[222:223], v[224:225], 0, s[26:27]
	s_addc_u32 s63, s63, 0
	s_add_i32 s64, s85, s69
	global_load_lds_dwordx4 v[222:223], off
	v_lshl_add_u64 v[222:223], s[62:63], 0, v[154:155]
	s_mov_b32 m0, s64
	s_nop 0
	global_load_lds_dwordx4 v[222:223], off
	v_lshl_add_u64 v[222:223], s[62:63], 0, v[162:163]
	s_add_i32 m0, s64, 0x2000
	s_nop 0
	global_load_lds_dwordx4 v[222:223], off
	v_lshl_add_u64 v[222:223], v[226:227], 0, s[26:27]
	s_mov_b32 m0, s3
	s_nop 0
	global_load_lds_dwordx4 v[222:223], off
	v_lshl_add_u64 v[222:223], v[228:229], 0, s[26:27]
	s_mov_b32 m0, s75
	s_nop 0
	global_load_lds_dwordx4 v[222:223], off
	ds_read_b128 v[180:183], v191 offset:49152
	v_xor_b32_e32 v253, 64, v191
	ds_read_b128 v[194:197], v253 offset:49152
	ds_read_b128 v[198:201], v191 offset:51200
	ds_read_b128 v[202:205], v253 offset:51200
	ds_read_b128 v[206:209], v191 offset:53248
	ds_read_b128 v[210:213], v253 offset:53248
	ds_read_b128 v[214:217], v191 offset:55296
	ds_read_b128 v[218:221], v253 offset:55296
	s_waitcnt vmcnt(8)
	s_waitcnt lgkmcnt(0)
	s_setprio 1
	s_barrier
	v_mfma_f32_16x16x32_bf16 v[60:63], v[128:131], v[180:183], v[60:63]
	v_mfma_f32_16x16x32_bf16 v[60:63], v[132:135], v[194:197], v[60:63]
	v_mfma_f32_16x16x32_bf16 v[56:59], v[140:143], v[194:197], v[56:59]
	v_mfma_f32_16x16x32_bf16 v[56:59], v[136:139], v[180:183], v[56:59]
	v_mfma_f32_16x16x32_bf16 v[40:43], v[136:139], v[198:201], v[40:43]
	v_mfma_f32_16x16x32_bf16 v[40:43], v[140:143], v[202:205], v[40:43]
	v_mfma_f32_16x16x32_bf16 v[44:47], v[132:135], v[202:205], v[44:47]
	v_mfma_f32_16x16x32_bf16 v[44:47], v[128:131], v[198:201], v[44:47]
	v_mfma_f32_16x16x32_bf16 v[28:31], v[128:131], v[206:209], v[28:31]
	v_mfma_f32_16x16x32_bf16 v[28:31], v[132:135], v[210:213], v[28:31]
	v_mfma_f32_16x16x32_bf16 v[24:27], v[140:143], v[210:213], v[24:27]
	v_mfma_f32_16x16x32_bf16 v[24:27], v[136:139], v[206:209], v[24:27]
	v_mfma_f32_16x16x32_bf16 v[8:11], v[136:139], v[214:217], v[8:11]
	v_mfma_f32_16x16x32_bf16 v[8:11], v[140:143], v[218:221], v[8:11]
	v_mfma_f32_16x16x32_bf16 v[12:15], v[132:135], v[218:221], v[12:15]
	v_mfma_f32_16x16x32_bf16 v[12:15], v[128:131], v[214:217], v[12:15]
	s_setprio 0
	s_setprio 1
	v_mfma_f32_16x16x32_bf16 v[52:55], v[144:147], v[180:183], v[52:55]
	v_mfma_f32_16x16x32_bf16 v[52:55], v[148:151], v[194:197], v[52:55]
	v_mfma_f32_16x16x32_bf16 v[48:51], v[176:179], v[194:197], v[48:51]
	v_mfma_f32_16x16x32_bf16 v[48:51], v[172:175], v[180:183], v[48:51]
	v_mfma_f32_16x16x32_bf16 v[32:35], v[172:175], v[198:201], v[32:35]
	v_mfma_f32_16x16x32_bf16 v[32:35], v[176:179], v[202:205], v[32:35]
	v_mfma_f32_16x16x32_bf16 v[36:39], v[148:151], v[202:205], v[36:39]
	v_mfma_f32_16x16x32_bf16 v[36:39], v[144:147], v[198:201], v[36:39]
	v_mfma_f32_16x16x32_bf16 v[20:23], v[144:147], v[206:209], v[20:23]
	v_mfma_f32_16x16x32_bf16 v[20:23], v[148:151], v[210:213], v[20:23]
	v_mfma_f32_16x16x32_bf16 v[16:19], v[176:179], v[210:213], v[16:19]
	v_mfma_f32_16x16x32_bf16 v[16:19], v[172:175], v[206:209], v[16:19]
	v_mfma_f32_16x16x32_bf16 v[0:3], v[172:175], v[214:217], v[0:3]
	v_mfma_f32_16x16x32_bf16 v[0:3], v[176:179], v[218:221], v[0:3]
	v_mfma_f32_16x16x32_bf16 v[4:7], v[148:151], v[218:221], v[4:7]
	v_mfma_f32_16x16x32_bf16 v[4:7], v[144:147], v[214:217], v[4:7]
	s_barrier
	s_setprio 0
	s_add_i32 s83, s83, 2
	s_add_u32 s81, s81, 0x100
	s_addc_u32 s82, s82, 0
	s_add_u32 s60, s60, 0x100
	s_addc_u32 s61, s61, 0
	s_cmp_gt_u32 s83, 29
	s_branch .LBB0_440
.Lfa_3:
	ds_read_b128 v[128:131], v189
	v_xor_b32_e32 v253, 64, v189
	ds_read_b128 v[132:135], v253
	ds_read_b128 v[136:139], v189 offset:2048
	ds_read_b128 v[140:143], v253 offset:2048
	ds_read_b128 v[144:147], v190
	v_xor_b32_e32 v253, 64, v190
	ds_read_b128 v[148:151], v253
	ds_read_b128 v[172:175], v190 offset:2048
	ds_read_b128 v[176:179], v253 offset:2048
	s_add_u32 s62, s60, 0xfff80080
	s_addc_u32 s63, s61, -1
	s_cmp_eq_u32 s83, 28
	s_cselect_b32 s65, s15, s63
	s_cselect_b32 s64, s53, s62
	s_cselect_b32 s63, s51, s82
	s_cselect_b32 s62, s59, s81
	v_lshl_add_u64 v[222:223], s[60:61], 0, v[166:167]
	s_add_i32 m0, s70, 0xc000
	s_nop 0
	global_load_lds_dwordx4 v[222:223], off
	v_lshl_add_u64 v[222:223], s[60:61], 0, v[164:165]
	s_add_i32 m0, s70, 0xe000
	s_nop 0
	global_load_lds_dwordx4 v[222:223], off
	ds_read_b128 v[180:183], v191
	v_xor_b32_e32 v253, 64, v191
	ds_read_b128 v[194:197], v253
	ds_read_b128 v[198:201], v191 offset:2048
	ds_read_b128 v[202:205], v253 offset:2048
	ds_read_b128 v[206:209], v191 offset:4096
	ds_read_b128 v[210:213], v253 offset:4096
	ds_read_b128 v[214:217], v191 offset:6144
	ds_read_b128 v[218:221], v253 offset:6144
	s_waitcnt vmcnt(8)
	s_waitcnt lgkmcnt(0)
	s_setprio 1
	s_barrier
	v_mfma_f32_16x16x32_bf16 v[124:127], v[128:131], v[180:183], 0
	v_mfma_f32_16x16x32_bf16 v[120:123], v[136:139], v[180:183], 0
	v_mfma_f32_16x16x32_bf16 v[108:111], v[128:131], v[198:201], 0
	v_mfma_f32_16x16x32_bf16 v[104:107], v[136:139], v[198:201], 0
	v_mfma_f32_16x16x32_bf16 v[92:95], v[128:131], v[206:209], 0
	v_mfma_f32_16x16x32_bf16 v[88:91], v[136:139], v[206:209], 0
	v_mfma_f32_16x16x32_bf16 v[76:79], v[128:131], v[214:217], 0
	v_mfma_f32_16x16x32_bf16 v[72:75], v[136:139], v[214:217], 0
	v_mfma_f32_16x16x32_bf16 v[124:127], v[132:135], v[194:197], v[124:127]
	v_mfma_f32_16x16x32_bf16 v[120:123], v[140:143], v[194:197], v[120:123]
	v_mfma_f32_16x16x32_bf16 v[108:111], v[132:135], v[202:205], v[108:111]
	v_mfma_f32_16x16x32_bf16 v[104:107], v[140:143], v[202:205], v[104:107]
	v_mfma_f32_16x16x32_bf16 v[92:95], v[132:135], v[210:213], v[92:95]
	v_mfma_f32_16x16x32_bf16 v[88:91], v[140:143], v[210:213], v[88:91]
	v_mfma_f32_16x16x32_bf16 v[76:79], v[132:135], v[218:221], v[76:79]
	v_mfma_f32_16x16x32_bf16 v[72:75], v[140:143], v[218:221], v[72:75]
	s_setprio 0
	s_setprio 1
	v_mfma_f32_16x16x32_bf16 v[116:119], v[144:147], v[180:183], 0
	v_mfma_f32_16x16x32_bf16 v[112:115], v[172:175], v[180:183], 0
	v_mfma_f32_16x16x32_bf16 v[100:103], v[144:147], v[198:201], 0
	v_mfma_f32_16x16x32_bf16 v[96:99], v[172:175], v[198:201], 0
	v_mfma_f32_16x16x32_bf16 v[84:87], v[144:147], v[206:209], 0
	v_mfma_f32_16x16x32_bf16 v[80:83], v[172:175], v[206:209], 0
	v_mfma_f32_16x16x32_bf16 v[68:71], v[144:147], v[214:217], 0
	v_mfma_f32_16x16x32_bf16 v[64:67], v[172:175], v[214:217], 0
	v_mfma_f32_16x16x32_bf16 v[116:119], v[148:151], v[194:197], v[116:119]
	v_mfma_f32_16x16x32_bf16 v[112:115], v[176:179], v[194:197], v[112:115]
	v_mfma_f32_16x16x32_bf16 v[100:103], v[148:151], v[202:205], v[100:103]
	v_mfma_f32_16x16x32_bf16 v[96:99], v[176:179], v[202:205], v[96:99]
	v_mfma_f32_16x16x32_bf16 v[84:87], v[148:151], v[210:213], v[84:87]
	v_mfma_f32_16x16x32_bf16 v[80:83], v[176:179], v[210:213], v[80:83]
	v_mfma_f32_16x16x32_bf16 v[68:71], v[148:151], v[218:221], v[68:71]
	v_mfma_f32_16x16x32_bf16 v[64:67], v[176:179], v[218:221], v[64:67]
	s_barrier
	s_setprio 0
	s_add_i32 s84, s79, s69
	v_lshl_add_u64 v[222:223], s[62:63], 0, v[154:155]
	s_mov_b32 m0, s84
	s_nop 0
	global_load_lds_dwordx4 v[222:223], off
	s_add_i32 m0, s84, 0x2000
	s_add_u32 s84, s62, 0x80000
	v_lshl_add_u64 v[224:225], s[62:63], 0, v[162:163]
	s_addc_u32 s85, s63, 0
	s_add_i32 s86, s80, s69
	global_load_lds_dwordx4 v[224:225], off
	v_lshl_add_u64 v[226:227], s[84:85], 0, v[154:155]
	s_mov_b32 m0, s86
	v_lshl_add_u64 v[228:229], s[64:65], 0, v[160:161]
	global_load_lds_dwordx4 v[226:227], off
	v_lshl_add_u64 v[226:227], s[84:85], 0, v[162:163]
	s_add_i32 m0, s86, 0x2000
	s_nop 0
	global_load_lds_dwordx4 v[226:227], off
	v_lshl_add_u64 v[226:227], s[64:65], 0, v[152:153]
	s_mov_b32 m0, s70
	s_nop 0
	global_load_lds_dwordx4 v[226:227], off
	s_mov_b32 m0, s71
	s_nop 0
	global_load_lds_dwordx4 v[228:229], off
	ds_read_b128 v[180:183], v191 offset:16384
	v_xor_b32_e32 v253, 64, v191
	ds_read_b128 v[194:197], v253 offset:16384
	ds_read_b128 v[198:201], v191 offset:18432
	ds_read_b128 v[202:205], v253 offset:18432
	ds_read_b128 v[206:209], v191 offset:20480
	ds_read_b128 v[210:213], v253 offset:20480
	ds_read_b128 v[214:217], v191 offset:22528
	ds_read_b128 v[218:221], v253 offset:22528
	s_waitcnt vmcnt(8)
	s_waitcnt lgkmcnt(0)
	s_setprio 1
	s_barrier
	v_mfma_f32_16x16x32_bf16 v[60:63], v[128:131], v[180:183], 0
	v_mfma_f32_16x16x32_bf16 v[56:59], v[136:139], v[180:183], 0
	v_mfma_f32_16x16x32_bf16 v[44:47], v[128:131], v[198:201], 0
	v_mfma_f32_16x16x32_bf16 v[40:43], v[136:139], v[198:201], 0
	v_mfma_f32_16x16x32_bf16 v[28:31], v[128:131], v[206:209], 0
	v_mfma_f32_16x16x32_bf16 v[24:27], v[136:139], v[206:209], 0
	v_mfma_f32_16x16x32_bf16 v[12:15], v[128:131], v[214:217], 0
	v_mfma_f32_16x16x32_bf16 v[8:11], v[136:139], v[214:217], 0
	v_mfma_f32_16x16x32_bf16 v[60:63], v[132:135], v[194:197], v[60:63]
	v_mfma_f32_16x16x32_bf16 v[56:59], v[140:143], v[194:197], v[56:59]
	v_mfma_f32_16x16x32_bf16 v[44:47], v[132:135], v[202:205], v[44:47]
	v_mfma_f32_16x16x32_bf16 v[40:43], v[140:143], v[202:205], v[40:43]
	v_mfma_f32_16x16x32_bf16 v[28:31], v[132:135], v[210:213], v[28:31]
	v_mfma_f32_16x16x32_bf16 v[24:27], v[140:143], v[210:213], v[24:27]
	v_mfma_f32_16x16x32_bf16 v[12:15], v[132:135], v[218:221], v[12:15]
	v_mfma_f32_16x16x32_bf16 v[8:11], v[140:143], v[218:221], v[8:11]
	s_setprio 0
	s_setprio 1
	v_mfma_f32_16x16x32_bf16 v[52:55], v[144:147], v[180:183], 0
	v_mfma_f32_16x16x32_bf16 v[48:51], v[172:175], v[180:183], 0
	v_mfma_f32_16x16x32_bf16 v[36:39], v[144:147], v[198:201], 0
	v_mfma_f32_16x16x32_bf16 v[32:35], v[172:175], v[198:201], 0
	v_mfma_f32_16x16x32_bf16 v[20:23], v[144:147], v[206:209], 0
	v_mfma_f32_16x16x32_bf16 v[16:19], v[172:175], v[206:209], 0
	v_mfma_f32_16x16x32_bf16 v[4:7], v[144:147], v[214:217], 0
	v_mfma_f32_16x16x32_bf16 v[0:3], v[172:175], v[214:217], 0
	v_mfma_f32_16x16x32_bf16 v[52:55], v[148:151], v[194:197], v[52:55]
	v_mfma_f32_16x16x32_bf16 v[48:51], v[176:179], v[194:197], v[48:51]
	v_mfma_f32_16x16x32_bf16 v[36:39], v[148:151], v[202:205], v[36:39]
	v_mfma_f32_16x16x32_bf16 v[32:35], v[176:179], v[202:205], v[32:35]
	v_mfma_f32_16x16x32_bf16 v[20:23], v[148:151], v[210:213], v[20:23]
	v_mfma_f32_16x16x32_bf16 v[16:19], v[176:179], v[210:213], v[16:19]
	v_mfma_f32_16x16x32_bf16 v[4:7], v[148:151], v[218:221], v[4:7]
	v_mfma_f32_16x16x32_bf16 v[0:3], v[176:179], v[218:221], v[0:3]
	s_barrier
	s_setprio 0
	s_add_i32 s84, 0, 0x18000
	s_add_i32 s85, 0, 0x1c000
	v_add_u32_e32 v140, s84, v186
	v_add_u32_e32 v176, s85, v186
	s_add_u32 s64, s64, 0x80000
	s_addc_u32 s65, s65, 0
	s_mov_b32 m0, s72
	v_lshl_add_u64 v[230:231], s[64:65], 0, v[152:153]
	global_load_lds_dwordx4 v[230:231], off
	v_lshl_add_u64 v[230:231], s[64:65], 0, v[160:161]
	s_mov_b32 m0, s73
	s_nop 0
	global_load_lds_dwordx4 v[230:231], off
	ds_read_b128 v[128:131], v140
	v_xor_b32_e32 v253, 64, v140
	ds_read_b128 v[132:135], v253
	ds_read_b128 v[136:139], v140 offset:2048
	ds_read_b128 v[140:143], v253 offset:2048
	ds_read_b128 v[144:147], v176
	v_xor_b32_e32 v253, 64, v176
	ds_read_b128 v[148:151], v253
	ds_read_b128 v[172:175], v176 offset:2048
	ds_read_b128 v[176:179], v253 offset:2048
	ds_read_b128 v[180:183], v191 offset:32768
	v_xor_b32_e32 v253, 64, v191
	ds_read_b128 v[194:197], v253 offset:32768
	ds_read_b128 v[198:201], v191 offset:34816
	ds_read_b128 v[202:205], v253 offset:34816
	ds_read_b128 v[206:209], v191 offset:36864
	ds_read_b128 v[210:213], v253 offset:36864
	ds_read_b128 v[214:217], v191 offset:38912
	ds_read_b128 v[218:221], v253 offset:38912
	s_waitcnt vmcnt(8)
	s_waitcnt lgkmcnt(0)
	s_setprio 1
	s_barrier
	v_mfma_f32_16x16x32_bf16 v[124:127], v[128:131], v[180:183], v[124:127]
	v_mfma_f32_16x16x32_bf16 v[124:127], v[132:135], v[194:197], v[124:127]
	v_mfma_f32_16x16x32_bf16 v[120:123], v[140:143], v[194:197], v[120:123]
	v_mfma_f32_16x16x32_bf16 v[120:123], v[136:139], v[180:183], v[120:123]
	v_mfma_f32_16x16x32_bf16 v[104:107], v[136:139], v[198:201], v[104:107]
	v_mfma_f32_16x16x32_bf16 v[104:107], v[140:143], v[202:205], v[104:107]
	v_mfma_f32_16x16x32_bf16 v[108:111], v[132:135], v[202:205], v[108:111]
	v_mfma_f32_16x16x32_bf16 v[108:111], v[128:131], v[198:201], v[108:111]
	v_mfma_f32_16x16x32_bf16 v[92:95], v[128:131], v[206:209], v[92:95]
	v_mfma_f32_16x16x32_bf16 v[92:95], v[132:135], v[210:213], v[92:95]
	v_mfma_f32_16x16x32_bf16 v[88:91], v[140:143], v[210:213], v[88:91]
	v_mfma_f32_16x16x32_bf16 v[88:91], v[136:139], v[206:209], v[88:91]
	v_mfma_f32_16x16x32_bf16 v[72:75], v[136:139], v[214:217], v[72:75]
	v_mfma_f32_16x16x32_bf16 v[72:75], v[140:143], v[218:221], v[72:75]
	v_mfma_f32_16x16x32_bf16 v[76:79], v[132:135], v[218:221], v[76:79]
	v_mfma_f32_16x16x32_bf16 v[76:79], v[128:131], v[214:217], v[76:79]
	s_setprio 0
	s_setprio 1
	v_mfma_f32_16x16x32_bf16 v[116:119], v[144:147], v[180:183], v[116:119]
	v_mfma_f32_16x16x32_bf16 v[116:119], v[148:151], v[194:197], v[116:119]
	v_mfma_f32_16x16x32_bf16 v[112:115], v[176:179], v[194:197], v[112:115]
	v_mfma_f32_16x16x32_bf16 v[112:115], v[172:175], v[180:183], v[112:115]
	v_mfma_f32_16x16x32_bf16 v[96:99], v[172:175], v[198:201], v[96:99]
	v_mfma_f32_16x16x32_bf16 v[96:99], v[176:179], v[202:205], v[96:99]
	v_mfma_f32_16x16x32_bf16 v[100:103], v[148:151], v[202:205], v[100:103]
	v_mfma_f32_16x16x32_bf16 v[100:103], v[144:147], v[198:201], v[100:103]
	v_mfma_f32_16x16x32_bf16 v[84:87], v[144:147], v[206:209], v[84:87]
	v_mfma_f32_16x16x32_bf16 v[84:87], v[148:151], v[210:213], v[84:87]
	v_mfma_f32_16x16x32_bf16 v[80:83], v[176:179], v[210:213], v[80:83]
	v_mfma_f32_16x16x32_bf16 v[80:83], v[172:175], v[206:209], v[80:83]
	v_mfma_f32_16x16x32_bf16 v[64:67], v[172:175], v[214:217], v[64:67]
	v_mfma_f32_16x16x32_bf16 v[64:67], v[176:179], v[218:221], v[64:67]
	v_mfma_f32_16x16x32_bf16 v[68:71], v[148:151], v[218:221], v[68:71]
	v_mfma_f32_16x16x32_bf16 v[68:71], v[144:147], v[214:217], v[68:71]
	s_barrier
	s_setprio 0
	s_add_i32 s64, s84, s69
	v_lshl_add_u64 v[222:223], v[222:223], 0, s[26:27]
	s_mov_b32 m0, s64
	s_nop 0
	global_load_lds_dwordx4 v[222:223], off
	s_add_i32 m0, s64, 0x2000
	s_add_u32 s62, s62, 0x80080
	v_lshl_add_u64 v[222:223], v[224:225], 0, s[26:27]
	s_addc_u32 s63, s63, 0
	s_add_i32 s64, s85, s69
	global_load_lds_dwordx4 v[222:223], off
	v_lshl_add_u64 v[222:223], s[62:63], 0, v[154:155]
	s_mov_b32 m0, s64
	s_nop 0
	global_load_lds_dwordx4 v[222:223], off
	v_lshl_add_u64 v[222:223], s[62:63], 0, v[162:163]
	s_add_i32 m0, s64, 0x2000
	s_nop 0
	global_load_lds_dwordx4 v[222:223], off
	v_lshl_add_u64 v[222:223], v[226:227], 0, s[26:27]
	s_mov_b32 m0, s3
	s_nop 0
	global_load_lds_dwordx4 v[222:223], off
	v_lshl_add_u64 v[222:223], v[228:229], 0, s[26:27]
	s_mov_b32 m0, s75
	s_nop 0
	global_load_lds_dwordx4 v[222:223], off
	ds_read_b128 v[180:183], v191 offset:49152
	v_xor_b32_e32 v253, 64, v191
	ds_read_b128 v[194:197], v253 offset:49152
	ds_read_b128 v[198:201], v191 offset:51200
	ds_read_b128 v[202:205], v253 offset:51200
	ds_read_b128 v[206:209], v191 offset:53248
	ds_read_b128 v[210:213], v253 offset:53248
	ds_read_b128 v[214:217], v191 offset:55296
	ds_read_b128 v[218:221], v253 offset:55296
	s_waitcnt vmcnt(8)
	s_waitcnt lgkmcnt(0)
	s_setprio 1
	s_barrier
	v_mfma_f32_16x16x32_bf16 v[60:63], v[128:131], v[180:183], v[60:63]
	v_mfma_f32_16x16x32_bf16 v[60:63], v[132:135], v[194:197], v[60:63]
	v_mfma_f32_16x16x32_bf16 v[56:59], v[140:143], v[194:197], v[56:59]
	v_mfma_f32_16x16x32_bf16 v[56:59], v[136:139], v[180:183], v[56:59]
	v_mfma_f32_16x16x32_bf16 v[40:43], v[136:139], v[198:201], v[40:43]
	v_mfma_f32_16x16x32_bf16 v[40:43], v[140:143], v[202:205], v[40:43]
	v_mfma_f32_16x16x32_bf16 v[44:47], v[132:135], v[202:205], v[44:47]
	v_mfma_f32_16x16x32_bf16 v[44:47], v[128:131], v[198:201], v[44:47]
	v_mfma_f32_16x16x32_bf16 v[28:31], v[128:131], v[206:209], v[28:31]
	v_mfma_f32_16x16x32_bf16 v[28:31], v[132:135], v[210:213], v[28:31]
	v_mfma_f32_16x16x32_bf16 v[24:27], v[140:143], v[210:213], v[24:27]
	v_mfma_f32_16x16x32_bf16 v[24:27], v[136:139], v[206:209], v[24:27]
	v_mfma_f32_16x16x32_bf16 v[8:11], v[136:139], v[214:217], v[8:11]
	v_mfma_f32_16x16x32_bf16 v[8:11], v[140:143], v[218:221], v[8:11]
	v_mfma_f32_16x16x32_bf16 v[12:15], v[132:135], v[218:221], v[12:15]
	v_mfma_f32_16x16x32_bf16 v[12:15], v[128:131], v[214:217], v[12:15]
	s_setprio 0
	s_setprio 1
	v_mfma_f32_16x16x32_bf16 v[52:55], v[144:147], v[180:183], v[52:55]
	v_mfma_f32_16x16x32_bf16 v[52:55], v[148:151], v[194:197], v[52:55]
	v_mfma_f32_16x16x32_bf16 v[48:51], v[176:179], v[194:197], v[48:51]
	v_mfma_f32_16x16x32_bf16 v[48:51], v[172:175], v[180:183], v[48:51]
	v_mfma_f32_16x16x32_bf16 v[32:35], v[172:175], v[198:201], v[32:35]
	v_mfma_f32_16x16x32_bf16 v[32:35], v[176:179], v[202:205], v[32:35]
	v_mfma_f32_16x16x32_bf16 v[36:39], v[148:151], v[202:205], v[36:39]
	v_mfma_f32_16x16x32_bf16 v[36:39], v[144:147], v[198:201], v[36:39]
	v_mfma_f32_16x16x32_bf16 v[20:23], v[144:147], v[206:209], v[20:23]
	v_mfma_f32_16x16x32_bf16 v[20:23], v[148:151], v[210:213], v[20:23]
	v_mfma_f32_16x16x32_bf16 v[16:19], v[176:179], v[210:213], v[16:19]
	v_mfma_f32_16x16x32_bf16 v[16:19], v[172:175], v[206:209], v[16:19]
	v_mfma_f32_16x16x32_bf16 v[0:3], v[172:175], v[214:217], v[0:3]
	v_mfma_f32_16x16x32_bf16 v[0:3], v[176:179], v[218:221], v[0:3]
	v_mfma_f32_16x16x32_bf16 v[4:7], v[148:151], v[218:221], v[4:7]
	v_mfma_f32_16x16x32_bf16 v[4:7], v[144:147], v[214:217], v[4:7]
	s_barrier
	s_setprio 0
	s_add_i32 s83, s83, 2
	s_add_u32 s81, s81, 0x100
	s_addc_u32 s82, s82, 0
	s_add_u32 s60, s60, 0x100
	s_addc_u32 s61, s61, 0
	s_cmp_gt_u32 s83, 29
.LBB0_440:
	ds_read_b128 v[128:131], v189
	v_xor_b32_e32 v253, 64, v189
	ds_read_b128 v[132:135], v253
	ds_read_b128 v[136:139], v189 offset:2048
	ds_read_b128 v[140:143], v253 offset:2048
	ds_read_b128 v[144:147], v190
	v_xor_b32_e32 v253, 64, v190
	ds_read_b128 v[148:151], v253
	ds_read_b128 v[172:175], v190 offset:2048
	ds_read_b128 v[176:179], v253 offset:2048
	s_add_u32 s62, s60, 0xfff80080
	s_addc_u32 s63, s61, -1
	s_cmp_eq_u32 s83, 28
	s_cselect_b32 s65, s15, s63
	s_cselect_b32 s64, s53, s62
	s_cselect_b32 s63, s51, s82
	s_cselect_b32 s62, s59, s81
	v_lshl_add_u64 v[222:223], s[60:61], 0, v[166:167]
	s_add_i32 m0, s70, 0xc000
	s_nop 0
	global_load_lds_dwordx4 v[222:223], off
	v_lshl_add_u64 v[222:223], s[60:61], 0, v[164:165]
	s_add_i32 m0, s70, 0xe000
	s_nop 0
	global_load_lds_dwordx4 v[222:223], off
	ds_read_b128 v[180:183], v191
	v_xor_b32_e32 v253, 64, v191
	ds_read_b128 v[194:197], v253
	ds_read_b128 v[198:201], v191 offset:2048
	ds_read_b128 v[202:205], v253 offset:2048
	ds_read_b128 v[206:209], v191 offset:4096
	ds_read_b128 v[210:213], v253 offset:4096
	ds_read_b128 v[214:217], v191 offset:6144
	ds_read_b128 v[218:221], v253 offset:6144
	s_waitcnt vmcnt(8)
	s_waitcnt lgkmcnt(0)
	s_setprio 1
	s_barrier
	v_mfma_f32_16x16x32_bf16 v[124:127], v[128:131], v[180:183], v[124:127]
	v_mfma_f32_16x16x32_bf16 v[124:127], v[132:135], v[194:197], v[124:127]
	v_mfma_f32_16x16x32_bf16 v[120:123], v[140:143], v[194:197], v[120:123]
	v_mfma_f32_16x16x32_bf16 v[120:123], v[136:139], v[180:183], v[120:123]
	v_mfma_f32_16x16x32_bf16 v[104:107], v[136:139], v[198:201], v[104:107]
	v_mfma_f32_16x16x32_bf16 v[104:107], v[140:143], v[202:205], v[104:107]
	v_mfma_f32_16x16x32_bf16 v[108:111], v[132:135], v[202:205], v[108:111]
	v_mfma_f32_16x16x32_bf16 v[108:111], v[128:131], v[198:201], v[108:111]
	v_mfma_f32_16x16x32_bf16 v[92:95], v[128:131], v[206:209], v[92:95]
	v_mfma_f32_16x16x32_bf16 v[92:95], v[132:135], v[210:213], v[92:95]
	v_mfma_f32_16x16x32_bf16 v[88:91], v[140:143], v[210:213], v[88:91]
	v_mfma_f32_16x16x32_bf16 v[88:91], v[136:139], v[206:209], v[88:91]
	v_mfma_f32_16x16x32_bf16 v[72:75], v[136:139], v[214:217], v[72:75]
	v_mfma_f32_16x16x32_bf16 v[72:75], v[140:143], v[218:221], v[72:75]
	v_mfma_f32_16x16x32_bf16 v[76:79], v[132:135], v[218:221], v[76:79]
	v_mfma_f32_16x16x32_bf16 v[76:79], v[128:131], v[214:217], v[76:79]
	s_setprio 0
	s_setprio 1
	v_mfma_f32_16x16x32_bf16 v[116:119], v[144:147], v[180:183], v[116:119]
	v_mfma_f32_16x16x32_bf16 v[116:119], v[148:151], v[194:197], v[116:119]
	v_mfma_f32_16x16x32_bf16 v[112:115], v[176:179], v[194:197], v[112:115]
	v_mfma_f32_16x16x32_bf16 v[112:115], v[172:175], v[180:183], v[112:115]
	v_mfma_f32_16x16x32_bf16 v[96:99], v[172:175], v[198:201], v[96:99]
	v_mfma_f32_16x16x32_bf16 v[96:99], v[176:179], v[202:205], v[96:99]
	v_mfma_f32_16x16x32_bf16 v[100:103], v[148:151], v[202:205], v[100:103]
	v_mfma_f32_16x16x32_bf16 v[100:103], v[144:147], v[198:201], v[100:103]
	v_mfma_f32_16x16x32_bf16 v[84:87], v[144:147], v[206:209], v[84:87]
	v_mfma_f32_16x16x32_bf16 v[84:87], v[148:151], v[210:213], v[84:87]
	v_mfma_f32_16x16x32_bf16 v[80:83], v[176:179], v[210:213], v[80:83]
	v_mfma_f32_16x16x32_bf16 v[80:83], v[172:175], v[206:209], v[80:83]
	v_mfma_f32_16x16x32_bf16 v[64:67], v[172:175], v[214:217], v[64:67]
	v_mfma_f32_16x16x32_bf16 v[64:67], v[176:179], v[218:221], v[64:67]
	v_mfma_f32_16x16x32_bf16 v[68:71], v[148:151], v[218:221], v[68:71]
	v_mfma_f32_16x16x32_bf16 v[68:71], v[144:147], v[214:217], v[68:71]
	s_barrier
	s_setprio 0
	s_add_i32 s84, s79, s69
	v_lshl_add_u64 v[222:223], s[62:63], 0, v[154:155]
	s_mov_b32 m0, s84
	s_nop 0
	global_load_lds_dwordx4 v[222:223], off
	s_add_i32 m0, s84, 0x2000
	s_add_u32 s84, s62, 0x80000
	v_lshl_add_u64 v[224:225], s[62:63], 0, v[162:163]
	s_addc_u32 s85, s63, 0
	s_add_i32 s86, s80, s69
	global_load_lds_dwordx4 v[224:225], off
	v_lshl_add_u64 v[226:227], s[84:85], 0, v[154:155]
	s_mov_b32 m0, s86
	v_lshl_add_u64 v[228:229], s[64:65], 0, v[160:161]
	global_load_lds_dwordx4 v[226:227], off
	v_lshl_add_u64 v[226:227], s[84:85], 0, v[162:163]
	s_add_i32 m0, s86, 0x2000
	s_nop 0
	global_load_lds_dwordx4 v[226:227], off
	v_lshl_add_u64 v[226:227], s[64:65], 0, v[152:153]
	s_mov_b32 m0, s70
	s_nop 0
	global_load_lds_dwordx4 v[226:227], off
	s_mov_b32 m0, s71
	s_nop 0
	global_load_lds_dwordx4 v[228:229], off
	ds_read_b128 v[180:183], v191 offset:16384
	v_xor_b32_e32 v253, 64, v191
	ds_read_b128 v[194:197], v253 offset:16384
	ds_read_b128 v[198:201], v191 offset:18432
	ds_read_b128 v[202:205], v253 offset:18432
	ds_read_b128 v[206:209], v191 offset:20480
	ds_read_b128 v[210:213], v253 offset:20480
	ds_read_b128 v[214:217], v191 offset:22528
	ds_read_b128 v[218:221], v253 offset:22528
	s_waitcnt vmcnt(8)
	s_waitcnt lgkmcnt(0)
	s_setprio 1
	s_barrier
	v_mfma_f32_16x16x32_bf16 v[60:63], v[128:131], v[180:183], v[60:63]
	v_mfma_f32_16x16x32_bf16 v[60:63], v[132:135], v[194:197], v[60:63]
	v_mfma_f32_16x16x32_bf16 v[56:59], v[140:143], v[194:197], v[56:59]
	v_mfma_f32_16x16x32_bf16 v[56:59], v[136:139], v[180:183], v[56:59]
	v_mfma_f32_16x16x32_bf16 v[40:43], v[136:139], v[198:201], v[40:43]
	v_mfma_f32_16x16x32_bf16 v[40:43], v[140:143], v[202:205], v[40:43]
	v_mfma_f32_16x16x32_bf16 v[44:47], v[132:135], v[202:205], v[44:47]
	v_mfma_f32_16x16x32_bf16 v[44:47], v[128:131], v[198:201], v[44:47]
	v_mfma_f32_16x16x32_bf16 v[28:31], v[128:131], v[206:209], v[28:31]
	v_mfma_f32_16x16x32_bf16 v[28:31], v[132:135], v[210:213], v[28:31]
	v_mfma_f32_16x16x32_bf16 v[24:27], v[140:143], v[210:213], v[24:27]
	v_mfma_f32_16x16x32_bf16 v[24:27], v[136:139], v[206:209], v[24:27]
	v_mfma_f32_16x16x32_bf16 v[8:11], v[136:139], v[214:217], v[8:11]
	v_mfma_f32_16x16x32_bf16 v[8:11], v[140:143], v[218:221], v[8:11]
	v_mfma_f32_16x16x32_bf16 v[12:15], v[132:135], v[218:221], v[12:15]
	v_mfma_f32_16x16x32_bf16 v[12:15], v[128:131], v[214:217], v[12:15]
	s_setprio 0
	s_setprio 1
	v_mfma_f32_16x16x32_bf16 v[52:55], v[144:147], v[180:183], v[52:55]
	v_mfma_f32_16x16x32_bf16 v[52:55], v[148:151], v[194:197], v[52:55]
	v_mfma_f32_16x16x32_bf16 v[48:51], v[176:179], v[194:197], v[48:51]
	v_mfma_f32_16x16x32_bf16 v[48:51], v[172:175], v[180:183], v[48:51]
	v_mfma_f32_16x16x32_bf16 v[32:35], v[172:175], v[198:201], v[32:35]
	v_mfma_f32_16x16x32_bf16 v[32:35], v[176:179], v[202:205], v[32:35]
	v_mfma_f32_16x16x32_bf16 v[36:39], v[148:151], v[202:205], v[36:39]
	v_mfma_f32_16x16x32_bf16 v[36:39], v[144:147], v[198:201], v[36:39]
	v_mfma_f32_16x16x32_bf16 v[20:23], v[144:147], v[206:209], v[20:23]
	v_mfma_f32_16x16x32_bf16 v[20:23], v[148:151], v[210:213], v[20:23]
	v_mfma_f32_16x16x32_bf16 v[16:19], v[176:179], v[210:213], v[16:19]
	v_mfma_f32_16x16x32_bf16 v[16:19], v[172:175], v[206:209], v[16:19]
	v_mfma_f32_16x16x32_bf16 v[0:3], v[172:175], v[214:217], v[0:3]
	v_mfma_f32_16x16x32_bf16 v[0:3], v[176:179], v[218:221], v[0:3]
	v_mfma_f32_16x16x32_bf16 v[4:7], v[148:151], v[218:221], v[4:7]
	v_mfma_f32_16x16x32_bf16 v[4:7], v[144:147], v[214:217], v[4:7]
	s_barrier
	s_setprio 0
	s_add_i32 s84, 0, 0x18000
	s_add_i32 s85, 0, 0x1c000
	v_add_u32_e32 v140, s84, v186
	v_add_u32_e32 v176, s85, v186
	s_add_u32 s64, s64, 0x80000
	s_addc_u32 s65, s65, 0
	s_mov_b32 m0, s72
	v_lshl_add_u64 v[230:231], s[64:65], 0, v[152:153]
	global_load_lds_dwordx4 v[230:231], off
	v_lshl_add_u64 v[230:231], s[64:65], 0, v[160:161]
	s_mov_b32 m0, s73
	s_nop 0
	global_load_lds_dwordx4 v[230:231], off
	ds_read_b128 v[128:131], v140
	v_xor_b32_e32 v253, 64, v140
	ds_read_b128 v[132:135], v253
	ds_read_b128 v[136:139], v140 offset:2048
	ds_read_b128 v[140:143], v253 offset:2048
	ds_read_b128 v[144:147], v176
	v_xor_b32_e32 v253, 64, v176
	ds_read_b128 v[148:151], v253
	ds_read_b128 v[172:175], v176 offset:2048
	ds_read_b128 v[176:179], v253 offset:2048
	ds_read_b128 v[180:183], v191 offset:32768
	v_xor_b32_e32 v253, 64, v191
	ds_read_b128 v[194:197], v253 offset:32768
	ds_read_b128 v[198:201], v191 offset:34816
	ds_read_b128 v[202:205], v253 offset:34816
	ds_read_b128 v[206:209], v191 offset:36864
	ds_read_b128 v[210:213], v253 offset:36864
	ds_read_b128 v[214:217], v191 offset:38912
	ds_read_b128 v[218:221], v253 offset:38912
	s_waitcnt vmcnt(8)
	s_waitcnt lgkmcnt(0)
	s_setprio 1
	s_barrier
	v_mfma_f32_16x16x32_bf16 v[124:127], v[128:131], v[180:183], v[124:127]
	v_mfma_f32_16x16x32_bf16 v[124:127], v[132:135], v[194:197], v[124:127]
	v_mfma_f32_16x16x32_bf16 v[120:123], v[140:143], v[194:197], v[120:123]
	v_mfma_f32_16x16x32_bf16 v[120:123], v[136:139], v[180:183], v[120:123]
	v_mfma_f32_16x16x32_bf16 v[104:107], v[136:139], v[198:201], v[104:107]
	v_mfma_f32_16x16x32_bf16 v[104:107], v[140:143], v[202:205], v[104:107]
	v_mfma_f32_16x16x32_bf16 v[108:111], v[132:135], v[202:205], v[108:111]
	v_mfma_f32_16x16x32_bf16 v[108:111], v[128:131], v[198:201], v[108:111]
	v_mfma_f32_16x16x32_bf16 v[92:95], v[128:131], v[206:209], v[92:95]
	v_mfma_f32_16x16x32_bf16 v[92:95], v[132:135], v[210:213], v[92:95]
	v_mfma_f32_16x16x32_bf16 v[88:91], v[140:143], v[210:213], v[88:91]
	v_mfma_f32_16x16x32_bf16 v[88:91], v[136:139], v[206:209], v[88:91]
	v_mfma_f32_16x16x32_bf16 v[72:75], v[136:139], v[214:217], v[72:75]
	v_mfma_f32_16x16x32_bf16 v[72:75], v[140:143], v[218:221], v[72:75]
	v_mfma_f32_16x16x32_bf16 v[76:79], v[132:135], v[218:221], v[76:79]
	v_mfma_f32_16x16x32_bf16 v[76:79], v[128:131], v[214:217], v[76:79]
	s_setprio 0
	s_setprio 1
	v_mfma_f32_16x16x32_bf16 v[116:119], v[144:147], v[180:183], v[116:119]
	v_mfma_f32_16x16x32_bf16 v[116:119], v[148:151], v[194:197], v[116:119]
	v_mfma_f32_16x16x32_bf16 v[112:115], v[176:179], v[194:197], v[112:115]
	v_mfma_f32_16x16x32_bf16 v[112:115], v[172:175], v[180:183], v[112:115]
	v_mfma_f32_16x16x32_bf16 v[96:99], v[172:175], v[198:201], v[96:99]
	v_mfma_f32_16x16x32_bf16 v[96:99], v[176:179], v[202:205], v[96:99]
	v_mfma_f32_16x16x32_bf16 v[100:103], v[148:151], v[202:205], v[100:103]
	v_mfma_f32_16x16x32_bf16 v[100:103], v[144:147], v[198:201], v[100:103]
	v_mfma_f32_16x16x32_bf16 v[84:87], v[144:147], v[206:209], v[84:87]
	v_mfma_f32_16x16x32_bf16 v[84:87], v[148:151], v[210:213], v[84:87]
	v_mfma_f32_16x16x32_bf16 v[80:83], v[176:179], v[210:213], v[80:83]
	v_mfma_f32_16x16x32_bf16 v[80:83], v[172:175], v[206:209], v[80:83]
	v_mfma_f32_16x16x32_bf16 v[64:67], v[172:175], v[214:217], v[64:67]
	v_mfma_f32_16x16x32_bf16 v[64:67], v[176:179], v[218:221], v[64:67]
	v_mfma_f32_16x16x32_bf16 v[68:71], v[148:151], v[218:221], v[68:71]
	v_mfma_f32_16x16x32_bf16 v[68:71], v[144:147], v[214:217], v[68:71]
	s_barrier
	s_setprio 0
	s_add_i32 s64, s84, s69
	v_lshl_add_u64 v[222:223], v[222:223], 0, s[26:27]
	s_mov_b32 m0, s64
	s_nop 0
	global_load_lds_dwordx4 v[222:223], off
	s_add_i32 m0, s64, 0x2000
	s_add_u32 s62, s62, 0x80080
	v_lshl_add_u64 v[222:223], v[224:225], 0, s[26:27]
	s_addc_u32 s63, s63, 0
	s_add_i32 s64, s85, s69
	global_load_lds_dwordx4 v[222:223], off
	v_lshl_add_u64 v[222:223], s[62:63], 0, v[154:155]
	s_mov_b32 m0, s64
	s_nop 0
	global_load_lds_dwordx4 v[222:223], off
	v_lshl_add_u64 v[222:223], s[62:63], 0, v[162:163]
	s_add_i32 m0, s64, 0x2000
	s_nop 0
	global_load_lds_dwordx4 v[222:223], off
	v_lshl_add_u64 v[222:223], v[226:227], 0, s[26:27]
	s_mov_b32 m0, s3
	s_nop 0
	global_load_lds_dwordx4 v[222:223], off
	v_lshl_add_u64 v[222:223], v[228:229], 0, s[26:27]
	s_mov_b32 m0, s75
	s_nop 0
	global_load_lds_dwordx4 v[222:223], off
	ds_read_b128 v[180:183], v191 offset:49152
	v_xor_b32_e32 v253, 64, v191
	ds_read_b128 v[194:197], v253 offset:49152
	ds_read_b128 v[198:201], v191 offset:51200
	ds_read_b128 v[202:205], v253 offset:51200
	ds_read_b128 v[206:209], v191 offset:53248
	ds_read_b128 v[210:213], v253 offset:53248
	ds_read_b128 v[214:217], v191 offset:55296
	ds_read_b128 v[218:221], v253 offset:55296
	s_waitcnt vmcnt(8)
	s_waitcnt lgkmcnt(0)
	s_setprio 1
	s_barrier
	v_mfma_f32_16x16x32_bf16 v[60:63], v[128:131], v[180:183], v[60:63]
	v_mfma_f32_16x16x32_bf16 v[60:63], v[132:135], v[194:197], v[60:63]
	v_mfma_f32_16x16x32_bf16 v[56:59], v[140:143], v[194:197], v[56:59]
	v_mfma_f32_16x16x32_bf16 v[56:59], v[136:139], v[180:183], v[56:59]
	v_mfma_f32_16x16x32_bf16 v[40:43], v[136:139], v[198:201], v[40:43]
	v_mfma_f32_16x16x32_bf16 v[40:43], v[140:143], v[202:205], v[40:43]
	v_mfma_f32_16x16x32_bf16 v[44:47], v[132:135], v[202:205], v[44:47]
	v_mfma_f32_16x16x32_bf16 v[44:47], v[128:131], v[198:201], v[44:47]
	v_mfma_f32_16x16x32_bf16 v[28:31], v[128:131], v[206:209], v[28:31]
	v_mfma_f32_16x16x32_bf16 v[28:31], v[132:135], v[210:213], v[28:31]
	v_mfma_f32_16x16x32_bf16 v[24:27], v[140:143], v[210:213], v[24:27]
	v_mfma_f32_16x16x32_bf16 v[24:27], v[136:139], v[206:209], v[24:27]
	v_mfma_f32_16x16x32_bf16 v[8:11], v[136:139], v[214:217], v[8:11]
	v_mfma_f32_16x16x32_bf16 v[8:11], v[140:143], v[218:221], v[8:11]
	v_mfma_f32_16x16x32_bf16 v[12:15], v[132:135], v[218:221], v[12:15]
	v_mfma_f32_16x16x32_bf16 v[12:15], v[128:131], v[214:217], v[12:15]
	s_setprio 0
	s_setprio 1
	v_mfma_f32_16x16x32_bf16 v[52:55], v[144:147], v[180:183], v[52:55]
	v_mfma_f32_16x16x32_bf16 v[52:55], v[148:151], v[194:197], v[52:55]
	v_mfma_f32_16x16x32_bf16 v[48:51], v[176:179], v[194:197], v[48:51]
	v_mfma_f32_16x16x32_bf16 v[48:51], v[172:175], v[180:183], v[48:51]
	v_mfma_f32_16x16x32_bf16 v[32:35], v[172:175], v[198:201], v[32:35]
	v_mfma_f32_16x16x32_bf16 v[32:35], v[176:179], v[202:205], v[32:35]
	v_mfma_f32_16x16x32_bf16 v[36:39], v[148:151], v[202:205], v[36:39]
	v_mfma_f32_16x16x32_bf16 v[36:39], v[144:147], v[198:201], v[36:39]
	v_mfma_f32_16x16x32_bf16 v[20:23], v[144:147], v[206:209], v[20:23]
	v_mfma_f32_16x16x32_bf16 v[20:23], v[148:151], v[210:213], v[20:23]
	v_mfma_f32_16x16x32_bf16 v[16:19], v[176:179], v[210:213], v[16:19]
	v_mfma_f32_16x16x32_bf16 v[16:19], v[172:175], v[206:209], v[16:19]
	v_mfma_f32_16x16x32_bf16 v[0:3], v[172:175], v[214:217], v[0:3]
	v_mfma_f32_16x16x32_bf16 v[0:3], v[176:179], v[218:221], v[0:3]
	v_mfma_f32_16x16x32_bf16 v[4:7], v[148:151], v[218:221], v[4:7]
	v_mfma_f32_16x16x32_bf16 v[4:7], v[144:147], v[214:217], v[4:7]
	s_barrier
	s_setprio 0
	s_add_i32 s83, s83, 2
	s_add_u32 s81, s81, 0x100
	s_addc_u32 s82, s82, 0
	s_add_u32 s60, s60, 0x100
	s_addc_u32 s61, s61, 0
	s_cmp_gt_u32 s83, 29
	s_cbranch_scc0 .LBB0_440
	s_and_b64 vcc, exec, s[28:29]
	s_cbranch_vccz .LBB0_443
	s_barrier

.LBB0_525:
	s_ashr_i32 s29, s28, 31
	s_lshl_b64 s[30:31], s[28:29], 19
	s_add_u32 s30, s3, s30
	s_addc_u32 s31, s35, s31
	s_and_b64 s[44:45], s[10:11], exec
	s_cselect_b32 s29, s31, s51
	s_cselect_b32 s70, s30, s50
	s_ashr_i32 s27, s26, 31
	s_lshl_b64 s[44:45], s[26:27], 19
	s_add_u32 s44, s52, s44
	s_addc_u32 s45, s53, s45
	s_and_b64 s[72:73], s[10:11], exec
	s_cselect_b32 s71, s45, s49
	s_cselect_b32 s72, s44, s48
	s_lshl_b32 s27, s46, 8
	v_add_u32_e32 v0, s27, v148
	s_add_u32 s73, s48, 0x100
	v_ashrrev_i32_e32 v1, 31, v0
	s_addc_u32 s74, s49, 0
	v_lshl_add_u64 v[144:145], v[0:1], 4, s[16:17]
	s_add_u32 s46, s50, 0x40080
	s_addc_u32 s47, s51, 0
	s_mov_b32 s75, -2
	s_mov_b64 s[48:49], 0
	s_cmp_eq_u32 s61, 1
	s_cbranch_scc1 .Lfa_4
	s_add_u32 s50, s46, 0xfffc0080
	s_addc_u32 s51, s47, -1
	s_and_b64 s[48:49], s[48:49], exec
	s_cselect_b32 s51, s29, s51
	s_cselect_b32 s50, s70, s50
	s_cselect_b32 s49, s71, s74
	s_cselect_b32 s48, s72, s73
	v_lshl_add_u64 v[154:155], s[46:47], 0, v[138:139]
	s_add_i32 m0, s57, 0xc000
	s_nop 0
	global_load_lds_dwordx4 v[154:155], off
	v_lshl_add_u64 v[154:155], s[46:47], 0, v[136:137]
	s_add_i32 m0, s57, 0xe000
	s_nop 0
	global_load_lds_dwordx4 v[154:155], off
	v_add_u32_e32 v153, s66, v147
	ds_read_b128 v[160:163], v153
	v_xor_b32_e32 v253, 64, v153
	ds_read_b128 v[164:167], v253
	ds_read_b128 v[168:171], v153 offset:2048
	ds_read_b128 v[172:175], v253 offset:2048
	v_add_u32_e32 v153, s67, v147
	ds_read_b128 v[176:179], v153
	v_xor_b32_e32 v253, 64, v153
	ds_read_b128 v[180:183], v253
	ds_read_b128 v[186:189], v153 offset:2048
	ds_read_b128 v[190:193], v253 offset:2048
	ds_read_b128 v[194:197], v150
	v_xor_b32_e32 v253, 64, v150
	ds_read_b128 v[198:201], v253
	ds_read_b128 v[202:205], v150 offset:2048
	ds_read_b128 v[206:209], v253 offset:2048
	ds_read_b128 v[210:213], v150 offset:4096
	ds_read_b128 v[214:217], v253 offset:4096
	ds_read_b128 v[218:221], v150 offset:6144
	ds_read_b128 v[222:225], v253 offset:6144
	s_waitcnt vmcnt(16)
	s_waitcnt lgkmcnt(0)
	s_setprio 1
	s_barrier
	v_mfma_f32_16x16x32_bf16 v[124:127], v[160:163], v[194:197], 0
	v_mfma_f32_16x16x32_bf16 v[116:119], v[168:171], v[194:197], 0
	v_mfma_f32_16x16x32_bf16 v[108:111], v[160:163], v[202:205], 0
	v_mfma_f32_16x16x32_bf16 v[100:103], v[168:171], v[202:205], 0
	v_mfma_f32_16x16x32_bf16 v[92:95], v[160:163], v[210:213], 0
	v_mfma_f32_16x16x32_bf16 v[84:87], v[168:171], v[210:213], 0
	v_mfma_f32_16x16x32_bf16 v[76:79], v[160:163], v[218:221], 0
	v_mfma_f32_16x16x32_bf16 v[68:71], v[168:171], v[218:221], 0
	v_mfma_f32_16x16x32_bf16 v[124:127], v[164:167], v[198:201], v[124:127]
	v_mfma_f32_16x16x32_bf16 v[116:119], v[172:175], v[198:201], v[116:119]
	v_mfma_f32_16x16x32_bf16 v[108:111], v[164:167], v[206:209], v[108:111]
	v_mfma_f32_16x16x32_bf16 v[100:103], v[172:175], v[206:209], v[100:103]
	v_mfma_f32_16x16x32_bf16 v[92:95], v[164:167], v[214:217], v[92:95]
	v_mfma_f32_16x16x32_bf16 v[84:87], v[172:175], v[214:217], v[84:87]
	v_mfma_f32_16x16x32_bf16 v[76:79], v[164:167], v[222:225], v[76:79]
	v_mfma_f32_16x16x32_bf16 v[68:71], v[172:175], v[222:225], v[68:71]
	s_setprio 0
	s_setprio 1
	v_mfma_f32_16x16x32_bf16 v[120:123], v[176:179], v[194:197], 0
	v_mfma_f32_16x16x32_bf16 v[112:115], v[186:189], v[194:197], 0
	v_mfma_f32_16x16x32_bf16 v[104:107], v[176:179], v[202:205], 0
	v_mfma_f32_16x16x32_bf16 v[96:99], v[186:189], v[202:205], 0
	v_mfma_f32_16x16x32_bf16 v[88:91], v[176:179], v[210:213], 0
	v_mfma_f32_16x16x32_bf16 v[80:83], v[186:189], v[210:213], 0
	v_mfma_f32_16x16x32_bf16 v[72:75], v[176:179], v[218:221], 0
	v_mfma_f32_16x16x32_bf16 v[64:67], v[186:189], v[218:221], 0
	v_mfma_f32_16x16x32_bf16 v[120:123], v[180:183], v[198:201], v[120:123]
	v_mfma_f32_16x16x32_bf16 v[112:115], v[190:193], v[198:201], v[112:115]
	v_mfma_f32_16x16x32_bf16 v[104:107], v[180:183], v[206:209], v[104:107]
	v_mfma_f32_16x16x32_bf16 v[96:99], v[190:193], v[206:209], v[96:99]
	v_mfma_f32_16x16x32_bf16 v[88:91], v[180:183], v[214:217], v[88:91]
	v_mfma_f32_16x16x32_bf16 v[80:83], v[190:193], v[214:217], v[80:83]
	v_mfma_f32_16x16x32_bf16 v[72:75], v[180:183], v[222:225], v[72:75]
	v_mfma_f32_16x16x32_bf16 v[64:67], v[190:193], v[222:225], v[64:67]
	s_barrier
	s_setprio 0
	s_add_i32 s76, s66, s54
	v_lshl_add_u64 v[154:155], s[48:49], 0, v[132:133]
	s_mov_b32 m0, s76
	s_nop 0
	global_load_lds_dwordx4 v[154:155], off
	s_add_i32 m0, s76, 0x2000
	s_add_u32 s76, s48, 0x40000
	v_lshl_add_u64 v[226:227], s[48:49], 0, v[128:129]
	s_addc_u32 s77, s49, 0
	s_add_i32 s78, s67, s54
	global_load_lds_dwordx4 v[226:227], off
	v_lshl_add_u64 v[228:229], s[76:77], 0, v[132:133]
	s_mov_b32 m0, s78
	v_lshl_add_u64 v[230:231], s[50:51], 0, v[130:131]
	global_load_lds_dwordx4 v[228:229], off
	v_lshl_add_u64 v[228:229], s[76:77], 0, v[128:129]
	s_add_i32 m0, s78, 0x2000
	s_nop 0
	global_load_lds_dwordx4 v[228:229], off
	v_lshl_add_u64 v[228:229], s[50:51], 0, v[134:135]
	s_mov_b32 m0, s57
	s_nop 0
	global_load_lds_dwordx4 v[228:229], off
	s_mov_b32 m0, s58
	s_nop 0
	global_load_lds_dwordx4 v[230:231], off
	ds_read_b128 v[194:197], v150 offset:16384
	v_xor_b32_e32 v253, 64, v150
	ds_read_b128 v[198:201], v253 offset:16384
	ds_read_b128 v[202:205], v150 offset:18432
	ds_read_b128 v[206:209], v253 offset:18432
	ds_read_b128 v[210:213], v150 offset:20480
	ds_read_b128 v[214:217], v253 offset:20480
	ds_read_b128 v[218:221], v150 offset:22528
	ds_read_b128 v[222:225], v253 offset:22528
	s_waitcnt vmcnt(16)
	s_waitcnt lgkmcnt(0)
	s_setprio 1
	s_barrier
	v_mfma_f32_16x16x32_bf16 v[60:63], v[160:163], v[194:197], 0
	v_mfma_f32_16x16x32_bf16 v[52:55], v[168:171], v[194:197], 0
	v_mfma_f32_16x16x32_bf16 v[44:47], v[160:163], v[202:205], 0
	v_mfma_f32_16x16x32_bf16 v[36:39], v[168:171], v[202:205], 0
	v_mfma_f32_16x16x32_bf16 v[28:31], v[160:163], v[210:213], 0
	v_mfma_f32_16x16x32_bf16 v[20:23], v[168:171], v[210:213], 0
	v_mfma_f32_16x16x32_bf16 v[12:15], v[160:163], v[218:221], 0
	v_mfma_f32_16x16x32_bf16 v[4:7], v[168:171], v[218:221], 0
	v_mfma_f32_16x16x32_bf16 v[60:63], v[164:167], v[198:201], v[60:63]
	v_mfma_f32_16x16x32_bf16 v[52:55], v[172:175], v[198:201], v[52:55]
	v_mfma_f32_16x16x32_bf16 v[44:47], v[164:167], v[206:209], v[44:47]
	v_mfma_f32_16x16x32_bf16 v[36:39], v[172:175], v[206:209], v[36:39]
	v_mfma_f32_16x16x32_bf16 v[28:31], v[164:167], v[214:217], v[28:31]
	v_mfma_f32_16x16x32_bf16 v[20:23], v[172:175], v[214:217], v[20:23]
	v_mfma_f32_16x16x32_bf16 v[12:15], v[164:167], v[222:225], v[12:15]
	v_mfma_f32_16x16x32_bf16 v[4:7], v[172:175], v[222:225], v[4:7]
	s_setprio 0
	s_setprio 1
	v_mfma_f32_16x16x32_bf16 v[56:59], v[176:179], v[194:197], 0
	v_mfma_f32_16x16x32_bf16 v[48:51], v[186:189], v[194:197], 0
	v_mfma_f32_16x16x32_bf16 v[40:43], v[176:179], v[202:205], 0
	v_mfma_f32_16x16x32_bf16 v[32:35], v[186:189], v[202:205], 0
	v_mfma_f32_16x16x32_bf16 v[24:27], v[176:179], v[210:213], 0
	v_mfma_f32_16x16x32_bf16 v[16:19], v[186:189], v[210:213], 0
	v_mfma_f32_16x16x32_bf16 v[8:11], v[176:179], v[218:221], 0
	v_mfma_f32_16x16x32_bf16 v[0:3], v[186:189], v[218:221], 0
	v_mfma_f32_16x16x32_bf16 v[56:59], v[180:183], v[198:201], v[56:59]
	v_mfma_f32_16x16x32_bf16 v[48:51], v[190:193], v[198:201], v[48:51]
	v_mfma_f32_16x16x32_bf16 v[40:43], v[180:183], v[206:209], v[40:43]
	v_mfma_f32_16x16x32_bf16 v[32:35], v[190:193], v[206:209], v[32:35]
	v_mfma_f32_16x16x32_bf16 v[24:27], v[180:183], v[214:217], v[24:27]
	v_mfma_f32_16x16x32_bf16 v[16:19], v[190:193], v[214:217], v[16:19]
	v_mfma_f32_16x16x32_bf16 v[8:11], v[180:183], v[222:225], v[8:11]
	v_mfma_f32_16x16x32_bf16 v[0:3], v[190:193], v[222:225], v[0:3]
	s_barrier
	s_setprio 0
	s_add_i32 s76, 0, 0x18000
	s_add_i32 s77, 0, 0x1c000
	s_add_u32 s50, s50, 0x40000
	s_addc_u32 s51, s51, 0
	s_mov_b32 m0, s59
	v_lshl_add_u64 v[232:233], s[50:51], 0, v[134:135]
	global_load_lds_dwordx4 v[232:233], off
	v_lshl_add_u64 v[232:233], s[50:51], 0, v[130:131]
	s_mov_b32 m0, s60
	s_nop 0
	global_load_lds_dwordx4 v[232:233], off
	v_add_u32_e32 v153, s76, v147
	ds_read_b128 v[160:163], v153
	v_xor_b32_e32 v253, 64, v153
	ds_read_b128 v[164:167], v253
	ds_read_b128 v[168:171], v153 offset:2048
	ds_read_b128 v[172:175], v253 offset:2048
	v_add_u32_e32 v153, s77, v147
	ds_read_b128 v[176:179], v153
	v_xor_b32_e32 v253, 64, v153
	ds_read_b128 v[180:183], v253
	ds_read_b128 v[186:189], v153 offset:2048
	ds_read_b128 v[190:193], v253 offset:2048
	ds_read_b128 v[194:197], v150 offset:32768
	v_xor_b32_e32 v253, 64, v150
	ds_read_b128 v[198:201], v253 offset:32768
	ds_read_b128 v[202:205], v150 offset:34816
	ds_read_b128 v[206:209], v253 offset:34816
	ds_read_b128 v[210:213], v150 offset:36864
	ds_read_b128 v[214:217], v253 offset:36864
	ds_read_b128 v[218:221], v150 offset:38912
	ds_read_b128 v[222:225], v253 offset:38912
	s_waitcnt vmcnt(8)
	s_waitcnt lgkmcnt(0)
	s_setprio 1
	s_barrier
	v_mfma_f32_16x16x32_bf16 v[124:127], v[160:163], v[194:197], v[124:127]
	v_mfma_f32_16x16x32_bf16 v[124:127], v[164:167], v[198:201], v[124:127]
	v_mfma_f32_16x16x32_bf16 v[116:119], v[172:175], v[198:201], v[116:119]
	v_mfma_f32_16x16x32_bf16 v[116:119], v[168:171], v[194:197], v[116:119]
	v_mfma_f32_16x16x32_bf16 v[100:103], v[168:171], v[202:205], v[100:103]
	v_mfma_f32_16x16x32_bf16 v[100:103], v[172:175], v[206:209], v[100:103]
	v_mfma_f32_16x16x32_bf16 v[108:111], v[164:167], v[206:209], v[108:111]
	v_mfma_f32_16x16x32_bf16 v[108:111], v[160:163], v[202:205], v[108:111]
	v_mfma_f32_16x16x32_bf16 v[92:95], v[160:163], v[210:213], v[92:95]
	v_mfma_f32_16x16x32_bf16 v[92:95], v[164:167], v[214:217], v[92:95]
	v_mfma_f32_16x16x32_bf16 v[84:87], v[172:175], v[214:217], v[84:87]
	v_mfma_f32_16x16x32_bf16 v[84:87], v[168:171], v[210:213], v[84:87]
	v_mfma_f32_16x16x32_bf16 v[68:71], v[168:171], v[218:221], v[68:71]
	v_mfma_f32_16x16x32_bf16 v[68:71], v[172:175], v[222:225], v[68:71]
	v_mfma_f32_16x16x32_bf16 v[76:79], v[164:167], v[222:225], v[76:79]
	v_mfma_f32_16x16x32_bf16 v[76:79], v[160:163], v[218:221], v[76:79]
	s_setprio 0
	s_setprio 1
	v_mfma_f32_16x16x32_bf16 v[120:123], v[176:179], v[194:197], v[120:123]
	v_mfma_f32_16x16x32_bf16 v[120:123], v[180:183], v[198:201], v[120:123]
	v_mfma_f32_16x16x32_bf16 v[112:115], v[190:193], v[198:201], v[112:115]
	v_mfma_f32_16x16x32_bf16 v[112:115], v[186:189], v[194:197], v[112:115]
	v_mfma_f32_16x16x32_bf16 v[96:99], v[186:189], v[202:205], v[96:99]
	v_mfma_f32_16x16x32_bf16 v[96:99], v[190:193], v[206:209], v[96:99]
	v_mfma_f32_16x16x32_bf16 v[104:107], v[180:183], v[206:209], v[104:107]
	v_mfma_f32_16x16x32_bf16 v[104:107], v[176:179], v[202:205], v[104:107]
	v_mfma_f32_16x16x32_bf16 v[88:91], v[176:179], v[210:213], v[88:91]
	v_mfma_f32_16x16x32_bf16 v[88:91], v[180:183], v[214:217], v[88:91]
	v_mfma_f32_16x16x32_bf16 v[80:83], v[190:193], v[214:217], v[80:83]
	v_mfma_f32_16x16x32_bf16 v[80:83], v[186:189], v[210:213], v[80:83]
	v_mfma_f32_16x16x32_bf16 v[64:67], v[186:189], v[218:221], v[64:67]
	v_mfma_f32_16x16x32_bf16 v[64:67], v[190:193], v[222:225], v[64:67]
	v_mfma_f32_16x16x32_bf16 v[72:75], v[180:183], v[222:225], v[72:75]
	v_mfma_f32_16x16x32_bf16 v[72:75], v[176:179], v[218:221], v[72:75]
	s_barrier
	s_setprio 0
	s_add_i32 s50, s76, s54
	v_lshl_add_u64 v[154:155], v[154:155], 0, s[20:21]
	s_mov_b32 m0, s50
	s_nop 0
	global_load_lds_dwordx4 v[154:155], off
	s_add_i32 m0, s50, 0x2000
	s_add_u32 s48, s48, 0x40080
	v_lshl_add_u64 v[154:155], v[226:227], 0, s[20:21]
	s_addc_u32 s49, s49, 0
	s_add_i32 s50, s77, s54
	global_load_lds_dwordx4 v[154:155], off
	v_lshl_add_u64 v[154:155], s[48:49], 0, v[132:133]
	s_mov_b32 m0, s50
	s_nop 0
	global_load_lds_dwordx4 v[154:155], off
	v_lshl_add_u64 v[154:155], s[48:49], 0, v[128:129]
	s_add_i32 m0, s50, 0x2000
	s_nop 0
	global_load_lds_dwordx4 v[154:155], off
	v_lshl_add_u64 v[154:155], v[228:229], 0, s[20:21]
	s_mov_b32 m0, s62
	s_nop 0
	global_load_lds_dwordx4 v[154:155], off
	v_lshl_add_u64 v[154:155], v[230:231], 0, s[20:21]
	s_mov_b32 m0, s63
	s_nop 0
	global_load_lds_dwordx4 v[154:155], off
	ds_read_b128 v[194:197], v150 offset:49152
	v_xor_b32_e32 v253, 64, v150
	ds_read_b128 v[198:201], v253 offset:49152
	ds_read_b128 v[202:205], v150 offset:51200
	ds_read_b128 v[206:209], v253 offset:51200
	ds_read_b128 v[210:213], v150 offset:53248
	ds_read_b128 v[214:217], v253 offset:53248
	ds_read_b128 v[218:221], v150 offset:55296
	ds_read_b128 v[222:225], v253 offset:55296
	s_waitcnt vmcnt(8)
	s_waitcnt lgkmcnt(0)
	s_setprio 1
	s_barrier
	v_mfma_f32_16x16x32_bf16 v[60:63], v[160:163], v[194:197], v[60:63]
	v_mfma_f32_16x16x32_bf16 v[60:63], v[164:167], v[198:201], v[60:63]
	v_mfma_f32_16x16x32_bf16 v[52:55], v[172:175], v[198:201], v[52:55]
	v_mfma_f32_16x16x32_bf16 v[52:55], v[168:171], v[194:197], v[52:55]
	v_mfma_f32_16x16x32_bf16 v[36:39], v[168:171], v[202:205], v[36:39]
	v_mfma_f32_16x16x32_bf16 v[36:39], v[172:175], v[206:209], v[36:39]
	v_mfma_f32_16x16x32_bf16 v[44:47], v[164:167], v[206:209], v[44:47]
	v_mfma_f32_16x16x32_bf16 v[44:47], v[160:163], v[202:205], v[44:47]
	v_mfma_f32_16x16x32_bf16 v[28:31], v[160:163], v[210:213], v[28:31]
	v_mfma_f32_16x16x32_bf16 v[28:31], v[164:167], v[214:217], v[28:31]
	v_mfma_f32_16x16x32_bf16 v[20:23], v[172:175], v[214:217], v[20:23]
	v_mfma_f32_16x16x32_bf16 v[20:23], v[168:171], v[210:213], v[20:23]
	v_mfma_f32_16x16x32_bf16 v[4:7], v[168:171], v[218:221], v[4:7]
	v_mfma_f32_16x16x32_bf16 v[4:7], v[172:175], v[222:225], v[4:7]
	v_mfma_f32_16x16x32_bf16 v[12:15], v[164:167], v[222:225], v[12:15]
	v_mfma_f32_16x16x32_bf16 v[12:15], v[160:163], v[218:221], v[12:15]
	s_setprio 0
	s_setprio 1
	v_mfma_f32_16x16x32_bf16 v[56:59], v[176:179], v[194:197], v[56:59]
	v_mfma_f32_16x16x32_bf16 v[56:59], v[180:183], v[198:201], v[56:59]
	v_mfma_f32_16x16x32_bf16 v[48:51], v[190:193], v[198:201], v[48:51]
	v_mfma_f32_16x16x32_bf16 v[48:51], v[186:189], v[194:197], v[48:51]
	v_mfma_f32_16x16x32_bf16 v[32:35], v[186:189], v[202:205], v[32:35]
	v_mfma_f32_16x16x32_bf16 v[32:35], v[190:193], v[206:209], v[32:35]
	v_mfma_f32_16x16x32_bf16 v[40:43], v[180:183], v[206:209], v[40:43]
	v_mfma_f32_16x16x32_bf16 v[40:43], v[176:179], v[202:205], v[40:43]
	v_mfma_f32_16x16x32_bf16 v[24:27], v[176:179], v[210:213], v[24:27]
	v_mfma_f32_16x16x32_bf16 v[24:27], v[180:183], v[214:217], v[24:27]
	v_mfma_f32_16x16x32_bf16 v[16:19], v[190:193], v[214:217], v[16:19]
	v_mfma_f32_16x16x32_bf16 v[16:19], v[186:189], v[210:213], v[16:19]
	v_mfma_f32_16x16x32_bf16 v[0:3], v[186:189], v[218:221], v[0:3]
	v_mfma_f32_16x16x32_bf16 v[0:3], v[190:193], v[222:225], v[0:3]
	v_mfma_f32_16x16x32_bf16 v[8:11], v[180:183], v[222:225], v[8:11]
	v_mfma_f32_16x16x32_bf16 v[8:11], v[176:179], v[218:221], v[8:11]
	s_barrier
	s_setprio 0
	s_add_i32 s75, s75, 2
	s_add_u32 s73, s73, 0x100
	s_addc_u32 s74, s74, 0
	s_add_u32 s46, s46, 0x100
	s_addc_u32 s47, s47, 0
	s_branch .LBB0_527
.Lfa_4:
	s_add_u32 s50, s46, 0xfffc0080
	s_addc_u32 s51, s47, -1
	s_and_b64 s[48:49], s[48:49], exec
	s_cselect_b32 s51, s29, s51
	s_cselect_b32 s50, s70, s50
	s_cselect_b32 s49, s71, s74
	s_cselect_b32 s48, s72, s73
	v_lshl_add_u64 v[154:155], s[46:47], 0, v[138:139]
	s_add_i32 m0, s57, 0xc000
	s_nop 0
	global_load_lds_dwordx4 v[154:155], off
	v_lshl_add_u64 v[154:155], s[46:47], 0, v[136:137]
	s_add_i32 m0, s57, 0xe000
	s_nop 0
	global_load_lds_dwordx4 v[154:155], off
	v_add_u32_e32 v153, s66, v147
	ds_read_b128 v[160:163], v153
	v_xor_b32_e32 v253, 64, v153
	ds_read_b128 v[164:167], v253
	ds_read_b128 v[168:171], v153 offset:2048
	ds_read_b128 v[172:175], v253 offset:2048
	v_add_u32_e32 v153, s67, v147
	ds_read_b128 v[176:179], v153
	v_xor_b32_e32 v253, 64, v153
	ds_read_b128 v[180:183], v253
	ds_read_b128 v[186:189], v153 offset:2048
	ds_read_b128 v[190:193], v253 offset:2048
	ds_read_b128 v[194:197], v150
	v_xor_b32_e32 v253, 64, v150
	ds_read_b128 v[198:201], v253
	ds_read_b128 v[202:205], v150 offset:2048
	ds_read_b128 v[206:209], v253 offset:2048
	ds_read_b128 v[210:213], v150 offset:4096
	ds_read_b128 v[214:217], v253 offset:4096
	ds_read_b128 v[218:221], v150 offset:6144
	ds_read_b128 v[222:225], v253 offset:6144
	s_waitcnt vmcnt(8)
	s_waitcnt lgkmcnt(0)
	s_setprio 1
	s_barrier
	v_mfma_f32_16x16x32_bf16 v[124:127], v[160:163], v[194:197], 0
	v_mfma_f32_16x16x32_bf16 v[116:119], v[168:171], v[194:197], 0
	v_mfma_f32_16x16x32_bf16 v[108:111], v[160:163], v[202:205], 0
	v_mfma_f32_16x16x32_bf16 v[100:103], v[168:171], v[202:205], 0
	v_mfma_f32_16x16x32_bf16 v[92:95], v[160:163], v[210:213], 0
	v_mfma_f32_16x16x32_bf16 v[84:87], v[168:171], v[210:213], 0
	v_mfma_f32_16x16x32_bf16 v[76:79], v[160:163], v[218:221], 0
	v_mfma_f32_16x16x32_bf16 v[68:71], v[168:171], v[218:221], 0
	v_mfma_f32_16x16x32_bf16 v[124:127], v[164:167], v[198:201], v[124:127]
	v_mfma_f32_16x16x32_bf16 v[116:119], v[172:175], v[198:201], v[116:119]
	v_mfma_f32_16x16x32_bf16 v[108:111], v[164:167], v[206:209], v[108:111]
	v_mfma_f32_16x16x32_bf16 v[100:103], v[172:175], v[206:209], v[100:103]
	v_mfma_f32_16x16x32_bf16 v[92:95], v[164:167], v[214:217], v[92:95]
	v_mfma_f32_16x16x32_bf16 v[84:87], v[172:175], v[214:217], v[84:87]
	v_mfma_f32_16x16x32_bf16 v[76:79], v[164:167], v[222:225], v[76:79]
	v_mfma_f32_16x16x32_bf16 v[68:71], v[172:175], v[222:225], v[68:71]
	s_setprio 0
	s_setprio 1
	v_mfma_f32_16x16x32_bf16 v[120:123], v[176:179], v[194:197], 0
	v_mfma_f32_16x16x32_bf16 v[112:115], v[186:189], v[194:197], 0
	v_mfma_f32_16x16x32_bf16 v[104:107], v[176:179], v[202:205], 0
	v_mfma_f32_16x16x32_bf16 v[96:99], v[186:189], v[202:205], 0
	v_mfma_f32_16x16x32_bf16 v[88:91], v[176:179], v[210:213], 0
	v_mfma_f32_16x16x32_bf16 v[80:83], v[186:189], v[210:213], 0
	v_mfma_f32_16x16x32_bf16 v[72:75], v[176:179], v[218:221], 0
	v_mfma_f32_16x16x32_bf16 v[64:67], v[186:189], v[218:221], 0
	v_mfma_f32_16x16x32_bf16 v[120:123], v[180:183], v[198:201], v[120:123]
	v_mfma_f32_16x16x32_bf16 v[112:115], v[190:193], v[198:201], v[112:115]
	v_mfma_f32_16x16x32_bf16 v[104:107], v[180:183], v[206:209], v[104:107]
	v_mfma_f32_16x16x32_bf16 v[96:99], v[190:193], v[206:209], v[96:99]
	v_mfma_f32_16x16x32_bf16 v[88:91], v[180:183], v[214:217], v[88:91]
	v_mfma_f32_16x16x32_bf16 v[80:83], v[190:193], v[214:217], v[80:83]
	v_mfma_f32_16x16x32_bf16 v[72:75], v[180:183], v[222:225], v[72:75]
	v_mfma_f32_16x16x32_bf16 v[64:67], v[190:193], v[222:225], v[64:67]
	s_barrier
	s_setprio 0
	s_add_i32 s76, s66, s54
	v_lshl_add_u64 v[154:155], s[48:49], 0, v[132:133]
	s_mov_b32 m0, s76
	s_nop 0
	global_load_lds_dwordx4 v[154:155], off
	s_add_i32 m0, s76, 0x2000
	s_add_u32 s76, s48, 0x40000
	v_lshl_add_u64 v[226:227], s[48:49], 0, v[128:129]
	s_addc_u32 s77, s49, 0
	s_add_i32 s78, s67, s54
	global_load_lds_dwordx4 v[226:227], off
	v_lshl_add_u64 v[228:229], s[76:77], 0, v[132:133]
	s_mov_b32 m0, s78
	v_lshl_add_u64 v[230:231], s[50:51], 0, v[130:131]
	global_load_lds_dwordx4 v[228:229], off
	v_lshl_add_u64 v[228:229], s[76:77], 0, v[128:129]
	s_add_i32 m0, s78, 0x2000
	s_nop 0
	global_load_lds_dwordx4 v[228:229], off
	v_lshl_add_u64 v[228:229], s[50:51], 0, v[134:135]
	s_mov_b32 m0, s57
	s_nop 0
	global_load_lds_dwordx4 v[228:229], off
	s_mov_b32 m0, s58
	s_nop 0
	global_load_lds_dwordx4 v[230:231], off
	ds_read_b128 v[194:197], v150 offset:16384
	v_xor_b32_e32 v253, 64, v150
	ds_read_b128 v[198:201], v253 offset:16384
	ds_read_b128 v[202:205], v150 offset:18432
	ds_read_b128 v[206:209], v253 offset:18432
	ds_read_b128 v[210:213], v150 offset:20480
	ds_read_b128 v[214:217], v253 offset:20480
	ds_read_b128 v[218:221], v150 offset:22528
	ds_read_b128 v[222:225], v253 offset:22528
	s_waitcnt vmcnt(8)
	s_waitcnt lgkmcnt(0)
	s_setprio 1
	s_barrier
	v_mfma_f32_16x16x32_bf16 v[60:63], v[160:163], v[194:197], 0
	v_mfma_f32_16x16x32_bf16 v[52:55], v[168:171], v[194:197], 0
	v_mfma_f32_16x16x32_bf16 v[44:47], v[160:163], v[202:205], 0
	v_mfma_f32_16x16x32_bf16 v[36:39], v[168:171], v[202:205], 0
	v_mfma_f32_16x16x32_bf16 v[28:31], v[160:163], v[210:213], 0
	v_mfma_f32_16x16x32_bf16 v[20:23], v[168:171], v[210:213], 0
	v_mfma_f32_16x16x32_bf16 v[12:15], v[160:163], v[218:221], 0
	v_mfma_f32_16x16x32_bf16 v[4:7], v[168:171], v[218:221], 0
	v_mfma_f32_16x16x32_bf16 v[60:63], v[164:167], v[198:201], v[60:63]
	v_mfma_f32_16x16x32_bf16 v[52:55], v[172:175], v[198:201], v[52:55]
	v_mfma_f32_16x16x32_bf16 v[44:47], v[164:167], v[206:209], v[44:47]
	v_mfma_f32_16x16x32_bf16 v[36:39], v[172:175], v[206:209], v[36:39]
	v_mfma_f32_16x16x32_bf16 v[28:31], v[164:167], v[214:217], v[28:31]
	v_mfma_f32_16x16x32_bf16 v[20:23], v[172:175], v[214:217], v[20:23]
	v_mfma_f32_16x16x32_bf16 v[12:15], v[164:167], v[222:225], v[12:15]
	v_mfma_f32_16x16x32_bf16 v[4:7], v[172:175], v[222:225], v[4:7]
	s_setprio 0
	s_setprio 1
	v_mfma_f32_16x16x32_bf16 v[56:59], v[176:179], v[194:197], 0
	v_mfma_f32_16x16x32_bf16 v[48:51], v[186:189], v[194:197], 0
	v_mfma_f32_16x16x32_bf16 v[40:43], v[176:179], v[202:205], 0
	v_mfma_f32_16x16x32_bf16 v[32:35], v[186:189], v[202:205], 0
	v_mfma_f32_16x16x32_bf16 v[24:27], v[176:179], v[210:213], 0
	v_mfma_f32_16x16x32_bf16 v[16:19], v[186:189], v[210:213], 0
	v_mfma_f32_16x16x32_bf16 v[8:11], v[176:179], v[218:221], 0
	v_mfma_f32_16x16x32_bf16 v[0:3], v[186:189], v[218:221], 0
	v_mfma_f32_16x16x32_bf16 v[56:59], v[180:183], v[198:201], v[56:59]
	v_mfma_f32_16x16x32_bf16 v[48:51], v[190:193], v[198:201], v[48:51]
	v_mfma_f32_16x16x32_bf16 v[40:43], v[180:183], v[206:209], v[40:43]
	v_mfma_f32_16x16x32_bf16 v[32:35], v[190:193], v[206:209], v[32:35]
	v_mfma_f32_16x16x32_bf16 v[24:27], v[180:183], v[214:217], v[24:27]
	v_mfma_f32_16x16x32_bf16 v[16:19], v[190:193], v[214:217], v[16:19]
	v_mfma_f32_16x16x32_bf16 v[8:11], v[180:183], v[222:225], v[8:11]
	v_mfma_f32_16x16x32_bf16 v[0:3], v[190:193], v[222:225], v[0:3]
	s_barrier
	s_setprio 0
	s_add_i32 s76, 0, 0x18000
	s_add_i32 s77, 0, 0x1c000
	s_add_u32 s50, s50, 0x40000
	s_addc_u32 s51, s51, 0
	s_mov_b32 m0, s59
	v_lshl_add_u64 v[232:233], s[50:51], 0, v[134:135]
	global_load_lds_dwordx4 v[232:233], off
	v_lshl_add_u64 v[232:233], s[50:51], 0, v[130:131]
	s_mov_b32 m0, s60
	s_nop 0
	global_load_lds_dwordx4 v[232:233], off
	v_add_u32_e32 v153, s76, v147
	ds_read_b128 v[160:163], v153
	v_xor_b32_e32 v253, 64, v153
	ds_read_b128 v[164:167], v253
	ds_read_b128 v[168:171], v153 offset:2048
	ds_read_b128 v[172:175], v253 offset:2048
	v_add_u32_e32 v153, s77, v147
	ds_read_b128 v[176:179], v153
	v_xor_b32_e32 v253, 64, v153
	ds_read_b128 v[180:183], v253
	ds_read_b128 v[186:189], v153 offset:2048
	ds_read_b128 v[190:193], v253 offset:2048
	ds_read_b128 v[194:197], v150 offset:32768
	v_xor_b32_e32 v253, 64, v150
	ds_read_b128 v[198:201], v253 offset:32768
	ds_read_b128 v[202:205], v150 offset:34816
	ds_read_b128 v[206:209], v253 offset:34816
	ds_read_b128 v[210:213], v150 offset:36864
	ds_read_b128 v[214:217], v253 offset:36864
	ds_read_b128 v[218:221], v150 offset:38912
	ds_read_b128 v[222:225], v253 offset:38912
	s_waitcnt vmcnt(8)
	s_waitcnt lgkmcnt(0)
	s_setprio 1
	s_barrier
	v_mfma_f32_16x16x32_bf16 v[124:127], v[160:163], v[194:197], v[124:127]
	v_mfma_f32_16x16x32_bf16 v[124:127], v[164:167], v[198:201], v[124:127]
	v_mfma_f32_16x16x32_bf16 v[116:119], v[172:175], v[198:201], v[116:119]
	v_mfma_f32_16x16x32_bf16 v[116:119], v[168:171], v[194:197], v[116:119]
	v_mfma_f32_16x16x32_bf16 v[100:103], v[168:171], v[202:205], v[100:103]
	v_mfma_f32_16x16x32_bf16 v[100:103], v[172:175], v[206:209], v[100:103]
	v_mfma_f32_16x16x32_bf16 v[108:111], v[164:167], v[206:209], v[108:111]
	v_mfma_f32_16x16x32_bf16 v[108:111], v[160:163], v[202:205], v[108:111]
	v_mfma_f32_16x16x32_bf16 v[92:95], v[160:163], v[210:213], v[92:95]
	v_mfma_f32_16x16x32_bf16 v[92:95], v[164:167], v[214:217], v[92:95]
	v_mfma_f32_16x16x32_bf16 v[84:87], v[172:175], v[214:217], v[84:87]
	v_mfma_f32_16x16x32_bf16 v[84:87], v[168:171], v[210:213], v[84:87]
	v_mfma_f32_16x16x32_bf16 v[68:71], v[168:171], v[218:221], v[68:71]
	v_mfma_f32_16x16x32_bf16 v[68:71], v[172:175], v[222:225], v[68:71]
	v_mfma_f32_16x16x32_bf16 v[76:79], v[164:167], v[222:225], v[76:79]
	v_mfma_f32_16x16x32_bf16 v[76:79], v[160:163], v[218:221], v[76:79]
	s_setprio 0
	s_setprio 1
	v_mfma_f32_16x16x32_bf16 v[120:123], v[176:179], v[194:197], v[120:123]
	v_mfma_f32_16x16x32_bf16 v[120:123], v[180:183], v[198:201], v[120:123]
	v_mfma_f32_16x16x32_bf16 v[112:115], v[190:193], v[198:201], v[112:115]
	v_mfma_f32_16x16x32_bf16 v[112:115], v[186:189], v[194:197], v[112:115]
	v_mfma_f32_16x16x32_bf16 v[96:99], v[186:189], v[202:205], v[96:99]
	v_mfma_f32_16x16x32_bf16 v[96:99], v[190:193], v[206:209], v[96:99]
	v_mfma_f32_16x16x32_bf16 v[104:107], v[180:183], v[206:209], v[104:107]
	v_mfma_f32_16x16x32_bf16 v[104:107], v[176:179], v[202:205], v[104:107]
	v_mfma_f32_16x16x32_bf16 v[88:91], v[176:179], v[210:213], v[88:91]
	v_mfma_f32_16x16x32_bf16 v[88:91], v[180:183], v[214:217], v[88:91]
	v_mfma_f32_16x16x32_bf16 v[80:83], v[190:193], v[214:217], v[80:83]
	v_mfma_f32_16x16x32_bf16 v[80:83], v[186:189], v[210:213], v[80:83]
	v_mfma_f32_16x16x32_bf16 v[64:67], v[186:189], v[218:221], v[64:67]
	v_mfma_f32_16x16x32_bf16 v[64:67], v[190:193], v[222:225], v[64:67]
	v_mfma_f32_16x16x32_bf16 v[72:75], v[180:183], v[222:225], v[72:75]
	v_mfma_f32_16x16x32_bf16 v[72:75], v[176:179], v[218:221], v[72:75]
	s_barrier
	s_setprio 0
	s_add_i32 s50, s76, s54
	v_lshl_add_u64 v[154:155], v[154:155], 0, s[20:21]
	s_mov_b32 m0, s50
	s_nop 0
	global_load_lds_dwordx4 v[154:155], off
	s_add_i32 m0, s50, 0x2000
	s_add_u32 s48, s48, 0x40080
	v_lshl_add_u64 v[154:155], v[226:227], 0, s[20:21]
	s_addc_u32 s49, s49, 0
	s_add_i32 s50, s77, s54
	global_load_lds_dwordx4 v[154:155], off
	v_lshl_add_u64 v[154:155], s[48:49], 0, v[132:133]
	s_mov_b32 m0, s50
	s_nop 0
	global_load_lds_dwordx4 v[154:155], off
	v_lshl_add_u64 v[154:155], s[48:49], 0, v[128:129]
	s_add_i32 m0, s50, 0x2000
	s_nop 0
	global_load_lds_dwordx4 v[154:155], off
	v_lshl_add_u64 v[154:155], v[228:229], 0, s[20:21]
	s_mov_b32 m0, s62
	s_nop 0
	global_load_lds_dwordx4 v[154:155], off
	v_lshl_add_u64 v[154:155], v[230:231], 0, s[20:21]
	s_mov_b32 m0, s63
	s_nop 0
	global_load_lds_dwordx4 v[154:155], off
	ds_read_b128 v[194:197], v150 offset:49152
	v_xor_b32_e32 v253, 64, v150
	ds_read_b128 v[198:201], v253 offset:49152
	ds_read_b128 v[202:205], v150 offset:51200
	ds_read_b128 v[206:209], v253 offset:51200
	ds_read_b128 v[210:213], v150 offset:53248
	ds_read_b128 v[214:217], v253 offset:53248
	ds_read_b128 v[218:221], v150 offset:55296
	ds_read_b128 v[222:225], v253 offset:55296
	s_waitcnt vmcnt(8)
	s_waitcnt lgkmcnt(0)
	s_setprio 1
	s_barrier
	v_mfma_f32_16x16x32_bf16 v[60:63], v[160:163], v[194:197], v[60:63]
	v_mfma_f32_16x16x32_bf16 v[60:63], v[164:167], v[198:201], v[60:63]
	v_mfma_f32_16x16x32_bf16 v[52:55], v[172:175], v[198:201], v[52:55]
	v_mfma_f32_16x16x32_bf16 v[52:55], v[168:171], v[194:197], v[52:55]
	v_mfma_f32_16x16x32_bf16 v[36:39], v[168:171], v[202:205], v[36:39]
	v_mfma_f32_16x16x32_bf16 v[36:39], v[172:175], v[206:209], v[36:39]
	v_mfma_f32_16x16x32_bf16 v[44:47], v[164:167], v[206:209], v[44:47]
	v_mfma_f32_16x16x32_bf16 v[44:47], v[160:163], v[202:205], v[44:47]
	v_mfma_f32_16x16x32_bf16 v[28:31], v[160:163], v[210:213], v[28:31]
	v_mfma_f32_16x16x32_bf16 v[28:31], v[164:167], v[214:217], v[28:31]
	v_mfma_f32_16x16x32_bf16 v[20:23], v[172:175], v[214:217], v[20:23]
	v_mfma_f32_16x16x32_bf16 v[20:23], v[168:171], v[210:213], v[20:23]
	v_mfma_f32_16x16x32_bf16 v[4:7], v[168:171], v[218:221], v[4:7]
	v_mfma_f32_16x16x32_bf16 v[4:7], v[172:175], v[222:225], v[4:7]
	v_mfma_f32_16x16x32_bf16 v[12:15], v[164:167], v[222:225], v[12:15]
	v_mfma_f32_16x16x32_bf16 v[12:15], v[160:163], v[218:221], v[12:15]
	s_setprio 0
	s_setprio 1
	v_mfma_f32_16x16x32_bf16 v[56:59], v[176:179], v[194:197], v[56:59]
	v_mfma_f32_16x16x32_bf16 v[56:59], v[180:183], v[198:201], v[56:59]
	v_mfma_f32_16x16x32_bf16 v[48:51], v[190:193], v[198:201], v[48:51]
	v_mfma_f32_16x16x32_bf16 v[48:51], v[186:189], v[194:197], v[48:51]
	v_mfma_f32_16x16x32_bf16 v[32:35], v[186:189], v[202:205], v[32:35]
	v_mfma_f32_16x16x32_bf16 v[32:35], v[190:193], v[206:209], v[32:35]
	v_mfma_f32_16x16x32_bf16 v[40:43], v[180:183], v[206:209], v[40:43]
	v_mfma_f32_16x16x32_bf16 v[40:43], v[176:179], v[202:205], v[40:43]
	v_mfma_f32_16x16x32_bf16 v[24:27], v[176:179], v[210:213], v[24:27]
	v_mfma_f32_16x16x32_bf16 v[24:27], v[180:183], v[214:217], v[24:27]
	v_mfma_f32_16x16x32_bf16 v[16:19], v[190:193], v[214:217], v[16:19]
	v_mfma_f32_16x16x32_bf16 v[16:19], v[186:189], v[210:213], v[16:19]
	v_mfma_f32_16x16x32_bf16 v[0:3], v[186:189], v[218:221], v[0:3]
	v_mfma_f32_16x16x32_bf16 v[0:3], v[190:193], v[222:225], v[0:3]
	v_mfma_f32_16x16x32_bf16 v[8:11], v[180:183], v[222:225], v[8:11]
	v_mfma_f32_16x16x32_bf16 v[8:11], v[176:179], v[218:221], v[8:11]
	s_barrier
	s_setprio 0
	s_add_i32 s75, s75, 2
	s_add_u32 s73, s73, 0x100
	s_addc_u32 s74, s74, 0
	s_add_u32 s46, s46, 0x100
	s_addc_u32 s47, s47, 0
	s_branch .LBB0_527
.LBB0_526:
	s_add_u32 s50, s46, 0xfffc0080
	s_addc_u32 s51, s47, -1
	s_and_b64 s[48:49], s[48:49], exec
	s_cselect_b32 s51, s29, s51
	s_cselect_b32 s50, s70, s50
	s_cselect_b32 s49, s71, s74
	s_cselect_b32 s48, s72, s73
	v_lshl_add_u64 v[154:155], s[46:47], 0, v[138:139]
	s_add_i32 m0, s57, 0xc000
	s_nop 0
	global_load_lds_dwordx4 v[154:155], off
	v_lshl_add_u64 v[154:155], s[46:47], 0, v[136:137]
	s_add_i32 m0, s57, 0xe000
	s_nop 0
	global_load_lds_dwordx4 v[154:155], off
	v_add_u32_e32 v153, s66, v147
	ds_read_b128 v[160:163], v153
	v_xor_b32_e32 v253, 64, v153
	ds_read_b128 v[164:167], v253
	ds_read_b128 v[168:171], v153 offset:2048
	ds_read_b128 v[172:175], v253 offset:2048
	v_add_u32_e32 v153, s67, v147
	ds_read_b128 v[176:179], v153
	v_xor_b32_e32 v253, 64, v153
	ds_read_b128 v[180:183], v253
	ds_read_b128 v[186:189], v153 offset:2048
	ds_read_b128 v[190:193], v253 offset:2048
	ds_read_b128 v[194:197], v150
	v_xor_b32_e32 v253, 64, v150
	ds_read_b128 v[198:201], v253
	ds_read_b128 v[202:205], v150 offset:2048
	ds_read_b128 v[206:209], v253 offset:2048
	ds_read_b128 v[210:213], v150 offset:4096
	ds_read_b128 v[214:217], v253 offset:4096
	ds_read_b128 v[218:221], v150 offset:6144
	ds_read_b128 v[222:225], v253 offset:6144
	s_waitcnt vmcnt(8)
	s_waitcnt lgkmcnt(0)
	s_setprio 1
	s_barrier
	v_mfma_f32_16x16x32_bf16 v[124:127], v[160:163], v[194:197], v[124:127]
	v_mfma_f32_16x16x32_bf16 v[124:127], v[164:167], v[198:201], v[124:127]
	v_mfma_f32_16x16x32_bf16 v[116:119], v[172:175], v[198:201], v[116:119]
	v_mfma_f32_16x16x32_bf16 v[116:119], v[168:171], v[194:197], v[116:119]
	v_mfma_f32_16x16x32_bf16 v[100:103], v[168:171], v[202:205], v[100:103]
	v_mfma_f32_16x16x32_bf16 v[100:103], v[172:175], v[206:209], v[100:103]
	v_mfma_f32_16x16x32_bf16 v[108:111], v[164:167], v[206:209], v[108:111]
	v_mfma_f32_16x16x32_bf16 v[108:111], v[160:163], v[202:205], v[108:111]
	v_mfma_f32_16x16x32_bf16 v[92:95], v[160:163], v[210:213], v[92:95]
	v_mfma_f32_16x16x32_bf16 v[92:95], v[164:167], v[214:217], v[92:95]
	v_mfma_f32_16x16x32_bf16 v[84:87], v[172:175], v[214:217], v[84:87]
	v_mfma_f32_16x16x32_bf16 v[84:87], v[168:171], v[210:213], v[84:87]
	v_mfma_f32_16x16x32_bf16 v[68:71], v[168:171], v[218:221], v[68:71]
	v_mfma_f32_16x16x32_bf16 v[68:71], v[172:175], v[222:225], v[68:71]
	v_mfma_f32_16x16x32_bf16 v[76:79], v[164:167], v[222:225], v[76:79]
	v_mfma_f32_16x16x32_bf16 v[76:79], v[160:163], v[218:221], v[76:79]
	s_setprio 0
	s_setprio 1
	v_mfma_f32_16x16x32_bf16 v[120:123], v[176:179], v[194:197], v[120:123]
	v_mfma_f32_16x16x32_bf16 v[120:123], v[180:183], v[198:201], v[120:123]
	v_mfma_f32_16x16x32_bf16 v[112:115], v[190:193], v[198:201], v[112:115]
	v_mfma_f32_16x16x32_bf16 v[112:115], v[186:189], v[194:197], v[112:115]
	v_mfma_f32_16x16x32_bf16 v[96:99], v[186:189], v[202:205], v[96:99]
	v_mfma_f32_16x16x32_bf16 v[96:99], v[190:193], v[206:209], v[96:99]
	v_mfma_f32_16x16x32_bf16 v[104:107], v[180:183], v[206:209], v[104:107]
	v_mfma_f32_16x16x32_bf16 v[104:107], v[176:179], v[202:205], v[104:107]
	v_mfma_f32_16x16x32_bf16 v[88:91], v[176:179], v[210:213], v[88:91]
	v_mfma_f32_16x16x32_bf16 v[88:91], v[180:183], v[214:217], v[88:91]
	v_mfma_f32_16x16x32_bf16 v[80:83], v[190:193], v[214:217], v[80:83]
	v_mfma_f32_16x16x32_bf16 v[80:83], v[186:189], v[210:213], v[80:83]
	v_mfma_f32_16x16x32_bf16 v[64:67], v[186:189], v[218:221], v[64:67]
	v_mfma_f32_16x16x32_bf16 v[64:67], v[190:193], v[222:225], v[64:67]
	v_mfma_f32_16x16x32_bf16 v[72:75], v[180:183], v[222:225], v[72:75]
	v_mfma_f32_16x16x32_bf16 v[72:75], v[176:179], v[218:221], v[72:75]
	s_barrier
	s_setprio 0
	s_add_i32 s76, s66, s54
	v_lshl_add_u64 v[154:155], s[48:49], 0, v[132:133]
	s_mov_b32 m0, s76
	s_nop 0
	global_load_lds_dwordx4 v[154:155], off
	s_add_i32 m0, s76, 0x2000
	s_add_u32 s76, s48, 0x40000
	v_lshl_add_u64 v[226:227], s[48:49], 0, v[128:129]
	s_addc_u32 s77, s49, 0
	s_add_i32 s78, s67, s54
	global_load_lds_dwordx4 v[226:227], off
	v_lshl_add_u64 v[228:229], s[76:77], 0, v[132:133]
	s_mov_b32 m0, s78
	v_lshl_add_u64 v[230:231], s[50:51], 0, v[130:131]
	global_load_lds_dwordx4 v[228:229], off
	v_lshl_add_u64 v[228:229], s[76:77], 0, v[128:129]
	s_add_i32 m0, s78, 0x2000
	s_nop 0
	global_load_lds_dwordx4 v[228:229], off
	v_lshl_add_u64 v[228:229], s[50:51], 0, v[134:135]
	s_mov_b32 m0, s57
	s_nop 0
	global_load_lds_dwordx4 v[228:229], off
	s_mov_b32 m0, s58
	s_nop 0
	global_load_lds_dwordx4 v[230:231], off
	ds_read_b128 v[194:197], v150 offset:16384
	v_xor_b32_e32 v253, 64, v150
	ds_read_b128 v[198:201], v253 offset:16384
	ds_read_b128 v[202:205], v150 offset:18432
	ds_read_b128 v[206:209], v253 offset:18432
	ds_read_b128 v[210:213], v150 offset:20480
	ds_read_b128 v[214:217], v253 offset:20480
	ds_read_b128 v[218:221], v150 offset:22528
	ds_read_b128 v[222:225], v253 offset:22528
	s_waitcnt vmcnt(8)
	s_waitcnt lgkmcnt(0)
	s_setprio 1
	s_barrier
	v_mfma_f32_16x16x32_bf16 v[60:63], v[160:163], v[194:197], v[60:63]
	v_mfma_f32_16x16x32_bf16 v[60:63], v[164:167], v[198:201], v[60:63]
	v_mfma_f32_16x16x32_bf16 v[52:55], v[172:175], v[198:201], v[52:55]
	v_mfma_f32_16x16x32_bf16 v[52:55], v[168:171], v[194:197], v[52:55]
	v_mfma_f32_16x16x32_bf16 v[36:39], v[168:171], v[202:205], v[36:39]
	v_mfma_f32_16x16x32_bf16 v[36:39], v[172:175], v[206:209], v[36:39]
	v_mfma_f32_16x16x32_bf16 v[44:47], v[164:167], v[206:209], v[44:47]
	v_mfma_f32_16x16x32_bf16 v[44:47], v[160:163], v[202:205], v[44:47]
	v_mfma_f32_16x16x32_bf16 v[28:31], v[160:163], v[210:213], v[28:31]
	v_mfma_f32_16x16x32_bf16 v[28:31], v[164:167], v[214:217], v[28:31]
	v_mfma_f32_16x16x32_bf16 v[20:23], v[172:175], v[214:217], v[20:23]
	v_mfma_f32_16x16x32_bf16 v[20:23], v[168:171], v[210:213], v[20:23]
	v_mfma_f32_16x16x32_bf16 v[4:7], v[168:171], v[218:221], v[4:7]
	v_mfma_f32_16x16x32_bf16 v[4:7], v[172:175], v[222:225], v[4:7]
	v_mfma_f32_16x16x32_bf16 v[12:15], v[164:167], v[222:225], v[12:15]
	v_mfma_f32_16x16x32_bf16 v[12:15], v[160:163], v[218:221], v[12:15]
	s_setprio 0
	s_setprio 1
	v_mfma_f32_16x16x32_bf16 v[56:59], v[176:179], v[194:197], v[56:59]
	v_mfma_f32_16x16x32_bf16 v[56:59], v[180:183], v[198:201], v[56:59]
	v_mfma_f32_16x16x32_bf16 v[48:51], v[190:193], v[198:201], v[48:51]
	v_mfma_f32_16x16x32_bf16 v[48:51], v[186:189], v[194:197], v[48:51]
	v_mfma_f32_16x16x32_bf16 v[32:35], v[186:189], v[202:205], v[32:35]
	v_mfma_f32_16x16x32_bf16 v[32:35], v[190:193], v[206:209], v[32:35]
	v_mfma_f32_16x16x32_bf16 v[40:43], v[180:183], v[206:209], v[40:43]
	v_mfma_f32_16x16x32_bf16 v[40:43], v[176:179], v[202:205], v[40:43]
	v_mfma_f32_16x16x32_bf16 v[24:27], v[176:179], v[210:213], v[24:27]
	v_mfma_f32_16x16x32_bf16 v[24:27], v[180:183], v[214:217], v[24:27]
	v_mfma_f32_16x16x32_bf16 v[16:19], v[190:193], v[214:217], v[16:19]
	v_mfma_f32_16x16x32_bf16 v[16:19], v[186:189], v[210:213], v[16:19]
	v_mfma_f32_16x16x32_bf16 v[0:3], v[186:189], v[218:221], v[0:3]
	v_mfma_f32_16x16x32_bf16 v[0:3], v[190:193], v[222:225], v[0:3]
	v_mfma_f32_16x16x32_bf16 v[8:11], v[180:183], v[222:225], v[8:11]
	v_mfma_f32_16x16x32_bf16 v[8:11], v[176:179], v[218:221], v[8:11]
	s_barrier
	s_setprio 0
	s_add_i32 s76, 0, 0x18000
	s_add_i32 s77, 0, 0x1c000
	s_add_u32 s50, s50, 0x40000
	s_addc_u32 s51, s51, 0
	s_mov_b32 m0, s59
	v_lshl_add_u64 v[232:233], s[50:51], 0, v[134:135]
	global_load_lds_dwordx4 v[232:233], off
	v_lshl_add_u64 v[232:233], s[50:51], 0, v[130:131]
	s_mov_b32 m0, s60
	s_nop 0
	global_load_lds_dwordx4 v[232:233], off
	v_add_u32_e32 v153, s76, v147
	ds_read_b128 v[160:163], v153
	v_xor_b32_e32 v253, 64, v153
	ds_read_b128 v[164:167], v253
	ds_read_b128 v[168:171], v153 offset:2048
	ds_read_b128 v[172:175], v253 offset:2048
	v_add_u32_e32 v153, s77, v147
	ds_read_b128 v[176:179], v153
	v_xor_b32_e32 v253, 64, v153
	ds_read_b128 v[180:183], v253
	ds_read_b128 v[186:189], v153 offset:2048
	ds_read_b128 v[190:193], v253 offset:2048
	ds_read_b128 v[194:197], v150 offset:32768
	v_xor_b32_e32 v253, 64, v150
	ds_read_b128 v[198:201], v253 offset:32768
	ds_read_b128 v[202:205], v150 offset:34816
	ds_read_b128 v[206:209], v253 offset:34816
	ds_read_b128 v[210:213], v150 offset:36864
	ds_read_b128 v[214:217], v253 offset:36864
	ds_read_b128 v[218:221], v150 offset:38912
	ds_read_b128 v[222:225], v253 offset:38912
	s_waitcnt vmcnt(8)
	s_waitcnt lgkmcnt(0)
	s_setprio 1
	s_barrier
	v_mfma_f32_16x16x32_bf16 v[124:127], v[160:163], v[194:197], v[124:127]
	v_mfma_f32_16x16x32_bf16 v[124:127], v[164:167], v[198:201], v[124:127]
	v_mfma_f32_16x16x32_bf16 v[116:119], v[172:175], v[198:201], v[116:119]
	v_mfma_f32_16x16x32_bf16 v[116:119], v[168:171], v[194:197], v[116:119]
	v_mfma_f32_16x16x32_bf16 v[100:103], v[168:171], v[202:205], v[100:103]
	v_mfma_f32_16x16x32_bf16 v[100:103], v[172:175], v[206:209], v[100:103]
	v_mfma_f32_16x16x32_bf16 v[108:111], v[164:167], v[206:209], v[108:111]
	v_mfma_f32_16x16x32_bf16 v[108:111], v[160:163], v[202:205], v[108:111]
	v_mfma_f32_16x16x32_bf16 v[92:95], v[160:163], v[210:213], v[92:95]
	v_mfma_f32_16x16x32_bf16 v[92:95], v[164:167], v[214:217], v[92:95]
	v_mfma_f32_16x16x32_bf16 v[84:87], v[172:175], v[214:217], v[84:87]
	v_mfma_f32_16x16x32_bf16 v[84:87], v[168:171], v[210:213], v[84:87]
	v_mfma_f32_16x16x32_bf16 v[68:71], v[168:171], v[218:221], v[68:71]
	v_mfma_f32_16x16x32_bf16 v[68:71], v[172:175], v[222:225], v[68:71]
	v_mfma_f32_16x16x32_bf16 v[76:79], v[164:167], v[222:225], v[76:79]
	v_mfma_f32_16x16x32_bf16 v[76:79], v[160:163], v[218:221], v[76:79]
	s_setprio 0
	s_setprio 1
	v_mfma_f32_16x16x32_bf16 v[120:123], v[176:179], v[194:197], v[120:123]
	v_mfma_f32_16x16x32_bf16 v[120:123], v[180:183], v[198:201], v[120:123]
	v_mfma_f32_16x16x32_bf16 v[112:115], v[190:193], v[198:201], v[112:115]
	v_mfma_f32_16x16x32_bf16 v[112:115], v[186:189], v[194:197], v[112:115]
	v_mfma_f32_16x16x32_bf16 v[96:99], v[186:189], v[202:205], v[96:99]
	v_mfma_f32_16x16x32_bf16 v[96:99], v[190:193], v[206:209], v[96:99]
	v_mfma_f32_16x16x32_bf16 v[104:107], v[180:183], v[206:209], v[104:107]
	v_mfma_f32_16x16x32_bf16 v[104:107], v[176:179], v[202:205], v[104:107]
	v_mfma_f32_16x16x32_bf16 v[88:91], v[176:179], v[210:213], v[88:91]
	v_mfma_f32_16x16x32_bf16 v[88:91], v[180:183], v[214:217], v[88:91]
	v_mfma_f32_16x16x32_bf16 v[80:83], v[190:193], v[214:217], v[80:83]
	v_mfma_f32_16x16x32_bf16 v[80:83], v[186:189], v[210:213], v[80:83]
	v_mfma_f32_16x16x32_bf16 v[64:67], v[186:189], v[218:221], v[64:67]
	v_mfma_f32_16x16x32_bf16 v[64:67], v[190:193], v[222:225], v[64:67]
	v_mfma_f32_16x16x32_bf16 v[72:75], v[180:183], v[222:225], v[72:75]
	v_mfma_f32_16x16x32_bf16 v[72:75], v[176:179], v[218:221], v[72:75]
	s_barrier
	s_setprio 0
	s_add_i32 s50, s76, s54
	v_lshl_add_u64 v[154:155], v[154:155], 0, s[20:21]
	s_mov_b32 m0, s50
	s_nop 0
	global_load_lds_dwordx4 v[154:155], off
	s_add_i32 m0, s50, 0x2000
	s_add_u32 s48, s48, 0x40080
	v_lshl_add_u64 v[154:155], v[226:227], 0, s[20:21]
	s_addc_u32 s49, s49, 0
	s_add_i32 s50, s77, s54
	global_load_lds_dwordx4 v[154:155], off
	v_lshl_add_u64 v[154:155], s[48:49], 0, v[132:133]
	s_mov_b32 m0, s50
	s_nop 0
	global_load_lds_dwordx4 v[154:155], off
	v_lshl_add_u64 v[154:155], s[48:49], 0, v[128:129]
	s_add_i32 m0, s50, 0x2000
	s_nop 0
	global_load_lds_dwordx4 v[154:155], off
	v_lshl_add_u64 v[154:155], v[228:229], 0, s[20:21]
	s_mov_b32 m0, s62
	s_nop 0
	global_load_lds_dwordx4 v[154:155], off
	v_lshl_add_u64 v[154:155], v[230:231], 0, s[20:21]
	s_mov_b32 m0, s63
	s_nop 0
	global_load_lds_dwordx4 v[154:155], off
	ds_read_b128 v[194:197], v150 offset:49152
	v_xor_b32_e32 v253, 64, v150
	ds_read_b128 v[198:201], v253 offset:49152
	ds_read_b128 v[202:205], v150 offset:51200
	ds_read_b128 v[206:209], v253 offset:51200
	ds_read_b128 v[210:213], v150 offset:53248
	ds_read_b128 v[214:217], v253 offset:53248
	ds_read_b128 v[218:221], v150 offset:55296
	ds_read_b128 v[222:225], v253 offset:55296
	s_waitcnt vmcnt(8)
	s_waitcnt lgkmcnt(0)
	s_setprio 1
	s_barrier
	v_mfma_f32_16x16x32_bf16 v[60:63], v[160:163], v[194:197], v[60:63]
	v_mfma_f32_16x16x32_bf16 v[60:63], v[164:167], v[198:201], v[60:63]
	v_mfma_f32_16x16x32_bf16 v[52:55], v[172:175], v[198:201], v[52:55]
	v_mfma_f32_16x16x32_bf16 v[52:55], v[168:171], v[194:197], v[52:55]
	v_mfma_f32_16x16x32_bf16 v[36:39], v[168:171], v[202:205], v[36:39]
	v_mfma_f32_16x16x32_bf16 v[36:39], v[172:175], v[206:209], v[36:39]
	v_mfma_f32_16x16x32_bf16 v[44:47], v[164:167], v[206:209], v[44:47]
	v_mfma_f32_16x16x32_bf16 v[44:47], v[160:163], v[202:205], v[44:47]
	v_mfma_f32_16x16x32_bf16 v[28:31], v[160:163], v[210:213], v[28:31]
	v_mfma_f32_16x16x32_bf16 v[28:31], v[164:167], v[214:217], v[28:31]
	v_mfma_f32_16x16x32_bf16 v[20:23], v[172:175], v[214:217], v[20:23]
	v_mfma_f32_16x16x32_bf16 v[20:23], v[168:171], v[210:213], v[20:23]
	v_mfma_f32_16x16x32_bf16 v[4:7], v[168:171], v[218:221], v[4:7]
	v_mfma_f32_16x16x32_bf16 v[4:7], v[172:175], v[222:225], v[4:7]
	v_mfma_f32_16x16x32_bf16 v[12:15], v[164:167], v[222:225], v[12:15]
	v_mfma_f32_16x16x32_bf16 v[12:15], v[160:163], v[218:221], v[12:15]
	s_setprio 0
	s_setprio 1
	v_mfma_f32_16x16x32_bf16 v[56:59], v[176:179], v[194:197], v[56:59]
	v_mfma_f32_16x16x32_bf16 v[56:59], v[180:183], v[198:201], v[56:59]
	v_mfma_f32_16x16x32_bf16 v[48:51], v[190:193], v[198:201], v[48:51]
	v_mfma_f32_16x16x32_bf16 v[48:51], v[186:189], v[194:197], v[48:51]
	v_mfma_f32_16x16x32_bf16 v[32:35], v[186:189], v[202:205], v[32:35]
	v_mfma_f32_16x16x32_bf16 v[32:35], v[190:193], v[206:209], v[32:35]
	v_mfma_f32_16x16x32_bf16 v[40:43], v[180:183], v[206:209], v[40:43]
	v_mfma_f32_16x16x32_bf16 v[40:43], v[176:179], v[202:205], v[40:43]
	v_mfma_f32_16x16x32_bf16 v[24:27], v[176:179], v[210:213], v[24:27]
	v_mfma_f32_16x16x32_bf16 v[24:27], v[180:183], v[214:217], v[24:27]
	v_mfma_f32_16x16x32_bf16 v[16:19], v[190:193], v[214:217], v[16:19]
	v_mfma_f32_16x16x32_bf16 v[16:19], v[186:189], v[210:213], v[16:19]
	v_mfma_f32_16x16x32_bf16 v[0:3], v[186:189], v[218:221], v[0:3]
	v_mfma_f32_16x16x32_bf16 v[0:3], v[190:193], v[222:225], v[0:3]
	v_mfma_f32_16x16x32_bf16 v[8:11], v[180:183], v[222:225], v[8:11]
	v_mfma_f32_16x16x32_bf16 v[8:11], v[176:179], v[218:221], v[8:11]
	s_barrier
	s_setprio 0
	s_add_i32 s75, s75, 2
	s_add_u32 s73, s73, 0x100
	s_addc_u32 s74, s74, 0
	s_add_u32 s46, s46, 0x100
	s_addc_u32 s47, s47, 0
	s_cmp_gt_u32 s75, 13
	s_cbranch_scc1 .LBB0_529

.Llast_4:
	s_add_u32 s50, s46, 0xfffc0080
	s_addc_u32 s51, s47, -1
	s_and_b64 s[48:49], s[48:49], exec
	s_cselect_b32 s51, s29, s51
	s_cselect_b32 s50, s70, s50
	s_cselect_b32 s49, s71, s74
	s_cselect_b32 s48, s72, s73
	v_lshl_add_u64 v[154:155], s[46:47], 0, v[138:139]
	s_add_i32 m0, s57, 0xc000
	s_nop 0
	global_load_lds_dwordx4 v[154:155], off
	v_lshl_add_u64 v[154:155], s[46:47], 0, v[136:137]
	s_add_i32 m0, s57, 0xe000
	s_nop 0
	global_load_lds_dwordx4 v[154:155], off
	v_add_u32_e32 v153, s66, v147
	ds_read_b128 v[160:163], v153
	v_xor_b32_e32 v253, 64, v153
	ds_read_b128 v[164:167], v253
	ds_read_b128 v[168:171], v153 offset:2048
	ds_read_b128 v[172:175], v253 offset:2048
	v_add_u32_e32 v153, s67, v147
	ds_read_b128 v[176:179], v153
	v_xor_b32_e32 v253, 64, v153
	ds_read_b128 v[180:183], v253
	ds_read_b128 v[186:189], v153 offset:2048
	ds_read_b128 v[190:193], v253 offset:2048
	ds_read_b128 v[194:197], v150
	v_xor_b32_e32 v253, 64, v150
	ds_read_b128 v[198:201], v253
	ds_read_b128 v[202:205], v150 offset:2048
	ds_read_b128 v[206:209], v253 offset:2048
	ds_read_b128 v[210:213], v150 offset:4096
	ds_read_b128 v[214:217], v253 offset:4096
	ds_read_b128 v[218:221], v150 offset:6144
	ds_read_b128 v[222:225], v253 offset:6144
	s_waitcnt vmcnt(8)
	s_waitcnt lgkmcnt(0)
	s_setprio 1
	s_barrier
	v_mfma_f32_16x16x32_bf16 v[124:127], v[160:163], v[194:197], v[124:127]
	v_mfma_f32_16x16x32_bf16 v[124:127], v[164:167], v[198:201], v[124:127]
	v_mfma_f32_16x16x32_bf16 v[116:119], v[172:175], v[198:201], v[116:119]
	v_mfma_f32_16x16x32_bf16 v[116:119], v[168:171], v[194:197], v[116:119]
	v_mfma_f32_16x16x32_bf16 v[100:103], v[168:171], v[202:205], v[100:103]
	v_mfma_f32_16x16x32_bf16 v[100:103], v[172:175], v[206:209], v[100:103]
	v_mfma_f32_16x16x32_bf16 v[108:111], v[164:167], v[206:209], v[108:111]
	v_mfma_f32_16x16x32_bf16 v[108:111], v[160:163], v[202:205], v[108:111]
	v_mfma_f32_16x16x32_bf16 v[92:95], v[160:163], v[210:213], v[92:95]
	v_mfma_f32_16x16x32_bf16 v[92:95], v[164:167], v[214:217], v[92:95]
	v_mfma_f32_16x16x32_bf16 v[84:87], v[172:175], v[214:217], v[84:87]
	v_mfma_f32_16x16x32_bf16 v[84:87], v[168:171], v[210:213], v[84:87]
	v_mfma_f32_16x16x32_bf16 v[68:71], v[168:171], v[218:221], v[68:71]
	v_mfma_f32_16x16x32_bf16 v[68:71], v[172:175], v[222:225], v[68:71]
	v_mfma_f32_16x16x32_bf16 v[76:79], v[164:167], v[222:225], v[76:79]
	v_mfma_f32_16x16x32_bf16 v[76:79], v[160:163], v[218:221], v[76:79]
	s_setprio 0
	s_setprio 1
	v_mfma_f32_16x16x32_bf16 v[120:123], v[176:179], v[194:197], v[120:123]
	v_mfma_f32_16x16x32_bf16 v[120:123], v[180:183], v[198:201], v[120:123]
	v_mfma_f32_16x16x32_bf16 v[112:115], v[190:193], v[198:201], v[112:115]
	v_mfma_f32_16x16x32_bf16 v[112:115], v[186:189], v[194:197], v[112:115]
	v_mfma_f32_16x16x32_bf16 v[96:99], v[186:189], v[202:205], v[96:99]
	v_mfma_f32_16x16x32_bf16 v[96:99], v[190:193], v[206:209], v[96:99]
	v_mfma_f32_16x16x32_bf16 v[104:107], v[180:183], v[206:209], v[104:107]
	v_mfma_f32_16x16x32_bf16 v[104:107], v[176:179], v[202:205], v[104:107]
	v_mfma_f32_16x16x32_bf16 v[88:91], v[176:179], v[210:213], v[88:91]
	v_mfma_f32_16x16x32_bf16 v[88:91], v[180:183], v[214:217], v[88:91]
	v_mfma_f32_16x16x32_bf16 v[80:83], v[190:193], v[214:217], v[80:83]
	v_mfma_f32_16x16x32_bf16 v[80:83], v[186:189], v[210:213], v[80:83]
	v_mfma_f32_16x16x32_bf16 v[64:67], v[186:189], v[218:221], v[64:67]
	v_mfma_f32_16x16x32_bf16 v[64:67], v[190:193], v[222:225], v[64:67]
	v_mfma_f32_16x16x32_bf16 v[72:75], v[180:183], v[222:225], v[72:75]
	v_mfma_f32_16x16x32_bf16 v[72:75], v[176:179], v[218:221], v[72:75]
	s_barrier
	s_setprio 0
	s_add_i32 s76, s66, s54
	v_lshl_add_u64 v[154:155], s[48:49], 0, v[132:133]
	s_mov_b32 m0, s76
	s_nop 0
	global_load_lds_dwordx4 v[154:155], off
	s_add_i32 m0, s76, 0x2000
	s_add_u32 s76, s48, 0x40000
	v_lshl_add_u64 v[226:227], s[48:49], 0, v[128:129]
	s_addc_u32 s77, s49, 0
	s_add_i32 s78, s67, s54
	global_load_lds_dwordx4 v[226:227], off
	v_lshl_add_u64 v[228:229], s[76:77], 0, v[132:133]
	s_mov_b32 m0, s78
	v_lshl_add_u64 v[230:231], s[50:51], 0, v[130:131]
	global_load_lds_dwordx4 v[228:229], off
	v_lshl_add_u64 v[228:229], s[76:77], 0, v[128:129]
	s_add_i32 m0, s78, 0x2000
	s_nop 0
	global_load_lds_dwordx4 v[228:229], off
	v_lshl_add_u64 v[228:229], s[50:51], 0, v[134:135]
	s_mov_b32 m0, s57
	s_nop 0
	global_load_lds_dwordx4 v[228:229], off
	s_mov_b32 m0, s58
	s_nop 0
	global_load_lds_dwordx4 v[230:231], off
	ds_read_b128 v[194:197], v150 offset:16384
	v_xor_b32_e32 v253, 64, v150
	ds_read_b128 v[198:201], v253 offset:16384
	ds_read_b128 v[202:205], v150 offset:18432
	ds_read_b128 v[206:209], v253 offset:18432
	ds_read_b128 v[210:213], v150 offset:20480
	ds_read_b128 v[214:217], v253 offset:20480
	ds_read_b128 v[218:221], v150 offset:22528
	ds_read_b128 v[222:225], v253 offset:22528
	s_waitcnt vmcnt(8)
	s_waitcnt lgkmcnt(0)
	s_setprio 1
	s_barrier
	v_mfma_f32_16x16x32_bf16 v[60:63], v[160:163], v[194:197], v[60:63]
	v_mfma_f32_16x16x32_bf16 v[60:63], v[164:167], v[198:201], v[60:63]
	v_mfma_f32_16x16x32_bf16 v[52:55], v[172:175], v[198:201], v[52:55]
	v_mfma_f32_16x16x32_bf16 v[52:55], v[168:171], v[194:197], v[52:55]
	v_mfma_f32_16x16x32_bf16 v[36:39], v[168:171], v[202:205], v[36:39]
	v_mfma_f32_16x16x32_bf16 v[36:39], v[172:175], v[206:209], v[36:39]
	v_mfma_f32_16x16x32_bf16 v[44:47], v[164:167], v[206:209], v[44:47]
	v_mfma_f32_16x16x32_bf16 v[44:47], v[160:163], v[202:205], v[44:47]
	v_mfma_f32_16x16x32_bf16 v[28:31], v[160:163], v[210:213], v[28:31]
	v_mfma_f32_16x16x32_bf16 v[28:31], v[164:167], v[214:217], v[28:31]
	v_mfma_f32_16x16x32_bf16 v[20:23], v[172:175], v[214:217], v[20:23]
	v_mfma_f32_16x16x32_bf16 v[20:23], v[168:171], v[210:213], v[20:23]
	v_mfma_f32_16x16x32_bf16 v[4:7], v[168:171], v[218:221], v[4:7]
	v_mfma_f32_16x16x32_bf16 v[4:7], v[172:175], v[222:225], v[4:7]
	v_mfma_f32_16x16x32_bf16 v[12:15], v[164:167], v[222:225], v[12:15]
	v_mfma_f32_16x16x32_bf16 v[12:15], v[160:163], v[218:221], v[12:15]
	s_setprio 0
	s_setprio 1
	v_mfma_f32_16x16x32_bf16 v[56:59], v[176:179], v[194:197], v[56:59]
	v_mfma_f32_16x16x32_bf16 v[56:59], v[180:183], v[198:201], v[56:59]
	v_mfma_f32_16x16x32_bf16 v[48:51], v[190:193], v[198:201], v[48:51]
	v_mfma_f32_16x16x32_bf16 v[48:51], v[186:189], v[194:197], v[48:51]
	v_mfma_f32_16x16x32_bf16 v[32:35], v[186:189], v[202:205], v[32:35]
	v_mfma_f32_16x16x32_bf16 v[32:35], v[190:193], v[206:209], v[32:35]
	v_mfma_f32_16x16x32_bf16 v[40:43], v[180:183], v[206:209], v[40:43]
	v_mfma_f32_16x16x32_bf16 v[40:43], v[176:179], v[202:205], v[40:43]
	v_mfma_f32_16x16x32_bf16 v[24:27], v[176:179], v[210:213], v[24:27]
	v_mfma_f32_16x16x32_bf16 v[24:27], v[180:183], v[214:217], v[24:27]
	v_mfma_f32_16x16x32_bf16 v[16:19], v[190:193], v[214:217], v[16:19]
	v_mfma_f32_16x16x32_bf16 v[16:19], v[186:189], v[210:213], v[16:19]
	v_mfma_f32_16x16x32_bf16 v[0:3], v[186:189], v[218:221], v[0:3]
	v_mfma_f32_16x16x32_bf16 v[0:3], v[190:193], v[222:225], v[0:3]
	v_mfma_f32_16x16x32_bf16 v[8:11], v[180:183], v[222:225], v[8:11]
	v_mfma_f32_16x16x32_bf16 v[8:11], v[176:179], v[218:221], v[8:11]
	s_barrier
	s_setprio 0
	s_add_i32 s76, 0, 0x18000
	s_add_i32 s77, 0, 0x1c000
	s_add_u32 s50, s50, 0x40000
	s_addc_u32 s51, s51, 0
	s_mov_b32 m0, s59
	v_lshl_add_u64 v[232:233], s[50:51], 0, v[134:135]
	global_load_lds_dwordx4 v[232:233], off
	v_lshl_add_u64 v[232:233], s[50:51], 0, v[130:131]
	s_mov_b32 m0, s60
	s_nop 0
	global_load_lds_dwordx4 v[232:233], off
	v_add_u32_e32 v153, s76, v147
	ds_read_b128 v[160:163], v153
	v_xor_b32_e32 v253, 64, v153
	ds_read_b128 v[164:167], v253
	ds_read_b128 v[168:171], v153 offset:2048
	ds_read_b128 v[172:175], v253 offset:2048
	v_add_u32_e32 v153, s77, v147
	ds_read_b128 v[176:179], v153
	v_xor_b32_e32 v253, 64, v153
	ds_read_b128 v[180:183], v253
	ds_read_b128 v[186:189], v153 offset:2048
	ds_read_b128 v[190:193], v253 offset:2048
	ds_read_b128 v[194:197], v150 offset:32768
	v_xor_b32_e32 v253, 64, v150
	ds_read_b128 v[198:201], v253 offset:32768
	ds_read_b128 v[202:205], v150 offset:34816
	ds_read_b128 v[206:209], v253 offset:34816
	ds_read_b128 v[210:213], v150 offset:36864
	ds_read_b128 v[214:217], v253 offset:36864
	ds_read_b128 v[218:221], v150 offset:38912
	ds_read_b128 v[222:225], v253 offset:38912
	s_waitcnt vmcnt(8)
	s_waitcnt lgkmcnt(0)
	s_setprio 1
	s_barrier
	v_mfma_f32_16x16x32_bf16 v[124:127], v[160:163], v[194:197], v[124:127]
	v_mfma_f32_16x16x32_bf16 v[124:127], v[164:167], v[198:201], v[124:127]
	v_mfma_f32_16x16x32_bf16 v[116:119], v[172:175], v[198:201], v[116:119]
	v_mfma_f32_16x16x32_bf16 v[116:119], v[168:171], v[194:197], v[116:119]
	v_mfma_f32_16x16x32_bf16 v[100:103], v[168:171], v[202:205], v[100:103]
	v_mfma_f32_16x16x32_bf16 v[100:103], v[172:175], v[206:209], v[100:103]
	v_mfma_f32_16x16x32_bf16 v[108:111], v[164:167], v[206:209], v[108:111]
	v_mfma_f32_16x16x32_bf16 v[108:111], v[160:163], v[202:205], v[108:111]
	v_mfma_f32_16x16x32_bf16 v[92:95], v[160:163], v[210:213], v[92:95]
	v_mfma_f32_16x16x32_bf16 v[92:95], v[164:167], v[214:217], v[92:95]
	v_mfma_f32_16x16x32_bf16 v[84:87], v[172:175], v[214:217], v[84:87]
	v_mfma_f32_16x16x32_bf16 v[84:87], v[168:171], v[210:213], v[84:87]
	v_mfma_f32_16x16x32_bf16 v[68:71], v[168:171], v[218:221], v[68:71]
	v_mfma_f32_16x16x32_bf16 v[68:71], v[172:175], v[222:225], v[68:71]
	v_mfma_f32_16x16x32_bf16 v[76:79], v[164:167], v[222:225], v[76:79]
	v_mfma_f32_16x16x32_bf16 v[76:79], v[160:163], v[218:221], v[76:79]
	s_setprio 0
	s_setprio 1
	v_mfma_f32_16x16x32_bf16 v[120:123], v[176:179], v[194:197], v[120:123]
	v_mfma_f32_16x16x32_bf16 v[120:123], v[180:183], v[198:201], v[120:123]
	v_mfma_f32_16x16x32_bf16 v[112:115], v[190:193], v[198:201], v[112:115]
	v_mfma_f32_16x16x32_bf16 v[112:115], v[186:189], v[194:197], v[112:115]
	v_mfma_f32_16x16x32_bf16 v[96:99], v[186:189], v[202:205], v[96:99]
	v_mfma_f32_16x16x32_bf16 v[96:99], v[190:193], v[206:209], v[96:99]
	v_mfma_f32_16x16x32_bf16 v[104:107], v[180:183], v[206:209], v[104:107]
	v_mfma_f32_16x16x32_bf16 v[104:107], v[176:179], v[202:205], v[104:107]
	v_mfma_f32_16x16x32_bf16 v[88:91], v[176:179], v[210:213], v[88:91]
	v_mfma_f32_16x16x32_bf16 v[88:91], v[180:183], v[214:217], v[88:91]
	v_mfma_f32_16x16x32_bf16 v[80:83], v[190:193], v[214:217], v[80:83]
	v_mfma_f32_16x16x32_bf16 v[80:83], v[186:189], v[210:213], v[80:83]
	v_mfma_f32_16x16x32_bf16 v[64:67], v[186:189], v[218:221], v[64:67]
	v_mfma_f32_16x16x32_bf16 v[64:67], v[190:193], v[222:225], v[64:67]
	v_mfma_f32_16x16x32_bf16 v[72:75], v[180:183], v[222:225], v[72:75]
	v_mfma_f32_16x16x32_bf16 v[72:75], v[176:179], v[218:221], v[72:75]
	s_barrier
	s_setprio 0
	v_add_u32_e32 v234, 0x21000, v151
	ds_read_b128 v[236:239], v234
	ds_read_b128 v[240:243], v234 offset:256
	ds_read_b128 v[244:247], v234 offset:512
	ds_read_b128 v[248:251], v234 offset:768
	v_add_u32_e32 v235, s27, v146
	v_mul_u32_u24_e32 v235, 0x1600, v235
	v_lshl_or_b32 v234, s69, 7, v149
	v_lshl_add_u32 v235, v234, 1, v235
	s_add_i32 s50, s76, s54
	v_lshl_add_u64 v[154:155], v[154:155], 0, s[20:21]
	s_mov_b32 m0, s50
	ds_read_b128 v[194:197], v150 offset:49152
	v_xor_b32_e32 v253, 64, v150
	ds_read_b128 v[198:201], v253 offset:49152
	ds_read_b128 v[202:205], v150 offset:51200
	ds_read_b128 v[206:209], v253 offset:51200
	ds_read_b128 v[210:213], v150 offset:53248
	ds_read_b128 v[214:217], v253 offset:53248
	ds_read_b128 v[218:221], v150 offset:55296
	ds_read_b128 v[222:225], v253 offset:55296
	global_load_lds_dwordx4 v[154:155], off
	s_add_i32 m0, s50, 0x2000
	s_add_u32 s48, s48, 0x40080
	v_lshl_add_u64 v[154:155], v[226:227], 0, s[20:21]
	s_addc_u32 s49, s49, 0
	s_add_i32 s50, s77, s54
	global_load_lds_dwordx4 v[154:155], off
	v_lshl_add_u64 v[154:155], s[48:49], 0, v[132:133]
	s_mov_b32 m0, s50
	s_nop 0
	global_load_lds_dwordx4 v[154:155], off
	v_lshl_add_u64 v[154:155], s[48:49], 0, v[128:129]
	s_add_i32 m0, s50, 0x2000
	s_nop 0
	global_load_lds_dwordx4 v[154:155], off
	v_lshl_add_u64 v[154:155], v[228:229], 0, s[20:21]
	s_mov_b32 m0, s62
	s_nop 0
	global_load_lds_dwordx4 v[154:155], off
	v_lshl_add_u64 v[154:155], v[230:231], 0, s[20:21]
	s_mov_b32 m0, s63
	s_nop 0
	global_load_lds_dwordx4 v[154:155], off
	s_waitcnt lgkmcnt(8)
	v_add_f32_e32 v236, v236, v237
	v_add_f32_e32 v238, v238, v239
	v_add_f32_e32 v240, v240, v241
	v_add_f32_e32 v242, v242, v243
	v_add_f32_e32 v244, v244, v245
	v_add_f32_e32 v246, v246, v247
	v_add_f32_e32 v248, v248, v249
	v_add_f32_e32 v250, v250, v251
	v_add_f32_e32 v236, v236, v238
	v_add_f32_e32 v240, v240, v242
	v_add_f32_e32 v244, v244, v246
	v_add_f32_e32 v248, v248, v250
	v_fmamk_f32 v236, v236, 0x3a800000, v152
	v_fmamk_f32 v240, v240, 0x3a800000, v152
	v_fmamk_f32 v244, v244, 0x3a800000, v152
	v_fmamk_f32 v248, v248, 0x3a800000, v152
	v_rsq_f32_e32 v236, v236
	v_rsq_f32_e32 v240, v240
	v_rsq_f32_e32 v244, v244
	v_rsq_f32_e32 v248, v248
	v_mul_f32_e32 v252, 0xbfb8aa3b, v236
	v_mul_f32_e32 v254, v236, v236
	v_rcp_f32_e32 v254, v254
	v_pk_mul_f32 v[120:121], v[124:125], v[120:121]
	v_pk_mul_f32 v[122:123], v[126:127], v[122:123]
	v_pk_mul_f32 v[112:113], v[116:117], v[112:113]
	v_pk_mul_f32 v[114:115], v[118:119], v[114:115]
	v_pk_mul_f32 v[124:125], v[124:125], v[252:253] op_sel_hi:[1,0]
	v_pk_mul_f32 v[126:127], v[126:127], v[252:253] op_sel_hi:[1,0]
	v_pk_mul_f32 v[116:117], v[116:117], v[252:253] op_sel_hi:[1,0]
	v_pk_mul_f32 v[118:119], v[118:119], v[252:253] op_sel_hi:[1,0]
	v_exp_f32_e32 v124, v124
	v_exp_f32_e32 v125, v125
	v_exp_f32_e32 v126, v126
	v_exp_f32_e32 v127, v127
	v_exp_f32_e32 v116, v116
	v_exp_f32_e32 v117, v117
	v_exp_f32_e32 v118, v118
	v_exp_f32_e32 v119, v119
	v_pk_fma_f32 v[124:125], v[124:125], v[254:255], v[254:255] op_sel_hi:[1,0,0]
	v_pk_fma_f32 v[126:127], v[126:127], v[254:255], v[254:255] op_sel_hi:[1,0,0]
	v_pk_fma_f32 v[116:117], v[116:117], v[254:255], v[254:255] op_sel_hi:[1,0,0]
	v_pk_fma_f32 v[118:119], v[118:119], v[254:255], v[254:255] op_sel_hi:[1,0,0]
	v_rcp_f32_e32 v124, v124
	v_rcp_f32_e32 v125, v125
	v_rcp_f32_e32 v126, v126
	v_rcp_f32_e32 v127, v127
	v_rcp_f32_e32 v116, v116
	v_rcp_f32_e32 v117, v117
	v_rcp_f32_e32 v118, v118
	v_rcp_f32_e32 v119, v119
	v_pk_mul_f32 v[120:121], v[120:121], v[124:125]
	v_pk_mul_f32 v[122:123], v[122:123], v[126:127]
	v_pk_mul_f32 v[112:113], v[112:113], v[116:117]
	v_pk_mul_f32 v[114:115], v[114:115], v[118:119]
	v_cvt_pk_bf16_f32 v120, v120, v121
	v_cvt_pk_bf16_f32 v121, v122, v123
	v_cvt_pk_bf16_f32 v122, v112, v113
	v_cvt_pk_bf16_f32 v123, v114, v115
	global_store_dwordx4 v235, v[120:123], s[14:15]
	v_add_u32_e32 v234, 0x16000, v235
	v_mul_f32_e32 v252, 0xbfb8aa3b, v240
	v_mul_f32_e32 v254, v240, v240
	v_rcp_f32_e32 v254, v254
	v_pk_mul_f32 v[104:105], v[108:109], v[104:105]
	v_pk_mul_f32 v[106:107], v[110:111], v[106:107]
	v_pk_mul_f32 v[96:97], v[100:101], v[96:97]
	v_pk_mul_f32 v[98:99], v[102:103], v[98:99]
	v_pk_mul_f32 v[108:109], v[108:109], v[252:253] op_sel_hi:[1,0]
	v_pk_mul_f32 v[110:111], v[110:111], v[252:253] op_sel_hi:[1,0]
	v_pk_mul_f32 v[100:101], v[100:101], v[252:253] op_sel_hi:[1,0]
	v_pk_mul_f32 v[102:103], v[102:103], v[252:253] op_sel_hi:[1,0]
	v_exp_f32_e32 v108, v108
	v_exp_f32_e32 v109, v109
	v_exp_f32_e32 v110, v110
	v_exp_f32_e32 v111, v111
	v_exp_f32_e32 v100, v100
	v_exp_f32_e32 v101, v101
	v_exp_f32_e32 v102, v102
	v_exp_f32_e32 v103, v103
	v_pk_fma_f32 v[108:109], v[108:109], v[254:255], v[254:255] op_sel_hi:[1,0,0]
	v_pk_fma_f32 v[110:111], v[110:111], v[254:255], v[254:255] op_sel_hi:[1,0,0]
	v_pk_fma_f32 v[100:101], v[100:101], v[254:255], v[254:255] op_sel_hi:[1,0,0]
	v_pk_fma_f32 v[102:103], v[102:103], v[254:255], v[254:255] op_sel_hi:[1,0,0]
	v_rcp_f32_e32 v108, v108
	v_rcp_f32_e32 v109, v109
	v_rcp_f32_e32 v110, v110
	v_rcp_f32_e32 v111, v111
	v_rcp_f32_e32 v100, v100
	v_rcp_f32_e32 v101, v101
	v_rcp_f32_e32 v102, v102
	v_rcp_f32_e32 v103, v103
	v_pk_mul_f32 v[104:105], v[104:105], v[108:109]
	v_pk_mul_f32 v[106:107], v[106:107], v[110:111]
	v_pk_mul_f32 v[96:97], v[96:97], v[100:101]
	v_pk_mul_f32 v[98:99], v[98:99], v[102:103]
	v_cvt_pk_bf16_f32 v104, v104, v105
	v_cvt_pk_bf16_f32 v105, v106, v107
	v_cvt_pk_bf16_f32 v106, v96, v97
	v_cvt_pk_bf16_f32 v107, v98, v99
	global_store_dwordx4 v234, v[104:107], s[14:15]
	v_add_u32_e32 v235, 0x16000, v234
	v_mul_f32_e32 v252, 0xbfb8aa3b, v244
	v_mul_f32_e32 v254, v244, v244
	v_rcp_f32_e32 v254, v254
	v_pk_mul_f32 v[88:89], v[92:93], v[88:89]
	v_pk_mul_f32 v[90:91], v[94:95], v[90:91]
	v_pk_mul_f32 v[80:81], v[84:85], v[80:81]
	v_pk_mul_f32 v[82:83], v[86:87], v[82:83]
	v_pk_mul_f32 v[92:93], v[92:93], v[252:253] op_sel_hi:[1,0]
	v_pk_mul_f32 v[94:95], v[94:95], v[252:253] op_sel_hi:[1,0]
	v_pk_mul_f32 v[84:85], v[84:85], v[252:253] op_sel_hi:[1,0]
	v_pk_mul_f32 v[86:87], v[86:87], v[252:253] op_sel_hi:[1,0]
	v_exp_f32_e32 v92, v92
	v_exp_f32_e32 v93, v93
	v_exp_f32_e32 v94, v94
	v_exp_f32_e32 v95, v95
	v_exp_f32_e32 v84, v84
	v_exp_f32_e32 v85, v85
	v_exp_f32_e32 v86, v86
	v_exp_f32_e32 v87, v87
	v_pk_fma_f32 v[92:93], v[92:93], v[254:255], v[254:255] op_sel_hi:[1,0,0]
	v_pk_fma_f32 v[94:95], v[94:95], v[254:255], v[254:255] op_sel_hi:[1,0,0]
	v_pk_fma_f32 v[84:85], v[84:85], v[254:255], v[254:255] op_sel_hi:[1,0,0]
	v_pk_fma_f32 v[86:87], v[86:87], v[254:255], v[254:255] op_sel_hi:[1,0,0]
	v_rcp_f32_e32 v92, v92
	v_rcp_f32_e32 v93, v93
	v_rcp_f32_e32 v94, v94
	v_rcp_f32_e32 v95, v95
	v_rcp_f32_e32 v84, v84
	v_rcp_f32_e32 v85, v85
	v_rcp_f32_e32 v86, v86
	v_rcp_f32_e32 v87, v87
	v_pk_mul_f32 v[88:89], v[88:89], v[92:93]
	v_pk_mul_f32 v[90:91], v[90:91], v[94:95]
	v_pk_mul_f32 v[80:81], v[80:81], v[84:85]
	v_pk_mul_f32 v[82:83], v[82:83], v[86:87]
	v_cvt_pk_bf16_f32 v88, v88, v89
	v_cvt_pk_bf16_f32 v89, v90, v91
	v_cvt_pk_bf16_f32 v90, v80, v81
	v_cvt_pk_bf16_f32 v91, v82, v83
	global_store_dwordx4 v235, v[88:91], s[14:15]
	v_add_u32_e32 v234, 0x16000, v235
	v_mul_f32_e32 v252, 0xbfb8aa3b, v248
	v_mul_f32_e32 v254, v248, v248
	v_rcp_f32_e32 v254, v254
	v_pk_mul_f32 v[72:73], v[76:77], v[72:73]
	v_pk_mul_f32 v[74:75], v[78:79], v[74:75]
	v_pk_mul_f32 v[64:65], v[68:69], v[64:65]
	v_pk_mul_f32 v[66:67], v[70:71], v[66:67]
	v_pk_mul_f32 v[76:77], v[76:77], v[252:253] op_sel_hi:[1,0]
	v_pk_mul_f32 v[78:79], v[78:79], v[252:253] op_sel_hi:[1,0]
	v_pk_mul_f32 v[68:69], v[68:69], v[252:253] op_sel_hi:[1,0]
	v_pk_mul_f32 v[70:71], v[70:71], v[252:253] op_sel_hi:[1,0]
	v_exp_f32_e32 v76, v76
	v_exp_f32_e32 v77, v77
	v_exp_f32_e32 v78, v78
	v_exp_f32_e32 v79, v79
	v_exp_f32_e32 v68, v68
	v_exp_f32_e32 v69, v69
	v_exp_f32_e32 v70, v70
	v_exp_f32_e32 v71, v71
	v_pk_fma_f32 v[76:77], v[76:77], v[254:255], v[254:255] op_sel_hi:[1,0,0]
	v_pk_fma_f32 v[78:79], v[78:79], v[254:255], v[254:255] op_sel_hi:[1,0,0]
	v_pk_fma_f32 v[68:69], v[68:69], v[254:255], v[254:255] op_sel_hi:[1,0,0]
	v_pk_fma_f32 v[70:71], v[70:71], v[254:255], v[254:255] op_sel_hi:[1,0,0]
	v_rcp_f32_e32 v76, v76
	v_rcp_f32_e32 v77, v77
	v_rcp_f32_e32 v78, v78
	v_rcp_f32_e32 v79, v79
	v_rcp_f32_e32 v68, v68
	v_rcp_f32_e32 v69, v69
	v_rcp_f32_e32 v70, v70
	v_rcp_f32_e32 v71, v71
	v_pk_mul_f32 v[72:73], v[72:73], v[76:77]
	v_pk_mul_f32 v[74:75], v[74:75], v[78:79]
	v_pk_mul_f32 v[64:65], v[64:65], v[68:69]
	v_pk_mul_f32 v[66:67], v[66:67], v[70:71]
	v_cvt_pk_bf16_f32 v72, v72, v73
	v_cvt_pk_bf16_f32 v73, v74, v75
	v_cvt_pk_bf16_f32 v74, v64, v65
	v_cvt_pk_bf16_f32 v75, v66, v67
	global_store_dwordx4 v234, v[72:75], s[14:15]
	s_waitcnt vmcnt(12)
	s_waitcnt lgkmcnt(0)
	s_setprio 1
	s_barrier
	v_mfma_f32_16x16x32_bf16 v[60:63], v[160:163], v[194:197], v[60:63]
	v_mfma_f32_16x16x32_bf16 v[60:63], v[164:167], v[198:201], v[60:63]
	v_mfma_f32_16x16x32_bf16 v[52:55], v[172:175], v[198:201], v[52:55]
	v_mfma_f32_16x16x32_bf16 v[52:55], v[168:171], v[194:197], v[52:55]
	v_mfma_f32_16x16x32_bf16 v[36:39], v[168:171], v[202:205], v[36:39]
	v_mfma_f32_16x16x32_bf16 v[36:39], v[172:175], v[206:209], v[36:39]
	v_mfma_f32_16x16x32_bf16 v[44:47], v[164:167], v[206:209], v[44:47]
	v_mfma_f32_16x16x32_bf16 v[44:47], v[160:163], v[202:205], v[44:47]
	v_mfma_f32_16x16x32_bf16 v[28:31], v[160:163], v[210:213], v[28:31]
	v_mfma_f32_16x16x32_bf16 v[28:31], v[164:167], v[214:217], v[28:31]
	v_mfma_f32_16x16x32_bf16 v[20:23], v[172:175], v[214:217], v[20:23]
	v_mfma_f32_16x16x32_bf16 v[20:23], v[168:171], v[210:213], v[20:23]
	v_mfma_f32_16x16x32_bf16 v[4:7], v[168:171], v[218:221], v[4:7]
	v_mfma_f32_16x16x32_bf16 v[4:7], v[172:175], v[222:225], v[4:7]
	v_mfma_f32_16x16x32_bf16 v[12:15], v[164:167], v[222:225], v[12:15]
	v_mfma_f32_16x16x32_bf16 v[12:15], v[160:163], v[218:221], v[12:15]
	s_setprio 0
	s_setprio 1
	v_mfma_f32_16x16x32_bf16 v[56:59], v[176:179], v[194:197], v[56:59]
	v_mfma_f32_16x16x32_bf16 v[56:59], v[180:183], v[198:201], v[56:59]
	v_mfma_f32_16x16x32_bf16 v[48:51], v[190:193], v[198:201], v[48:51]
	v_mfma_f32_16x16x32_bf16 v[48:51], v[186:189], v[194:197], v[48:51]
	v_mfma_f32_16x16x32_bf16 v[32:35], v[186:189], v[202:205], v[32:35]
	v_mfma_f32_16x16x32_bf16 v[32:35], v[190:193], v[206:209], v[32:35]
	v_mfma_f32_16x16x32_bf16 v[40:43], v[180:183], v[206:209], v[40:43]
	v_mfma_f32_16x16x32_bf16 v[40:43], v[176:179], v[202:205], v[40:43]
	v_mfma_f32_16x16x32_bf16 v[24:27], v[176:179], v[210:213], v[24:27]
	v_mfma_f32_16x16x32_bf16 v[24:27], v[180:183], v[214:217], v[24:27]
	v_mfma_f32_16x16x32_bf16 v[16:19], v[190:193], v[214:217], v[16:19]
	v_mfma_f32_16x16x32_bf16 v[16:19], v[186:189], v[210:213], v[16:19]
	v_mfma_f32_16x16x32_bf16 v[0:3], v[186:189], v[218:221], v[0:3]
	v_mfma_f32_16x16x32_bf16 v[0:3], v[190:193], v[222:225], v[0:3]
	v_mfma_f32_16x16x32_bf16 v[8:11], v[180:183], v[222:225], v[8:11]
	v_mfma_f32_16x16x32_bf16 v[8:11], v[176:179], v[218:221], v[8:11]
	s_barrier
	s_setprio 0
	s_add_i32 s75, s75, 2
	s_add_u32 s73, s73, 0x100
	s_addc_u32 s74, s74, 0
	s_add_u32 s46, s46, 0x100
	s_addc_u32 s47, s47, 0

.LBB0_609:
	s_add_u32 s79, s56, 0x100
	s_addc_u32 s80, s57, 0
	s_mov_b32 s81, -2
	s_waitcnt lgkmcnt(0)
	s_cmp_eq_u32 s70, 1
	s_cbranch_scc1 .Lfa_5
	ds_read_b128 v[128:131], v189
	v_xor_b32_e32 v253, 64, v189
	ds_read_b128 v[132:135], v253
	ds_read_b128 v[136:139], v189 offset:2048
	ds_read_b128 v[140:143], v253 offset:2048
	ds_read_b128 v[144:147], v190
	v_xor_b32_e32 v253, 64, v190
	ds_read_b128 v[148:151], v253
	ds_read_b128 v[172:175], v190 offset:2048
	ds_read_b128 v[176:179], v253 offset:2048
	s_add_u32 s56, s54, 0x100
	s_addc_u32 s57, s55, 0
	s_cmp_eq_u32 s81, 40
	s_cselect_b32 s61, s17, s57
	s_cselect_b32 s60, s16, s56
	s_cselect_b32 s59, s53, s80
	s_cselect_b32 s58, s52, s79
	v_lshl_add_u64 v[222:223], s[54:55], 0, v[166:167]
	s_add_i32 m0, s66, 0xc000
	s_nop 0
	global_load_lds_dwordx4 v[222:223], off
	v_lshl_add_u64 v[222:223], s[54:55], 0, v[164:165]
	s_add_i32 m0, s66, 0xe000
	s_nop 0
	global_load_lds_dwordx4 v[222:223], off
	ds_read_b128 v[180:183], v191
	v_xor_b32_e32 v253, 64, v191
	ds_read_b128 v[194:197], v253
	ds_read_b128 v[198:201], v191 offset:2048
	ds_read_b128 v[202:205], v253 offset:2048
	ds_read_b128 v[206:209], v191 offset:4096
	ds_read_b128 v[210:213], v253 offset:4096
	ds_read_b128 v[214:217], v191 offset:6144
	ds_read_b128 v[218:221], v253 offset:6144
	s_waitcnt vmcnt(24)
	s_waitcnt lgkmcnt(0)
	s_setprio 1
	s_barrier
	v_mfma_f32_16x16x32_bf16 v[124:127], v[128:131], v[180:183], 0
	v_mfma_f32_16x16x32_bf16 v[120:123], v[136:139], v[180:183], 0
	v_mfma_f32_16x16x32_bf16 v[108:111], v[128:131], v[198:201], 0
	v_mfma_f32_16x16x32_bf16 v[104:107], v[136:139], v[198:201], 0
	v_mfma_f32_16x16x32_bf16 v[92:95], v[128:131], v[206:209], 0
	v_mfma_f32_16x16x32_bf16 v[88:91], v[136:139], v[206:209], 0
	v_mfma_f32_16x16x32_bf16 v[76:79], v[128:131], v[214:217], 0
	v_mfma_f32_16x16x32_bf16 v[72:75], v[136:139], v[214:217], 0
	v_mfma_f32_16x16x32_bf16 v[124:127], v[132:135], v[194:197], v[124:127]
	v_mfma_f32_16x16x32_bf16 v[120:123], v[140:143], v[194:197], v[120:123]
	v_mfma_f32_16x16x32_bf16 v[108:111], v[132:135], v[202:205], v[108:111]
	v_mfma_f32_16x16x32_bf16 v[104:107], v[140:143], v[202:205], v[104:107]
	v_mfma_f32_16x16x32_bf16 v[92:95], v[132:135], v[210:213], v[92:95]
	v_mfma_f32_16x16x32_bf16 v[88:91], v[140:143], v[210:213], v[88:91]
	v_mfma_f32_16x16x32_bf16 v[76:79], v[132:135], v[218:221], v[76:79]
	v_mfma_f32_16x16x32_bf16 v[72:75], v[140:143], v[218:221], v[72:75]
	s_setprio 0
	s_setprio 1
	v_mfma_f32_16x16x32_bf16 v[116:119], v[144:147], v[180:183], 0
	v_mfma_f32_16x16x32_bf16 v[112:115], v[172:175], v[180:183], 0
	v_mfma_f32_16x16x32_bf16 v[100:103], v[144:147], v[198:201], 0
	v_mfma_f32_16x16x32_bf16 v[96:99], v[172:175], v[198:201], 0
	v_mfma_f32_16x16x32_bf16 v[84:87], v[144:147], v[206:209], 0
	v_mfma_f32_16x16x32_bf16 v[80:83], v[172:175], v[206:209], 0
	v_mfma_f32_16x16x32_bf16 v[68:71], v[144:147], v[214:217], 0
	v_mfma_f32_16x16x32_bf16 v[64:67], v[172:175], v[214:217], 0
	v_mfma_f32_16x16x32_bf16 v[116:119], v[148:151], v[194:197], v[116:119]
	v_mfma_f32_16x16x32_bf16 v[112:115], v[176:179], v[194:197], v[112:115]
	v_mfma_f32_16x16x32_bf16 v[100:103], v[148:151], v[202:205], v[100:103]
	v_mfma_f32_16x16x32_bf16 v[96:99], v[176:179], v[202:205], v[96:99]
	v_mfma_f32_16x16x32_bf16 v[84:87], v[148:151], v[210:213], v[84:87]
	v_mfma_f32_16x16x32_bf16 v[80:83], v[176:179], v[210:213], v[80:83]
	v_mfma_f32_16x16x32_bf16 v[68:71], v[148:151], v[218:221], v[68:71]
	v_mfma_f32_16x16x32_bf16 v[64:67], v[176:179], v[218:221], v[64:67]
	s_barrier
	s_setprio 0
	s_add_i32 s54, s75, s65
	v_lshl_add_u64 v[222:223], s[58:59], 0, v[154:155]
	s_mov_b32 m0, s54
	s_nop 0
	global_load_lds_dwordx4 v[222:223], off
	s_add_i32 m0, s54, 0x2000
	s_add_u32 s54, s58, 0xb0000
	v_lshl_add_u64 v[224:225], s[58:59], 0, v[162:163]
	s_addc_u32 s55, s59, 0
	s_add_i32 s82, s76, s65
	global_load_lds_dwordx4 v[224:225], off
	v_lshl_add_u64 v[226:227], s[54:55], 0, v[154:155]
	s_mov_b32 m0, s82
	v_lshl_add_u64 v[228:229], s[60:61], 0, v[160:161]
	global_load_lds_dwordx4 v[226:227], off
	v_lshl_add_u64 v[226:227], s[54:55], 0, v[162:163]
	s_add_i32 m0, s82, 0x2000
	s_nop 0
	global_load_lds_dwordx4 v[226:227], off
	v_lshl_add_u64 v[226:227], s[60:61], 0, v[152:153]
	s_mov_b32 m0, s66
	s_nop 0
	global_load_lds_dwordx4 v[226:227], off
	s_mov_b32 m0, s67
	s_nop 0
	global_load_lds_dwordx4 v[228:229], off
	ds_read_b128 v[180:183], v191 offset:16384
	v_xor_b32_e32 v253, 64, v191
	ds_read_b128 v[194:197], v253 offset:16384
	ds_read_b128 v[198:201], v191 offset:18432
	ds_read_b128 v[202:205], v253 offset:18432
	ds_read_b128 v[206:209], v191 offset:20480
	ds_read_b128 v[210:213], v253 offset:20480
	ds_read_b128 v[214:217], v191 offset:22528
	ds_read_b128 v[218:221], v253 offset:22528
	s_waitcnt vmcnt(24)
	s_waitcnt lgkmcnt(0)
	s_setprio 1
	s_barrier
	v_mfma_f32_16x16x32_bf16 v[60:63], v[128:131], v[180:183], 0
	v_mfma_f32_16x16x32_bf16 v[56:59], v[136:139], v[180:183], 0
	v_mfma_f32_16x16x32_bf16 v[44:47], v[128:131], v[198:201], 0
	v_mfma_f32_16x16x32_bf16 v[40:43], v[136:139], v[198:201], 0
	v_mfma_f32_16x16x32_bf16 v[28:31], v[128:131], v[206:209], 0
	v_mfma_f32_16x16x32_bf16 v[24:27], v[136:139], v[206:209], 0
	v_mfma_f32_16x16x32_bf16 v[12:15], v[128:131], v[214:217], 0
	v_mfma_f32_16x16x32_bf16 v[8:11], v[136:139], v[214:217], 0
	v_mfma_f32_16x16x32_bf16 v[60:63], v[132:135], v[194:197], v[60:63]
	v_mfma_f32_16x16x32_bf16 v[56:59], v[140:143], v[194:197], v[56:59]
	v_mfma_f32_16x16x32_bf16 v[44:47], v[132:135], v[202:205], v[44:47]
	v_mfma_f32_16x16x32_bf16 v[40:43], v[140:143], v[202:205], v[40:43]
	v_mfma_f32_16x16x32_bf16 v[28:31], v[132:135], v[210:213], v[28:31]
	v_mfma_f32_16x16x32_bf16 v[24:27], v[140:143], v[210:213], v[24:27]
	v_mfma_f32_16x16x32_bf16 v[12:15], v[132:135], v[218:221], v[12:15]
	v_mfma_f32_16x16x32_bf16 v[8:11], v[140:143], v[218:221], v[8:11]
	s_setprio 0
	s_setprio 1
	v_mfma_f32_16x16x32_bf16 v[52:55], v[144:147], v[180:183], 0
	v_mfma_f32_16x16x32_bf16 v[48:51], v[172:175], v[180:183], 0
	v_mfma_f32_16x16x32_bf16 v[36:39], v[144:147], v[198:201], 0
	v_mfma_f32_16x16x32_bf16 v[32:35], v[172:175], v[198:201], 0
	v_mfma_f32_16x16x32_bf16 v[20:23], v[144:147], v[206:209], 0
	v_mfma_f32_16x16x32_bf16 v[16:19], v[172:175], v[206:209], 0
	v_mfma_f32_16x16x32_bf16 v[4:7], v[144:147], v[214:217], 0
	v_mfma_f32_16x16x32_bf16 v[0:3], v[172:175], v[214:217], 0
	v_mfma_f32_16x16x32_bf16 v[52:55], v[148:151], v[194:197], v[52:55]
	v_mfma_f32_16x16x32_bf16 v[48:51], v[176:179], v[194:197], v[48:51]
	v_mfma_f32_16x16x32_bf16 v[36:39], v[148:151], v[202:205], v[36:39]
	v_mfma_f32_16x16x32_bf16 v[32:35], v[176:179], v[202:205], v[32:35]
	v_mfma_f32_16x16x32_bf16 v[20:23], v[148:151], v[210:213], v[20:23]
	v_mfma_f32_16x16x32_bf16 v[16:19], v[176:179], v[210:213], v[16:19]
	v_mfma_f32_16x16x32_bf16 v[4:7], v[148:151], v[218:221], v[4:7]
	v_mfma_f32_16x16x32_bf16 v[0:3], v[176:179], v[218:221], v[0:3]
	s_barrier
	s_setprio 0
	s_add_i32 s82, 0, 0x18000
	s_add_i32 s83, 0, 0x1c000
	v_add_u32_e32 v140, s82, v186
	v_add_u32_e32 v176, s83, v186
	s_add_u32 s54, s60, 0xb0000
	s_addc_u32 s55, s61, 0
	s_mov_b32 m0, s68
	v_lshl_add_u64 v[230:231], s[54:55], 0, v[152:153]
	global_load_lds_dwordx4 v[230:231], off
	v_lshl_add_u64 v[230:231], s[54:55], 0, v[160:161]
	s_mov_b32 m0, s69
	s_nop 0
	global_load_lds_dwordx4 v[230:231], off
	ds_read_b128 v[128:131], v140
	v_xor_b32_e32 v253, 64, v140
	ds_read_b128 v[132:135], v253
	ds_read_b128 v[136:139], v140 offset:2048
	ds_read_b128 v[140:143], v253 offset:2048
	ds_read_b128 v[144:147], v176
	v_xor_b32_e32 v253, 64, v176
	ds_read_b128 v[148:151], v253
	ds_read_b128 v[172:175], v176 offset:2048
	ds_read_b128 v[176:179], v253 offset:2048
	ds_read_b128 v[180:183], v191 offset:32768
	v_xor_b32_e32 v253, 64, v191
	ds_read_b128 v[194:197], v253 offset:32768
	ds_read_b128 v[198:201], v191 offset:34816
	ds_read_b128 v[202:205], v253 offset:34816
	ds_read_b128 v[206:209], v191 offset:36864
	ds_read_b128 v[210:213], v253 offset:36864
	ds_read_b128 v[214:217], v191 offset:38912
	ds_read_b128 v[218:221], v253 offset:38912
	s_waitcnt vmcnt(8)
	s_waitcnt lgkmcnt(0)
	s_setprio 1
	s_barrier
	v_mfma_f32_16x16x32_bf16 v[124:127], v[128:131], v[180:183], v[124:127]
	v_mfma_f32_16x16x32_bf16 v[124:127], v[132:135], v[194:197], v[124:127]
	v_mfma_f32_16x16x32_bf16 v[120:123], v[140:143], v[194:197], v[120:123]
	v_mfma_f32_16x16x32_bf16 v[120:123], v[136:139], v[180:183], v[120:123]
	v_mfma_f32_16x16x32_bf16 v[104:107], v[136:139], v[198:201], v[104:107]
	v_mfma_f32_16x16x32_bf16 v[104:107], v[140:143], v[202:205], v[104:107]
	v_mfma_f32_16x16x32_bf16 v[108:111], v[132:135], v[202:205], v[108:111]
	v_mfma_f32_16x16x32_bf16 v[108:111], v[128:131], v[198:201], v[108:111]
	v_mfma_f32_16x16x32_bf16 v[92:95], v[128:131], v[206:209], v[92:95]
	v_mfma_f32_16x16x32_bf16 v[92:95], v[132:135], v[210:213], v[92:95]
	v_mfma_f32_16x16x32_bf16 v[88:91], v[140:143], v[210:213], v[88:91]
	v_mfma_f32_16x16x32_bf16 v[88:91], v[136:139], v[206:209], v[88:91]
	v_mfma_f32_16x16x32_bf16 v[72:75], v[136:139], v[214:217], v[72:75]
	v_mfma_f32_16x16x32_bf16 v[72:75], v[140:143], v[218:221], v[72:75]
	v_mfma_f32_16x16x32_bf16 v[76:79], v[132:135], v[218:221], v[76:79]
	v_mfma_f32_16x16x32_bf16 v[76:79], v[128:131], v[214:217], v[76:79]
	s_setprio 0
	s_setprio 1
	v_mfma_f32_16x16x32_bf16 v[116:119], v[144:147], v[180:183], v[116:119]
	v_mfma_f32_16x16x32_bf16 v[116:119], v[148:151], v[194:197], v[116:119]
	v_mfma_f32_16x16x32_bf16 v[112:115], v[176:179], v[194:197], v[112:115]
	v_mfma_f32_16x16x32_bf16 v[112:115], v[172:175], v[180:183], v[112:115]
	v_mfma_f32_16x16x32_bf16 v[96:99], v[172:175], v[198:201], v[96:99]
	v_mfma_f32_16x16x32_bf16 v[96:99], v[176:179], v[202:205], v[96:99]
	v_mfma_f32_16x16x32_bf16 v[100:103], v[148:151], v[202:205], v[100:103]
	v_mfma_f32_16x16x32_bf16 v[100:103], v[144:147], v[198:201], v[100:103]
	v_mfma_f32_16x16x32_bf16 v[84:87], v[144:147], v[206:209], v[84:87]
	v_mfma_f32_16x16x32_bf16 v[84:87], v[148:151], v[210:213], v[84:87]
	v_mfma_f32_16x16x32_bf16 v[80:83], v[176:179], v[210:213], v[80:83]
	v_mfma_f32_16x16x32_bf16 v[80:83], v[172:175], v[206:209], v[80:83]
	v_mfma_f32_16x16x32_bf16 v[64:67], v[172:175], v[214:217], v[64:67]
	v_mfma_f32_16x16x32_bf16 v[64:67], v[176:179], v[218:221], v[64:67]
	v_mfma_f32_16x16x32_bf16 v[68:71], v[148:151], v[218:221], v[68:71]
	v_mfma_f32_16x16x32_bf16 v[68:71], v[144:147], v[214:217], v[68:71]
	s_barrier
	s_setprio 0
	s_add_i32 s54, s82, s65
	v_lshl_add_u64 v[222:223], v[222:223], 0, s[28:29]
	s_mov_b32 m0, s54
	s_nop 0
	global_load_lds_dwordx4 v[222:223], off
	s_add_i32 m0, s54, 0x2000
	s_add_u32 s54, s58, 0xb0080
	v_lshl_add_u64 v[222:223], v[224:225], 0, s[28:29]
	s_addc_u32 s55, s59, 0
	s_add_i32 s58, s83, s65
	global_load_lds_dwordx4 v[222:223], off
	v_lshl_add_u64 v[222:223], s[54:55], 0, v[154:155]
	s_mov_b32 m0, s58
	s_nop 0
	global_load_lds_dwordx4 v[222:223], off
	v_lshl_add_u64 v[222:223], s[54:55], 0, v[162:163]
	s_add_i32 m0, s58, 0x2000
	s_nop 0
	global_load_lds_dwordx4 v[222:223], off
	v_lshl_add_u64 v[222:223], v[226:227], 0, s[28:29]
	s_mov_b32 m0, s3
	s_nop 0
	global_load_lds_dwordx4 v[222:223], off
	v_lshl_add_u64 v[222:223], v[228:229], 0, s[28:29]
	s_mov_b32 m0, s71
	s_nop 0
	global_load_lds_dwordx4 v[222:223], off
	ds_read_b128 v[180:183], v191 offset:49152
	v_xor_b32_e32 v253, 64, v191
	ds_read_b128 v[194:197], v253 offset:49152
	ds_read_b128 v[198:201], v191 offset:51200
	ds_read_b128 v[202:205], v253 offset:51200
	ds_read_b128 v[206:209], v191 offset:53248
	ds_read_b128 v[210:213], v253 offset:53248
	ds_read_b128 v[214:217], v191 offset:55296
	ds_read_b128 v[218:221], v253 offset:55296
	s_waitcnt vmcnt(8)
	s_waitcnt lgkmcnt(0)
	s_setprio 1
	s_barrier
	v_mfma_f32_16x16x32_bf16 v[60:63], v[128:131], v[180:183], v[60:63]
	v_mfma_f32_16x16x32_bf16 v[60:63], v[132:135], v[194:197], v[60:63]
	v_mfma_f32_16x16x32_bf16 v[56:59], v[140:143], v[194:197], v[56:59]
	v_mfma_f32_16x16x32_bf16 v[56:59], v[136:139], v[180:183], v[56:59]
	v_mfma_f32_16x16x32_bf16 v[40:43], v[136:139], v[198:201], v[40:43]
	v_mfma_f32_16x16x32_bf16 v[40:43], v[140:143], v[202:205], v[40:43]
	v_mfma_f32_16x16x32_bf16 v[44:47], v[132:135], v[202:205], v[44:47]
	v_mfma_f32_16x16x32_bf16 v[44:47], v[128:131], v[198:201], v[44:47]
	v_mfma_f32_16x16x32_bf16 v[28:31], v[128:131], v[206:209], v[28:31]
	v_mfma_f32_16x16x32_bf16 v[28:31], v[132:135], v[210:213], v[28:31]
	v_mfma_f32_16x16x32_bf16 v[24:27], v[140:143], v[210:213], v[24:27]
	v_mfma_f32_16x16x32_bf16 v[24:27], v[136:139], v[206:209], v[24:27]
	v_mfma_f32_16x16x32_bf16 v[8:11], v[136:139], v[214:217], v[8:11]
	v_mfma_f32_16x16x32_bf16 v[8:11], v[140:143], v[218:221], v[8:11]
	v_mfma_f32_16x16x32_bf16 v[12:15], v[132:135], v[218:221], v[12:15]
	v_mfma_f32_16x16x32_bf16 v[12:15], v[128:131], v[214:217], v[12:15]
	s_setprio 0
	s_setprio 1
	v_mfma_f32_16x16x32_bf16 v[52:55], v[144:147], v[180:183], v[52:55]
	v_mfma_f32_16x16x32_bf16 v[52:55], v[148:151], v[194:197], v[52:55]
	v_mfma_f32_16x16x32_bf16 v[48:51], v[176:179], v[194:197], v[48:51]
	v_mfma_f32_16x16x32_bf16 v[48:51], v[172:175], v[180:183], v[48:51]
	v_mfma_f32_16x16x32_bf16 v[32:35], v[172:175], v[198:201], v[32:35]
	v_mfma_f32_16x16x32_bf16 v[32:35], v[176:179], v[202:205], v[32:35]
	v_mfma_f32_16x16x32_bf16 v[36:39], v[148:151], v[202:205], v[36:39]
	v_mfma_f32_16x16x32_bf16 v[36:39], v[144:147], v[198:201], v[36:39]
	v_mfma_f32_16x16x32_bf16 v[20:23], v[144:147], v[206:209], v[20:23]
	v_mfma_f32_16x16x32_bf16 v[20:23], v[148:151], v[210:213], v[20:23]
	v_mfma_f32_16x16x32_bf16 v[16:19], v[176:179], v[210:213], v[16:19]
	v_mfma_f32_16x16x32_bf16 v[16:19], v[172:175], v[206:209], v[16:19]
	v_mfma_f32_16x16x32_bf16 v[0:3], v[172:175], v[214:217], v[0:3]
	v_mfma_f32_16x16x32_bf16 v[0:3], v[176:179], v[218:221], v[0:3]
	v_mfma_f32_16x16x32_bf16 v[4:7], v[148:151], v[218:221], v[4:7]
	v_mfma_f32_16x16x32_bf16 v[4:7], v[144:147], v[214:217], v[4:7]
	s_barrier
	s_setprio 0
	s_add_i32 s81, s81, 2
	s_add_u32 s79, s79, 0x100
	s_addc_u32 s80, s80, 0
	s_cmp_gt_u32 s81, 41
	s_mov_b64 s[54:55], s[56:57]
	s_branch .LBB0_610
.Lfa_5:
	ds_read_b128 v[128:131], v189
	v_xor_b32_e32 v253, 64, v189
	ds_read_b128 v[132:135], v253
	ds_read_b128 v[136:139], v189 offset:2048
	ds_read_b128 v[140:143], v253 offset:2048
	ds_read_b128 v[144:147], v190
	v_xor_b32_e32 v253, 64, v190
	ds_read_b128 v[148:151], v253
	ds_read_b128 v[172:175], v190 offset:2048
	ds_read_b128 v[176:179], v253 offset:2048
	s_add_u32 s56, s54, 0x100
	s_addc_u32 s57, s55, 0
	s_cmp_eq_u32 s81, 40
	s_cselect_b32 s61, s17, s57
	s_cselect_b32 s60, s16, s56
	s_cselect_b32 s59, s53, s80
	s_cselect_b32 s58, s52, s79
	v_lshl_add_u64 v[222:223], s[54:55], 0, v[166:167]
	s_add_i32 m0, s66, 0xc000
	s_nop 0
	global_load_lds_dwordx4 v[222:223], off
	v_lshl_add_u64 v[222:223], s[54:55], 0, v[164:165]
	s_add_i32 m0, s66, 0xe000
	s_nop 0
	global_load_lds_dwordx4 v[222:223], off
	ds_read_b128 v[180:183], v191
	v_xor_b32_e32 v253, 64, v191
	ds_read_b128 v[194:197], v253
	ds_read_b128 v[198:201], v191 offset:2048
	ds_read_b128 v[202:205], v253 offset:2048
	ds_read_b128 v[206:209], v191 offset:4096
	ds_read_b128 v[210:213], v253 offset:4096
	ds_read_b128 v[214:217], v191 offset:6144
	ds_read_b128 v[218:221], v253 offset:6144
	s_waitcnt vmcnt(8)
	s_waitcnt lgkmcnt(0)
	s_setprio 1
	s_barrier
	v_mfma_f32_16x16x32_bf16 v[124:127], v[128:131], v[180:183], 0
	v_mfma_f32_16x16x32_bf16 v[120:123], v[136:139], v[180:183], 0
	v_mfma_f32_16x16x32_bf16 v[108:111], v[128:131], v[198:201], 0
	v_mfma_f32_16x16x32_bf16 v[104:107], v[136:139], v[198:201], 0
	v_mfma_f32_16x16x32_bf16 v[92:95], v[128:131], v[206:209], 0
	v_mfma_f32_16x16x32_bf16 v[88:91], v[136:139], v[206:209], 0
	v_mfma_f32_16x16x32_bf16 v[76:79], v[128:131], v[214:217], 0
	v_mfma_f32_16x16x32_bf16 v[72:75], v[136:139], v[214:217], 0
	v_mfma_f32_16x16x32_bf16 v[124:127], v[132:135], v[194:197], v[124:127]
	v_mfma_f32_16x16x32_bf16 v[120:123], v[140:143], v[194:197], v[120:123]
	v_mfma_f32_16x16x32_bf16 v[108:111], v[132:135], v[202:205], v[108:111]
	v_mfma_f32_16x16x32_bf16 v[104:107], v[140:143], v[202:205], v[104:107]
	v_mfma_f32_16x16x32_bf16 v[92:95], v[132:135], v[210:213], v[92:95]
	v_mfma_f32_16x16x32_bf16 v[88:91], v[140:143], v[210:213], v[88:91]
	v_mfma_f32_16x16x32_bf16 v[76:79], v[132:135], v[218:221], v[76:79]
	v_mfma_f32_16x16x32_bf16 v[72:75], v[140:143], v[218:221], v[72:75]
	s_setprio 0
	s_setprio 1
	v_mfma_f32_16x16x32_bf16 v[116:119], v[144:147], v[180:183], 0
	v_mfma_f32_16x16x32_bf16 v[112:115], v[172:175], v[180:183], 0
	v_mfma_f32_16x16x32_bf16 v[100:103], v[144:147], v[198:201], 0
	v_mfma_f32_16x16x32_bf16 v[96:99], v[172:175], v[198:201], 0
	v_mfma_f32_16x16x32_bf16 v[84:87], v[144:147], v[206:209], 0
	v_mfma_f32_16x16x32_bf16 v[80:83], v[172:175], v[206:209], 0
	v_mfma_f32_16x16x32_bf16 v[68:71], v[144:147], v[214:217], 0
	v_mfma_f32_16x16x32_bf16 v[64:67], v[172:175], v[214:217], 0
	v_mfma_f32_16x16x32_bf16 v[116:119], v[148:151], v[194:197], v[116:119]
	v_mfma_f32_16x16x32_bf16 v[112:115], v[176:179], v[194:197], v[112:115]
	v_mfma_f32_16x16x32_bf16 v[100:103], v[148:151], v[202:205], v[100:103]
	v_mfma_f32_16x16x32_bf16 v[96:99], v[176:179], v[202:205], v[96:99]
	v_mfma_f32_16x16x32_bf16 v[84:87], v[148:151], v[210:213], v[84:87]
	v_mfma_f32_16x16x32_bf16 v[80:83], v[176:179], v[210:213], v[80:83]
	v_mfma_f32_16x16x32_bf16 v[68:71], v[148:151], v[218:221], v[68:71]
	v_mfma_f32_16x16x32_bf16 v[64:67], v[176:179], v[218:221], v[64:67]
	s_barrier
	s_setprio 0
	s_add_i32 s54, s75, s65
	v_lshl_add_u64 v[222:223], s[58:59], 0, v[154:155]
	s_mov_b32 m0, s54
	s_nop 0
	global_load_lds_dwordx4 v[222:223], off
	s_add_i32 m0, s54, 0x2000
	s_add_u32 s54, s58, 0xb0000
	v_lshl_add_u64 v[224:225], s[58:59], 0, v[162:163]
	s_addc_u32 s55, s59, 0
	s_add_i32 s82, s76, s65
	global_load_lds_dwordx4 v[224:225], off
	v_lshl_add_u64 v[226:227], s[54:55], 0, v[154:155]
	s_mov_b32 m0, s82
	v_lshl_add_u64 v[228:229], s[60:61], 0, v[160:161]
	global_load_lds_dwordx4 v[226:227], off
	v_lshl_add_u64 v[226:227], s[54:55], 0, v[162:163]
	s_add_i32 m0, s82, 0x2000
	s_nop 0
	global_load_lds_dwordx4 v[226:227], off
	v_lshl_add_u64 v[226:227], s[60:61], 0, v[152:153]
	s_mov_b32 m0, s66
	s_nop 0
	global_load_lds_dwordx4 v[226:227], off
	s_mov_b32 m0, s67
	s_nop 0
	global_load_lds_dwordx4 v[228:229], off
	ds_read_b128 v[180:183], v191 offset:16384
	v_xor_b32_e32 v253, 64, v191
	ds_read_b128 v[194:197], v253 offset:16384
	ds_read_b128 v[198:201], v191 offset:18432
	ds_read_b128 v[202:205], v253 offset:18432
	ds_read_b128 v[206:209], v191 offset:20480
	ds_read_b128 v[210:213], v253 offset:20480
	ds_read_b128 v[214:217], v191 offset:22528
	ds_read_b128 v[218:221], v253 offset:22528
	s_waitcnt vmcnt(8)
	s_waitcnt lgkmcnt(0)
	s_setprio 1
	s_barrier
	v_mfma_f32_16x16x32_bf16 v[60:63], v[128:131], v[180:183], 0
	v_mfma_f32_16x16x32_bf16 v[56:59], v[136:139], v[180:183], 0
	v_mfma_f32_16x16x32_bf16 v[44:47], v[128:131], v[198:201], 0
	v_mfma_f32_16x16x32_bf16 v[40:43], v[136:139], v[198:201], 0
	v_mfma_f32_16x16x32_bf16 v[28:31], v[128:131], v[206:209], 0
	v_mfma_f32_16x16x32_bf16 v[24:27], v[136:139], v[206:209], 0
	v_mfma_f32_16x16x32_bf16 v[12:15], v[128:131], v[214:217], 0
	v_mfma_f32_16x16x32_bf16 v[8:11], v[136:139], v[214:217], 0
	v_mfma_f32_16x16x32_bf16 v[60:63], v[132:135], v[194:197], v[60:63]
	v_mfma_f32_16x16x32_bf16 v[56:59], v[140:143], v[194:197], v[56:59]
	v_mfma_f32_16x16x32_bf16 v[44:47], v[132:135], v[202:205], v[44:47]
	v_mfma_f32_16x16x32_bf16 v[40:43], v[140:143], v[202:205], v[40:43]
	v_mfma_f32_16x16x32_bf16 v[28:31], v[132:135], v[210:213], v[28:31]
	v_mfma_f32_16x16x32_bf16 v[24:27], v[140:143], v[210:213], v[24:27]
	v_mfma_f32_16x16x32_bf16 v[12:15], v[132:135], v[218:221], v[12:15]
	v_mfma_f32_16x16x32_bf16 v[8:11], v[140:143], v[218:221], v[8:11]
	s_setprio 0
	s_setprio 1
	v_mfma_f32_16x16x32_bf16 v[52:55], v[144:147], v[180:183], 0
	v_mfma_f32_16x16x32_bf16 v[48:51], v[172:175], v[180:183], 0
	v_mfma_f32_16x16x32_bf16 v[36:39], v[144:147], v[198:201], 0
	v_mfma_f32_16x16x32_bf16 v[32:35], v[172:175], v[198:201], 0
	v_mfma_f32_16x16x32_bf16 v[20:23], v[144:147], v[206:209], 0
	v_mfma_f32_16x16x32_bf16 v[16:19], v[172:175], v[206:209], 0
	v_mfma_f32_16x16x32_bf16 v[4:7], v[144:147], v[214:217], 0
	v_mfma_f32_16x16x32_bf16 v[0:3], v[172:175], v[214:217], 0
	v_mfma_f32_16x16x32_bf16 v[52:55], v[148:151], v[194:197], v[52:55]
	v_mfma_f32_16x16x32_bf16 v[48:51], v[176:179], v[194:197], v[48:51]
	v_mfma_f32_16x16x32_bf16 v[36:39], v[148:151], v[202:205], v[36:39]
	v_mfma_f32_16x16x32_bf16 v[32:35], v[176:179], v[202:205], v[32:35]
	v_mfma_f32_16x16x32_bf16 v[20:23], v[148:151], v[210:213], v[20:23]
	v_mfma_f32_16x16x32_bf16 v[16:19], v[176:179], v[210:213], v[16:19]
	v_mfma_f32_16x16x32_bf16 v[4:7], v[148:151], v[218:221], v[4:7]
	v_mfma_f32_16x16x32_bf16 v[0:3], v[176:179], v[218:221], v[0:3]
	s_barrier
	s_setprio 0
	s_add_i32 s82, 0, 0x18000
	s_add_i32 s83, 0, 0x1c000
	v_add_u32_e32 v140, s82, v186
	v_add_u32_e32 v176, s83, v186
	s_add_u32 s54, s60, 0xb0000
	s_addc_u32 s55, s61, 0
	s_mov_b32 m0, s68
	v_lshl_add_u64 v[230:231], s[54:55], 0, v[152:153]
	global_load_lds_dwordx4 v[230:231], off
	v_lshl_add_u64 v[230:231], s[54:55], 0, v[160:161]
	s_mov_b32 m0, s69
	s_nop 0
	global_load_lds_dwordx4 v[230:231], off
	ds_read_b128 v[128:131], v140
	v_xor_b32_e32 v253, 64, v140
	ds_read_b128 v[132:135], v253
	ds_read_b128 v[136:139], v140 offset:2048
	ds_read_b128 v[140:143], v253 offset:2048
	ds_read_b128 v[144:147], v176
	v_xor_b32_e32 v253, 64, v176
	ds_read_b128 v[148:151], v253
	ds_read_b128 v[172:175], v176 offset:2048
	ds_read_b128 v[176:179], v253 offset:2048
	ds_read_b128 v[180:183], v191 offset:32768
	v_xor_b32_e32 v253, 64, v191
	ds_read_b128 v[194:197], v253 offset:32768
	ds_read_b128 v[198:201], v191 offset:34816
	ds_read_b128 v[202:205], v253 offset:34816
	ds_read_b128 v[206:209], v191 offset:36864
	ds_read_b128 v[210:213], v253 offset:36864
	ds_read_b128 v[214:217], v191 offset:38912
	ds_read_b128 v[218:221], v253 offset:38912
	s_waitcnt vmcnt(8)
	s_waitcnt lgkmcnt(0)
	s_setprio 1
	s_barrier
	v_mfma_f32_16x16x32_bf16 v[124:127], v[128:131], v[180:183], v[124:127]
	v_mfma_f32_16x16x32_bf16 v[124:127], v[132:135], v[194:197], v[124:127]
	v_mfma_f32_16x16x32_bf16 v[120:123], v[140:143], v[194:197], v[120:123]
	v_mfma_f32_16x16x32_bf16 v[120:123], v[136:139], v[180:183], v[120:123]
	v_mfma_f32_16x16x32_bf16 v[104:107], v[136:139], v[198:201], v[104:107]
	v_mfma_f32_16x16x32_bf16 v[104:107], v[140:143], v[202:205], v[104:107]
	v_mfma_f32_16x16x32_bf16 v[108:111], v[132:135], v[202:205], v[108:111]
	v_mfma_f32_16x16x32_bf16 v[108:111], v[128:131], v[198:201], v[108:111]
	v_mfma_f32_16x16x32_bf16 v[92:95], v[128:131], v[206:209], v[92:95]
	v_mfma_f32_16x16x32_bf16 v[92:95], v[132:135], v[210:213], v[92:95]
	v_mfma_f32_16x16x32_bf16 v[88:91], v[140:143], v[210:213], v[88:91]
	v_mfma_f32_16x16x32_bf16 v[88:91], v[136:139], v[206:209], v[88:91]
	v_mfma_f32_16x16x32_bf16 v[72:75], v[136:139], v[214:217], v[72:75]
	v_mfma_f32_16x16x32_bf16 v[72:75], v[140:143], v[218:221], v[72:75]
	v_mfma_f32_16x16x32_bf16 v[76:79], v[132:135], v[218:221], v[76:79]
	v_mfma_f32_16x16x32_bf16 v[76:79], v[128:131], v[214:217], v[76:79]
	s_setprio 0
	s_setprio 1
	v_mfma_f32_16x16x32_bf16 v[116:119], v[144:147], v[180:183], v[116:119]
	v_mfma_f32_16x16x32_bf16 v[116:119], v[148:151], v[194:197], v[116:119]
	v_mfma_f32_16x16x32_bf16 v[112:115], v[176:179], v[194:197], v[112:115]
	v_mfma_f32_16x16x32_bf16 v[112:115], v[172:175], v[180:183], v[112:115]
	v_mfma_f32_16x16x32_bf16 v[96:99], v[172:175], v[198:201], v[96:99]
	v_mfma_f32_16x16x32_bf16 v[96:99], v[176:179], v[202:205], v[96:99]
	v_mfma_f32_16x16x32_bf16 v[100:103], v[148:151], v[202:205], v[100:103]
	v_mfma_f32_16x16x32_bf16 v[100:103], v[144:147], v[198:201], v[100:103]
	v_mfma_f32_16x16x32_bf16 v[84:87], v[144:147], v[206:209], v[84:87]
	v_mfma_f32_16x16x32_bf16 v[84:87], v[148:151], v[210:213], v[84:87]
	v_mfma_f32_16x16x32_bf16 v[80:83], v[176:179], v[210:213], v[80:83]
	v_mfma_f32_16x16x32_bf16 v[80:83], v[172:175], v[206:209], v[80:83]
	v_mfma_f32_16x16x32_bf16 v[64:67], v[172:175], v[214:217], v[64:67]
	v_mfma_f32_16x16x32_bf16 v[64:67], v[176:179], v[218:221], v[64:67]
	v_mfma_f32_16x16x32_bf16 v[68:71], v[148:151], v[218:221], v[68:71]
	v_mfma_f32_16x16x32_bf16 v[68:71], v[144:147], v[214:217], v[68:71]
	s_barrier
	s_setprio 0
	s_add_i32 s54, s82, s65
	v_lshl_add_u64 v[222:223], v[222:223], 0, s[28:29]
	s_mov_b32 m0, s54
	s_nop 0
	global_load_lds_dwordx4 v[222:223], off
	s_add_i32 m0, s54, 0x2000
	s_add_u32 s54, s58, 0xb0080
	v_lshl_add_u64 v[222:223], v[224:225], 0, s[28:29]
	s_addc_u32 s55, s59, 0
	s_add_i32 s58, s83, s65
	global_load_lds_dwordx4 v[222:223], off
	v_lshl_add_u64 v[222:223], s[54:55], 0, v[154:155]
	s_mov_b32 m0, s58
	s_nop 0
	global_load_lds_dwordx4 v[222:223], off
	v_lshl_add_u64 v[222:223], s[54:55], 0, v[162:163]
	s_add_i32 m0, s58, 0x2000
	s_nop 0
	global_load_lds_dwordx4 v[222:223], off
	v_lshl_add_u64 v[222:223], v[226:227], 0, s[28:29]
	s_mov_b32 m0, s3
	s_nop 0
	global_load_lds_dwordx4 v[222:223], off
	v_lshl_add_u64 v[222:223], v[228:229], 0, s[28:29]
	s_mov_b32 m0, s71
	s_nop 0
	global_load_lds_dwordx4 v[222:223], off
	ds_read_b128 v[180:183], v191 offset:49152
	v_xor_b32_e32 v253, 64, v191
	ds_read_b128 v[194:197], v253 offset:49152
	ds_read_b128 v[198:201], v191 offset:51200
	ds_read_b128 v[202:205], v253 offset:51200
	ds_read_b128 v[206:209], v191 offset:53248
	ds_read_b128 v[210:213], v253 offset:53248
	ds_read_b128 v[214:217], v191 offset:55296
	ds_read_b128 v[218:221], v253 offset:55296
	s_waitcnt vmcnt(8)
	s_waitcnt lgkmcnt(0)
	s_setprio 1
	s_barrier
	v_mfma_f32_16x16x32_bf16 v[60:63], v[128:131], v[180:183], v[60:63]
	v_mfma_f32_16x16x32_bf16 v[60:63], v[132:135], v[194:197], v[60:63]
	v_mfma_f32_16x16x32_bf16 v[56:59], v[140:143], v[194:197], v[56:59]
	v_mfma_f32_16x16x32_bf16 v[56:59], v[136:139], v[180:183], v[56:59]
	v_mfma_f32_16x16x32_bf16 v[40:43], v[136:139], v[198:201], v[40:43]
	v_mfma_f32_16x16x32_bf16 v[40:43], v[140:143], v[202:205], v[40:43]
	v_mfma_f32_16x16x32_bf16 v[44:47], v[132:135], v[202:205], v[44:47]
	v_mfma_f32_16x16x32_bf16 v[44:47], v[128:131], v[198:201], v[44:47]
	v_mfma_f32_16x16x32_bf16 v[28:31], v[128:131], v[206:209], v[28:31]
	v_mfma_f32_16x16x32_bf16 v[28:31], v[132:135], v[210:213], v[28:31]
	v_mfma_f32_16x16x32_bf16 v[24:27], v[140:143], v[210:213], v[24:27]
	v_mfma_f32_16x16x32_bf16 v[24:27], v[136:139], v[206:209], v[24:27]
	v_mfma_f32_16x16x32_bf16 v[8:11], v[136:139], v[214:217], v[8:11]
	v_mfma_f32_16x16x32_bf16 v[8:11], v[140:143], v[218:221], v[8:11]
	v_mfma_f32_16x16x32_bf16 v[12:15], v[132:135], v[218:221], v[12:15]
	v_mfma_f32_16x16x32_bf16 v[12:15], v[128:131], v[214:217], v[12:15]
	s_setprio 0
	s_setprio 1
	v_mfma_f32_16x16x32_bf16 v[52:55], v[144:147], v[180:183], v[52:55]
	v_mfma_f32_16x16x32_bf16 v[52:55], v[148:151], v[194:197], v[52:55]
	v_mfma_f32_16x16x32_bf16 v[48:51], v[176:179], v[194:197], v[48:51]
	v_mfma_f32_16x16x32_bf16 v[48:51], v[172:175], v[180:183], v[48:51]
	v_mfma_f32_16x16x32_bf16 v[32:35], v[172:175], v[198:201], v[32:35]
	v_mfma_f32_16x16x32_bf16 v[32:35], v[176:179], v[202:205], v[32:35]
	v_mfma_f32_16x16x32_bf16 v[36:39], v[148:151], v[202:205], v[36:39]
	v_mfma_f32_16x16x32_bf16 v[36:39], v[144:147], v[198:201], v[36:39]
	v_mfma_f32_16x16x32_bf16 v[20:23], v[144:147], v[206:209], v[20:23]
	v_mfma_f32_16x16x32_bf16 v[20:23], v[148:151], v[210:213], v[20:23]
	v_mfma_f32_16x16x32_bf16 v[16:19], v[176:179], v[210:213], v[16:19]
	v_mfma_f32_16x16x32_bf16 v[16:19], v[172:175], v[206:209], v[16:19]
	v_mfma_f32_16x16x32_bf16 v[0:3], v[172:175], v[214:217], v[0:3]
	v_mfma_f32_16x16x32_bf16 v[0:3], v[176:179], v[218:221], v[0:3]
	v_mfma_f32_16x16x32_bf16 v[4:7], v[148:151], v[218:221], v[4:7]
	v_mfma_f32_16x16x32_bf16 v[4:7], v[144:147], v[214:217], v[4:7]
	s_barrier
	s_setprio 0
	s_add_i32 s81, s81, 2
	s_add_u32 s79, s79, 0x100
	s_addc_u32 s80, s80, 0
	s_cmp_gt_u32 s81, 41
	s_mov_b64 s[54:55], s[56:57]
.LBB0_610:
	ds_read_b128 v[128:131], v189
	v_xor_b32_e32 v253, 64, v189
	ds_read_b128 v[132:135], v253
	ds_read_b128 v[136:139], v189 offset:2048
	ds_read_b128 v[140:143], v253 offset:2048
	ds_read_b128 v[144:147], v190
	v_xor_b32_e32 v253, 64, v190
	ds_read_b128 v[148:151], v253
	ds_read_b128 v[172:175], v190 offset:2048
	ds_read_b128 v[176:179], v253 offset:2048
	s_add_u32 s56, s54, 0x100
	s_addc_u32 s57, s55, 0
	s_cmp_eq_u32 s81, 40
	s_cselect_b32 s61, s17, s57
	s_cselect_b32 s60, s16, s56
	s_cselect_b32 s59, s53, s80
	s_cselect_b32 s58, s52, s79
	v_lshl_add_u64 v[222:223], s[54:55], 0, v[166:167]
	s_add_i32 m0, s66, 0xc000
	s_nop 0
	global_load_lds_dwordx4 v[222:223], off
	v_lshl_add_u64 v[222:223], s[54:55], 0, v[164:165]
	s_add_i32 m0, s66, 0xe000
	s_nop 0
	global_load_lds_dwordx4 v[222:223], off
	ds_read_b128 v[180:183], v191
	v_xor_b32_e32 v253, 64, v191
	ds_read_b128 v[194:197], v253
	ds_read_b128 v[198:201], v191 offset:2048
	ds_read_b128 v[202:205], v253 offset:2048
	ds_read_b128 v[206:209], v191 offset:4096
	ds_read_b128 v[210:213], v253 offset:4096
	ds_read_b128 v[214:217], v191 offset:6144
	ds_read_b128 v[218:221], v253 offset:6144
	s_waitcnt vmcnt(8)
	s_waitcnt lgkmcnt(0)
	s_setprio 1
	s_barrier
	v_mfma_f32_16x16x32_bf16 v[124:127], v[128:131], v[180:183], v[124:127]
	v_mfma_f32_16x16x32_bf16 v[124:127], v[132:135], v[194:197], v[124:127]
	v_mfma_f32_16x16x32_bf16 v[120:123], v[140:143], v[194:197], v[120:123]
	v_mfma_f32_16x16x32_bf16 v[120:123], v[136:139], v[180:183], v[120:123]
	v_mfma_f32_16x16x32_bf16 v[104:107], v[136:139], v[198:201], v[104:107]
	v_mfma_f32_16x16x32_bf16 v[104:107], v[140:143], v[202:205], v[104:107]
	v_mfma_f32_16x16x32_bf16 v[108:111], v[132:135], v[202:205], v[108:111]
	v_mfma_f32_16x16x32_bf16 v[108:111], v[128:131], v[198:201], v[108:111]
	v_mfma_f32_16x16x32_bf16 v[92:95], v[128:131], v[206:209], v[92:95]
	v_mfma_f32_16x16x32_bf16 v[92:95], v[132:135], v[210:213], v[92:95]
	v_mfma_f32_16x16x32_bf16 v[88:91], v[140:143], v[210:213], v[88:91]
	v_mfma_f32_16x16x32_bf16 v[88:91], v[136:139], v[206:209], v[88:91]
	v_mfma_f32_16x16x32_bf16 v[72:75], v[136:139], v[214:217], v[72:75]
	v_mfma_f32_16x16x32_bf16 v[72:75], v[140:143], v[218:221], v[72:75]
	v_mfma_f32_16x16x32_bf16 v[76:79], v[132:135], v[218:221], v[76:79]
	v_mfma_f32_16x16x32_bf16 v[76:79], v[128:131], v[214:217], v[76:79]
	s_setprio 0
	s_setprio 1
	v_mfma_f32_16x16x32_bf16 v[116:119], v[144:147], v[180:183], v[116:119]
	v_mfma_f32_16x16x32_bf16 v[116:119], v[148:151], v[194:197], v[116:119]
	v_mfma_f32_16x16x32_bf16 v[112:115], v[176:179], v[194:197], v[112:115]
	v_mfma_f32_16x16x32_bf16 v[112:115], v[172:175], v[180:183], v[112:115]
	v_mfma_f32_16x16x32_bf16 v[96:99], v[172:175], v[198:201], v[96:99]
	v_mfma_f32_16x16x32_bf16 v[96:99], v[176:179], v[202:205], v[96:99]
	v_mfma_f32_16x16x32_bf16 v[100:103], v[148:151], v[202:205], v[100:103]
	v_mfma_f32_16x16x32_bf16 v[100:103], v[144:147], v[198:201], v[100:103]
	v_mfma_f32_16x16x32_bf16 v[84:87], v[144:147], v[206:209], v[84:87]
	v_mfma_f32_16x16x32_bf16 v[84:87], v[148:151], v[210:213], v[84:87]
	v_mfma_f32_16x16x32_bf16 v[80:83], v[176:179], v[210:213], v[80:83]
	v_mfma_f32_16x16x32_bf16 v[80:83], v[172:175], v[206:209], v[80:83]
	v_mfma_f32_16x16x32_bf16 v[64:67], v[172:175], v[214:217], v[64:67]
	v_mfma_f32_16x16x32_bf16 v[64:67], v[176:179], v[218:221], v[64:67]
	v_mfma_f32_16x16x32_bf16 v[68:71], v[148:151], v[218:221], v[68:71]
	v_mfma_f32_16x16x32_bf16 v[68:71], v[144:147], v[214:217], v[68:71]
	s_barrier
	s_setprio 0
	s_add_i32 s54, s75, s65
	v_lshl_add_u64 v[222:223], s[58:59], 0, v[154:155]
	s_mov_b32 m0, s54
	s_nop 0
	global_load_lds_dwordx4 v[222:223], off
	s_add_i32 m0, s54, 0x2000
	s_add_u32 s54, s58, 0xb0000
	v_lshl_add_u64 v[224:225], s[58:59], 0, v[162:163]
	s_addc_u32 s55, s59, 0
	s_add_i32 s82, s76, s65
	global_load_lds_dwordx4 v[224:225], off
	v_lshl_add_u64 v[226:227], s[54:55], 0, v[154:155]
	s_mov_b32 m0, s82
	v_lshl_add_u64 v[228:229], s[60:61], 0, v[160:161]
	global_load_lds_dwordx4 v[226:227], off
	v_lshl_add_u64 v[226:227], s[54:55], 0, v[162:163]
	s_add_i32 m0, s82, 0x2000
	s_nop 0
	global_load_lds_dwordx4 v[226:227], off
	v_lshl_add_u64 v[226:227], s[60:61], 0, v[152:153]
	s_mov_b32 m0, s66
	s_nop 0
	global_load_lds_dwordx4 v[226:227], off
	s_mov_b32 m0, s67
	s_nop 0
	global_load_lds_dwordx4 v[228:229], off
	ds_read_b128 v[180:183], v191 offset:16384
	v_xor_b32_e32 v253, 64, v191
	ds_read_b128 v[194:197], v253 offset:16384
	ds_read_b128 v[198:201], v191 offset:18432
	ds_read_b128 v[202:205], v253 offset:18432
	ds_read_b128 v[206:209], v191 offset:20480
	ds_read_b128 v[210:213], v253 offset:20480
	ds_read_b128 v[214:217], v191 offset:22528
	ds_read_b128 v[218:221], v253 offset:22528
	s_waitcnt vmcnt(8)
	s_waitcnt lgkmcnt(0)
	s_setprio 1
	s_barrier
	v_mfma_f32_16x16x32_bf16 v[60:63], v[128:131], v[180:183], v[60:63]
	v_mfma_f32_16x16x32_bf16 v[60:63], v[132:135], v[194:197], v[60:63]
	v_mfma_f32_16x16x32_bf16 v[56:59], v[140:143], v[194:197], v[56:59]
	v_mfma_f32_16x16x32_bf16 v[56:59], v[136:139], v[180:183], v[56:59]
	v_mfma_f32_16x16x32_bf16 v[40:43], v[136:139], v[198:201], v[40:43]
	v_mfma_f32_16x16x32_bf16 v[40:43], v[140:143], v[202:205], v[40:43]
	v_mfma_f32_16x16x32_bf16 v[44:47], v[132:135], v[202:205], v[44:47]
	v_mfma_f32_16x16x32_bf16 v[44:47], v[128:131], v[198:201], v[44:47]
	v_mfma_f32_16x16x32_bf16 v[28:31], v[128:131], v[206:209], v[28:31]
	v_mfma_f32_16x16x32_bf16 v[28:31], v[132:135], v[210:213], v[28:31]
	v_mfma_f32_16x16x32_bf16 v[24:27], v[140:143], v[210:213], v[24:27]
	v_mfma_f32_16x16x32_bf16 v[24:27], v[136:139], v[206:209], v[24:27]
	v_mfma_f32_16x16x32_bf16 v[8:11], v[136:139], v[214:217], v[8:11]
	v_mfma_f32_16x16x32_bf16 v[8:11], v[140:143], v[218:221], v[8:11]
	v_mfma_f32_16x16x32_bf16 v[12:15], v[132:135], v[218:221], v[12:15]
	v_mfma_f32_16x16x32_bf16 v[12:15], v[128:131], v[214:217], v[12:15]
	s_setprio 0
	s_setprio 1
	v_mfma_f32_16x16x32_bf16 v[52:55], v[144:147], v[180:183], v[52:55]
	v_mfma_f32_16x16x32_bf16 v[52:55], v[148:151], v[194:197], v[52:55]
	v_mfma_f32_16x16x32_bf16 v[48:51], v[176:179], v[194:197], v[48:51]
	v_mfma_f32_16x16x32_bf16 v[48:51], v[172:175], v[180:183], v[48:51]
	v_mfma_f32_16x16x32_bf16 v[32:35], v[172:175], v[198:201], v[32:35]
	v_mfma_f32_16x16x32_bf16 v[32:35], v[176:179], v[202:205], v[32:35]
	v_mfma_f32_16x16x32_bf16 v[36:39], v[148:151], v[202:205], v[36:39]
	v_mfma_f32_16x16x32_bf16 v[36:39], v[144:147], v[198:201], v[36:39]
	v_mfma_f32_16x16x32_bf16 v[20:23], v[144:147], v[206:209], v[20:23]
	v_mfma_f32_16x16x32_bf16 v[20:23], v[148:151], v[210:213], v[20:23]
	v_mfma_f32_16x16x32_bf16 v[16:19], v[176:179], v[210:213], v[16:19]
	v_mfma_f32_16x16x32_bf16 v[16:19], v[172:175], v[206:209], v[16:19]
	v_mfma_f32_16x16x32_bf16 v[0:3], v[172:175], v[214:217], v[0:3]
	v_mfma_f32_16x16x32_bf16 v[0:3], v[176:179], v[218:221], v[0:3]
	v_mfma_f32_16x16x32_bf16 v[4:7], v[148:151], v[218:221], v[4:7]
	v_mfma_f32_16x16x32_bf16 v[4:7], v[144:147], v[214:217], v[4:7]
	s_barrier
	s_setprio 0
	s_add_i32 s82, 0, 0x18000
	s_add_i32 s83, 0, 0x1c000
	v_add_u32_e32 v140, s82, v186
	v_add_u32_e32 v176, s83, v186
	s_add_u32 s54, s60, 0xb0000
	s_addc_u32 s55, s61, 0
	s_mov_b32 m0, s68
	v_lshl_add_u64 v[230:231], s[54:55], 0, v[152:153]
	global_load_lds_dwordx4 v[230:231], off
	v_lshl_add_u64 v[230:231], s[54:55], 0, v[160:161]
	s_mov_b32 m0, s69
	s_nop 0
	global_load_lds_dwordx4 v[230:231], off
	ds_read_b128 v[128:131], v140
	v_xor_b32_e32 v253, 64, v140
	ds_read_b128 v[132:135], v253
	ds_read_b128 v[136:139], v140 offset:2048
	ds_read_b128 v[140:143], v253 offset:2048
	ds_read_b128 v[144:147], v176
	v_xor_b32_e32 v253, 64, v176
	ds_read_b128 v[148:151], v253
	ds_read_b128 v[172:175], v176 offset:2048
	ds_read_b128 v[176:179], v253 offset:2048
	ds_read_b128 v[180:183], v191 offset:32768
	v_xor_b32_e32 v253, 64, v191
	ds_read_b128 v[194:197], v253 offset:32768
	ds_read_b128 v[198:201], v191 offset:34816
	ds_read_b128 v[202:205], v253 offset:34816
	ds_read_b128 v[206:209], v191 offset:36864
	ds_read_b128 v[210:213], v253 offset:36864
	ds_read_b128 v[214:217], v191 offset:38912
	ds_read_b128 v[218:221], v253 offset:38912
	s_waitcnt vmcnt(8)
	s_waitcnt lgkmcnt(0)
	s_setprio 1
	s_barrier
	v_mfma_f32_16x16x32_bf16 v[124:127], v[128:131], v[180:183], v[124:127]
	v_mfma_f32_16x16x32_bf16 v[124:127], v[132:135], v[194:197], v[124:127]
	v_mfma_f32_16x16x32_bf16 v[120:123], v[140:143], v[194:197], v[120:123]
	v_mfma_f32_16x16x32_bf16 v[120:123], v[136:139], v[180:183], v[120:123]
	v_mfma_f32_16x16x32_bf16 v[104:107], v[136:139], v[198:201], v[104:107]
	v_mfma_f32_16x16x32_bf16 v[104:107], v[140:143], v[202:205], v[104:107]
	v_mfma_f32_16x16x32_bf16 v[108:111], v[132:135], v[202:205], v[108:111]
	v_mfma_f32_16x16x32_bf16 v[108:111], v[128:131], v[198:201], v[108:111]
	v_mfma_f32_16x16x32_bf16 v[92:95], v[128:131], v[206:209], v[92:95]
	v_mfma_f32_16x16x32_bf16 v[92:95], v[132:135], v[210:213], v[92:95]
	v_mfma_f32_16x16x32_bf16 v[88:91], v[140:143], v[210:213], v[88:91]
	v_mfma_f32_16x16x32_bf16 v[88:91], v[136:139], v[206:209], v[88:91]
	v_mfma_f32_16x16x32_bf16 v[72:75], v[136:139], v[214:217], v[72:75]
	v_mfma_f32_16x16x32_bf16 v[72:75], v[140:143], v[218:221], v[72:75]
	v_mfma_f32_16x16x32_bf16 v[76:79], v[132:135], v[218:221], v[76:79]
	v_mfma_f32_16x16x32_bf16 v[76:79], v[128:131], v[214:217], v[76:79]
	s_setprio 0
	s_setprio 1
	v_mfma_f32_16x16x32_bf16 v[116:119], v[144:147], v[180:183], v[116:119]
	v_mfma_f32_16x16x32_bf16 v[116:119], v[148:151], v[194:197], v[116:119]
	v_mfma_f32_16x16x32_bf16 v[112:115], v[176:179], v[194:197], v[112:115]
	v_mfma_f32_16x16x32_bf16 v[112:115], v[172:175], v[180:183], v[112:115]
	v_mfma_f32_16x16x32_bf16 v[96:99], v[172:175], v[198:201], v[96:99]
	v_mfma_f32_16x16x32_bf16 v[96:99], v[176:179], v[202:205], v[96:99]
	v_mfma_f32_16x16x32_bf16 v[100:103], v[148:151], v[202:205], v[100:103]
	v_mfma_f32_16x16x32_bf16 v[100:103], v[144:147], v[198:201], v[100:103]
	v_mfma_f32_16x16x32_bf16 v[84:87], v[144:147], v[206:209], v[84:87]
	v_mfma_f32_16x16x32_bf16 v[84:87], v[148:151], v[210:213], v[84:87]
	v_mfma_f32_16x16x32_bf16 v[80:83], v[176:179], v[210:213], v[80:83]
	v_mfma_f32_16x16x32_bf16 v[80:83], v[172:175], v[206:209], v[80:83]
	v_mfma_f32_16x16x32_bf16 v[64:67], v[172:175], v[214:217], v[64:67]
	v_mfma_f32_16x16x32_bf16 v[64:67], v[176:179], v[218:221], v[64:67]
	v_mfma_f32_16x16x32_bf16 v[68:71], v[148:151], v[218:221], v[68:71]
	v_mfma_f32_16x16x32_bf16 v[68:71], v[144:147], v[214:217], v[68:71]
	s_barrier
	s_setprio 0
	s_add_i32 s54, s82, s65
	v_lshl_add_u64 v[222:223], v[222:223], 0, s[28:29]
	s_mov_b32 m0, s54
	s_nop 0
	global_load_lds_dwordx4 v[222:223], off
	s_add_i32 m0, s54, 0x2000
	s_add_u32 s54, s58, 0xb0080
	v_lshl_add_u64 v[222:223], v[224:225], 0, s[28:29]
	s_addc_u32 s55, s59, 0
	s_add_i32 s58, s83, s65
	global_load_lds_dwordx4 v[222:223], off
	v_lshl_add_u64 v[222:223], s[54:55], 0, v[154:155]
	s_mov_b32 m0, s58
	s_nop 0
	global_load_lds_dwordx4 v[222:223], off
	v_lshl_add_u64 v[222:223], s[54:55], 0, v[162:163]
	s_add_i32 m0, s58, 0x2000
	s_nop 0
	global_load_lds_dwordx4 v[222:223], off
	v_lshl_add_u64 v[222:223], v[226:227], 0, s[28:29]
	s_mov_b32 m0, s3
	s_nop 0
	global_load_lds_dwordx4 v[222:223], off
	v_lshl_add_u64 v[222:223], v[228:229], 0, s[28:29]
	s_mov_b32 m0, s71
	s_nop 0
	global_load_lds_dwordx4 v[222:223], off
	ds_read_b128 v[180:183], v191 offset:49152
	v_xor_b32_e32 v253, 64, v191
	ds_read_b128 v[194:197], v253 offset:49152
	ds_read_b128 v[198:201], v191 offset:51200
	ds_read_b128 v[202:205], v253 offset:51200
	ds_read_b128 v[206:209], v191 offset:53248
	ds_read_b128 v[210:213], v253 offset:53248
	ds_read_b128 v[214:217], v191 offset:55296
	ds_read_b128 v[218:221], v253 offset:55296
	s_waitcnt vmcnt(8)
	s_waitcnt lgkmcnt(0)
	s_setprio 1
	s_barrier
	v_mfma_f32_16x16x32_bf16 v[60:63], v[128:131], v[180:183], v[60:63]
	v_mfma_f32_16x16x32_bf16 v[60:63], v[132:135], v[194:197], v[60:63]
	v_mfma_f32_16x16x32_bf16 v[56:59], v[140:143], v[194:197], v[56:59]
	v_mfma_f32_16x16x32_bf16 v[56:59], v[136:139], v[180:183], v[56:59]
	v_mfma_f32_16x16x32_bf16 v[40:43], v[136:139], v[198:201], v[40:43]
	v_mfma_f32_16x16x32_bf16 v[40:43], v[140:143], v[202:205], v[40:43]
	v_mfma_f32_16x16x32_bf16 v[44:47], v[132:135], v[202:205], v[44:47]
	v_mfma_f32_16x16x32_bf16 v[44:47], v[128:131], v[198:201], v[44:47]
	v_mfma_f32_16x16x32_bf16 v[28:31], v[128:131], v[206:209], v[28:31]
	v_mfma_f32_16x16x32_bf16 v[28:31], v[132:135], v[210:213], v[28:31]
	v_mfma_f32_16x16x32_bf16 v[24:27], v[140:143], v[210:213], v[24:27]
	v_mfma_f32_16x16x32_bf16 v[24:27], v[136:139], v[206:209], v[24:27]
	v_mfma_f32_16x16x32_bf16 v[8:11], v[136:139], v[214:217], v[8:11]
	v_mfma_f32_16x16x32_bf16 v[8:11], v[140:143], v[218:221], v[8:11]
	v_mfma_f32_16x16x32_bf16 v[12:15], v[132:135], v[218:221], v[12:15]
	v_mfma_f32_16x16x32_bf16 v[12:15], v[128:131], v[214:217], v[12:15]
	s_setprio 0
	s_setprio 1
	v_mfma_f32_16x16x32_bf16 v[52:55], v[144:147], v[180:183], v[52:55]
	v_mfma_f32_16x16x32_bf16 v[52:55], v[148:151], v[194:197], v[52:55]
	v_mfma_f32_16x16x32_bf16 v[48:51], v[176:179], v[194:197], v[48:51]
	v_mfma_f32_16x16x32_bf16 v[48:51], v[172:175], v[180:183], v[48:51]
	v_mfma_f32_16x16x32_bf16 v[32:35], v[172:175], v[198:201], v[32:35]
	v_mfma_f32_16x16x32_bf16 v[32:35], v[176:179], v[202:205], v[32:35]
	v_mfma_f32_16x16x32_bf16 v[36:39], v[148:151], v[202:205], v[36:39]
	v_mfma_f32_16x16x32_bf16 v[36:39], v[144:147], v[198:201], v[36:39]
	v_mfma_f32_16x16x32_bf16 v[20:23], v[144:147], v[206:209], v[20:23]
	v_mfma_f32_16x16x32_bf16 v[20:23], v[148:151], v[210:213], v[20:23]
	v_mfma_f32_16x16x32_bf16 v[16:19], v[176:179], v[210:213], v[16:19]
	v_mfma_f32_16x16x32_bf16 v[16:19], v[172:175], v[206:209], v[16:19]
	v_mfma_f32_16x16x32_bf16 v[0:3], v[172:175], v[214:217], v[0:3]
	v_mfma_f32_16x16x32_bf16 v[0:3], v[176:179], v[218:221], v[0:3]
	v_mfma_f32_16x16x32_bf16 v[4:7], v[148:151], v[218:221], v[4:7]
	v_mfma_f32_16x16x32_bf16 v[4:7], v[144:147], v[214:217], v[4:7]
	s_barrier
	s_setprio 0
	s_add_i32 s81, s81, 2
	s_add_u32 s79, s79, 0x100
	s_addc_u32 s80, s80, 0
	s_cmp_gt_u32 s81, 41
	s_mov_b64 s[54:55], s[56:57]
	s_cbranch_scc0 .LBB0_610
	s_and_b64 vcc, exec, s[30:31]
	s_cbranch_vccz .LBB0_613
	s_barrier

.LBB0_873:
	s_ashr_i32 s49, s48, 31
	s_lshl_b64 s[50:51], s[48:49], 19
	s_add_u32 s50, s35, s50
	s_addc_u32 s51, s60, s51
	s_and_b64 s[52:53], s[10:11], exec
	s_cselect_b32 s49, s51, s59
	s_cselect_b32 s80, s50, s58
	s_ashr_i32 s47, s46, 31
	s_lshl_b64 s[52:53], s[46:47], 19
	s_add_u32 s52, s61, s52
	s_addc_u32 s53, s62, s53
	s_and_b64 s[82:83], s[10:11], exec
	s_cselect_b32 s81, s53, s57
	s_cselect_b32 s82, s52, s56
	s_lshl_b32 s47, s54, 8
	v_add_u32_e32 v0, s47, v151
	s_add_u32 s83, s56, 0x100
	v_ashrrev_i32_e32 v1, 31, v0
	s_addc_u32 s84, s57, 0
	v_lshl_add_u64 v[144:145], v[0:1], 4, s[20:21]
	s_add_u32 s54, s58, 0x40080
	s_addc_u32 s55, s59, 0
	s_mov_b32 s85, -2
	s_mov_b64 s[56:57], 0
	s_cmp_eq_u32 s68, 1
	s_cbranch_scc1 .Lfa_8
	v_add_u32_e32 v146, s73, v149
	ds_read_b128 v[162:165], v146
	v_xor_b32_e32 v253, 64, v146
	ds_read_b128 v[166:169], v253
	ds_read_b128 v[170:173], v146 offset:2048
	ds_read_b128 v[174:177], v253 offset:2048
	v_add_u32_e32 v146, s74, v149
	ds_read_b128 v[178:181], v146
	v_xor_b32_e32 v253, 64, v146
	ds_read_b128 v[186:189], v253
	ds_read_b128 v[190:193], v146 offset:2048
	ds_read_b128 v[194:197], v253 offset:2048
	s_add_u32 s58, s54, 0xfffc0080
	s_addc_u32 s59, s55, -1
	s_and_b64 s[56:57], s[56:57], exec
	s_cselect_b32 s59, s49, s59
	s_cselect_b32 s58, s80, s58
	s_cselect_b32 s57, s81, s84
	s_cselect_b32 s56, s82, s83
	v_lshl_add_u64 v[182:183], s[54:55], 0, v[138:139]
	s_add_i32 m0, s64, 0xc000
	ds_read_b128 v[198:201], v154
	v_xor_b32_e32 v253, 64, v154
	ds_read_b128 v[202:205], v253
	ds_read_b128 v[206:209], v154 offset:2048
	ds_read_b128 v[210:213], v253 offset:2048
	ds_read_b128 v[214:217], v154 offset:4096
	ds_read_b128 v[218:221], v253 offset:4096
	ds_read_b128 v[222:225], v154 offset:6144
	ds_read_b128 v[226:229], v253 offset:6144
	global_load_lds_dwordx4 v[182:183], off
	v_lshl_add_u64 v[182:183], s[54:55], 0, v[136:137]
	s_add_i32 m0, s64, 0xe000
	s_nop 0
	global_load_lds_dwordx4 v[182:183], off
	s_waitcnt vmcnt(24)
	s_waitcnt lgkmcnt(0)
	s_setprio 1
	s_barrier
	v_mfma_f32_16x16x32_bf16 v[124:127], v[162:165], v[198:201], 0
	v_mfma_f32_16x16x32_bf16 v[120:123], v[170:173], v[198:201], 0
	v_mfma_f32_16x16x32_bf16 v[112:115], v[162:165], v[206:209], 0
	v_mfma_f32_16x16x32_bf16 v[104:107], v[170:173], v[206:209], 0
	v_mfma_f32_16x16x32_bf16 v[96:99], v[162:165], v[214:217], 0
	v_mfma_f32_16x16x32_bf16 v[88:91], v[170:173], v[214:217], 0
	v_mfma_f32_16x16x32_bf16 v[80:83], v[162:165], v[222:225], 0
	v_mfma_f32_16x16x32_bf16 v[72:75], v[170:173], v[222:225], 0
	v_mfma_f32_16x16x32_bf16 v[124:127], v[166:169], v[202:205], v[124:127]
	v_mfma_f32_16x16x32_bf16 v[120:123], v[174:177], v[202:205], v[120:123]
	v_mfma_f32_16x16x32_bf16 v[112:115], v[166:169], v[210:213], v[112:115]
	v_mfma_f32_16x16x32_bf16 v[104:107], v[174:177], v[210:213], v[104:107]
	v_mfma_f32_16x16x32_bf16 v[96:99], v[166:169], v[218:221], v[96:99]
	v_mfma_f32_16x16x32_bf16 v[88:91], v[174:177], v[218:221], v[88:91]
	v_mfma_f32_16x16x32_bf16 v[80:83], v[166:169], v[226:229], v[80:83]
	v_mfma_f32_16x16x32_bf16 v[72:75], v[174:177], v[226:229], v[72:75]
	s_setprio 0
	s_setprio 1
	v_mfma_f32_16x16x32_bf16 v[116:119], v[178:181], v[198:201], 0
	v_mfma_f32_16x16x32_bf16 v[108:111], v[190:193], v[198:201], 0
	v_mfma_f32_16x16x32_bf16 v[100:103], v[178:181], v[206:209], 0
	v_mfma_f32_16x16x32_bf16 v[92:95], v[190:193], v[206:209], 0
	v_mfma_f32_16x16x32_bf16 v[84:87], v[178:181], v[214:217], 0
	v_mfma_f32_16x16x32_bf16 v[76:79], v[190:193], v[214:217], 0
	v_mfma_f32_16x16x32_bf16 v[68:71], v[178:181], v[222:225], 0
	v_mfma_f32_16x16x32_bf16 v[64:67], v[190:193], v[222:225], 0
	v_mfma_f32_16x16x32_bf16 v[116:119], v[186:189], v[202:205], v[116:119]
	v_mfma_f32_16x16x32_bf16 v[108:111], v[194:197], v[202:205], v[108:111]
	v_mfma_f32_16x16x32_bf16 v[100:103], v[186:189], v[210:213], v[100:103]
	v_mfma_f32_16x16x32_bf16 v[92:95], v[194:197], v[210:213], v[92:95]
	v_mfma_f32_16x16x32_bf16 v[84:87], v[186:189], v[218:221], v[84:87]
	v_mfma_f32_16x16x32_bf16 v[76:79], v[194:197], v[218:221], v[76:79]
	v_mfma_f32_16x16x32_bf16 v[68:71], v[186:189], v[226:229], v[68:71]
	v_mfma_f32_16x16x32_bf16 v[64:67], v[194:197], v[226:229], v[64:67]
	s_barrier
	s_setprio 0
	s_add_i32 s86, s73, s63
	v_lshl_add_u64 v[182:183], s[56:57], 0, v[130:131]
	s_mov_b32 m0, s86
	s_nop 0
	global_load_lds_dwordx4 v[182:183], off
	s_add_i32 m0, s86, 0x2000
	s_add_u32 s86, s56, 0x40000
	v_lshl_add_u64 v[230:231], s[56:57], 0, v[134:135]
	s_addc_u32 s87, s57, 0
	s_add_i32 s88, s74, s63
	global_load_lds_dwordx4 v[230:231], off
	v_lshl_add_u64 v[232:233], s[86:87], 0, v[130:131]
	s_mov_b32 m0, s88
	v_lshl_add_u64 v[234:235], s[58:59], 0, v[132:133]
	global_load_lds_dwordx4 v[232:233], off
	v_lshl_add_u64 v[232:233], s[86:87], 0, v[134:135]
	s_add_i32 m0, s88, 0x2000
	s_nop 0
	global_load_lds_dwordx4 v[232:233], off
	v_lshl_add_u64 v[232:233], s[58:59], 0, v[128:129]
	s_mov_b32 m0, s64
	s_nop 0
	global_load_lds_dwordx4 v[232:233], off
	s_mov_b32 m0, s65
	s_nop 0
	global_load_lds_dwordx4 v[234:235], off
	ds_read_b128 v[198:201], v154 offset:16384
	v_xor_b32_e32 v253, 64, v154
	ds_read_b128 v[202:205], v253 offset:16384
	ds_read_b128 v[206:209], v154 offset:18432
	ds_read_b128 v[210:213], v253 offset:18432
	ds_read_b128 v[214:217], v154 offset:20480
	ds_read_b128 v[218:221], v253 offset:20480
	ds_read_b128 v[222:225], v154 offset:22528
	ds_read_b128 v[226:229], v253 offset:22528
	s_waitcnt vmcnt(24)
	s_waitcnt lgkmcnt(0)
	s_setprio 1
	s_barrier
	v_mfma_f32_16x16x32_bf16 v[60:63], v[162:165], v[198:201], 0
	v_mfma_f32_16x16x32_bf16 v[56:59], v[170:173], v[198:201], 0
	v_mfma_f32_16x16x32_bf16 v[48:51], v[162:165], v[206:209], 0
	v_mfma_f32_16x16x32_bf16 v[40:43], v[170:173], v[206:209], 0
	v_mfma_f32_16x16x32_bf16 v[32:35], v[162:165], v[214:217], 0
	v_mfma_f32_16x16x32_bf16 v[24:27], v[170:173], v[214:217], 0
	v_mfma_f32_16x16x32_bf16 v[16:19], v[162:165], v[222:225], 0
	v_mfma_f32_16x16x32_bf16 v[8:11], v[170:173], v[222:225], 0
	v_mfma_f32_16x16x32_bf16 v[60:63], v[166:169], v[202:205], v[60:63]
	v_mfma_f32_16x16x32_bf16 v[56:59], v[174:177], v[202:205], v[56:59]
	v_mfma_f32_16x16x32_bf16 v[48:51], v[166:169], v[210:213], v[48:51]
	v_mfma_f32_16x16x32_bf16 v[40:43], v[174:177], v[210:213], v[40:43]
	v_mfma_f32_16x16x32_bf16 v[32:35], v[166:169], v[218:221], v[32:35]
	v_mfma_f32_16x16x32_bf16 v[24:27], v[174:177], v[218:221], v[24:27]
	v_mfma_f32_16x16x32_bf16 v[16:19], v[166:169], v[226:229], v[16:19]
	v_mfma_f32_16x16x32_bf16 v[8:11], v[174:177], v[226:229], v[8:11]
	s_setprio 0
	s_setprio 1
	v_mfma_f32_16x16x32_bf16 v[52:55], v[178:181], v[198:201], 0
	v_mfma_f32_16x16x32_bf16 v[44:47], v[190:193], v[198:201], 0
	v_mfma_f32_16x16x32_bf16 v[36:39], v[178:181], v[206:209], 0
	v_mfma_f32_16x16x32_bf16 v[28:31], v[190:193], v[206:209], 0
	v_mfma_f32_16x16x32_bf16 v[20:23], v[178:181], v[214:217], 0
	v_mfma_f32_16x16x32_bf16 v[12:15], v[190:193], v[214:217], 0
	v_mfma_f32_16x16x32_bf16 v[4:7], v[178:181], v[222:225], 0
	v_mfma_f32_16x16x32_bf16 v[0:3], v[190:193], v[222:225], 0
	v_mfma_f32_16x16x32_bf16 v[52:55], v[186:189], v[202:205], v[52:55]
	v_mfma_f32_16x16x32_bf16 v[44:47], v[194:197], v[202:205], v[44:47]
	v_mfma_f32_16x16x32_bf16 v[36:39], v[186:189], v[210:213], v[36:39]
	v_mfma_f32_16x16x32_bf16 v[28:31], v[194:197], v[210:213], v[28:31]
	v_mfma_f32_16x16x32_bf16 v[20:23], v[186:189], v[218:221], v[20:23]
	v_mfma_f32_16x16x32_bf16 v[12:15], v[194:197], v[218:221], v[12:15]
	v_mfma_f32_16x16x32_bf16 v[4:7], v[186:189], v[226:229], v[4:7]
	v_mfma_f32_16x16x32_bf16 v[0:3], v[194:197], v[226:229], v[0:3]
	s_barrier
	s_setprio 0
	s_add_i32 s86, 0, 0x18000
	v_add_u32_e32 v146, s86, v149
	s_add_i32 s87, 0, 0x1c000
	ds_read_b128 v[162:165], v146
	v_xor_b32_e32 v253, 64, v146
	ds_read_b128 v[166:169], v253
	ds_read_b128 v[170:173], v146 offset:2048
	ds_read_b128 v[174:177], v253 offset:2048
	v_add_u32_e32 v146, s87, v149
	ds_read_b128 v[178:181], v146
	v_xor_b32_e32 v253, 64, v146
	ds_read_b128 v[186:189], v253
	ds_read_b128 v[190:193], v146 offset:2048
	ds_read_b128 v[194:197], v253 offset:2048
	s_add_u32 s58, s58, 0x40000
	s_addc_u32 s59, s59, 0
	s_mov_b32 m0, s66
	v_lshl_add_u64 v[236:237], s[58:59], 0, v[128:129]
	ds_read_b128 v[198:201], v154 offset:32768
	v_xor_b32_e32 v253, 64, v154
	ds_read_b128 v[202:205], v253 offset:32768
	ds_read_b128 v[206:209], v154 offset:34816
	ds_read_b128 v[210:213], v253 offset:34816
	ds_read_b128 v[214:217], v154 offset:36864
	ds_read_b128 v[218:221], v253 offset:36864
	ds_read_b128 v[222:225], v154 offset:38912
	ds_read_b128 v[226:229], v253 offset:38912
	global_load_lds_dwordx4 v[236:237], off
	v_lshl_add_u64 v[236:237], s[58:59], 0, v[132:133]
	s_mov_b32 m0, s67
	s_nop 0
	global_load_lds_dwordx4 v[236:237], off
	s_waitcnt vmcnt(8)
	s_waitcnt lgkmcnt(0)
	s_setprio 1
	s_barrier
	v_mfma_f32_16x16x32_bf16 v[124:127], v[162:165], v[198:201], v[124:127]
	v_mfma_f32_16x16x32_bf16 v[124:127], v[166:169], v[202:205], v[124:127]
	v_mfma_f32_16x16x32_bf16 v[120:123], v[174:177], v[202:205], v[120:123]
	v_mfma_f32_16x16x32_bf16 v[120:123], v[170:173], v[198:201], v[120:123]
	v_mfma_f32_16x16x32_bf16 v[104:107], v[170:173], v[206:209], v[104:107]
	v_mfma_f32_16x16x32_bf16 v[104:107], v[174:177], v[210:213], v[104:107]
	v_mfma_f32_16x16x32_bf16 v[112:115], v[166:169], v[210:213], v[112:115]
	v_mfma_f32_16x16x32_bf16 v[112:115], v[162:165], v[206:209], v[112:115]
	v_mfma_f32_16x16x32_bf16 v[96:99], v[162:165], v[214:217], v[96:99]
	v_mfma_f32_16x16x32_bf16 v[96:99], v[166:169], v[218:221], v[96:99]
	v_mfma_f32_16x16x32_bf16 v[88:91], v[174:177], v[218:221], v[88:91]
	v_mfma_f32_16x16x32_bf16 v[88:91], v[170:173], v[214:217], v[88:91]
	v_mfma_f32_16x16x32_bf16 v[72:75], v[170:173], v[222:225], v[72:75]
	v_mfma_f32_16x16x32_bf16 v[72:75], v[174:177], v[226:229], v[72:75]
	v_mfma_f32_16x16x32_bf16 v[80:83], v[166:169], v[226:229], v[80:83]
	v_mfma_f32_16x16x32_bf16 v[80:83], v[162:165], v[222:225], v[80:83]
	s_setprio 0
	s_setprio 1
	v_mfma_f32_16x16x32_bf16 v[116:119], v[178:181], v[198:201], v[116:119]
	v_mfma_f32_16x16x32_bf16 v[116:119], v[186:189], v[202:205], v[116:119]
	v_mfma_f32_16x16x32_bf16 v[108:111], v[194:197], v[202:205], v[108:111]
	v_mfma_f32_16x16x32_bf16 v[108:111], v[190:193], v[198:201], v[108:111]
	v_mfma_f32_16x16x32_bf16 v[92:95], v[190:193], v[206:209], v[92:95]
	v_mfma_f32_16x16x32_bf16 v[92:95], v[194:197], v[210:213], v[92:95]
	v_mfma_f32_16x16x32_bf16 v[100:103], v[186:189], v[210:213], v[100:103]
	v_mfma_f32_16x16x32_bf16 v[100:103], v[178:181], v[206:209], v[100:103]
	v_mfma_f32_16x16x32_bf16 v[84:87], v[178:181], v[214:217], v[84:87]
	v_mfma_f32_16x16x32_bf16 v[84:87], v[186:189], v[218:221], v[84:87]
	v_mfma_f32_16x16x32_bf16 v[76:79], v[194:197], v[218:221], v[76:79]
	v_mfma_f32_16x16x32_bf16 v[76:79], v[190:193], v[214:217], v[76:79]
	v_mfma_f32_16x16x32_bf16 v[64:67], v[190:193], v[222:225], v[64:67]
	v_mfma_f32_16x16x32_bf16 v[64:67], v[194:197], v[226:229], v[64:67]
	v_mfma_f32_16x16x32_bf16 v[68:71], v[186:189], v[226:229], v[68:71]
	v_mfma_f32_16x16x32_bf16 v[68:71], v[178:181], v[222:225], v[68:71]
	s_barrier
	s_setprio 0
	s_add_i32 s58, s86, s63
	v_lshl_add_u64 v[182:183], v[182:183], 0, s[22:23]
	s_mov_b32 m0, s58
	s_nop 0
	global_load_lds_dwordx4 v[182:183], off
	s_add_i32 m0, s58, 0x2000
	s_add_u32 s56, s56, 0x40080
	v_lshl_add_u64 v[182:183], v[230:231], 0, s[22:23]
	s_addc_u32 s57, s57, 0
	s_add_i32 s58, s87, s63
	global_load_lds_dwordx4 v[182:183], off
	v_lshl_add_u64 v[182:183], s[56:57], 0, v[130:131]
	s_mov_b32 m0, s58
	s_nop 0
	global_load_lds_dwordx4 v[182:183], off
	v_lshl_add_u64 v[182:183], s[56:57], 0, v[134:135]
	s_add_i32 m0, s58, 0x2000
	s_nop 0
	global_load_lds_dwordx4 v[182:183], off
	v_lshl_add_u64 v[182:183], v[232:233], 0, s[22:23]
	s_mov_b32 m0, s69
	s_nop 0
	global_load_lds_dwordx4 v[182:183], off
	v_lshl_add_u64 v[182:183], v[234:235], 0, s[22:23]
	s_mov_b32 m0, s70
	s_nop 0
	global_load_lds_dwordx4 v[182:183], off
	ds_read_b128 v[198:201], v154 offset:49152
	v_xor_b32_e32 v253, 64, v154
	ds_read_b128 v[202:205], v253 offset:49152
	ds_read_b128 v[206:209], v154 offset:51200
	ds_read_b128 v[210:213], v253 offset:51200
	ds_read_b128 v[214:217], v154 offset:53248
	ds_read_b128 v[218:221], v253 offset:53248
	ds_read_b128 v[222:225], v154 offset:55296
	ds_read_b128 v[226:229], v253 offset:55296
	s_waitcnt vmcnt(8)
	s_waitcnt lgkmcnt(0)
	s_setprio 1
	s_barrier
	v_mfma_f32_16x16x32_bf16 v[60:63], v[162:165], v[198:201], v[60:63]
	v_mfma_f32_16x16x32_bf16 v[60:63], v[166:169], v[202:205], v[60:63]
	v_mfma_f32_16x16x32_bf16 v[56:59], v[174:177], v[202:205], v[56:59]
	v_mfma_f32_16x16x32_bf16 v[56:59], v[170:173], v[198:201], v[56:59]
	v_mfma_f32_16x16x32_bf16 v[40:43], v[170:173], v[206:209], v[40:43]
	v_mfma_f32_16x16x32_bf16 v[40:43], v[174:177], v[210:213], v[40:43]
	v_mfma_f32_16x16x32_bf16 v[48:51], v[166:169], v[210:213], v[48:51]
	v_mfma_f32_16x16x32_bf16 v[48:51], v[162:165], v[206:209], v[48:51]
	v_mfma_f32_16x16x32_bf16 v[32:35], v[162:165], v[214:217], v[32:35]
	v_mfma_f32_16x16x32_bf16 v[32:35], v[166:169], v[218:221], v[32:35]
	v_mfma_f32_16x16x32_bf16 v[24:27], v[174:177], v[218:221], v[24:27]
	v_mfma_f32_16x16x32_bf16 v[24:27], v[170:173], v[214:217], v[24:27]
	v_mfma_f32_16x16x32_bf16 v[8:11], v[170:173], v[222:225], v[8:11]
	v_mfma_f32_16x16x32_bf16 v[8:11], v[174:177], v[226:229], v[8:11]
	v_mfma_f32_16x16x32_bf16 v[16:19], v[166:169], v[226:229], v[16:19]
	v_mfma_f32_16x16x32_bf16 v[16:19], v[162:165], v[222:225], v[16:19]
	s_setprio 0
	s_setprio 1
	v_mfma_f32_16x16x32_bf16 v[52:55], v[178:181], v[198:201], v[52:55]
	v_mfma_f32_16x16x32_bf16 v[52:55], v[186:189], v[202:205], v[52:55]
	v_mfma_f32_16x16x32_bf16 v[44:47], v[194:197], v[202:205], v[44:47]
	v_mfma_f32_16x16x32_bf16 v[44:47], v[190:193], v[198:201], v[44:47]
	v_mfma_f32_16x16x32_bf16 v[28:31], v[190:193], v[206:209], v[28:31]
	v_mfma_f32_16x16x32_bf16 v[28:31], v[194:197], v[210:213], v[28:31]
	v_mfma_f32_16x16x32_bf16 v[36:39], v[186:189], v[210:213], v[36:39]
	v_mfma_f32_16x16x32_bf16 v[36:39], v[178:181], v[206:209], v[36:39]
	v_mfma_f32_16x16x32_bf16 v[20:23], v[178:181], v[214:217], v[20:23]
	v_mfma_f32_16x16x32_bf16 v[20:23], v[186:189], v[218:221], v[20:23]
	v_mfma_f32_16x16x32_bf16 v[12:15], v[194:197], v[218:221], v[12:15]
	v_mfma_f32_16x16x32_bf16 v[12:15], v[190:193], v[214:217], v[12:15]
	v_mfma_f32_16x16x32_bf16 v[0:3], v[190:193], v[222:225], v[0:3]
	v_mfma_f32_16x16x32_bf16 v[0:3], v[194:197], v[226:229], v[0:3]
	v_mfma_f32_16x16x32_bf16 v[4:7], v[186:189], v[226:229], v[4:7]
	v_mfma_f32_16x16x32_bf16 v[4:7], v[178:181], v[222:225], v[4:7]
	s_barrier
	s_setprio 0
	s_add_i32 s85, s85, 2
	s_add_u32 s83, s83, 0x100
	s_addc_u32 s84, s84, 0
	s_add_u32 s54, s54, 0x100
	s_addc_u32 s55, s55, 0
	s_branch .LBB0_875
.Lfa_8:
	v_add_u32_e32 v146, s73, v149
	ds_read_b128 v[162:165], v146
	v_xor_b32_e32 v253, 64, v146
	ds_read_b128 v[166:169], v253
	ds_read_b128 v[170:173], v146 offset:2048
	ds_read_b128 v[174:177], v253 offset:2048
	v_add_u32_e32 v146, s74, v149
	ds_read_b128 v[178:181], v146
	v_xor_b32_e32 v253, 64, v146
	ds_read_b128 v[186:189], v253
	ds_read_b128 v[190:193], v146 offset:2048
	ds_read_b128 v[194:197], v253 offset:2048
	s_add_u32 s58, s54, 0xfffc0080
	s_addc_u32 s59, s55, -1
	s_and_b64 s[56:57], s[56:57], exec
	s_cselect_b32 s59, s49, s59
	s_cselect_b32 s58, s80, s58
	s_cselect_b32 s57, s81, s84
	s_cselect_b32 s56, s82, s83
	v_lshl_add_u64 v[182:183], s[54:55], 0, v[138:139]
	s_add_i32 m0, s64, 0xc000
	ds_read_b128 v[198:201], v154
	v_xor_b32_e32 v253, 64, v154
	ds_read_b128 v[202:205], v253
	ds_read_b128 v[206:209], v154 offset:2048
	ds_read_b128 v[210:213], v253 offset:2048
	ds_read_b128 v[214:217], v154 offset:4096
	ds_read_b128 v[218:221], v253 offset:4096
	ds_read_b128 v[222:225], v154 offset:6144
	ds_read_b128 v[226:229], v253 offset:6144
	global_load_lds_dwordx4 v[182:183], off
	v_lshl_add_u64 v[182:183], s[54:55], 0, v[136:137]
	s_add_i32 m0, s64, 0xe000
	s_nop 0
	global_load_lds_dwordx4 v[182:183], off
	s_waitcnt vmcnt(8)
	s_waitcnt lgkmcnt(0)
	s_setprio 1
	s_barrier
	v_mfma_f32_16x16x32_bf16 v[124:127], v[162:165], v[198:201], 0
	v_mfma_f32_16x16x32_bf16 v[120:123], v[170:173], v[198:201], 0
	v_mfma_f32_16x16x32_bf16 v[112:115], v[162:165], v[206:209], 0
	v_mfma_f32_16x16x32_bf16 v[104:107], v[170:173], v[206:209], 0
	v_mfma_f32_16x16x32_bf16 v[96:99], v[162:165], v[214:217], 0
	v_mfma_f32_16x16x32_bf16 v[88:91], v[170:173], v[214:217], 0
	v_mfma_f32_16x16x32_bf16 v[80:83], v[162:165], v[222:225], 0
	v_mfma_f32_16x16x32_bf16 v[72:75], v[170:173], v[222:225], 0
	v_mfma_f32_16x16x32_bf16 v[124:127], v[166:169], v[202:205], v[124:127]
	v_mfma_f32_16x16x32_bf16 v[120:123], v[174:177], v[202:205], v[120:123]
	v_mfma_f32_16x16x32_bf16 v[112:115], v[166:169], v[210:213], v[112:115]
	v_mfma_f32_16x16x32_bf16 v[104:107], v[174:177], v[210:213], v[104:107]
	v_mfma_f32_16x16x32_bf16 v[96:99], v[166:169], v[218:221], v[96:99]
	v_mfma_f32_16x16x32_bf16 v[88:91], v[174:177], v[218:221], v[88:91]
	v_mfma_f32_16x16x32_bf16 v[80:83], v[166:169], v[226:229], v[80:83]
	v_mfma_f32_16x16x32_bf16 v[72:75], v[174:177], v[226:229], v[72:75]
	s_setprio 0
	s_setprio 1
	v_mfma_f32_16x16x32_bf16 v[116:119], v[178:181], v[198:201], 0
	v_mfma_f32_16x16x32_bf16 v[108:111], v[190:193], v[198:201], 0
	v_mfma_f32_16x16x32_bf16 v[100:103], v[178:181], v[206:209], 0
	v_mfma_f32_16x16x32_bf16 v[92:95], v[190:193], v[206:209], 0
	v_mfma_f32_16x16x32_bf16 v[84:87], v[178:181], v[214:217], 0
	v_mfma_f32_16x16x32_bf16 v[76:79], v[190:193], v[214:217], 0
	v_mfma_f32_16x16x32_bf16 v[68:71], v[178:181], v[222:225], 0
	v_mfma_f32_16x16x32_bf16 v[64:67], v[190:193], v[222:225], 0
	v_mfma_f32_16x16x32_bf16 v[116:119], v[186:189], v[202:205], v[116:119]
	v_mfma_f32_16x16x32_bf16 v[108:111], v[194:197], v[202:205], v[108:111]
	v_mfma_f32_16x16x32_bf16 v[100:103], v[186:189], v[210:213], v[100:103]
	v_mfma_f32_16x16x32_bf16 v[92:95], v[194:197], v[210:213], v[92:95]
	v_mfma_f32_16x16x32_bf16 v[84:87], v[186:189], v[218:221], v[84:87]
	v_mfma_f32_16x16x32_bf16 v[76:79], v[194:197], v[218:221], v[76:79]
	v_mfma_f32_16x16x32_bf16 v[68:71], v[186:189], v[226:229], v[68:71]
	v_mfma_f32_16x16x32_bf16 v[64:67], v[194:197], v[226:229], v[64:67]
	s_barrier
	s_setprio 0
	s_add_i32 s86, s73, s63
	v_lshl_add_u64 v[182:183], s[56:57], 0, v[130:131]
	s_mov_b32 m0, s86
	s_nop 0
	global_load_lds_dwordx4 v[182:183], off
	s_add_i32 m0, s86, 0x2000
	s_add_u32 s86, s56, 0x40000
	v_lshl_add_u64 v[230:231], s[56:57], 0, v[134:135]
	s_addc_u32 s87, s57, 0
	s_add_i32 s88, s74, s63
	global_load_lds_dwordx4 v[230:231], off
	v_lshl_add_u64 v[232:233], s[86:87], 0, v[130:131]
	s_mov_b32 m0, s88
	v_lshl_add_u64 v[234:235], s[58:59], 0, v[132:133]
	global_load_lds_dwordx4 v[232:233], off
	v_lshl_add_u64 v[232:233], s[86:87], 0, v[134:135]
	s_add_i32 m0, s88, 0x2000
	s_nop 0
	global_load_lds_dwordx4 v[232:233], off
	v_lshl_add_u64 v[232:233], s[58:59], 0, v[128:129]
	s_mov_b32 m0, s64
	s_nop 0
	global_load_lds_dwordx4 v[232:233], off
	s_mov_b32 m0, s65
	s_nop 0
	global_load_lds_dwordx4 v[234:235], off
	ds_read_b128 v[198:201], v154 offset:16384
	v_xor_b32_e32 v253, 64, v154
	ds_read_b128 v[202:205], v253 offset:16384
	ds_read_b128 v[206:209], v154 offset:18432
	ds_read_b128 v[210:213], v253 offset:18432
	ds_read_b128 v[214:217], v154 offset:20480
	ds_read_b128 v[218:221], v253 offset:20480
	ds_read_b128 v[222:225], v154 offset:22528
	ds_read_b128 v[226:229], v253 offset:22528
	s_waitcnt vmcnt(8)
	s_waitcnt lgkmcnt(0)
	s_setprio 1
	s_barrier
	v_mfma_f32_16x16x32_bf16 v[60:63], v[162:165], v[198:201], 0
	v_mfma_f32_16x16x32_bf16 v[56:59], v[170:173], v[198:201], 0
	v_mfma_f32_16x16x32_bf16 v[48:51], v[162:165], v[206:209], 0
	v_mfma_f32_16x16x32_bf16 v[40:43], v[170:173], v[206:209], 0
	v_mfma_f32_16x16x32_bf16 v[32:35], v[162:165], v[214:217], 0
	v_mfma_f32_16x16x32_bf16 v[24:27], v[170:173], v[214:217], 0
	v_mfma_f32_16x16x32_bf16 v[16:19], v[162:165], v[222:225], 0
	v_mfma_f32_16x16x32_bf16 v[8:11], v[170:173], v[222:225], 0
	v_mfma_f32_16x16x32_bf16 v[60:63], v[166:169], v[202:205], v[60:63]
	v_mfma_f32_16x16x32_bf16 v[56:59], v[174:177], v[202:205], v[56:59]
	v_mfma_f32_16x16x32_bf16 v[48:51], v[166:169], v[210:213], v[48:51]
	v_mfma_f32_16x16x32_bf16 v[40:43], v[174:177], v[210:213], v[40:43]
	v_mfma_f32_16x16x32_bf16 v[32:35], v[166:169], v[218:221], v[32:35]
	v_mfma_f32_16x16x32_bf16 v[24:27], v[174:177], v[218:221], v[24:27]
	v_mfma_f32_16x16x32_bf16 v[16:19], v[166:169], v[226:229], v[16:19]
	v_mfma_f32_16x16x32_bf16 v[8:11], v[174:177], v[226:229], v[8:11]
	s_setprio 0
	s_setprio 1
	v_mfma_f32_16x16x32_bf16 v[52:55], v[178:181], v[198:201], 0
	v_mfma_f32_16x16x32_bf16 v[44:47], v[190:193], v[198:201], 0
	v_mfma_f32_16x16x32_bf16 v[36:39], v[178:181], v[206:209], 0
	v_mfma_f32_16x16x32_bf16 v[28:31], v[190:193], v[206:209], 0
	v_mfma_f32_16x16x32_bf16 v[20:23], v[178:181], v[214:217], 0
	v_mfma_f32_16x16x32_bf16 v[12:15], v[190:193], v[214:217], 0
	v_mfma_f32_16x16x32_bf16 v[4:7], v[178:181], v[222:225], 0
	v_mfma_f32_16x16x32_bf16 v[0:3], v[190:193], v[222:225], 0
	v_mfma_f32_16x16x32_bf16 v[52:55], v[186:189], v[202:205], v[52:55]
	v_mfma_f32_16x16x32_bf16 v[44:47], v[194:197], v[202:205], v[44:47]
	v_mfma_f32_16x16x32_bf16 v[36:39], v[186:189], v[210:213], v[36:39]
	v_mfma_f32_16x16x32_bf16 v[28:31], v[194:197], v[210:213], v[28:31]
	v_mfma_f32_16x16x32_bf16 v[20:23], v[186:189], v[218:221], v[20:23]
	v_mfma_f32_16x16x32_bf16 v[12:15], v[194:197], v[218:221], v[12:15]
	v_mfma_f32_16x16x32_bf16 v[4:7], v[186:189], v[226:229], v[4:7]
	v_mfma_f32_16x16x32_bf16 v[0:3], v[194:197], v[226:229], v[0:3]
	s_barrier
	s_setprio 0
	s_add_i32 s86, 0, 0x18000
	v_add_u32_e32 v146, s86, v149
	s_add_i32 s87, 0, 0x1c000
	ds_read_b128 v[162:165], v146
	v_xor_b32_e32 v253, 64, v146
	ds_read_b128 v[166:169], v253
	ds_read_b128 v[170:173], v146 offset:2048
	ds_read_b128 v[174:177], v253 offset:2048
	v_add_u32_e32 v146, s87, v149
	ds_read_b128 v[178:181], v146
	v_xor_b32_e32 v253, 64, v146
	ds_read_b128 v[186:189], v253
	ds_read_b128 v[190:193], v146 offset:2048
	ds_read_b128 v[194:197], v253 offset:2048
	s_add_u32 s58, s58, 0x40000
	s_addc_u32 s59, s59, 0
	s_mov_b32 m0, s66
	v_lshl_add_u64 v[236:237], s[58:59], 0, v[128:129]
	ds_read_b128 v[198:201], v154 offset:32768
	v_xor_b32_e32 v253, 64, v154
	ds_read_b128 v[202:205], v253 offset:32768
	ds_read_b128 v[206:209], v154 offset:34816
	ds_read_b128 v[210:213], v253 offset:34816
	ds_read_b128 v[214:217], v154 offset:36864
	ds_read_b128 v[218:221], v253 offset:36864
	ds_read_b128 v[222:225], v154 offset:38912
	ds_read_b128 v[226:229], v253 offset:38912
	global_load_lds_dwordx4 v[236:237], off
	v_lshl_add_u64 v[236:237], s[58:59], 0, v[132:133]
	s_mov_b32 m0, s67
	s_nop 0
	global_load_lds_dwordx4 v[236:237], off
	s_waitcnt vmcnt(8)
	s_waitcnt lgkmcnt(0)
	s_setprio 1
	s_barrier
	v_mfma_f32_16x16x32_bf16 v[124:127], v[162:165], v[198:201], v[124:127]
	v_mfma_f32_16x16x32_bf16 v[124:127], v[166:169], v[202:205], v[124:127]
	v_mfma_f32_16x16x32_bf16 v[120:123], v[174:177], v[202:205], v[120:123]
	v_mfma_f32_16x16x32_bf16 v[120:123], v[170:173], v[198:201], v[120:123]
	v_mfma_f32_16x16x32_bf16 v[104:107], v[170:173], v[206:209], v[104:107]
	v_mfma_f32_16x16x32_bf16 v[104:107], v[174:177], v[210:213], v[104:107]
	v_mfma_f32_16x16x32_bf16 v[112:115], v[166:169], v[210:213], v[112:115]
	v_mfma_f32_16x16x32_bf16 v[112:115], v[162:165], v[206:209], v[112:115]
	v_mfma_f32_16x16x32_bf16 v[96:99], v[162:165], v[214:217], v[96:99]
	v_mfma_f32_16x16x32_bf16 v[96:99], v[166:169], v[218:221], v[96:99]
	v_mfma_f32_16x16x32_bf16 v[88:91], v[174:177], v[218:221], v[88:91]
	v_mfma_f32_16x16x32_bf16 v[88:91], v[170:173], v[214:217], v[88:91]
	v_mfma_f32_16x16x32_bf16 v[72:75], v[170:173], v[222:225], v[72:75]
	v_mfma_f32_16x16x32_bf16 v[72:75], v[174:177], v[226:229], v[72:75]
	v_mfma_f32_16x16x32_bf16 v[80:83], v[166:169], v[226:229], v[80:83]
	v_mfma_f32_16x16x32_bf16 v[80:83], v[162:165], v[222:225], v[80:83]
	s_setprio 0
	s_setprio 1
	v_mfma_f32_16x16x32_bf16 v[116:119], v[178:181], v[198:201], v[116:119]
	v_mfma_f32_16x16x32_bf16 v[116:119], v[186:189], v[202:205], v[116:119]
	v_mfma_f32_16x16x32_bf16 v[108:111], v[194:197], v[202:205], v[108:111]
	v_mfma_f32_16x16x32_bf16 v[108:111], v[190:193], v[198:201], v[108:111]
	v_mfma_f32_16x16x32_bf16 v[92:95], v[190:193], v[206:209], v[92:95]
	v_mfma_f32_16x16x32_bf16 v[92:95], v[194:197], v[210:213], v[92:95]
	v_mfma_f32_16x16x32_bf16 v[100:103], v[186:189], v[210:213], v[100:103]
	v_mfma_f32_16x16x32_bf16 v[100:103], v[178:181], v[206:209], v[100:103]
	v_mfma_f32_16x16x32_bf16 v[84:87], v[178:181], v[214:217], v[84:87]
	v_mfma_f32_16x16x32_bf16 v[84:87], v[186:189], v[218:221], v[84:87]
	v_mfma_f32_16x16x32_bf16 v[76:79], v[194:197], v[218:221], v[76:79]
	v_mfma_f32_16x16x32_bf16 v[76:79], v[190:193], v[214:217], v[76:79]
	v_mfma_f32_16x16x32_bf16 v[64:67], v[190:193], v[222:225], v[64:67]
	v_mfma_f32_16x16x32_bf16 v[64:67], v[194:197], v[226:229], v[64:67]
	v_mfma_f32_16x16x32_bf16 v[68:71], v[186:189], v[226:229], v[68:71]
	v_mfma_f32_16x16x32_bf16 v[68:71], v[178:181], v[222:225], v[68:71]
	s_barrier
	s_setprio 0
	s_add_i32 s58, s86, s63
	v_lshl_add_u64 v[182:183], v[182:183], 0, s[22:23]
	s_mov_b32 m0, s58
	s_nop 0
	global_load_lds_dwordx4 v[182:183], off
	s_add_i32 m0, s58, 0x2000
	s_add_u32 s56, s56, 0x40080
	v_lshl_add_u64 v[182:183], v[230:231], 0, s[22:23]
	s_addc_u32 s57, s57, 0
	s_add_i32 s58, s87, s63
	global_load_lds_dwordx4 v[182:183], off
	v_lshl_add_u64 v[182:183], s[56:57], 0, v[130:131]
	s_mov_b32 m0, s58
	s_nop 0
	global_load_lds_dwordx4 v[182:183], off
	v_lshl_add_u64 v[182:183], s[56:57], 0, v[134:135]
	s_add_i32 m0, s58, 0x2000
	s_nop 0
	global_load_lds_dwordx4 v[182:183], off
	v_lshl_add_u64 v[182:183], v[232:233], 0, s[22:23]
	s_mov_b32 m0, s69
	s_nop 0
	global_load_lds_dwordx4 v[182:183], off
	v_lshl_add_u64 v[182:183], v[234:235], 0, s[22:23]
	s_mov_b32 m0, s70
	s_nop 0
	global_load_lds_dwordx4 v[182:183], off
	ds_read_b128 v[198:201], v154 offset:49152
	v_xor_b32_e32 v253, 64, v154
	ds_read_b128 v[202:205], v253 offset:49152
	ds_read_b128 v[206:209], v154 offset:51200
	ds_read_b128 v[210:213], v253 offset:51200
	ds_read_b128 v[214:217], v154 offset:53248
	ds_read_b128 v[218:221], v253 offset:53248
	ds_read_b128 v[222:225], v154 offset:55296
	ds_read_b128 v[226:229], v253 offset:55296
	s_waitcnt vmcnt(8)
	s_waitcnt lgkmcnt(0)
	s_setprio 1
	s_barrier
	v_mfma_f32_16x16x32_bf16 v[60:63], v[162:165], v[198:201], v[60:63]
	v_mfma_f32_16x16x32_bf16 v[60:63], v[166:169], v[202:205], v[60:63]
	v_mfma_f32_16x16x32_bf16 v[56:59], v[174:177], v[202:205], v[56:59]
	v_mfma_f32_16x16x32_bf16 v[56:59], v[170:173], v[198:201], v[56:59]
	v_mfma_f32_16x16x32_bf16 v[40:43], v[170:173], v[206:209], v[40:43]
	v_mfma_f32_16x16x32_bf16 v[40:43], v[174:177], v[210:213], v[40:43]
	v_mfma_f32_16x16x32_bf16 v[48:51], v[166:169], v[210:213], v[48:51]
	v_mfma_f32_16x16x32_bf16 v[48:51], v[162:165], v[206:209], v[48:51]
	v_mfma_f32_16x16x32_bf16 v[32:35], v[162:165], v[214:217], v[32:35]
	v_mfma_f32_16x16x32_bf16 v[32:35], v[166:169], v[218:221], v[32:35]
	v_mfma_f32_16x16x32_bf16 v[24:27], v[174:177], v[218:221], v[24:27]
	v_mfma_f32_16x16x32_bf16 v[24:27], v[170:173], v[214:217], v[24:27]
	v_mfma_f32_16x16x32_bf16 v[8:11], v[170:173], v[222:225], v[8:11]
	v_mfma_f32_16x16x32_bf16 v[8:11], v[174:177], v[226:229], v[8:11]
	v_mfma_f32_16x16x32_bf16 v[16:19], v[166:169], v[226:229], v[16:19]
	v_mfma_f32_16x16x32_bf16 v[16:19], v[162:165], v[222:225], v[16:19]
	s_setprio 0
	s_setprio 1
	v_mfma_f32_16x16x32_bf16 v[52:55], v[178:181], v[198:201], v[52:55]
	v_mfma_f32_16x16x32_bf16 v[52:55], v[186:189], v[202:205], v[52:55]
	v_mfma_f32_16x16x32_bf16 v[44:47], v[194:197], v[202:205], v[44:47]
	v_mfma_f32_16x16x32_bf16 v[44:47], v[190:193], v[198:201], v[44:47]
	v_mfma_f32_16x16x32_bf16 v[28:31], v[190:193], v[206:209], v[28:31]
	v_mfma_f32_16x16x32_bf16 v[28:31], v[194:197], v[210:213], v[28:31]
	v_mfma_f32_16x16x32_bf16 v[36:39], v[186:189], v[210:213], v[36:39]
	v_mfma_f32_16x16x32_bf16 v[36:39], v[178:181], v[206:209], v[36:39]
	v_mfma_f32_16x16x32_bf16 v[20:23], v[178:181], v[214:217], v[20:23]
	v_mfma_f32_16x16x32_bf16 v[20:23], v[186:189], v[218:221], v[20:23]
	v_mfma_f32_16x16x32_bf16 v[12:15], v[194:197], v[218:221], v[12:15]
	v_mfma_f32_16x16x32_bf16 v[12:15], v[190:193], v[214:217], v[12:15]
	v_mfma_f32_16x16x32_bf16 v[0:3], v[190:193], v[222:225], v[0:3]
	v_mfma_f32_16x16x32_bf16 v[0:3], v[194:197], v[226:229], v[0:3]
	v_mfma_f32_16x16x32_bf16 v[4:7], v[186:189], v[226:229], v[4:7]
	v_mfma_f32_16x16x32_bf16 v[4:7], v[178:181], v[222:225], v[4:7]
	s_barrier
	s_setprio 0
	s_add_i32 s85, s85, 2
	s_add_u32 s83, s83, 0x100
	s_addc_u32 s84, s84, 0
	s_add_u32 s54, s54, 0x100
	s_addc_u32 s55, s55, 0
	s_branch .LBB0_875
.LBB0_874:
	v_add_u32_e32 v146, s73, v149
	ds_read_b128 v[162:165], v146
	v_xor_b32_e32 v253, 64, v146
	ds_read_b128 v[166:169], v253
	ds_read_b128 v[170:173], v146 offset:2048
	ds_read_b128 v[174:177], v253 offset:2048
	v_add_u32_e32 v146, s74, v149
	ds_read_b128 v[178:181], v146
	v_xor_b32_e32 v253, 64, v146
	ds_read_b128 v[186:189], v253
	ds_read_b128 v[190:193], v146 offset:2048
	ds_read_b128 v[194:197], v253 offset:2048
	s_add_u32 s58, s54, 0xfffc0080
	s_addc_u32 s59, s55, -1
	s_and_b64 s[56:57], s[56:57], exec
	s_cselect_b32 s59, s49, s59
	s_cselect_b32 s58, s80, s58
	s_cselect_b32 s57, s81, s84
	s_cselect_b32 s56, s82, s83
	v_lshl_add_u64 v[182:183], s[54:55], 0, v[138:139]
	s_add_i32 m0, s64, 0xc000
	ds_read_b128 v[198:201], v154
	v_xor_b32_e32 v253, 64, v154
	ds_read_b128 v[202:205], v253
	ds_read_b128 v[206:209], v154 offset:2048
	ds_read_b128 v[210:213], v253 offset:2048
	ds_read_b128 v[214:217], v154 offset:4096
	ds_read_b128 v[218:221], v253 offset:4096
	ds_read_b128 v[222:225], v154 offset:6144
	ds_read_b128 v[226:229], v253 offset:6144
	global_load_lds_dwordx4 v[182:183], off
	v_lshl_add_u64 v[182:183], s[54:55], 0, v[136:137]
	s_add_i32 m0, s64, 0xe000
	s_nop 0
	global_load_lds_dwordx4 v[182:183], off
	s_waitcnt vmcnt(8)
	s_waitcnt lgkmcnt(0)
	s_setprio 1
	s_barrier
	v_mfma_f32_16x16x32_bf16 v[124:127], v[162:165], v[198:201], v[124:127]
	v_mfma_f32_16x16x32_bf16 v[124:127], v[166:169], v[202:205], v[124:127]
	v_mfma_f32_16x16x32_bf16 v[120:123], v[174:177], v[202:205], v[120:123]
	v_mfma_f32_16x16x32_bf16 v[120:123], v[170:173], v[198:201], v[120:123]
	v_mfma_f32_16x16x32_bf16 v[104:107], v[170:173], v[206:209], v[104:107]
	v_mfma_f32_16x16x32_bf16 v[104:107], v[174:177], v[210:213], v[104:107]
	v_mfma_f32_16x16x32_bf16 v[112:115], v[166:169], v[210:213], v[112:115]
	v_mfma_f32_16x16x32_bf16 v[112:115], v[162:165], v[206:209], v[112:115]
	v_mfma_f32_16x16x32_bf16 v[96:99], v[162:165], v[214:217], v[96:99]
	v_mfma_f32_16x16x32_bf16 v[96:99], v[166:169], v[218:221], v[96:99]
	v_mfma_f32_16x16x32_bf16 v[88:91], v[174:177], v[218:221], v[88:91]
	v_mfma_f32_16x16x32_bf16 v[88:91], v[170:173], v[214:217], v[88:91]
	v_mfma_f32_16x16x32_bf16 v[72:75], v[170:173], v[222:225], v[72:75]
	v_mfma_f32_16x16x32_bf16 v[72:75], v[174:177], v[226:229], v[72:75]
	v_mfma_f32_16x16x32_bf16 v[80:83], v[166:169], v[226:229], v[80:83]
	v_mfma_f32_16x16x32_bf16 v[80:83], v[162:165], v[222:225], v[80:83]
	s_setprio 0
	s_setprio 1
	v_mfma_f32_16x16x32_bf16 v[116:119], v[178:181], v[198:201], v[116:119]
	v_mfma_f32_16x16x32_bf16 v[116:119], v[186:189], v[202:205], v[116:119]
	v_mfma_f32_16x16x32_bf16 v[108:111], v[194:197], v[202:205], v[108:111]
	v_mfma_f32_16x16x32_bf16 v[108:111], v[190:193], v[198:201], v[108:111]
	v_mfma_f32_16x16x32_bf16 v[92:95], v[190:193], v[206:209], v[92:95]
	v_mfma_f32_16x16x32_bf16 v[92:95], v[194:197], v[210:213], v[92:95]
	v_mfma_f32_16x16x32_bf16 v[100:103], v[186:189], v[210:213], v[100:103]
	v_mfma_f32_16x16x32_bf16 v[100:103], v[178:181], v[206:209], v[100:103]
	v_mfma_f32_16x16x32_bf16 v[84:87], v[178:181], v[214:217], v[84:87]
	v_mfma_f32_16x16x32_bf16 v[84:87], v[186:189], v[218:221], v[84:87]
	v_mfma_f32_16x16x32_bf16 v[76:79], v[194:197], v[218:221], v[76:79]
	v_mfma_f32_16x16x32_bf16 v[76:79], v[190:193], v[214:217], v[76:79]
	v_mfma_f32_16x16x32_bf16 v[64:67], v[190:193], v[222:225], v[64:67]
	v_mfma_f32_16x16x32_bf16 v[64:67], v[194:197], v[226:229], v[64:67]
	v_mfma_f32_16x16x32_bf16 v[68:71], v[186:189], v[226:229], v[68:71]
	v_mfma_f32_16x16x32_bf16 v[68:71], v[178:181], v[222:225], v[68:71]
	s_barrier
	s_setprio 0
	s_add_i32 s86, s73, s63
	v_lshl_add_u64 v[182:183], s[56:57], 0, v[130:131]
	s_mov_b32 m0, s86
	s_nop 0
	global_load_lds_dwordx4 v[182:183], off
	s_add_i32 m0, s86, 0x2000
	s_add_u32 s86, s56, 0x40000
	v_lshl_add_u64 v[230:231], s[56:57], 0, v[134:135]
	s_addc_u32 s87, s57, 0
	s_add_i32 s88, s74, s63
	global_load_lds_dwordx4 v[230:231], off
	v_lshl_add_u64 v[232:233], s[86:87], 0, v[130:131]
	s_mov_b32 m0, s88
	v_lshl_add_u64 v[234:235], s[58:59], 0, v[132:133]
	global_load_lds_dwordx4 v[232:233], off
	v_lshl_add_u64 v[232:233], s[86:87], 0, v[134:135]
	s_add_i32 m0, s88, 0x2000
	s_nop 0
	global_load_lds_dwordx4 v[232:233], off
	v_lshl_add_u64 v[232:233], s[58:59], 0, v[128:129]
	s_mov_b32 m0, s64
	s_nop 0
	global_load_lds_dwordx4 v[232:233], off
	s_mov_b32 m0, s65
	s_nop 0
	global_load_lds_dwordx4 v[234:235], off
	ds_read_b128 v[198:201], v154 offset:16384
	v_xor_b32_e32 v253, 64, v154
	ds_read_b128 v[202:205], v253 offset:16384
	ds_read_b128 v[206:209], v154 offset:18432
	ds_read_b128 v[210:213], v253 offset:18432
	ds_read_b128 v[214:217], v154 offset:20480
	ds_read_b128 v[218:221], v253 offset:20480
	ds_read_b128 v[222:225], v154 offset:22528
	ds_read_b128 v[226:229], v253 offset:22528
	s_waitcnt vmcnt(8)
	s_waitcnt lgkmcnt(0)
	s_setprio 1
	s_barrier
	v_mfma_f32_16x16x32_bf16 v[60:63], v[162:165], v[198:201], v[60:63]
	v_mfma_f32_16x16x32_bf16 v[60:63], v[166:169], v[202:205], v[60:63]
	v_mfma_f32_16x16x32_bf16 v[56:59], v[174:177], v[202:205], v[56:59]
	v_mfma_f32_16x16x32_bf16 v[56:59], v[170:173], v[198:201], v[56:59]
	v_mfma_f32_16x16x32_bf16 v[40:43], v[170:173], v[206:209], v[40:43]
	v_mfma_f32_16x16x32_bf16 v[40:43], v[174:177], v[210:213], v[40:43]
	v_mfma_f32_16x16x32_bf16 v[48:51], v[166:169], v[210:213], v[48:51]
	v_mfma_f32_16x16x32_bf16 v[48:51], v[162:165], v[206:209], v[48:51]
	v_mfma_f32_16x16x32_bf16 v[32:35], v[162:165], v[214:217], v[32:35]
	v_mfma_f32_16x16x32_bf16 v[32:35], v[166:169], v[218:221], v[32:35]
	v_mfma_f32_16x16x32_bf16 v[24:27], v[174:177], v[218:221], v[24:27]
	v_mfma_f32_16x16x32_bf16 v[24:27], v[170:173], v[214:217], v[24:27]
	v_mfma_f32_16x16x32_bf16 v[8:11], v[170:173], v[222:225], v[8:11]
	v_mfma_f32_16x16x32_bf16 v[8:11], v[174:177], v[226:229], v[8:11]
	v_mfma_f32_16x16x32_bf16 v[16:19], v[166:169], v[226:229], v[16:19]
	v_mfma_f32_16x16x32_bf16 v[16:19], v[162:165], v[222:225], v[16:19]
	s_setprio 0
	s_setprio 1
	v_mfma_f32_16x16x32_bf16 v[52:55], v[178:181], v[198:201], v[52:55]
	v_mfma_f32_16x16x32_bf16 v[52:55], v[186:189], v[202:205], v[52:55]
	v_mfma_f32_16x16x32_bf16 v[44:47], v[194:197], v[202:205], v[44:47]
	v_mfma_f32_16x16x32_bf16 v[44:47], v[190:193], v[198:201], v[44:47]
	v_mfma_f32_16x16x32_bf16 v[28:31], v[190:193], v[206:209], v[28:31]
	v_mfma_f32_16x16x32_bf16 v[28:31], v[194:197], v[210:213], v[28:31]
	v_mfma_f32_16x16x32_bf16 v[36:39], v[186:189], v[210:213], v[36:39]
	v_mfma_f32_16x16x32_bf16 v[36:39], v[178:181], v[206:209], v[36:39]
	v_mfma_f32_16x16x32_bf16 v[20:23], v[178:181], v[214:217], v[20:23]
	v_mfma_f32_16x16x32_bf16 v[20:23], v[186:189], v[218:221], v[20:23]
	v_mfma_f32_16x16x32_bf16 v[12:15], v[194:197], v[218:221], v[12:15]
	v_mfma_f32_16x16x32_bf16 v[12:15], v[190:193], v[214:217], v[12:15]
	v_mfma_f32_16x16x32_bf16 v[0:3], v[190:193], v[222:225], v[0:3]
	v_mfma_f32_16x16x32_bf16 v[0:3], v[194:197], v[226:229], v[0:3]
	v_mfma_f32_16x16x32_bf16 v[4:7], v[186:189], v[226:229], v[4:7]
	v_mfma_f32_16x16x32_bf16 v[4:7], v[178:181], v[222:225], v[4:7]
	s_barrier
	s_setprio 0
	s_add_i32 s86, 0, 0x18000
	v_add_u32_e32 v146, s86, v149
	s_add_i32 s87, 0, 0x1c000
	ds_read_b128 v[162:165], v146
	v_xor_b32_e32 v253, 64, v146
	ds_read_b128 v[166:169], v253
	ds_read_b128 v[170:173], v146 offset:2048
	ds_read_b128 v[174:177], v253 offset:2048
	v_add_u32_e32 v146, s87, v149
	ds_read_b128 v[178:181], v146
	v_xor_b32_e32 v253, 64, v146
	ds_read_b128 v[186:189], v253
	ds_read_b128 v[190:193], v146 offset:2048
	ds_read_b128 v[194:197], v253 offset:2048
	s_add_u32 s58, s58, 0x40000
	s_addc_u32 s59, s59, 0
	s_mov_b32 m0, s66
	v_lshl_add_u64 v[236:237], s[58:59], 0, v[128:129]
	ds_read_b128 v[198:201], v154 offset:32768
	v_xor_b32_e32 v253, 64, v154
	ds_read_b128 v[202:205], v253 offset:32768
	ds_read_b128 v[206:209], v154 offset:34816
	ds_read_b128 v[210:213], v253 offset:34816
	ds_read_b128 v[214:217], v154 offset:36864
	ds_read_b128 v[218:221], v253 offset:36864
	ds_read_b128 v[222:225], v154 offset:38912
	ds_read_b128 v[226:229], v253 offset:38912
	global_load_lds_dwordx4 v[236:237], off
	v_lshl_add_u64 v[236:237], s[58:59], 0, v[132:133]
	s_mov_b32 m0, s67
	s_nop 0
	global_load_lds_dwordx4 v[236:237], off
	s_waitcnt vmcnt(8)
	s_waitcnt lgkmcnt(0)
	s_setprio 1
	s_barrier
	v_mfma_f32_16x16x32_bf16 v[124:127], v[162:165], v[198:201], v[124:127]
	v_mfma_f32_16x16x32_bf16 v[124:127], v[166:169], v[202:205], v[124:127]
	v_mfma_f32_16x16x32_bf16 v[120:123], v[174:177], v[202:205], v[120:123]
	v_mfma_f32_16x16x32_bf16 v[120:123], v[170:173], v[198:201], v[120:123]
	v_mfma_f32_16x16x32_bf16 v[104:107], v[170:173], v[206:209], v[104:107]
	v_mfma_f32_16x16x32_bf16 v[104:107], v[174:177], v[210:213], v[104:107]
	v_mfma_f32_16x16x32_bf16 v[112:115], v[166:169], v[210:213], v[112:115]
	v_mfma_f32_16x16x32_bf16 v[112:115], v[162:165], v[206:209], v[112:115]
	v_mfma_f32_16x16x32_bf16 v[96:99], v[162:165], v[214:217], v[96:99]
	v_mfma_f32_16x16x32_bf16 v[96:99], v[166:169], v[218:221], v[96:99]
	v_mfma_f32_16x16x32_bf16 v[88:91], v[174:177], v[218:221], v[88:91]
	v_mfma_f32_16x16x32_bf16 v[88:91], v[170:173], v[214:217], v[88:91]
	v_mfma_f32_16x16x32_bf16 v[72:75], v[170:173], v[222:225], v[72:75]
	v_mfma_f32_16x16x32_bf16 v[72:75], v[174:177], v[226:229], v[72:75]
	v_mfma_f32_16x16x32_bf16 v[80:83], v[166:169], v[226:229], v[80:83]
	v_mfma_f32_16x16x32_bf16 v[80:83], v[162:165], v[222:225], v[80:83]
	s_setprio 0
	s_setprio 1
	v_mfma_f32_16x16x32_bf16 v[116:119], v[178:181], v[198:201], v[116:119]
	v_mfma_f32_16x16x32_bf16 v[116:119], v[186:189], v[202:205], v[116:119]
	v_mfma_f32_16x16x32_bf16 v[108:111], v[194:197], v[202:205], v[108:111]
	v_mfma_f32_16x16x32_bf16 v[108:111], v[190:193], v[198:201], v[108:111]
	v_mfma_f32_16x16x32_bf16 v[92:95], v[190:193], v[206:209], v[92:95]
	v_mfma_f32_16x16x32_bf16 v[92:95], v[194:197], v[210:213], v[92:95]
	v_mfma_f32_16x16x32_bf16 v[100:103], v[186:189], v[210:213], v[100:103]
	v_mfma_f32_16x16x32_bf16 v[100:103], v[178:181], v[206:209], v[100:103]
	v_mfma_f32_16x16x32_bf16 v[84:87], v[178:181], v[214:217], v[84:87]
	v_mfma_f32_16x16x32_bf16 v[84:87], v[186:189], v[218:221], v[84:87]
	v_mfma_f32_16x16x32_bf16 v[76:79], v[194:197], v[218:221], v[76:79]
	v_mfma_f32_16x16x32_bf16 v[76:79], v[190:193], v[214:217], v[76:79]
	v_mfma_f32_16x16x32_bf16 v[64:67], v[190:193], v[222:225], v[64:67]
	v_mfma_f32_16x16x32_bf16 v[64:67], v[194:197], v[226:229], v[64:67]
	v_mfma_f32_16x16x32_bf16 v[68:71], v[186:189], v[226:229], v[68:71]
	v_mfma_f32_16x16x32_bf16 v[68:71], v[178:181], v[222:225], v[68:71]
	s_barrier
	s_setprio 0
	s_add_i32 s58, s86, s63
	v_lshl_add_u64 v[182:183], v[182:183], 0, s[22:23]
	s_mov_b32 m0, s58
	s_nop 0
	global_load_lds_dwordx4 v[182:183], off
	s_add_i32 m0, s58, 0x2000
	s_add_u32 s56, s56, 0x40080
	v_lshl_add_u64 v[182:183], v[230:231], 0, s[22:23]
	s_addc_u32 s57, s57, 0
	s_add_i32 s58, s87, s63
	global_load_lds_dwordx4 v[182:183], off
	v_lshl_add_u64 v[182:183], s[56:57], 0, v[130:131]
	s_mov_b32 m0, s58
	s_nop 0
	global_load_lds_dwordx4 v[182:183], off
	v_lshl_add_u64 v[182:183], s[56:57], 0, v[134:135]
	s_add_i32 m0, s58, 0x2000
	s_nop 0
	global_load_lds_dwordx4 v[182:183], off
	v_lshl_add_u64 v[182:183], v[232:233], 0, s[22:23]
	s_mov_b32 m0, s69
	s_nop 0
	global_load_lds_dwordx4 v[182:183], off
	v_lshl_add_u64 v[182:183], v[234:235], 0, s[22:23]
	s_mov_b32 m0, s70
	s_nop 0
	global_load_lds_dwordx4 v[182:183], off
	ds_read_b128 v[198:201], v154 offset:49152
	v_xor_b32_e32 v253, 64, v154
	ds_read_b128 v[202:205], v253 offset:49152
	ds_read_b128 v[206:209], v154 offset:51200
	ds_read_b128 v[210:213], v253 offset:51200
	ds_read_b128 v[214:217], v154 offset:53248
	ds_read_b128 v[218:221], v253 offset:53248
	ds_read_b128 v[222:225], v154 offset:55296
	ds_read_b128 v[226:229], v253 offset:55296
	s_waitcnt vmcnt(8)
	s_waitcnt lgkmcnt(0)
	s_setprio 1
	s_barrier
	v_mfma_f32_16x16x32_bf16 v[60:63], v[162:165], v[198:201], v[60:63]
	v_mfma_f32_16x16x32_bf16 v[60:63], v[166:169], v[202:205], v[60:63]
	v_mfma_f32_16x16x32_bf16 v[56:59], v[174:177], v[202:205], v[56:59]
	v_mfma_f32_16x16x32_bf16 v[56:59], v[170:173], v[198:201], v[56:59]
	v_mfma_f32_16x16x32_bf16 v[40:43], v[170:173], v[206:209], v[40:43]
	v_mfma_f32_16x16x32_bf16 v[40:43], v[174:177], v[210:213], v[40:43]
	v_mfma_f32_16x16x32_bf16 v[48:51], v[166:169], v[210:213], v[48:51]
	v_mfma_f32_16x16x32_bf16 v[48:51], v[162:165], v[206:209], v[48:51]
	v_mfma_f32_16x16x32_bf16 v[32:35], v[162:165], v[214:217], v[32:35]
	v_mfma_f32_16x16x32_bf16 v[32:35], v[166:169], v[218:221], v[32:35]
	v_mfma_f32_16x16x32_bf16 v[24:27], v[174:177], v[218:221], v[24:27]
	v_mfma_f32_16x16x32_bf16 v[24:27], v[170:173], v[214:217], v[24:27]
	v_mfma_f32_16x16x32_bf16 v[8:11], v[170:173], v[222:225], v[8:11]
	v_mfma_f32_16x16x32_bf16 v[8:11], v[174:177], v[226:229], v[8:11]
	v_mfma_f32_16x16x32_bf16 v[16:19], v[166:169], v[226:229], v[16:19]
	v_mfma_f32_16x16x32_bf16 v[16:19], v[162:165], v[222:225], v[16:19]
	s_setprio 0
	s_setprio 1
	v_mfma_f32_16x16x32_bf16 v[52:55], v[178:181], v[198:201], v[52:55]
	v_mfma_f32_16x16x32_bf16 v[52:55], v[186:189], v[202:205], v[52:55]
	v_mfma_f32_16x16x32_bf16 v[44:47], v[194:197], v[202:205], v[44:47]
	v_mfma_f32_16x16x32_bf16 v[44:47], v[190:193], v[198:201], v[44:47]
	v_mfma_f32_16x16x32_bf16 v[28:31], v[190:193], v[206:209], v[28:31]
	v_mfma_f32_16x16x32_bf16 v[28:31], v[194:197], v[210:213], v[28:31]
	v_mfma_f32_16x16x32_bf16 v[36:39], v[186:189], v[210:213], v[36:39]
	v_mfma_f32_16x16x32_bf16 v[36:39], v[178:181], v[206:209], v[36:39]
	v_mfma_f32_16x16x32_bf16 v[20:23], v[178:181], v[214:217], v[20:23]
	v_mfma_f32_16x16x32_bf16 v[20:23], v[186:189], v[218:221], v[20:23]
	v_mfma_f32_16x16x32_bf16 v[12:15], v[194:197], v[218:221], v[12:15]
	v_mfma_f32_16x16x32_bf16 v[12:15], v[190:193], v[214:217], v[12:15]
	v_mfma_f32_16x16x32_bf16 v[0:3], v[190:193], v[222:225], v[0:3]
	v_mfma_f32_16x16x32_bf16 v[0:3], v[194:197], v[226:229], v[0:3]
	v_mfma_f32_16x16x32_bf16 v[4:7], v[186:189], v[226:229], v[4:7]
	v_mfma_f32_16x16x32_bf16 v[4:7], v[178:181], v[222:225], v[4:7]
	s_barrier
	s_setprio 0
	s_add_i32 s85, s85, 2
	s_add_u32 s83, s83, 0x100
	s_addc_u32 s84, s84, 0
	s_add_u32 s54, s54, 0x100
	s_addc_u32 s55, s55, 0
	s_cmp_gt_u32 s85, 13
	s_cbranch_scc1 .LBB0_877

.LBB0_1010:
	s_ashr_i32 s51, s50, 31
	s_lshl_b64 s[52:53], s[50:51], 19
	s_add_u32 s52, s33, s52
	s_addc_u32 s53, s35, s53
	s_and_b64 s[54:55], s[12:13], exec
	s_cselect_b32 s15, s53, s61
	s_cselect_b32 s51, s52, s60
	s_ashr_i32 s49, s48, 31
	s_lshl_b64 s[54:55], s[48:49], 19
	s_add_u32 s54, s64, s54
	s_addc_u32 s55, s65, s55
	s_and_b64 s[62:63], s[12:13], exec
	s_cselect_b32 s49, s55, s59
	s_cselect_b32 s57, s54, s58
	s_add_u32 s78, s58, 0x100
	s_addc_u32 s79, s59, 0
	s_add_u32 s58, s60, 0x40080
	s_addc_u32 s59, s61, 0
	s_mov_b32 s80, -2
	s_waitcnt lgkmcnt(0)
	s_cmp_eq_u32 s71, 1
	s_cbranch_scc1 .Lfa_9
	ds_read_b128 v[128:131], v188
	v_xor_b32_e32 v253, 64, v188
	ds_read_b128 v[132:135], v253
	ds_read_b128 v[136:139], v188 offset:2048
	ds_read_b128 v[140:143], v253 offset:2048
	ds_read_b128 v[144:147], v189
	v_xor_b32_e32 v253, 64, v189
	ds_read_b128 v[148:151], v253
	ds_read_b128 v[172:175], v189 offset:2048
	ds_read_b128 v[176:179], v253 offset:2048
	s_add_u32 s60, s58, 0xfffc0080
	s_addc_u32 s61, s59, -1
	s_cmp_eq_u32 s80, 12
	s_cselect_b32 s63, s15, s61
	s_cselect_b32 s62, s51, s60
	s_cselect_b32 s61, s49, s79
	s_cselect_b32 s60, s57, s78
	v_lshl_add_u64 v[220:221], s[58:59], 0, v[166:167]
	s_add_i32 m0, s67, 0xc000
	s_nop 0
	global_load_lds_dwordx4 v[220:221], off
	v_lshl_add_u64 v[220:221], s[58:59], 0, v[164:165]
	s_add_i32 m0, s67, 0xe000
	s_nop 0
	global_load_lds_dwordx4 v[220:221], off
	ds_read_b128 v[180:183], v190
	v_xor_b32_e32 v253, 64, v190
	ds_read_b128 v[192:195], v253
	ds_read_b128 v[196:199], v190 offset:2048
	ds_read_b128 v[200:203], v253 offset:2048
	ds_read_b128 v[204:207], v190 offset:4096
	ds_read_b128 v[208:211], v253 offset:4096
	ds_read_b128 v[212:215], v190 offset:6144
	ds_read_b128 v[216:219], v253 offset:6144
	s_waitcnt vmcnt(24)
	s_waitcnt lgkmcnt(0)
	s_setprio 1
	s_barrier
	v_mfma_f32_16x16x32_bf16 v[124:127], v[128:131], v[180:183], 0
	v_mfma_f32_16x16x32_bf16 v[120:123], v[136:139], v[180:183], 0
	v_mfma_f32_16x16x32_bf16 v[108:111], v[128:131], v[196:199], 0
	v_mfma_f32_16x16x32_bf16 v[104:107], v[136:139], v[196:199], 0
	v_mfma_f32_16x16x32_bf16 v[92:95], v[128:131], v[204:207], 0
	v_mfma_f32_16x16x32_bf16 v[88:91], v[136:139], v[204:207], 0
	v_mfma_f32_16x16x32_bf16 v[76:79], v[128:131], v[212:215], 0
	v_mfma_f32_16x16x32_bf16 v[72:75], v[136:139], v[212:215], 0
	v_mfma_f32_16x16x32_bf16 v[124:127], v[132:135], v[192:195], v[124:127]
	v_mfma_f32_16x16x32_bf16 v[120:123], v[140:143], v[192:195], v[120:123]
	v_mfma_f32_16x16x32_bf16 v[108:111], v[132:135], v[200:203], v[108:111]
	v_mfma_f32_16x16x32_bf16 v[104:107], v[140:143], v[200:203], v[104:107]
	v_mfma_f32_16x16x32_bf16 v[92:95], v[132:135], v[208:211], v[92:95]
	v_mfma_f32_16x16x32_bf16 v[88:91], v[140:143], v[208:211], v[88:91]
	v_mfma_f32_16x16x32_bf16 v[76:79], v[132:135], v[216:219], v[76:79]
	v_mfma_f32_16x16x32_bf16 v[72:75], v[140:143], v[216:219], v[72:75]
	s_setprio 0
	s_setprio 1
	v_mfma_f32_16x16x32_bf16 v[116:119], v[144:147], v[180:183], 0
	v_mfma_f32_16x16x32_bf16 v[112:115], v[172:175], v[180:183], 0
	v_mfma_f32_16x16x32_bf16 v[100:103], v[144:147], v[196:199], 0
	v_mfma_f32_16x16x32_bf16 v[96:99], v[172:175], v[196:199], 0
	v_mfma_f32_16x16x32_bf16 v[84:87], v[144:147], v[204:207], 0
	v_mfma_f32_16x16x32_bf16 v[80:83], v[172:175], v[204:207], 0
	v_mfma_f32_16x16x32_bf16 v[68:71], v[144:147], v[212:215], 0
	v_mfma_f32_16x16x32_bf16 v[64:67], v[172:175], v[212:215], 0
	v_mfma_f32_16x16x32_bf16 v[116:119], v[148:151], v[192:195], v[116:119]
	v_mfma_f32_16x16x32_bf16 v[112:115], v[176:179], v[192:195], v[112:115]
	v_mfma_f32_16x16x32_bf16 v[100:103], v[148:151], v[200:203], v[100:103]
	v_mfma_f32_16x16x32_bf16 v[96:99], v[176:179], v[200:203], v[96:99]
	v_mfma_f32_16x16x32_bf16 v[84:87], v[148:151], v[208:211], v[84:87]
	v_mfma_f32_16x16x32_bf16 v[80:83], v[176:179], v[208:211], v[80:83]
	v_mfma_f32_16x16x32_bf16 v[68:71], v[148:151], v[216:219], v[68:71]
	v_mfma_f32_16x16x32_bf16 v[64:67], v[176:179], v[216:219], v[64:67]
	s_barrier
	s_setprio 0
	s_add_i32 s81, s76, s66
	v_lshl_add_u64 v[220:221], s[60:61], 0, v[154:155]
	s_mov_b32 m0, s81
	s_nop 0
	global_load_lds_dwordx4 v[220:221], off
	s_add_i32 m0, s81, 0x2000
	s_add_u32 s82, s60, 0x40000
	v_lshl_add_u64 v[222:223], s[60:61], 0, v[162:163]
	s_addc_u32 s83, s61, 0
	s_add_i32 s81, s77, s66
	global_load_lds_dwordx4 v[222:223], off
	v_lshl_add_u64 v[224:225], s[82:83], 0, v[154:155]
	s_mov_b32 m0, s81
	v_lshl_add_u64 v[226:227], s[62:63], 0, v[160:161]
	global_load_lds_dwordx4 v[224:225], off
	v_lshl_add_u64 v[224:225], s[82:83], 0, v[162:163]
	s_add_i32 m0, s81, 0x2000
	s_nop 0
	global_load_lds_dwordx4 v[224:225], off
	v_lshl_add_u64 v[224:225], s[62:63], 0, v[152:153]
	s_mov_b32 m0, s67
	s_nop 0
	global_load_lds_dwordx4 v[224:225], off
	s_mov_b32 m0, s68
	s_nop 0
	global_load_lds_dwordx4 v[226:227], off
	ds_read_b128 v[180:183], v190 offset:16384
	v_xor_b32_e32 v253, 64, v190
	ds_read_b128 v[192:195], v253 offset:16384
	ds_read_b128 v[196:199], v190 offset:18432
	ds_read_b128 v[200:203], v253 offset:18432
	ds_read_b128 v[204:207], v190 offset:20480
	ds_read_b128 v[208:211], v253 offset:20480
	ds_read_b128 v[212:215], v190 offset:22528
	ds_read_b128 v[216:219], v253 offset:22528
	s_waitcnt vmcnt(24)
	s_waitcnt lgkmcnt(0)
	s_setprio 1
	s_barrier
	v_mfma_f32_16x16x32_bf16 v[60:63], v[128:131], v[180:183], 0
	v_mfma_f32_16x16x32_bf16 v[56:59], v[136:139], v[180:183], 0
	v_mfma_f32_16x16x32_bf16 v[44:47], v[128:131], v[196:199], 0
	v_mfma_f32_16x16x32_bf16 v[40:43], v[136:139], v[196:199], 0
	v_mfma_f32_16x16x32_bf16 v[28:31], v[128:131], v[204:207], 0
	v_mfma_f32_16x16x32_bf16 v[24:27], v[136:139], v[204:207], 0
	v_mfma_f32_16x16x32_bf16 v[12:15], v[128:131], v[212:215], 0
	v_mfma_f32_16x16x32_bf16 v[8:11], v[136:139], v[212:215], 0
	v_mfma_f32_16x16x32_bf16 v[60:63], v[132:135], v[192:195], v[60:63]
	v_mfma_f32_16x16x32_bf16 v[56:59], v[140:143], v[192:195], v[56:59]
	v_mfma_f32_16x16x32_bf16 v[44:47], v[132:135], v[200:203], v[44:47]
	v_mfma_f32_16x16x32_bf16 v[40:43], v[140:143], v[200:203], v[40:43]
	v_mfma_f32_16x16x32_bf16 v[28:31], v[132:135], v[208:211], v[28:31]
	v_mfma_f32_16x16x32_bf16 v[24:27], v[140:143], v[208:211], v[24:27]
	v_mfma_f32_16x16x32_bf16 v[12:15], v[132:135], v[216:219], v[12:15]
	v_mfma_f32_16x16x32_bf16 v[8:11], v[140:143], v[216:219], v[8:11]
	s_setprio 0
	s_setprio 1
	v_mfma_f32_16x16x32_bf16 v[52:55], v[144:147], v[180:183], 0
	v_mfma_f32_16x16x32_bf16 v[48:51], v[172:175], v[180:183], 0
	v_mfma_f32_16x16x32_bf16 v[36:39], v[144:147], v[196:199], 0
	v_mfma_f32_16x16x32_bf16 v[32:35], v[172:175], v[196:199], 0
	v_mfma_f32_16x16x32_bf16 v[20:23], v[144:147], v[204:207], 0
	v_mfma_f32_16x16x32_bf16 v[16:19], v[172:175], v[204:207], 0
	v_mfma_f32_16x16x32_bf16 v[4:7], v[144:147], v[212:215], 0
	v_mfma_f32_16x16x32_bf16 v[0:3], v[172:175], v[212:215], 0
	v_mfma_f32_16x16x32_bf16 v[52:55], v[148:151], v[192:195], v[52:55]
	v_mfma_f32_16x16x32_bf16 v[48:51], v[176:179], v[192:195], v[48:51]
	v_mfma_f32_16x16x32_bf16 v[36:39], v[148:151], v[200:203], v[36:39]
	v_mfma_f32_16x16x32_bf16 v[32:35], v[176:179], v[200:203], v[32:35]
	v_mfma_f32_16x16x32_bf16 v[20:23], v[148:151], v[208:211], v[20:23]
	v_mfma_f32_16x16x32_bf16 v[16:19], v[176:179], v[208:211], v[16:19]
	v_mfma_f32_16x16x32_bf16 v[4:7], v[148:151], v[216:219], v[4:7]
	v_mfma_f32_16x16x32_bf16 v[0:3], v[176:179], v[216:219], v[0:3]
	s_barrier
	s_setprio 0
	s_add_i32 s81, 0, 0x18000
	s_add_i32 s82, 0, 0x1c000
	v_add_u32_e32 v140, s81, v185
	v_add_u32_e32 v176, s82, v185
	s_add_u32 s62, s62, 0x40000
	s_addc_u32 s63, s63, 0
	s_mov_b32 m0, s69
	v_lshl_add_u64 v[228:229], s[62:63], 0, v[152:153]
	global_load_lds_dwordx4 v[228:229], off
	v_lshl_add_u64 v[228:229], s[62:63], 0, v[160:161]
	s_mov_b32 m0, s70
	s_nop 0
	global_load_lds_dwordx4 v[228:229], off
	ds_read_b128 v[128:131], v140
	v_xor_b32_e32 v253, 64, v140
	ds_read_b128 v[132:135], v253
	ds_read_b128 v[136:139], v140 offset:2048
	ds_read_b128 v[140:143], v253 offset:2048
	ds_read_b128 v[144:147], v176
	v_xor_b32_e32 v253, 64, v176
	ds_read_b128 v[148:151], v253
	ds_read_b128 v[172:175], v176 offset:2048
	ds_read_b128 v[176:179], v253 offset:2048
	ds_read_b128 v[180:183], v190 offset:32768
	v_xor_b32_e32 v253, 64, v190
	ds_read_b128 v[192:195], v253 offset:32768
	ds_read_b128 v[196:199], v190 offset:34816
	ds_read_b128 v[200:203], v253 offset:34816
	ds_read_b128 v[204:207], v190 offset:36864
	ds_read_b128 v[208:211], v253 offset:36864
	ds_read_b128 v[212:215], v190 offset:38912
	ds_read_b128 v[216:219], v253 offset:38912
	s_waitcnt vmcnt(8)
	s_waitcnt lgkmcnt(0)
	s_setprio 1
	s_barrier
	v_mfma_f32_16x16x32_bf16 v[124:127], v[128:131], v[180:183], v[124:127]
	v_mfma_f32_16x16x32_bf16 v[124:127], v[132:135], v[192:195], v[124:127]
	v_mfma_f32_16x16x32_bf16 v[120:123], v[140:143], v[192:195], v[120:123]
	v_mfma_f32_16x16x32_bf16 v[120:123], v[136:139], v[180:183], v[120:123]
	v_mfma_f32_16x16x32_bf16 v[104:107], v[136:139], v[196:199], v[104:107]
	v_mfma_f32_16x16x32_bf16 v[104:107], v[140:143], v[200:203], v[104:107]
	v_mfma_f32_16x16x32_bf16 v[108:111], v[132:135], v[200:203], v[108:111]
	v_mfma_f32_16x16x32_bf16 v[108:111], v[128:131], v[196:199], v[108:111]
	v_mfma_f32_16x16x32_bf16 v[92:95], v[128:131], v[204:207], v[92:95]
	v_mfma_f32_16x16x32_bf16 v[92:95], v[132:135], v[208:211], v[92:95]
	v_mfma_f32_16x16x32_bf16 v[88:91], v[140:143], v[208:211], v[88:91]
	v_mfma_f32_16x16x32_bf16 v[88:91], v[136:139], v[204:207], v[88:91]
	v_mfma_f32_16x16x32_bf16 v[72:75], v[136:139], v[212:215], v[72:75]
	v_mfma_f32_16x16x32_bf16 v[72:75], v[140:143], v[216:219], v[72:75]
	v_mfma_f32_16x16x32_bf16 v[76:79], v[132:135], v[216:219], v[76:79]
	v_mfma_f32_16x16x32_bf16 v[76:79], v[128:131], v[212:215], v[76:79]
	s_setprio 0
	s_setprio 1
	v_mfma_f32_16x16x32_bf16 v[116:119], v[144:147], v[180:183], v[116:119]
	v_mfma_f32_16x16x32_bf16 v[116:119], v[148:151], v[192:195], v[116:119]
	v_mfma_f32_16x16x32_bf16 v[112:115], v[176:179], v[192:195], v[112:115]
	v_mfma_f32_16x16x32_bf16 v[112:115], v[172:175], v[180:183], v[112:115]
	v_mfma_f32_16x16x32_bf16 v[96:99], v[172:175], v[196:199], v[96:99]
	v_mfma_f32_16x16x32_bf16 v[96:99], v[176:179], v[200:203], v[96:99]
	v_mfma_f32_16x16x32_bf16 v[100:103], v[148:151], v[200:203], v[100:103]
	v_mfma_f32_16x16x32_bf16 v[100:103], v[144:147], v[196:199], v[100:103]
	v_mfma_f32_16x16x32_bf16 v[84:87], v[144:147], v[204:207], v[84:87]
	v_mfma_f32_16x16x32_bf16 v[84:87], v[148:151], v[208:211], v[84:87]
	v_mfma_f32_16x16x32_bf16 v[80:83], v[176:179], v[208:211], v[80:83]
	v_mfma_f32_16x16x32_bf16 v[80:83], v[172:175], v[204:207], v[80:83]
	v_mfma_f32_16x16x32_bf16 v[64:67], v[172:175], v[212:215], v[64:67]
	v_mfma_f32_16x16x32_bf16 v[64:67], v[176:179], v[216:219], v[64:67]
	v_mfma_f32_16x16x32_bf16 v[68:71], v[148:151], v[216:219], v[68:71]
	v_mfma_f32_16x16x32_bf16 v[68:71], v[144:147], v[212:215], v[68:71]
	s_barrier
	s_setprio 0
	s_add_i32 s62, s81, s66
	v_lshl_add_u64 v[220:221], v[220:221], 0, s[26:27]
	s_mov_b32 m0, s62
	s_nop 0
	global_load_lds_dwordx4 v[220:221], off
	s_add_i32 m0, s62, 0x2000
	s_add_u32 s60, s60, 0x40080
	v_lshl_add_u64 v[220:221], v[222:223], 0, s[26:27]
	s_addc_u32 s61, s61, 0
	s_add_i32 s62, s82, s66
	global_load_lds_dwordx4 v[220:221], off
	v_lshl_add_u64 v[220:221], s[60:61], 0, v[154:155]
	s_mov_b32 m0, s62
	s_nop 0
	global_load_lds_dwordx4 v[220:221], off
	v_lshl_add_u64 v[220:221], s[60:61], 0, v[162:163]
	s_add_i32 m0, s62, 0x2000
	s_nop 0
	global_load_lds_dwordx4 v[220:221], off
	v_lshl_add_u64 v[220:221], v[224:225], 0, s[26:27]
	s_mov_b32 m0, s3
	s_nop 0
	global_load_lds_dwordx4 v[220:221], off
	v_lshl_add_u64 v[220:221], v[226:227], 0, s[26:27]
	s_mov_b32 m0, s72
	s_nop 0
	global_load_lds_dwordx4 v[220:221], off
	ds_read_b128 v[180:183], v190 offset:49152
	v_xor_b32_e32 v253, 64, v190
	ds_read_b128 v[192:195], v253 offset:49152
	ds_read_b128 v[196:199], v190 offset:51200
	ds_read_b128 v[200:203], v253 offset:51200
	ds_read_b128 v[204:207], v190 offset:53248
	ds_read_b128 v[208:211], v253 offset:53248
	ds_read_b128 v[212:215], v190 offset:55296
	ds_read_b128 v[216:219], v253 offset:55296
	s_waitcnt vmcnt(8)
	s_waitcnt lgkmcnt(0)
	s_setprio 1
	s_barrier
	v_mfma_f32_16x16x32_bf16 v[60:63], v[128:131], v[180:183], v[60:63]
	v_mfma_f32_16x16x32_bf16 v[60:63], v[132:135], v[192:195], v[60:63]
	v_mfma_f32_16x16x32_bf16 v[56:59], v[140:143], v[192:195], v[56:59]
	v_mfma_f32_16x16x32_bf16 v[56:59], v[136:139], v[180:183], v[56:59]
	v_mfma_f32_16x16x32_bf16 v[40:43], v[136:139], v[196:199], v[40:43]
	v_mfma_f32_16x16x32_bf16 v[40:43], v[140:143], v[200:203], v[40:43]
	v_mfma_f32_16x16x32_bf16 v[44:47], v[132:135], v[200:203], v[44:47]
	v_mfma_f32_16x16x32_bf16 v[44:47], v[128:131], v[196:199], v[44:47]
	v_mfma_f32_16x16x32_bf16 v[28:31], v[128:131], v[204:207], v[28:31]
	v_mfma_f32_16x16x32_bf16 v[28:31], v[132:135], v[208:211], v[28:31]
	v_mfma_f32_16x16x32_bf16 v[24:27], v[140:143], v[208:211], v[24:27]
	v_mfma_f32_16x16x32_bf16 v[24:27], v[136:139], v[204:207], v[24:27]
	v_mfma_f32_16x16x32_bf16 v[8:11], v[136:139], v[212:215], v[8:11]
	v_mfma_f32_16x16x32_bf16 v[8:11], v[140:143], v[216:219], v[8:11]
	v_mfma_f32_16x16x32_bf16 v[12:15], v[132:135], v[216:219], v[12:15]
	v_mfma_f32_16x16x32_bf16 v[12:15], v[128:131], v[212:215], v[12:15]
	s_setprio 0
	s_setprio 1
	v_mfma_f32_16x16x32_bf16 v[52:55], v[144:147], v[180:183], v[52:55]
	v_mfma_f32_16x16x32_bf16 v[52:55], v[148:151], v[192:195], v[52:55]
	v_mfma_f32_16x16x32_bf16 v[48:51], v[176:179], v[192:195], v[48:51]
	v_mfma_f32_16x16x32_bf16 v[48:51], v[172:175], v[180:183], v[48:51]
	v_mfma_f32_16x16x32_bf16 v[32:35], v[172:175], v[196:199], v[32:35]
	v_mfma_f32_16x16x32_bf16 v[32:35], v[176:179], v[200:203], v[32:35]
	v_mfma_f32_16x16x32_bf16 v[36:39], v[148:151], v[200:203], v[36:39]
	v_mfma_f32_16x16x32_bf16 v[36:39], v[144:147], v[196:199], v[36:39]
	v_mfma_f32_16x16x32_bf16 v[20:23], v[144:147], v[204:207], v[20:23]
	v_mfma_f32_16x16x32_bf16 v[20:23], v[148:151], v[208:211], v[20:23]
	v_mfma_f32_16x16x32_bf16 v[16:19], v[176:179], v[208:211], v[16:19]
	v_mfma_f32_16x16x32_bf16 v[16:19], v[172:175], v[204:207], v[16:19]
	v_mfma_f32_16x16x32_bf16 v[0:3], v[172:175], v[212:215], v[0:3]
	v_mfma_f32_16x16x32_bf16 v[0:3], v[176:179], v[216:219], v[0:3]
	v_mfma_f32_16x16x32_bf16 v[4:7], v[148:151], v[216:219], v[4:7]
	v_mfma_f32_16x16x32_bf16 v[4:7], v[144:147], v[212:215], v[4:7]
	s_barrier
	s_setprio 0
	s_add_i32 s80, s80, 2
	s_add_u32 s78, s78, 0x100
	s_addc_u32 s79, s79, 0
	s_add_u32 s58, s58, 0x100
	s_addc_u32 s59, s59, 0
	s_cmp_gt_u32 s80, 13
	s_branch .LBB0_1011
.Lfa_9:
	ds_read_b128 v[128:131], v188
	v_xor_b32_e32 v253, 64, v188
	ds_read_b128 v[132:135], v253
	ds_read_b128 v[136:139], v188 offset:2048
	ds_read_b128 v[140:143], v253 offset:2048
	ds_read_b128 v[144:147], v189
	v_xor_b32_e32 v253, 64, v189
	ds_read_b128 v[148:151], v253
	ds_read_b128 v[172:175], v189 offset:2048
	ds_read_b128 v[176:179], v253 offset:2048
	s_add_u32 s60, s58, 0xfffc0080
	s_addc_u32 s61, s59, -1
	s_cmp_eq_u32 s80, 12
	s_cselect_b32 s63, s15, s61
	s_cselect_b32 s62, s51, s60
	s_cselect_b32 s61, s49, s79
	s_cselect_b32 s60, s57, s78
	v_lshl_add_u64 v[220:221], s[58:59], 0, v[166:167]
	s_add_i32 m0, s67, 0xc000
	s_nop 0
	global_load_lds_dwordx4 v[220:221], off
	v_lshl_add_u64 v[220:221], s[58:59], 0, v[164:165]
	s_add_i32 m0, s67, 0xe000
	s_nop 0
	global_load_lds_dwordx4 v[220:221], off
	ds_read_b128 v[180:183], v190
	v_xor_b32_e32 v253, 64, v190
	ds_read_b128 v[192:195], v253
	ds_read_b128 v[196:199], v190 offset:2048
	ds_read_b128 v[200:203], v253 offset:2048
	ds_read_b128 v[204:207], v190 offset:4096
	ds_read_b128 v[208:211], v253 offset:4096
	ds_read_b128 v[212:215], v190 offset:6144
	ds_read_b128 v[216:219], v253 offset:6144
	s_waitcnt vmcnt(8)
	s_waitcnt lgkmcnt(0)
	s_setprio 1
	s_barrier
	v_mfma_f32_16x16x32_bf16 v[124:127], v[128:131], v[180:183], 0
	v_mfma_f32_16x16x32_bf16 v[120:123], v[136:139], v[180:183], 0
	v_mfma_f32_16x16x32_bf16 v[108:111], v[128:131], v[196:199], 0
	v_mfma_f32_16x16x32_bf16 v[104:107], v[136:139], v[196:199], 0
	v_mfma_f32_16x16x32_bf16 v[92:95], v[128:131], v[204:207], 0
	v_mfma_f32_16x16x32_bf16 v[88:91], v[136:139], v[204:207], 0
	v_mfma_f32_16x16x32_bf16 v[76:79], v[128:131], v[212:215], 0
	v_mfma_f32_16x16x32_bf16 v[72:75], v[136:139], v[212:215], 0
	v_mfma_f32_16x16x32_bf16 v[124:127], v[132:135], v[192:195], v[124:127]
	v_mfma_f32_16x16x32_bf16 v[120:123], v[140:143], v[192:195], v[120:123]
	v_mfma_f32_16x16x32_bf16 v[108:111], v[132:135], v[200:203], v[108:111]
	v_mfma_f32_16x16x32_bf16 v[104:107], v[140:143], v[200:203], v[104:107]
	v_mfma_f32_16x16x32_bf16 v[92:95], v[132:135], v[208:211], v[92:95]
	v_mfma_f32_16x16x32_bf16 v[88:91], v[140:143], v[208:211], v[88:91]
	v_mfma_f32_16x16x32_bf16 v[76:79], v[132:135], v[216:219], v[76:79]
	v_mfma_f32_16x16x32_bf16 v[72:75], v[140:143], v[216:219], v[72:75]
	s_setprio 0
	s_setprio 1
	v_mfma_f32_16x16x32_bf16 v[116:119], v[144:147], v[180:183], 0
	v_mfma_f32_16x16x32_bf16 v[112:115], v[172:175], v[180:183], 0
	v_mfma_f32_16x16x32_bf16 v[100:103], v[144:147], v[196:199], 0
	v_mfma_f32_16x16x32_bf16 v[96:99], v[172:175], v[196:199], 0
	v_mfma_f32_16x16x32_bf16 v[84:87], v[144:147], v[204:207], 0
	v_mfma_f32_16x16x32_bf16 v[80:83], v[172:175], v[204:207], 0
	v_mfma_f32_16x16x32_bf16 v[68:71], v[144:147], v[212:215], 0
	v_mfma_f32_16x16x32_bf16 v[64:67], v[172:175], v[212:215], 0
	v_mfma_f32_16x16x32_bf16 v[116:119], v[148:151], v[192:195], v[116:119]
	v_mfma_f32_16x16x32_bf16 v[112:115], v[176:179], v[192:195], v[112:115]
	v_mfma_f32_16x16x32_bf16 v[100:103], v[148:151], v[200:203], v[100:103]
	v_mfma_f32_16x16x32_bf16 v[96:99], v[176:179], v[200:203], v[96:99]
	v_mfma_f32_16x16x32_bf16 v[84:87], v[148:151], v[208:211], v[84:87]
	v_mfma_f32_16x16x32_bf16 v[80:83], v[176:179], v[208:211], v[80:83]
	v_mfma_f32_16x16x32_bf16 v[68:71], v[148:151], v[216:219], v[68:71]
	v_mfma_f32_16x16x32_bf16 v[64:67], v[176:179], v[216:219], v[64:67]
	s_barrier
	s_setprio 0
	s_add_i32 s81, s76, s66
	v_lshl_add_u64 v[220:221], s[60:61], 0, v[154:155]
	s_mov_b32 m0, s81
	s_nop 0
	global_load_lds_dwordx4 v[220:221], off
	s_add_i32 m0, s81, 0x2000
	s_add_u32 s82, s60, 0x40000
	v_lshl_add_u64 v[222:223], s[60:61], 0, v[162:163]
	s_addc_u32 s83, s61, 0
	s_add_i32 s81, s77, s66
	global_load_lds_dwordx4 v[222:223], off
	v_lshl_add_u64 v[224:225], s[82:83], 0, v[154:155]
	s_mov_b32 m0, s81
	v_lshl_add_u64 v[226:227], s[62:63], 0, v[160:161]
	global_load_lds_dwordx4 v[224:225], off
	v_lshl_add_u64 v[224:225], s[82:83], 0, v[162:163]
	s_add_i32 m0, s81, 0x2000
	s_nop 0
	global_load_lds_dwordx4 v[224:225], off
	v_lshl_add_u64 v[224:225], s[62:63], 0, v[152:153]
	s_mov_b32 m0, s67
	s_nop 0
	global_load_lds_dwordx4 v[224:225], off
	s_mov_b32 m0, s68
	s_nop 0
	global_load_lds_dwordx4 v[226:227], off
	ds_read_b128 v[180:183], v190 offset:16384
	v_xor_b32_e32 v253, 64, v190
	ds_read_b128 v[192:195], v253 offset:16384
	ds_read_b128 v[196:199], v190 offset:18432
	ds_read_b128 v[200:203], v253 offset:18432
	ds_read_b128 v[204:207], v190 offset:20480
	ds_read_b128 v[208:211], v253 offset:20480
	ds_read_b128 v[212:215], v190 offset:22528
	ds_read_b128 v[216:219], v253 offset:22528
	s_waitcnt vmcnt(8)
	s_waitcnt lgkmcnt(0)
	s_setprio 1
	s_barrier
	v_mfma_f32_16x16x32_bf16 v[60:63], v[128:131], v[180:183], 0
	v_mfma_f32_16x16x32_bf16 v[56:59], v[136:139], v[180:183], 0
	v_mfma_f32_16x16x32_bf16 v[44:47], v[128:131], v[196:199], 0
	v_mfma_f32_16x16x32_bf16 v[40:43], v[136:139], v[196:199], 0
	v_mfma_f32_16x16x32_bf16 v[28:31], v[128:131], v[204:207], 0
	v_mfma_f32_16x16x32_bf16 v[24:27], v[136:139], v[204:207], 0
	v_mfma_f32_16x16x32_bf16 v[12:15], v[128:131], v[212:215], 0
	v_mfma_f32_16x16x32_bf16 v[8:11], v[136:139], v[212:215], 0
	v_mfma_f32_16x16x32_bf16 v[60:63], v[132:135], v[192:195], v[60:63]
	v_mfma_f32_16x16x32_bf16 v[56:59], v[140:143], v[192:195], v[56:59]
	v_mfma_f32_16x16x32_bf16 v[44:47], v[132:135], v[200:203], v[44:47]
	v_mfma_f32_16x16x32_bf16 v[40:43], v[140:143], v[200:203], v[40:43]
	v_mfma_f32_16x16x32_bf16 v[28:31], v[132:135], v[208:211], v[28:31]
	v_mfma_f32_16x16x32_bf16 v[24:27], v[140:143], v[208:211], v[24:27]
	v_mfma_f32_16x16x32_bf16 v[12:15], v[132:135], v[216:219], v[12:15]
	v_mfma_f32_16x16x32_bf16 v[8:11], v[140:143], v[216:219], v[8:11]
	s_setprio 0
	s_setprio 1
	v_mfma_f32_16x16x32_bf16 v[52:55], v[144:147], v[180:183], 0
	v_mfma_f32_16x16x32_bf16 v[48:51], v[172:175], v[180:183], 0
	v_mfma_f32_16x16x32_bf16 v[36:39], v[144:147], v[196:199], 0
	v_mfma_f32_16x16x32_bf16 v[32:35], v[172:175], v[196:199], 0
	v_mfma_f32_16x16x32_bf16 v[20:23], v[144:147], v[204:207], 0
	v_mfma_f32_16x16x32_bf16 v[16:19], v[172:175], v[204:207], 0
	v_mfma_f32_16x16x32_bf16 v[4:7], v[144:147], v[212:215], 0
	v_mfma_f32_16x16x32_bf16 v[0:3], v[172:175], v[212:215], 0
	v_mfma_f32_16x16x32_bf16 v[52:55], v[148:151], v[192:195], v[52:55]
	v_mfma_f32_16x16x32_bf16 v[48:51], v[176:179], v[192:195], v[48:51]
	v_mfma_f32_16x16x32_bf16 v[36:39], v[148:151], v[200:203], v[36:39]
	v_mfma_f32_16x16x32_bf16 v[32:35], v[176:179], v[200:203], v[32:35]
	v_mfma_f32_16x16x32_bf16 v[20:23], v[148:151], v[208:211], v[20:23]
	v_mfma_f32_16x16x32_bf16 v[16:19], v[176:179], v[208:211], v[16:19]
	v_mfma_f32_16x16x32_bf16 v[4:7], v[148:151], v[216:219], v[4:7]
	v_mfma_f32_16x16x32_bf16 v[0:3], v[176:179], v[216:219], v[0:3]
	s_barrier
	s_setprio 0
	s_add_i32 s81, 0, 0x18000
	s_add_i32 s82, 0, 0x1c000
	v_add_u32_e32 v140, s81, v185
	v_add_u32_e32 v176, s82, v185
	s_add_u32 s62, s62, 0x40000
	s_addc_u32 s63, s63, 0
	s_mov_b32 m0, s69
	v_lshl_add_u64 v[228:229], s[62:63], 0, v[152:153]
	global_load_lds_dwordx4 v[228:229], off
	v_lshl_add_u64 v[228:229], s[62:63], 0, v[160:161]
	s_mov_b32 m0, s70
	s_nop 0
	global_load_lds_dwordx4 v[228:229], off
	ds_read_b128 v[128:131], v140
	v_xor_b32_e32 v253, 64, v140
	ds_read_b128 v[132:135], v253
	ds_read_b128 v[136:139], v140 offset:2048
	ds_read_b128 v[140:143], v253 offset:2048
	ds_read_b128 v[144:147], v176
	v_xor_b32_e32 v253, 64, v176
	ds_read_b128 v[148:151], v253
	ds_read_b128 v[172:175], v176 offset:2048
	ds_read_b128 v[176:179], v253 offset:2048
	ds_read_b128 v[180:183], v190 offset:32768
	v_xor_b32_e32 v253, 64, v190
	ds_read_b128 v[192:195], v253 offset:32768
	ds_read_b128 v[196:199], v190 offset:34816
	ds_read_b128 v[200:203], v253 offset:34816
	ds_read_b128 v[204:207], v190 offset:36864
	ds_read_b128 v[208:211], v253 offset:36864
	ds_read_b128 v[212:215], v190 offset:38912
	ds_read_b128 v[216:219], v253 offset:38912
	s_waitcnt vmcnt(8)
	s_waitcnt lgkmcnt(0)
	s_setprio 1
	s_barrier
	v_mfma_f32_16x16x32_bf16 v[124:127], v[128:131], v[180:183], v[124:127]
	v_mfma_f32_16x16x32_bf16 v[124:127], v[132:135], v[192:195], v[124:127]
	v_mfma_f32_16x16x32_bf16 v[120:123], v[140:143], v[192:195], v[120:123]
	v_mfma_f32_16x16x32_bf16 v[120:123], v[136:139], v[180:183], v[120:123]
	v_mfma_f32_16x16x32_bf16 v[104:107], v[136:139], v[196:199], v[104:107]
	v_mfma_f32_16x16x32_bf16 v[104:107], v[140:143], v[200:203], v[104:107]
	v_mfma_f32_16x16x32_bf16 v[108:111], v[132:135], v[200:203], v[108:111]
	v_mfma_f32_16x16x32_bf16 v[108:111], v[128:131], v[196:199], v[108:111]
	v_mfma_f32_16x16x32_bf16 v[92:95], v[128:131], v[204:207], v[92:95]
	v_mfma_f32_16x16x32_bf16 v[92:95], v[132:135], v[208:211], v[92:95]
	v_mfma_f32_16x16x32_bf16 v[88:91], v[140:143], v[208:211], v[88:91]
	v_mfma_f32_16x16x32_bf16 v[88:91], v[136:139], v[204:207], v[88:91]
	v_mfma_f32_16x16x32_bf16 v[72:75], v[136:139], v[212:215], v[72:75]
	v_mfma_f32_16x16x32_bf16 v[72:75], v[140:143], v[216:219], v[72:75]
	v_mfma_f32_16x16x32_bf16 v[76:79], v[132:135], v[216:219], v[76:79]
	v_mfma_f32_16x16x32_bf16 v[76:79], v[128:131], v[212:215], v[76:79]
	s_setprio 0
	s_setprio 1
	v_mfma_f32_16x16x32_bf16 v[116:119], v[144:147], v[180:183], v[116:119]
	v_mfma_f32_16x16x32_bf16 v[116:119], v[148:151], v[192:195], v[116:119]
	v_mfma_f32_16x16x32_bf16 v[112:115], v[176:179], v[192:195], v[112:115]
	v_mfma_f32_16x16x32_bf16 v[112:115], v[172:175], v[180:183], v[112:115]
	v_mfma_f32_16x16x32_bf16 v[96:99], v[172:175], v[196:199], v[96:99]
	v_mfma_f32_16x16x32_bf16 v[96:99], v[176:179], v[200:203], v[96:99]
	v_mfma_f32_16x16x32_bf16 v[100:103], v[148:151], v[200:203], v[100:103]
	v_mfma_f32_16x16x32_bf16 v[100:103], v[144:147], v[196:199], v[100:103]
	v_mfma_f32_16x16x32_bf16 v[84:87], v[144:147], v[204:207], v[84:87]
	v_mfma_f32_16x16x32_bf16 v[84:87], v[148:151], v[208:211], v[84:87]
	v_mfma_f32_16x16x32_bf16 v[80:83], v[176:179], v[208:211], v[80:83]
	v_mfma_f32_16x16x32_bf16 v[80:83], v[172:175], v[204:207], v[80:83]
	v_mfma_f32_16x16x32_bf16 v[64:67], v[172:175], v[212:215], v[64:67]
	v_mfma_f32_16x16x32_bf16 v[64:67], v[176:179], v[216:219], v[64:67]
	v_mfma_f32_16x16x32_bf16 v[68:71], v[148:151], v[216:219], v[68:71]
	v_mfma_f32_16x16x32_bf16 v[68:71], v[144:147], v[212:215], v[68:71]
	s_barrier
	s_setprio 0
	s_add_i32 s62, s81, s66
	v_lshl_add_u64 v[220:221], v[220:221], 0, s[26:27]
	s_mov_b32 m0, s62
	s_nop 0
	global_load_lds_dwordx4 v[220:221], off
	s_add_i32 m0, s62, 0x2000
	s_add_u32 s60, s60, 0x40080
	v_lshl_add_u64 v[220:221], v[222:223], 0, s[26:27]
	s_addc_u32 s61, s61, 0
	s_add_i32 s62, s82, s66
	global_load_lds_dwordx4 v[220:221], off
	v_lshl_add_u64 v[220:221], s[60:61], 0, v[154:155]
	s_mov_b32 m0, s62
	s_nop 0
	global_load_lds_dwordx4 v[220:221], off
	v_lshl_add_u64 v[220:221], s[60:61], 0, v[162:163]
	s_add_i32 m0, s62, 0x2000
	s_nop 0
	global_load_lds_dwordx4 v[220:221], off
	v_lshl_add_u64 v[220:221], v[224:225], 0, s[26:27]
	s_mov_b32 m0, s3
	s_nop 0
	global_load_lds_dwordx4 v[220:221], off
	v_lshl_add_u64 v[220:221], v[226:227], 0, s[26:27]
	s_mov_b32 m0, s72
	s_nop 0
	global_load_lds_dwordx4 v[220:221], off
	ds_read_b128 v[180:183], v190 offset:49152
	v_xor_b32_e32 v253, 64, v190
	ds_read_b128 v[192:195], v253 offset:49152
	ds_read_b128 v[196:199], v190 offset:51200
	ds_read_b128 v[200:203], v253 offset:51200
	ds_read_b128 v[204:207], v190 offset:53248
	ds_read_b128 v[208:211], v253 offset:53248
	ds_read_b128 v[212:215], v190 offset:55296
	ds_read_b128 v[216:219], v253 offset:55296
	s_waitcnt vmcnt(8)
	s_waitcnt lgkmcnt(0)
	s_setprio 1
	s_barrier
	v_mfma_f32_16x16x32_bf16 v[60:63], v[128:131], v[180:183], v[60:63]
	v_mfma_f32_16x16x32_bf16 v[60:63], v[132:135], v[192:195], v[60:63]
	v_mfma_f32_16x16x32_bf16 v[56:59], v[140:143], v[192:195], v[56:59]
	v_mfma_f32_16x16x32_bf16 v[56:59], v[136:139], v[180:183], v[56:59]
	v_mfma_f32_16x16x32_bf16 v[40:43], v[136:139], v[196:199], v[40:43]
	v_mfma_f32_16x16x32_bf16 v[40:43], v[140:143], v[200:203], v[40:43]
	v_mfma_f32_16x16x32_bf16 v[44:47], v[132:135], v[200:203], v[44:47]
	v_mfma_f32_16x16x32_bf16 v[44:47], v[128:131], v[196:199], v[44:47]
	v_mfma_f32_16x16x32_bf16 v[28:31], v[128:131], v[204:207], v[28:31]
	v_mfma_f32_16x16x32_bf16 v[28:31], v[132:135], v[208:211], v[28:31]
	v_mfma_f32_16x16x32_bf16 v[24:27], v[140:143], v[208:211], v[24:27]
	v_mfma_f32_16x16x32_bf16 v[24:27], v[136:139], v[204:207], v[24:27]
	v_mfma_f32_16x16x32_bf16 v[8:11], v[136:139], v[212:215], v[8:11]
	v_mfma_f32_16x16x32_bf16 v[8:11], v[140:143], v[216:219], v[8:11]
	v_mfma_f32_16x16x32_bf16 v[12:15], v[132:135], v[216:219], v[12:15]
	v_mfma_f32_16x16x32_bf16 v[12:15], v[128:131], v[212:215], v[12:15]
	s_setprio 0
	s_setprio 1
	v_mfma_f32_16x16x32_bf16 v[52:55], v[144:147], v[180:183], v[52:55]
	v_mfma_f32_16x16x32_bf16 v[52:55], v[148:151], v[192:195], v[52:55]
	v_mfma_f32_16x16x32_bf16 v[48:51], v[176:179], v[192:195], v[48:51]
	v_mfma_f32_16x16x32_bf16 v[48:51], v[172:175], v[180:183], v[48:51]
	v_mfma_f32_16x16x32_bf16 v[32:35], v[172:175], v[196:199], v[32:35]
	v_mfma_f32_16x16x32_bf16 v[32:35], v[176:179], v[200:203], v[32:35]
	v_mfma_f32_16x16x32_bf16 v[36:39], v[148:151], v[200:203], v[36:39]
	v_mfma_f32_16x16x32_bf16 v[36:39], v[144:147], v[196:199], v[36:39]
	v_mfma_f32_16x16x32_bf16 v[20:23], v[144:147], v[204:207], v[20:23]
	v_mfma_f32_16x16x32_bf16 v[20:23], v[148:151], v[208:211], v[20:23]
	v_mfma_f32_16x16x32_bf16 v[16:19], v[176:179], v[208:211], v[16:19]
	v_mfma_f32_16x16x32_bf16 v[16:19], v[172:175], v[204:207], v[16:19]
	v_mfma_f32_16x16x32_bf16 v[0:3], v[172:175], v[212:215], v[0:3]
	v_mfma_f32_16x16x32_bf16 v[0:3], v[176:179], v[216:219], v[0:3]
	v_mfma_f32_16x16x32_bf16 v[4:7], v[148:151], v[216:219], v[4:7]
	v_mfma_f32_16x16x32_bf16 v[4:7], v[144:147], v[212:215], v[4:7]
	s_barrier
	s_setprio 0
	s_add_i32 s80, s80, 2
	s_add_u32 s78, s78, 0x100
	s_addc_u32 s79, s79, 0
	s_add_u32 s58, s58, 0x100
	s_addc_u32 s59, s59, 0
	s_cmp_gt_u32 s80, 13
.LBB0_1011:
	ds_read_b128 v[128:131], v188
	v_xor_b32_e32 v253, 64, v188
	ds_read_b128 v[132:135], v253
	ds_read_b128 v[136:139], v188 offset:2048
	ds_read_b128 v[140:143], v253 offset:2048
	ds_read_b128 v[144:147], v189
	v_xor_b32_e32 v253, 64, v189
	ds_read_b128 v[148:151], v253
	ds_read_b128 v[172:175], v189 offset:2048
	ds_read_b128 v[176:179], v253 offset:2048
	s_add_u32 s60, s58, 0xfffc0080
	s_addc_u32 s61, s59, -1
	s_cmp_eq_u32 s80, 12
	s_cselect_b32 s63, s15, s61
	s_cselect_b32 s62, s51, s60
	s_cselect_b32 s61, s49, s79
	s_cselect_b32 s60, s57, s78
	v_lshl_add_u64 v[220:221], s[58:59], 0, v[166:167]
	s_add_i32 m0, s67, 0xc000
	s_nop 0
	global_load_lds_dwordx4 v[220:221], off
	v_lshl_add_u64 v[220:221], s[58:59], 0, v[164:165]
	s_add_i32 m0, s67, 0xe000
	s_nop 0
	global_load_lds_dwordx4 v[220:221], off
	ds_read_b128 v[180:183], v190
	v_xor_b32_e32 v253, 64, v190
	ds_read_b128 v[192:195], v253
	ds_read_b128 v[196:199], v190 offset:2048
	ds_read_b128 v[200:203], v253 offset:2048
	ds_read_b128 v[204:207], v190 offset:4096
	ds_read_b128 v[208:211], v253 offset:4096
	ds_read_b128 v[212:215], v190 offset:6144
	ds_read_b128 v[216:219], v253 offset:6144
	s_waitcnt vmcnt(8)
	s_waitcnt lgkmcnt(0)
	s_setprio 1
	s_barrier
	v_mfma_f32_16x16x32_bf16 v[124:127], v[128:131], v[180:183], v[124:127]
	v_mfma_f32_16x16x32_bf16 v[124:127], v[132:135], v[192:195], v[124:127]
	v_mfma_f32_16x16x32_bf16 v[120:123], v[140:143], v[192:195], v[120:123]
	v_mfma_f32_16x16x32_bf16 v[120:123], v[136:139], v[180:183], v[120:123]
	v_mfma_f32_16x16x32_bf16 v[104:107], v[136:139], v[196:199], v[104:107]
	v_mfma_f32_16x16x32_bf16 v[104:107], v[140:143], v[200:203], v[104:107]
	v_mfma_f32_16x16x32_bf16 v[108:111], v[132:135], v[200:203], v[108:111]
	v_mfma_f32_16x16x32_bf16 v[108:111], v[128:131], v[196:199], v[108:111]
	v_mfma_f32_16x16x32_bf16 v[92:95], v[128:131], v[204:207], v[92:95]
	v_mfma_f32_16x16x32_bf16 v[92:95], v[132:135], v[208:211], v[92:95]
	v_mfma_f32_16x16x32_bf16 v[88:91], v[140:143], v[208:211], v[88:91]
	v_mfma_f32_16x16x32_bf16 v[88:91], v[136:139], v[204:207], v[88:91]
	v_mfma_f32_16x16x32_bf16 v[72:75], v[136:139], v[212:215], v[72:75]
	v_mfma_f32_16x16x32_bf16 v[72:75], v[140:143], v[216:219], v[72:75]
	v_mfma_f32_16x16x32_bf16 v[76:79], v[132:135], v[216:219], v[76:79]
	v_mfma_f32_16x16x32_bf16 v[76:79], v[128:131], v[212:215], v[76:79]
	s_setprio 0
	s_setprio 1
	v_mfma_f32_16x16x32_bf16 v[116:119], v[144:147], v[180:183], v[116:119]
	v_mfma_f32_16x16x32_bf16 v[116:119], v[148:151], v[192:195], v[116:119]
	v_mfma_f32_16x16x32_bf16 v[112:115], v[176:179], v[192:195], v[112:115]
	v_mfma_f32_16x16x32_bf16 v[112:115], v[172:175], v[180:183], v[112:115]
	v_mfma_f32_16x16x32_bf16 v[96:99], v[172:175], v[196:199], v[96:99]
	v_mfma_f32_16x16x32_bf16 v[96:99], v[176:179], v[200:203], v[96:99]
	v_mfma_f32_16x16x32_bf16 v[100:103], v[148:151], v[200:203], v[100:103]
	v_mfma_f32_16x16x32_bf16 v[100:103], v[144:147], v[196:199], v[100:103]
	v_mfma_f32_16x16x32_bf16 v[84:87], v[144:147], v[204:207], v[84:87]
	v_mfma_f32_16x16x32_bf16 v[84:87], v[148:151], v[208:211], v[84:87]
	v_mfma_f32_16x16x32_bf16 v[80:83], v[176:179], v[208:211], v[80:83]
	v_mfma_f32_16x16x32_bf16 v[80:83], v[172:175], v[204:207], v[80:83]
	v_mfma_f32_16x16x32_bf16 v[64:67], v[172:175], v[212:215], v[64:67]
	v_mfma_f32_16x16x32_bf16 v[64:67], v[176:179], v[216:219], v[64:67]
	v_mfma_f32_16x16x32_bf16 v[68:71], v[148:151], v[216:219], v[68:71]
	v_mfma_f32_16x16x32_bf16 v[68:71], v[144:147], v[212:215], v[68:71]
	s_barrier
	s_setprio 0
	s_add_i32 s81, s76, s66
	v_lshl_add_u64 v[220:221], s[60:61], 0, v[154:155]
	s_mov_b32 m0, s81
	s_nop 0
	global_load_lds_dwordx4 v[220:221], off
	s_add_i32 m0, s81, 0x2000
	s_add_u32 s82, s60, 0x40000
	v_lshl_add_u64 v[222:223], s[60:61], 0, v[162:163]
	s_addc_u32 s83, s61, 0
	s_add_i32 s81, s77, s66
	global_load_lds_dwordx4 v[222:223], off
	v_lshl_add_u64 v[224:225], s[82:83], 0, v[154:155]
	s_mov_b32 m0, s81
	v_lshl_add_u64 v[226:227], s[62:63], 0, v[160:161]
	global_load_lds_dwordx4 v[224:225], off
	v_lshl_add_u64 v[224:225], s[82:83], 0, v[162:163]
	s_add_i32 m0, s81, 0x2000
	s_nop 0
	global_load_lds_dwordx4 v[224:225], off
	v_lshl_add_u64 v[224:225], s[62:63], 0, v[152:153]
	s_mov_b32 m0, s67
	s_nop 0
	global_load_lds_dwordx4 v[224:225], off
	s_mov_b32 m0, s68
	s_nop 0
	global_load_lds_dwordx4 v[226:227], off
	ds_read_b128 v[180:183], v190 offset:16384
	v_xor_b32_e32 v253, 64, v190
	ds_read_b128 v[192:195], v253 offset:16384
	ds_read_b128 v[196:199], v190 offset:18432
	ds_read_b128 v[200:203], v253 offset:18432
	ds_read_b128 v[204:207], v190 offset:20480
	ds_read_b128 v[208:211], v253 offset:20480
	ds_read_b128 v[212:215], v190 offset:22528
	ds_read_b128 v[216:219], v253 offset:22528
	s_waitcnt vmcnt(8)
	s_waitcnt lgkmcnt(0)
	s_setprio 1
	s_barrier
	v_mfma_f32_16x16x32_bf16 v[60:63], v[128:131], v[180:183], v[60:63]
	v_mfma_f32_16x16x32_bf16 v[60:63], v[132:135], v[192:195], v[60:63]
	v_mfma_f32_16x16x32_bf16 v[56:59], v[140:143], v[192:195], v[56:59]
	v_mfma_f32_16x16x32_bf16 v[56:59], v[136:139], v[180:183], v[56:59]
	v_mfma_f32_16x16x32_bf16 v[40:43], v[136:139], v[196:199], v[40:43]
	v_mfma_f32_16x16x32_bf16 v[40:43], v[140:143], v[200:203], v[40:43]
	v_mfma_f32_16x16x32_bf16 v[44:47], v[132:135], v[200:203], v[44:47]
	v_mfma_f32_16x16x32_bf16 v[44:47], v[128:131], v[196:199], v[44:47]
	v_mfma_f32_16x16x32_bf16 v[28:31], v[128:131], v[204:207], v[28:31]
	v_mfma_f32_16x16x32_bf16 v[28:31], v[132:135], v[208:211], v[28:31]
	v_mfma_f32_16x16x32_bf16 v[24:27], v[140:143], v[208:211], v[24:27]
	v_mfma_f32_16x16x32_bf16 v[24:27], v[136:139], v[204:207], v[24:27]
	v_mfma_f32_16x16x32_bf16 v[8:11], v[136:139], v[212:215], v[8:11]
	v_mfma_f32_16x16x32_bf16 v[8:11], v[140:143], v[216:219], v[8:11]
	v_mfma_f32_16x16x32_bf16 v[12:15], v[132:135], v[216:219], v[12:15]
	v_mfma_f32_16x16x32_bf16 v[12:15], v[128:131], v[212:215], v[12:15]
	s_setprio 0
	s_setprio 1
	v_mfma_f32_16x16x32_bf16 v[52:55], v[144:147], v[180:183], v[52:55]
	v_mfma_f32_16x16x32_bf16 v[52:55], v[148:151], v[192:195], v[52:55]
	v_mfma_f32_16x16x32_bf16 v[48:51], v[176:179], v[192:195], v[48:51]
	v_mfma_f32_16x16x32_bf16 v[48:51], v[172:175], v[180:183], v[48:51]
	v_mfma_f32_16x16x32_bf16 v[32:35], v[172:175], v[196:199], v[32:35]
	v_mfma_f32_16x16x32_bf16 v[32:35], v[176:179], v[200:203], v[32:35]
	v_mfma_f32_16x16x32_bf16 v[36:39], v[148:151], v[200:203], v[36:39]
	v_mfma_f32_16x16x32_bf16 v[36:39], v[144:147], v[196:199], v[36:39]
	v_mfma_f32_16x16x32_bf16 v[20:23], v[144:147], v[204:207], v[20:23]
	v_mfma_f32_16x16x32_bf16 v[20:23], v[148:151], v[208:211], v[20:23]
	v_mfma_f32_16x16x32_bf16 v[16:19], v[176:179], v[208:211], v[16:19]
	v_mfma_f32_16x16x32_bf16 v[16:19], v[172:175], v[204:207], v[16:19]
	v_mfma_f32_16x16x32_bf16 v[0:3], v[172:175], v[212:215], v[0:3]
	v_mfma_f32_16x16x32_bf16 v[0:3], v[176:179], v[216:219], v[0:3]
	v_mfma_f32_16x16x32_bf16 v[4:7], v[148:151], v[216:219], v[4:7]
	v_mfma_f32_16x16x32_bf16 v[4:7], v[144:147], v[212:215], v[4:7]
	s_barrier
	s_setprio 0
	s_add_i32 s81, 0, 0x18000
	s_add_i32 s82, 0, 0x1c000
	v_add_u32_e32 v140, s81, v185
	v_add_u32_e32 v176, s82, v185
	s_add_u32 s62, s62, 0x40000
	s_addc_u32 s63, s63, 0
	s_mov_b32 m0, s69
	v_lshl_add_u64 v[228:229], s[62:63], 0, v[152:153]
	global_load_lds_dwordx4 v[228:229], off
	v_lshl_add_u64 v[228:229], s[62:63], 0, v[160:161]
	s_mov_b32 m0, s70
	s_nop 0
	global_load_lds_dwordx4 v[228:229], off
	ds_read_b128 v[128:131], v140
	v_xor_b32_e32 v253, 64, v140
	ds_read_b128 v[132:135], v253
	ds_read_b128 v[136:139], v140 offset:2048
	ds_read_b128 v[140:143], v253 offset:2048
	ds_read_b128 v[144:147], v176
	v_xor_b32_e32 v253, 64, v176
	ds_read_b128 v[148:151], v253
	ds_read_b128 v[172:175], v176 offset:2048
	ds_read_b128 v[176:179], v253 offset:2048
	ds_read_b128 v[180:183], v190 offset:32768
	v_xor_b32_e32 v253, 64, v190
	ds_read_b128 v[192:195], v253 offset:32768
	ds_read_b128 v[196:199], v190 offset:34816
	ds_read_b128 v[200:203], v253 offset:34816
	ds_read_b128 v[204:207], v190 offset:36864
	ds_read_b128 v[208:211], v253 offset:36864
	ds_read_b128 v[212:215], v190 offset:38912
	ds_read_b128 v[216:219], v253 offset:38912
	s_waitcnt vmcnt(8)
	s_waitcnt lgkmcnt(0)
	s_setprio 1
	s_barrier
	v_mfma_f32_16x16x32_bf16 v[124:127], v[128:131], v[180:183], v[124:127]
	v_mfma_f32_16x16x32_bf16 v[124:127], v[132:135], v[192:195], v[124:127]
	v_mfma_f32_16x16x32_bf16 v[120:123], v[140:143], v[192:195], v[120:123]
	v_mfma_f32_16x16x32_bf16 v[120:123], v[136:139], v[180:183], v[120:123]
	v_mfma_f32_16x16x32_bf16 v[104:107], v[136:139], v[196:199], v[104:107]
	v_mfma_f32_16x16x32_bf16 v[104:107], v[140:143], v[200:203], v[104:107]
	v_mfma_f32_16x16x32_bf16 v[108:111], v[132:135], v[200:203], v[108:111]
	v_mfma_f32_16x16x32_bf16 v[108:111], v[128:131], v[196:199], v[108:111]
	v_mfma_f32_16x16x32_bf16 v[92:95], v[128:131], v[204:207], v[92:95]
	v_mfma_f32_16x16x32_bf16 v[92:95], v[132:135], v[208:211], v[92:95]
	v_mfma_f32_16x16x32_bf16 v[88:91], v[140:143], v[208:211], v[88:91]
	v_mfma_f32_16x16x32_bf16 v[88:91], v[136:139], v[204:207], v[88:91]
	v_mfma_f32_16x16x32_bf16 v[72:75], v[136:139], v[212:215], v[72:75]
	v_mfma_f32_16x16x32_bf16 v[72:75], v[140:143], v[216:219], v[72:75]
	v_mfma_f32_16x16x32_bf16 v[76:79], v[132:135], v[216:219], v[76:79]
	v_mfma_f32_16x16x32_bf16 v[76:79], v[128:131], v[212:215], v[76:79]
	s_setprio 0
	s_setprio 1
	v_mfma_f32_16x16x32_bf16 v[116:119], v[144:147], v[180:183], v[116:119]
	v_mfma_f32_16x16x32_bf16 v[116:119], v[148:151], v[192:195], v[116:119]
	v_mfma_f32_16x16x32_bf16 v[112:115], v[176:179], v[192:195], v[112:115]
	v_mfma_f32_16x16x32_bf16 v[112:115], v[172:175], v[180:183], v[112:115]
	v_mfma_f32_16x16x32_bf16 v[96:99], v[172:175], v[196:199], v[96:99]
	v_mfma_f32_16x16x32_bf16 v[96:99], v[176:179], v[200:203], v[96:99]
	v_mfma_f32_16x16x32_bf16 v[100:103], v[148:151], v[200:203], v[100:103]
	v_mfma_f32_16x16x32_bf16 v[100:103], v[144:147], v[196:199], v[100:103]
	v_mfma_f32_16x16x32_bf16 v[84:87], v[144:147], v[204:207], v[84:87]
	v_mfma_f32_16x16x32_bf16 v[84:87], v[148:151], v[208:211], v[84:87]
	v_mfma_f32_16x16x32_bf16 v[80:83], v[176:179], v[208:211], v[80:83]
	v_mfma_f32_16x16x32_bf16 v[80:83], v[172:175], v[204:207], v[80:83]
	v_mfma_f32_16x16x32_bf16 v[64:67], v[172:175], v[212:215], v[64:67]
	v_mfma_f32_16x16x32_bf16 v[64:67], v[176:179], v[216:219], v[64:67]
	v_mfma_f32_16x16x32_bf16 v[68:71], v[148:151], v[216:219], v[68:71]
	v_mfma_f32_16x16x32_bf16 v[68:71], v[144:147], v[212:215], v[68:71]
	s_barrier
	s_setprio 0
	s_add_i32 s62, s81, s66
	v_lshl_add_u64 v[220:221], v[220:221], 0, s[26:27]
	s_mov_b32 m0, s62
	s_nop 0
	global_load_lds_dwordx4 v[220:221], off
	s_add_i32 m0, s62, 0x2000
	s_add_u32 s60, s60, 0x40080
	v_lshl_add_u64 v[220:221], v[222:223], 0, s[26:27]
	s_addc_u32 s61, s61, 0
	s_add_i32 s62, s82, s66
	global_load_lds_dwordx4 v[220:221], off
	v_lshl_add_u64 v[220:221], s[60:61], 0, v[154:155]
	s_mov_b32 m0, s62
	s_nop 0
	global_load_lds_dwordx4 v[220:221], off
	v_lshl_add_u64 v[220:221], s[60:61], 0, v[162:163]
	s_add_i32 m0, s62, 0x2000
	s_nop 0
	global_load_lds_dwordx4 v[220:221], off
	v_lshl_add_u64 v[220:221], v[224:225], 0, s[26:27]
	s_mov_b32 m0, s3
	s_nop 0
	global_load_lds_dwordx4 v[220:221], off
	v_lshl_add_u64 v[220:221], v[226:227], 0, s[26:27]
	s_mov_b32 m0, s72
	s_nop 0
	global_load_lds_dwordx4 v[220:221], off
	ds_read_b128 v[180:183], v190 offset:49152
	v_xor_b32_e32 v253, 64, v190
	ds_read_b128 v[192:195], v253 offset:49152
	ds_read_b128 v[196:199], v190 offset:51200
	ds_read_b128 v[200:203], v253 offset:51200
	ds_read_b128 v[204:207], v190 offset:53248
	ds_read_b128 v[208:211], v253 offset:53248
	ds_read_b128 v[212:215], v190 offset:55296
	ds_read_b128 v[216:219], v253 offset:55296
	s_waitcnt vmcnt(8)
	s_waitcnt lgkmcnt(0)
	s_setprio 1
	s_barrier
	v_mfma_f32_16x16x32_bf16 v[60:63], v[128:131], v[180:183], v[60:63]
	v_mfma_f32_16x16x32_bf16 v[60:63], v[132:135], v[192:195], v[60:63]
	v_mfma_f32_16x16x32_bf16 v[56:59], v[140:143], v[192:195], v[56:59]
	v_mfma_f32_16x16x32_bf16 v[56:59], v[136:139], v[180:183], v[56:59]
	v_mfma_f32_16x16x32_bf16 v[40:43], v[136:139], v[196:199], v[40:43]
	v_mfma_f32_16x16x32_bf16 v[40:43], v[140:143], v[200:203], v[40:43]
	v_mfma_f32_16x16x32_bf16 v[44:47], v[132:135], v[200:203], v[44:47]
	v_mfma_f32_16x16x32_bf16 v[44:47], v[128:131], v[196:199], v[44:47]
	v_mfma_f32_16x16x32_bf16 v[28:31], v[128:131], v[204:207], v[28:31]
	v_mfma_f32_16x16x32_bf16 v[28:31], v[132:135], v[208:211], v[28:31]
	v_mfma_f32_16x16x32_bf16 v[24:27], v[140:143], v[208:211], v[24:27]
	v_mfma_f32_16x16x32_bf16 v[24:27], v[136:139], v[204:207], v[24:27]
	v_mfma_f32_16x16x32_bf16 v[8:11], v[136:139], v[212:215], v[8:11]
	v_mfma_f32_16x16x32_bf16 v[8:11], v[140:143], v[216:219], v[8:11]
	v_mfma_f32_16x16x32_bf16 v[12:15], v[132:135], v[216:219], v[12:15]
	v_mfma_f32_16x16x32_bf16 v[12:15], v[128:131], v[212:215], v[12:15]
	s_setprio 0
	s_setprio 1
	v_mfma_f32_16x16x32_bf16 v[52:55], v[144:147], v[180:183], v[52:55]
	v_mfma_f32_16x16x32_bf16 v[52:55], v[148:151], v[192:195], v[52:55]
	v_mfma_f32_16x16x32_bf16 v[48:51], v[176:179], v[192:195], v[48:51]
	v_mfma_f32_16x16x32_bf16 v[48:51], v[172:175], v[180:183], v[48:51]
	v_mfma_f32_16x16x32_bf16 v[32:35], v[172:175], v[196:199], v[32:35]
	v_mfma_f32_16x16x32_bf16 v[32:35], v[176:179], v[200:203], v[32:35]
	v_mfma_f32_16x16x32_bf16 v[36:39], v[148:151], v[200:203], v[36:39]
	v_mfma_f32_16x16x32_bf16 v[36:39], v[144:147], v[196:199], v[36:39]
	v_mfma_f32_16x16x32_bf16 v[20:23], v[144:147], v[204:207], v[20:23]
	v_mfma_f32_16x16x32_bf16 v[20:23], v[148:151], v[208:211], v[20:23]
	v_mfma_f32_16x16x32_bf16 v[16:19], v[176:179], v[208:211], v[16:19]
	v_mfma_f32_16x16x32_bf16 v[16:19], v[172:175], v[204:207], v[16:19]
	v_mfma_f32_16x16x32_bf16 v[0:3], v[172:175], v[212:215], v[0:3]
	v_mfma_f32_16x16x32_bf16 v[0:3], v[176:179], v[216:219], v[0:3]
	v_mfma_f32_16x16x32_bf16 v[4:7], v[148:151], v[216:219], v[4:7]
	v_mfma_f32_16x16x32_bf16 v[4:7], v[144:147], v[212:215], v[4:7]
	s_barrier
	s_setprio 0
	s_add_i32 s80, s80, 2
	s_add_u32 s78, s78, 0x100
	s_addc_u32 s79, s79, 0
	s_add_u32 s58, s58, 0x100
	s_addc_u32 s59, s59, 0
	s_cmp_gt_u32 s80, 13
	s_cbranch_scc0 .LBB0_1011
	s_and_b64 vcc, exec, s[28:29]
	s_cbranch_vccz .LBB0_1014
	s_barrier

.LBB0_1096:
	s_ashr_i32 s25, s24, 31
	s_lshl_b64 s[26:27], s[24:25], 19
	s_add_u32 s26, s3, s26
	s_addc_u32 s27, s33, s27
	s_and_b64 s[28:29], s[6:7], exec
	s_cselect_b32 s25, s27, s47
	s_cselect_b32 s65, s26, s46
	s_ashr_i32 s23, s22, 31
	s_lshl_b64 s[28:29], s[22:23], 19
	s_add_u32 s28, s35, s28
	s_addc_u32 s29, s48, s29
	s_and_b64 s[66:67], s[6:7], exec
	s_cselect_b32 s66, s29, s45
	s_cselect_b32 s67, s28, s44
	s_lshl_b32 s23, s30, 8
	v_add_u32_e32 v0, s23, v148
	s_add_u32 s68, s44, 0x100
	v_ashrrev_i32_e32 v1, 31, v0
	s_addc_u32 s69, s45, 0
	v_lshl_add_u64 v[144:145], v[0:1], 4, s[12:13]
	s_add_u32 s30, s46, 0x40080
	s_addc_u32 s31, s47, 0
	s_mov_b32 s70, -2
	s_mov_b64 s[44:45], 0
	s_cmp_eq_u32 s56, 1
	s_cbranch_scc1 .Lfa_10
	s_add_u32 s46, s30, 0xfffc0080
	s_addc_u32 s47, s31, -1
	s_and_b64 s[44:45], s[44:45], exec
	s_cselect_b32 s47, s25, s47
	s_cselect_b32 s46, s65, s46
	s_cselect_b32 s45, s66, s69
	s_cselect_b32 s44, s67, s68
	v_lshl_add_u64 v[154:155], s[30:31], 0, v[138:139]
	s_add_i32 m0, s52, 0xc000
	s_nop 0
	global_load_lds_dwordx4 v[154:155], off
	v_lshl_add_u64 v[154:155], s[30:31], 0, v[136:137]
	s_add_i32 m0, s52, 0xe000
	s_nop 0
	global_load_lds_dwordx4 v[154:155], off
	v_add_u32_e32 v153, s61, v147
	ds_read_b128 v[160:163], v153
	v_xor_b32_e32 v253, 64, v153
	ds_read_b128 v[164:167], v253
	ds_read_b128 v[168:171], v153 offset:2048
	ds_read_b128 v[172:175], v253 offset:2048
	v_add_u32_e32 v153, s62, v147
	ds_read_b128 v[176:179], v153
	v_xor_b32_e32 v253, 64, v153
	ds_read_b128 v[180:183], v253
	ds_read_b128 v[184:187], v153 offset:2048
	ds_read_b128 v[188:191], v253 offset:2048
	ds_read_b128 v[192:195], v150
	v_xor_b32_e32 v253, 64, v150
	ds_read_b128 v[196:199], v253
	ds_read_b128 v[200:203], v150 offset:2048
	ds_read_b128 v[204:207], v253 offset:2048
	ds_read_b128 v[208:211], v150 offset:4096
	ds_read_b128 v[212:215], v253 offset:4096
	ds_read_b128 v[216:219], v150 offset:6144
	ds_read_b128 v[220:223], v253 offset:6144
	s_waitcnt vmcnt(16)
	s_waitcnt lgkmcnt(0)
	s_setprio 1
	s_barrier
	v_mfma_f32_16x16x32_bf16 v[124:127], v[160:163], v[192:195], 0
	v_mfma_f32_16x16x32_bf16 v[116:119], v[168:171], v[192:195], 0
	v_mfma_f32_16x16x32_bf16 v[108:111], v[160:163], v[200:203], 0
	v_mfma_f32_16x16x32_bf16 v[100:103], v[168:171], v[200:203], 0
	v_mfma_f32_16x16x32_bf16 v[92:95], v[160:163], v[208:211], 0
	v_mfma_f32_16x16x32_bf16 v[84:87], v[168:171], v[208:211], 0
	v_mfma_f32_16x16x32_bf16 v[76:79], v[160:163], v[216:219], 0
	v_mfma_f32_16x16x32_bf16 v[68:71], v[168:171], v[216:219], 0
	v_mfma_f32_16x16x32_bf16 v[124:127], v[164:167], v[196:199], v[124:127]
	v_mfma_f32_16x16x32_bf16 v[116:119], v[172:175], v[196:199], v[116:119]
	v_mfma_f32_16x16x32_bf16 v[108:111], v[164:167], v[204:207], v[108:111]
	v_mfma_f32_16x16x32_bf16 v[100:103], v[172:175], v[204:207], v[100:103]
	v_mfma_f32_16x16x32_bf16 v[92:95], v[164:167], v[212:215], v[92:95]
	v_mfma_f32_16x16x32_bf16 v[84:87], v[172:175], v[212:215], v[84:87]
	v_mfma_f32_16x16x32_bf16 v[76:79], v[164:167], v[220:223], v[76:79]
	v_mfma_f32_16x16x32_bf16 v[68:71], v[172:175], v[220:223], v[68:71]
	s_setprio 0
	s_setprio 1
	v_mfma_f32_16x16x32_bf16 v[120:123], v[176:179], v[192:195], 0
	v_mfma_f32_16x16x32_bf16 v[112:115], v[184:187], v[192:195], 0
	v_mfma_f32_16x16x32_bf16 v[104:107], v[176:179], v[200:203], 0
	v_mfma_f32_16x16x32_bf16 v[96:99], v[184:187], v[200:203], 0
	v_mfma_f32_16x16x32_bf16 v[88:91], v[176:179], v[208:211], 0
	v_mfma_f32_16x16x32_bf16 v[80:83], v[184:187], v[208:211], 0
	v_mfma_f32_16x16x32_bf16 v[72:75], v[176:179], v[216:219], 0
	v_mfma_f32_16x16x32_bf16 v[64:67], v[184:187], v[216:219], 0
	v_mfma_f32_16x16x32_bf16 v[120:123], v[180:183], v[196:199], v[120:123]
	v_mfma_f32_16x16x32_bf16 v[112:115], v[188:191], v[196:199], v[112:115]
	v_mfma_f32_16x16x32_bf16 v[104:107], v[180:183], v[204:207], v[104:107]
	v_mfma_f32_16x16x32_bf16 v[96:99], v[188:191], v[204:207], v[96:99]
	v_mfma_f32_16x16x32_bf16 v[88:91], v[180:183], v[212:215], v[88:91]
	v_mfma_f32_16x16x32_bf16 v[80:83], v[188:191], v[212:215], v[80:83]
	v_mfma_f32_16x16x32_bf16 v[72:75], v[180:183], v[220:223], v[72:75]
	v_mfma_f32_16x16x32_bf16 v[64:67], v[188:191], v[220:223], v[64:67]
	s_barrier
	s_setprio 0
	s_add_i32 s71, s61, s49
	v_lshl_add_u64 v[154:155], s[44:45], 0, v[132:133]
	s_mov_b32 m0, s71
	s_nop 0
	global_load_lds_dwordx4 v[154:155], off
	s_add_i32 m0, s71, 0x2000
	s_add_u32 s72, s44, 0x40000
	v_lshl_add_u64 v[224:225], s[44:45], 0, v[128:129]
	s_addc_u32 s73, s45, 0
	s_add_i32 s71, s62, s49
	global_load_lds_dwordx4 v[224:225], off
	v_lshl_add_u64 v[226:227], s[72:73], 0, v[132:133]
	s_mov_b32 m0, s71
	v_lshl_add_u64 v[228:229], s[46:47], 0, v[130:131]
	global_load_lds_dwordx4 v[226:227], off
	v_lshl_add_u64 v[226:227], s[72:73], 0, v[128:129]
	s_add_i32 m0, s71, 0x2000
	s_nop 0
	global_load_lds_dwordx4 v[226:227], off
	v_lshl_add_u64 v[226:227], s[46:47], 0, v[134:135]
	s_mov_b32 m0, s52
	s_nop 0
	global_load_lds_dwordx4 v[226:227], off
	s_mov_b32 m0, s53
	s_nop 0
	global_load_lds_dwordx4 v[228:229], off
	ds_read_b128 v[192:195], v150 offset:16384
	v_xor_b32_e32 v253, 64, v150
	ds_read_b128 v[196:199], v253 offset:16384
	ds_read_b128 v[200:203], v150 offset:18432
	ds_read_b128 v[204:207], v253 offset:18432
	ds_read_b128 v[208:211], v150 offset:20480
	ds_read_b128 v[212:215], v253 offset:20480
	ds_read_b128 v[216:219], v150 offset:22528
	ds_read_b128 v[220:223], v253 offset:22528
	s_waitcnt vmcnt(16)
	s_waitcnt lgkmcnt(0)
	s_setprio 1
	s_barrier
	v_mfma_f32_16x16x32_bf16 v[60:63], v[160:163], v[192:195], 0
	v_mfma_f32_16x16x32_bf16 v[52:55], v[168:171], v[192:195], 0
	v_mfma_f32_16x16x32_bf16 v[44:47], v[160:163], v[200:203], 0
	v_mfma_f32_16x16x32_bf16 v[36:39], v[168:171], v[200:203], 0
	v_mfma_f32_16x16x32_bf16 v[28:31], v[160:163], v[208:211], 0
	v_mfma_f32_16x16x32_bf16 v[20:23], v[168:171], v[208:211], 0
	v_mfma_f32_16x16x32_bf16 v[12:15], v[160:163], v[216:219], 0
	v_mfma_f32_16x16x32_bf16 v[4:7], v[168:171], v[216:219], 0
	v_mfma_f32_16x16x32_bf16 v[60:63], v[164:167], v[196:199], v[60:63]
	v_mfma_f32_16x16x32_bf16 v[52:55], v[172:175], v[196:199], v[52:55]
	v_mfma_f32_16x16x32_bf16 v[44:47], v[164:167], v[204:207], v[44:47]
	v_mfma_f32_16x16x32_bf16 v[36:39], v[172:175], v[204:207], v[36:39]
	v_mfma_f32_16x16x32_bf16 v[28:31], v[164:167], v[212:215], v[28:31]
	v_mfma_f32_16x16x32_bf16 v[20:23], v[172:175], v[212:215], v[20:23]
	v_mfma_f32_16x16x32_bf16 v[12:15], v[164:167], v[220:223], v[12:15]
	v_mfma_f32_16x16x32_bf16 v[4:7], v[172:175], v[220:223], v[4:7]
	s_setprio 0
	s_setprio 1
	v_mfma_f32_16x16x32_bf16 v[56:59], v[176:179], v[192:195], 0
	v_mfma_f32_16x16x32_bf16 v[48:51], v[184:187], v[192:195], 0
	v_mfma_f32_16x16x32_bf16 v[40:43], v[176:179], v[200:203], 0
	v_mfma_f32_16x16x32_bf16 v[32:35], v[184:187], v[200:203], 0
	v_mfma_f32_16x16x32_bf16 v[24:27], v[176:179], v[208:211], 0
	v_mfma_f32_16x16x32_bf16 v[16:19], v[184:187], v[208:211], 0
	v_mfma_f32_16x16x32_bf16 v[8:11], v[176:179], v[216:219], 0
	v_mfma_f32_16x16x32_bf16 v[0:3], v[184:187], v[216:219], 0
	v_mfma_f32_16x16x32_bf16 v[56:59], v[180:183], v[196:199], v[56:59]
	v_mfma_f32_16x16x32_bf16 v[48:51], v[188:191], v[196:199], v[48:51]
	v_mfma_f32_16x16x32_bf16 v[40:43], v[180:183], v[204:207], v[40:43]
	v_mfma_f32_16x16x32_bf16 v[32:35], v[188:191], v[204:207], v[32:35]
	v_mfma_f32_16x16x32_bf16 v[24:27], v[180:183], v[212:215], v[24:27]
	v_mfma_f32_16x16x32_bf16 v[16:19], v[188:191], v[212:215], v[16:19]
	v_mfma_f32_16x16x32_bf16 v[8:11], v[180:183], v[220:223], v[8:11]
	v_mfma_f32_16x16x32_bf16 v[0:3], v[188:191], v[220:223], v[0:3]
	s_barrier
	s_setprio 0
	s_add_i32 s71, 0, 0x18000
	s_add_i32 s72, 0, 0x1c000
	s_add_u32 s46, s46, 0x40000
	s_addc_u32 s47, s47, 0
	s_mov_b32 m0, s54
	v_lshl_add_u64 v[230:231], s[46:47], 0, v[134:135]
	global_load_lds_dwordx4 v[230:231], off
	v_lshl_add_u64 v[230:231], s[46:47], 0, v[130:131]
	s_mov_b32 m0, s55
	s_nop 0
	global_load_lds_dwordx4 v[230:231], off
	v_add_u32_e32 v153, s71, v147
	ds_read_b128 v[160:163], v153
	v_xor_b32_e32 v253, 64, v153
	ds_read_b128 v[164:167], v253
	ds_read_b128 v[168:171], v153 offset:2048
	ds_read_b128 v[172:175], v253 offset:2048
	v_add_u32_e32 v153, s72, v147
	ds_read_b128 v[176:179], v153
	v_xor_b32_e32 v253, 64, v153
	ds_read_b128 v[180:183], v253
	ds_read_b128 v[184:187], v153 offset:2048
	ds_read_b128 v[188:191], v253 offset:2048
	ds_read_b128 v[192:195], v150 offset:32768
	v_xor_b32_e32 v253, 64, v150
	ds_read_b128 v[196:199], v253 offset:32768
	ds_read_b128 v[200:203], v150 offset:34816
	ds_read_b128 v[204:207], v253 offset:34816
	ds_read_b128 v[208:211], v150 offset:36864
	ds_read_b128 v[212:215], v253 offset:36864
	ds_read_b128 v[216:219], v150 offset:38912
	ds_read_b128 v[220:223], v253 offset:38912
	s_waitcnt vmcnt(8)
	s_waitcnt lgkmcnt(0)
	s_setprio 1
	s_barrier
	v_mfma_f32_16x16x32_bf16 v[124:127], v[160:163], v[192:195], v[124:127]
	v_mfma_f32_16x16x32_bf16 v[124:127], v[164:167], v[196:199], v[124:127]
	v_mfma_f32_16x16x32_bf16 v[116:119], v[172:175], v[196:199], v[116:119]
	v_mfma_f32_16x16x32_bf16 v[116:119], v[168:171], v[192:195], v[116:119]
	v_mfma_f32_16x16x32_bf16 v[100:103], v[168:171], v[200:203], v[100:103]
	v_mfma_f32_16x16x32_bf16 v[100:103], v[172:175], v[204:207], v[100:103]
	v_mfma_f32_16x16x32_bf16 v[108:111], v[164:167], v[204:207], v[108:111]
	v_mfma_f32_16x16x32_bf16 v[108:111], v[160:163], v[200:203], v[108:111]
	v_mfma_f32_16x16x32_bf16 v[92:95], v[160:163], v[208:211], v[92:95]
	v_mfma_f32_16x16x32_bf16 v[92:95], v[164:167], v[212:215], v[92:95]
	v_mfma_f32_16x16x32_bf16 v[84:87], v[172:175], v[212:215], v[84:87]
	v_mfma_f32_16x16x32_bf16 v[84:87], v[168:171], v[208:211], v[84:87]
	v_mfma_f32_16x16x32_bf16 v[68:71], v[168:171], v[216:219], v[68:71]
	v_mfma_f32_16x16x32_bf16 v[68:71], v[172:175], v[220:223], v[68:71]
	v_mfma_f32_16x16x32_bf16 v[76:79], v[164:167], v[220:223], v[76:79]
	v_mfma_f32_16x16x32_bf16 v[76:79], v[160:163], v[216:219], v[76:79]
	s_setprio 0
	s_setprio 1
	v_mfma_f32_16x16x32_bf16 v[120:123], v[176:179], v[192:195], v[120:123]
	v_mfma_f32_16x16x32_bf16 v[120:123], v[180:183], v[196:199], v[120:123]
	v_mfma_f32_16x16x32_bf16 v[112:115], v[188:191], v[196:199], v[112:115]
	v_mfma_f32_16x16x32_bf16 v[112:115], v[184:187], v[192:195], v[112:115]
	v_mfma_f32_16x16x32_bf16 v[96:99], v[184:187], v[200:203], v[96:99]
	v_mfma_f32_16x16x32_bf16 v[96:99], v[188:191], v[204:207], v[96:99]
	v_mfma_f32_16x16x32_bf16 v[104:107], v[180:183], v[204:207], v[104:107]
	v_mfma_f32_16x16x32_bf16 v[104:107], v[176:179], v[200:203], v[104:107]
	v_mfma_f32_16x16x32_bf16 v[88:91], v[176:179], v[208:211], v[88:91]
	v_mfma_f32_16x16x32_bf16 v[88:91], v[180:183], v[212:215], v[88:91]
	v_mfma_f32_16x16x32_bf16 v[80:83], v[188:191], v[212:215], v[80:83]
	v_mfma_f32_16x16x32_bf16 v[80:83], v[184:187], v[208:211], v[80:83]
	v_mfma_f32_16x16x32_bf16 v[64:67], v[184:187], v[216:219], v[64:67]
	v_mfma_f32_16x16x32_bf16 v[64:67], v[188:191], v[220:223], v[64:67]
	v_mfma_f32_16x16x32_bf16 v[72:75], v[180:183], v[220:223], v[72:75]
	v_mfma_f32_16x16x32_bf16 v[72:75], v[176:179], v[216:219], v[72:75]
	s_barrier
	s_setprio 0
	s_add_i32 s46, s71, s49
	v_lshl_add_u64 v[154:155], v[154:155], 0, s[14:15]
	s_mov_b32 m0, s46
	s_nop 0
	global_load_lds_dwordx4 v[154:155], off
	s_add_i32 m0, s46, 0x2000
	s_add_u32 s44, s44, 0x40080
	v_lshl_add_u64 v[154:155], v[224:225], 0, s[14:15]
	s_addc_u32 s45, s45, 0
	s_add_i32 s46, s72, s49
	global_load_lds_dwordx4 v[154:155], off
	v_lshl_add_u64 v[154:155], s[44:45], 0, v[132:133]
	s_mov_b32 m0, s46
	s_nop 0
	global_load_lds_dwordx4 v[154:155], off
	v_lshl_add_u64 v[154:155], s[44:45], 0, v[128:129]
	s_add_i32 m0, s46, 0x2000
	s_nop 0
	global_load_lds_dwordx4 v[154:155], off
	v_lshl_add_u64 v[154:155], v[226:227], 0, s[14:15]
	s_mov_b32 m0, s57
	s_nop 0
	global_load_lds_dwordx4 v[154:155], off
	v_lshl_add_u64 v[154:155], v[228:229], 0, s[14:15]
	s_mov_b32 m0, s58
	s_nop 0
	global_load_lds_dwordx4 v[154:155], off
	ds_read_b128 v[192:195], v150 offset:49152
	v_xor_b32_e32 v253, 64, v150
	ds_read_b128 v[196:199], v253 offset:49152
	ds_read_b128 v[200:203], v150 offset:51200
	ds_read_b128 v[204:207], v253 offset:51200
	ds_read_b128 v[208:211], v150 offset:53248
	ds_read_b128 v[212:215], v253 offset:53248
	ds_read_b128 v[216:219], v150 offset:55296
	ds_read_b128 v[220:223], v253 offset:55296
	s_waitcnt vmcnt(8)
	s_waitcnt lgkmcnt(0)
	s_setprio 1
	s_barrier
	v_mfma_f32_16x16x32_bf16 v[60:63], v[160:163], v[192:195], v[60:63]
	v_mfma_f32_16x16x32_bf16 v[60:63], v[164:167], v[196:199], v[60:63]
	v_mfma_f32_16x16x32_bf16 v[52:55], v[172:175], v[196:199], v[52:55]
	v_mfma_f32_16x16x32_bf16 v[52:55], v[168:171], v[192:195], v[52:55]
	v_mfma_f32_16x16x32_bf16 v[36:39], v[168:171], v[200:203], v[36:39]
	v_mfma_f32_16x16x32_bf16 v[36:39], v[172:175], v[204:207], v[36:39]
	v_mfma_f32_16x16x32_bf16 v[44:47], v[164:167], v[204:207], v[44:47]
	v_mfma_f32_16x16x32_bf16 v[44:47], v[160:163], v[200:203], v[44:47]
	v_mfma_f32_16x16x32_bf16 v[28:31], v[160:163], v[208:211], v[28:31]
	v_mfma_f32_16x16x32_bf16 v[28:31], v[164:167], v[212:215], v[28:31]
	v_mfma_f32_16x16x32_bf16 v[20:23], v[172:175], v[212:215], v[20:23]
	v_mfma_f32_16x16x32_bf16 v[20:23], v[168:171], v[208:211], v[20:23]
	v_mfma_f32_16x16x32_bf16 v[4:7], v[168:171], v[216:219], v[4:7]
	v_mfma_f32_16x16x32_bf16 v[4:7], v[172:175], v[220:223], v[4:7]
	v_mfma_f32_16x16x32_bf16 v[12:15], v[164:167], v[220:223], v[12:15]
	v_mfma_f32_16x16x32_bf16 v[12:15], v[160:163], v[216:219], v[12:15]
	s_setprio 0
	s_setprio 1
	v_mfma_f32_16x16x32_bf16 v[56:59], v[176:179], v[192:195], v[56:59]
	v_mfma_f32_16x16x32_bf16 v[56:59], v[180:183], v[196:199], v[56:59]
	v_mfma_f32_16x16x32_bf16 v[48:51], v[188:191], v[196:199], v[48:51]
	v_mfma_f32_16x16x32_bf16 v[48:51], v[184:187], v[192:195], v[48:51]
	v_mfma_f32_16x16x32_bf16 v[32:35], v[184:187], v[200:203], v[32:35]
	v_mfma_f32_16x16x32_bf16 v[32:35], v[188:191], v[204:207], v[32:35]
	v_mfma_f32_16x16x32_bf16 v[40:43], v[180:183], v[204:207], v[40:43]
	v_mfma_f32_16x16x32_bf16 v[40:43], v[176:179], v[200:203], v[40:43]
	v_mfma_f32_16x16x32_bf16 v[24:27], v[176:179], v[208:211], v[24:27]
	v_mfma_f32_16x16x32_bf16 v[24:27], v[180:183], v[212:215], v[24:27]
	v_mfma_f32_16x16x32_bf16 v[16:19], v[188:191], v[212:215], v[16:19]
	v_mfma_f32_16x16x32_bf16 v[16:19], v[184:187], v[208:211], v[16:19]
	v_mfma_f32_16x16x32_bf16 v[0:3], v[184:187], v[216:219], v[0:3]
	v_mfma_f32_16x16x32_bf16 v[0:3], v[188:191], v[220:223], v[0:3]
	v_mfma_f32_16x16x32_bf16 v[8:11], v[180:183], v[220:223], v[8:11]
	v_mfma_f32_16x16x32_bf16 v[8:11], v[176:179], v[216:219], v[8:11]
	s_barrier
	s_setprio 0
	s_add_i32 s70, s70, 2
	s_add_u32 s68, s68, 0x100
	s_addc_u32 s69, s69, 0
	s_add_u32 s30, s30, 0x100
	s_addc_u32 s31, s31, 0
	s_branch .LBB0_1098
.Lfa_10:
	s_add_u32 s46, s30, 0xfffc0080
	s_addc_u32 s47, s31, -1
	s_and_b64 s[44:45], s[44:45], exec
	s_cselect_b32 s47, s25, s47
	s_cselect_b32 s46, s65, s46
	s_cselect_b32 s45, s66, s69
	s_cselect_b32 s44, s67, s68
	v_lshl_add_u64 v[154:155], s[30:31], 0, v[138:139]
	s_add_i32 m0, s52, 0xc000
	s_nop 0
	global_load_lds_dwordx4 v[154:155], off
	v_lshl_add_u64 v[154:155], s[30:31], 0, v[136:137]
	s_add_i32 m0, s52, 0xe000
	s_nop 0
	global_load_lds_dwordx4 v[154:155], off
	v_add_u32_e32 v153, s61, v147
	ds_read_b128 v[160:163], v153
	v_xor_b32_e32 v253, 64, v153
	ds_read_b128 v[164:167], v253
	ds_read_b128 v[168:171], v153 offset:2048
	ds_read_b128 v[172:175], v253 offset:2048
	v_add_u32_e32 v153, s62, v147
	ds_read_b128 v[176:179], v153
	v_xor_b32_e32 v253, 64, v153
	ds_read_b128 v[180:183], v253
	ds_read_b128 v[184:187], v153 offset:2048
	ds_read_b128 v[188:191], v253 offset:2048
	ds_read_b128 v[192:195], v150
	v_xor_b32_e32 v253, 64, v150
	ds_read_b128 v[196:199], v253
	ds_read_b128 v[200:203], v150 offset:2048
	ds_read_b128 v[204:207], v253 offset:2048
	ds_read_b128 v[208:211], v150 offset:4096
	ds_read_b128 v[212:215], v253 offset:4096
	ds_read_b128 v[216:219], v150 offset:6144
	ds_read_b128 v[220:223], v253 offset:6144
	s_waitcnt vmcnt(8)
	s_waitcnt lgkmcnt(0)
	s_setprio 1
	s_barrier
	v_mfma_f32_16x16x32_bf16 v[124:127], v[160:163], v[192:195], 0
	v_mfma_f32_16x16x32_bf16 v[116:119], v[168:171], v[192:195], 0
	v_mfma_f32_16x16x32_bf16 v[108:111], v[160:163], v[200:203], 0
	v_mfma_f32_16x16x32_bf16 v[100:103], v[168:171], v[200:203], 0
	v_mfma_f32_16x16x32_bf16 v[92:95], v[160:163], v[208:211], 0
	v_mfma_f32_16x16x32_bf16 v[84:87], v[168:171], v[208:211], 0
	v_mfma_f32_16x16x32_bf16 v[76:79], v[160:163], v[216:219], 0
	v_mfma_f32_16x16x32_bf16 v[68:71], v[168:171], v[216:219], 0
	v_mfma_f32_16x16x32_bf16 v[124:127], v[164:167], v[196:199], v[124:127]
	v_mfma_f32_16x16x32_bf16 v[116:119], v[172:175], v[196:199], v[116:119]
	v_mfma_f32_16x16x32_bf16 v[108:111], v[164:167], v[204:207], v[108:111]
	v_mfma_f32_16x16x32_bf16 v[100:103], v[172:175], v[204:207], v[100:103]
	v_mfma_f32_16x16x32_bf16 v[92:95], v[164:167], v[212:215], v[92:95]
	v_mfma_f32_16x16x32_bf16 v[84:87], v[172:175], v[212:215], v[84:87]
	v_mfma_f32_16x16x32_bf16 v[76:79], v[164:167], v[220:223], v[76:79]
	v_mfma_f32_16x16x32_bf16 v[68:71], v[172:175], v[220:223], v[68:71]
	s_setprio 0
	s_setprio 1
	v_mfma_f32_16x16x32_bf16 v[120:123], v[176:179], v[192:195], 0
	v_mfma_f32_16x16x32_bf16 v[112:115], v[184:187], v[192:195], 0
	v_mfma_f32_16x16x32_bf16 v[104:107], v[176:179], v[200:203], 0
	v_mfma_f32_16x16x32_bf16 v[96:99], v[184:187], v[200:203], 0
	v_mfma_f32_16x16x32_bf16 v[88:91], v[176:179], v[208:211], 0
	v_mfma_f32_16x16x32_bf16 v[80:83], v[184:187], v[208:211], 0
	v_mfma_f32_16x16x32_bf16 v[72:75], v[176:179], v[216:219], 0
	v_mfma_f32_16x16x32_bf16 v[64:67], v[184:187], v[216:219], 0
	v_mfma_f32_16x16x32_bf16 v[120:123], v[180:183], v[196:199], v[120:123]
	v_mfma_f32_16x16x32_bf16 v[112:115], v[188:191], v[196:199], v[112:115]
	v_mfma_f32_16x16x32_bf16 v[104:107], v[180:183], v[204:207], v[104:107]
	v_mfma_f32_16x16x32_bf16 v[96:99], v[188:191], v[204:207], v[96:99]
	v_mfma_f32_16x16x32_bf16 v[88:91], v[180:183], v[212:215], v[88:91]
	v_mfma_f32_16x16x32_bf16 v[80:83], v[188:191], v[212:215], v[80:83]
	v_mfma_f32_16x16x32_bf16 v[72:75], v[180:183], v[220:223], v[72:75]
	v_mfma_f32_16x16x32_bf16 v[64:67], v[188:191], v[220:223], v[64:67]
	s_barrier
	s_setprio 0
	s_add_i32 s71, s61, s49
	v_lshl_add_u64 v[154:155], s[44:45], 0, v[132:133]
	s_mov_b32 m0, s71
	s_nop 0
	global_load_lds_dwordx4 v[154:155], off
	s_add_i32 m0, s71, 0x2000
	s_add_u32 s72, s44, 0x40000
	v_lshl_add_u64 v[224:225], s[44:45], 0, v[128:129]
	s_addc_u32 s73, s45, 0
	s_add_i32 s71, s62, s49
	global_load_lds_dwordx4 v[224:225], off
	v_lshl_add_u64 v[226:227], s[72:73], 0, v[132:133]
	s_mov_b32 m0, s71
	v_lshl_add_u64 v[228:229], s[46:47], 0, v[130:131]
	global_load_lds_dwordx4 v[226:227], off
	v_lshl_add_u64 v[226:227], s[72:73], 0, v[128:129]
	s_add_i32 m0, s71, 0x2000
	s_nop 0
	global_load_lds_dwordx4 v[226:227], off
	v_lshl_add_u64 v[226:227], s[46:47], 0, v[134:135]
	s_mov_b32 m0, s52
	s_nop 0
	global_load_lds_dwordx4 v[226:227], off
	s_mov_b32 m0, s53
	s_nop 0
	global_load_lds_dwordx4 v[228:229], off
	ds_read_b128 v[192:195], v150 offset:16384
	v_xor_b32_e32 v253, 64, v150
	ds_read_b128 v[196:199], v253 offset:16384
	ds_read_b128 v[200:203], v150 offset:18432
	ds_read_b128 v[204:207], v253 offset:18432
	ds_read_b128 v[208:211], v150 offset:20480
	ds_read_b128 v[212:215], v253 offset:20480
	ds_read_b128 v[216:219], v150 offset:22528
	ds_read_b128 v[220:223], v253 offset:22528
	s_waitcnt vmcnt(8)
	s_waitcnt lgkmcnt(0)
	s_setprio 1
	s_barrier
	v_mfma_f32_16x16x32_bf16 v[60:63], v[160:163], v[192:195], 0
	v_mfma_f32_16x16x32_bf16 v[52:55], v[168:171], v[192:195], 0
	v_mfma_f32_16x16x32_bf16 v[44:47], v[160:163], v[200:203], 0
	v_mfma_f32_16x16x32_bf16 v[36:39], v[168:171], v[200:203], 0
	v_mfma_f32_16x16x32_bf16 v[28:31], v[160:163], v[208:211], 0
	v_mfma_f32_16x16x32_bf16 v[20:23], v[168:171], v[208:211], 0
	v_mfma_f32_16x16x32_bf16 v[12:15], v[160:163], v[216:219], 0
	v_mfma_f32_16x16x32_bf16 v[4:7], v[168:171], v[216:219], 0
	v_mfma_f32_16x16x32_bf16 v[60:63], v[164:167], v[196:199], v[60:63]
	v_mfma_f32_16x16x32_bf16 v[52:55], v[172:175], v[196:199], v[52:55]
	v_mfma_f32_16x16x32_bf16 v[44:47], v[164:167], v[204:207], v[44:47]
	v_mfma_f32_16x16x32_bf16 v[36:39], v[172:175], v[204:207], v[36:39]
	v_mfma_f32_16x16x32_bf16 v[28:31], v[164:167], v[212:215], v[28:31]
	v_mfma_f32_16x16x32_bf16 v[20:23], v[172:175], v[212:215], v[20:23]
	v_mfma_f32_16x16x32_bf16 v[12:15], v[164:167], v[220:223], v[12:15]
	v_mfma_f32_16x16x32_bf16 v[4:7], v[172:175], v[220:223], v[4:7]
	s_setprio 0
	s_setprio 1
	v_mfma_f32_16x16x32_bf16 v[56:59], v[176:179], v[192:195], 0
	v_mfma_f32_16x16x32_bf16 v[48:51], v[184:187], v[192:195], 0
	v_mfma_f32_16x16x32_bf16 v[40:43], v[176:179], v[200:203], 0
	v_mfma_f32_16x16x32_bf16 v[32:35], v[184:187], v[200:203], 0
	v_mfma_f32_16x16x32_bf16 v[24:27], v[176:179], v[208:211], 0
	v_mfma_f32_16x16x32_bf16 v[16:19], v[184:187], v[208:211], 0
	v_mfma_f32_16x16x32_bf16 v[8:11], v[176:179], v[216:219], 0
	v_mfma_f32_16x16x32_bf16 v[0:3], v[184:187], v[216:219], 0
	v_mfma_f32_16x16x32_bf16 v[56:59], v[180:183], v[196:199], v[56:59]
	v_mfma_f32_16x16x32_bf16 v[48:51], v[188:191], v[196:199], v[48:51]
	v_mfma_f32_16x16x32_bf16 v[40:43], v[180:183], v[204:207], v[40:43]
	v_mfma_f32_16x16x32_bf16 v[32:35], v[188:191], v[204:207], v[32:35]
	v_mfma_f32_16x16x32_bf16 v[24:27], v[180:183], v[212:215], v[24:27]
	v_mfma_f32_16x16x32_bf16 v[16:19], v[188:191], v[212:215], v[16:19]
	v_mfma_f32_16x16x32_bf16 v[8:11], v[180:183], v[220:223], v[8:11]
	v_mfma_f32_16x16x32_bf16 v[0:3], v[188:191], v[220:223], v[0:3]
	s_barrier
	s_setprio 0
	s_add_i32 s71, 0, 0x18000
	s_add_i32 s72, 0, 0x1c000
	s_add_u32 s46, s46, 0x40000
	s_addc_u32 s47, s47, 0
	s_mov_b32 m0, s54
	v_lshl_add_u64 v[230:231], s[46:47], 0, v[134:135]
	global_load_lds_dwordx4 v[230:231], off
	v_lshl_add_u64 v[230:231], s[46:47], 0, v[130:131]
	s_mov_b32 m0, s55
	s_nop 0
	global_load_lds_dwordx4 v[230:231], off
	v_add_u32_e32 v153, s71, v147
	ds_read_b128 v[160:163], v153
	v_xor_b32_e32 v253, 64, v153
	ds_read_b128 v[164:167], v253
	ds_read_b128 v[168:171], v153 offset:2048
	ds_read_b128 v[172:175], v253 offset:2048
	v_add_u32_e32 v153, s72, v147
	ds_read_b128 v[176:179], v153
	v_xor_b32_e32 v253, 64, v153
	ds_read_b128 v[180:183], v253
	ds_read_b128 v[184:187], v153 offset:2048
	ds_read_b128 v[188:191], v253 offset:2048
	ds_read_b128 v[192:195], v150 offset:32768
	v_xor_b32_e32 v253, 64, v150
	ds_read_b128 v[196:199], v253 offset:32768
	ds_read_b128 v[200:203], v150 offset:34816
	ds_read_b128 v[204:207], v253 offset:34816
	ds_read_b128 v[208:211], v150 offset:36864
	ds_read_b128 v[212:215], v253 offset:36864
	ds_read_b128 v[216:219], v150 offset:38912
	ds_read_b128 v[220:223], v253 offset:38912
	s_waitcnt vmcnt(8)
	s_waitcnt lgkmcnt(0)
	s_setprio 1
	s_barrier
	v_mfma_f32_16x16x32_bf16 v[124:127], v[160:163], v[192:195], v[124:127]
	v_mfma_f32_16x16x32_bf16 v[124:127], v[164:167], v[196:199], v[124:127]
	v_mfma_f32_16x16x32_bf16 v[116:119], v[172:175], v[196:199], v[116:119]
	v_mfma_f32_16x16x32_bf16 v[116:119], v[168:171], v[192:195], v[116:119]
	v_mfma_f32_16x16x32_bf16 v[100:103], v[168:171], v[200:203], v[100:103]
	v_mfma_f32_16x16x32_bf16 v[100:103], v[172:175], v[204:207], v[100:103]
	v_mfma_f32_16x16x32_bf16 v[108:111], v[164:167], v[204:207], v[108:111]
	v_mfma_f32_16x16x32_bf16 v[108:111], v[160:163], v[200:203], v[108:111]
	v_mfma_f32_16x16x32_bf16 v[92:95], v[160:163], v[208:211], v[92:95]
	v_mfma_f32_16x16x32_bf16 v[92:95], v[164:167], v[212:215], v[92:95]
	v_mfma_f32_16x16x32_bf16 v[84:87], v[172:175], v[212:215], v[84:87]
	v_mfma_f32_16x16x32_bf16 v[84:87], v[168:171], v[208:211], v[84:87]
	v_mfma_f32_16x16x32_bf16 v[68:71], v[168:171], v[216:219], v[68:71]
	v_mfma_f32_16x16x32_bf16 v[68:71], v[172:175], v[220:223], v[68:71]
	v_mfma_f32_16x16x32_bf16 v[76:79], v[164:167], v[220:223], v[76:79]
	v_mfma_f32_16x16x32_bf16 v[76:79], v[160:163], v[216:219], v[76:79]
	s_setprio 0
	s_setprio 1
	v_mfma_f32_16x16x32_bf16 v[120:123], v[176:179], v[192:195], v[120:123]
	v_mfma_f32_16x16x32_bf16 v[120:123], v[180:183], v[196:199], v[120:123]
	v_mfma_f32_16x16x32_bf16 v[112:115], v[188:191], v[196:199], v[112:115]
	v_mfma_f32_16x16x32_bf16 v[112:115], v[184:187], v[192:195], v[112:115]
	v_mfma_f32_16x16x32_bf16 v[96:99], v[184:187], v[200:203], v[96:99]
	v_mfma_f32_16x16x32_bf16 v[96:99], v[188:191], v[204:207], v[96:99]
	v_mfma_f32_16x16x32_bf16 v[104:107], v[180:183], v[204:207], v[104:107]
	v_mfma_f32_16x16x32_bf16 v[104:107], v[176:179], v[200:203], v[104:107]
	v_mfma_f32_16x16x32_bf16 v[88:91], v[176:179], v[208:211], v[88:91]
	v_mfma_f32_16x16x32_bf16 v[88:91], v[180:183], v[212:215], v[88:91]
	v_mfma_f32_16x16x32_bf16 v[80:83], v[188:191], v[212:215], v[80:83]
	v_mfma_f32_16x16x32_bf16 v[80:83], v[184:187], v[208:211], v[80:83]
	v_mfma_f32_16x16x32_bf16 v[64:67], v[184:187], v[216:219], v[64:67]
	v_mfma_f32_16x16x32_bf16 v[64:67], v[188:191], v[220:223], v[64:67]
	v_mfma_f32_16x16x32_bf16 v[72:75], v[180:183], v[220:223], v[72:75]
	v_mfma_f32_16x16x32_bf16 v[72:75], v[176:179], v[216:219], v[72:75]
	s_barrier
	s_setprio 0
	s_add_i32 s46, s71, s49
	v_lshl_add_u64 v[154:155], v[154:155], 0, s[14:15]
	s_mov_b32 m0, s46
	s_nop 0
	global_load_lds_dwordx4 v[154:155], off
	s_add_i32 m0, s46, 0x2000
	s_add_u32 s44, s44, 0x40080
	v_lshl_add_u64 v[154:155], v[224:225], 0, s[14:15]
	s_addc_u32 s45, s45, 0
	s_add_i32 s46, s72, s49
	global_load_lds_dwordx4 v[154:155], off
	v_lshl_add_u64 v[154:155], s[44:45], 0, v[132:133]
	s_mov_b32 m0, s46
	s_nop 0
	global_load_lds_dwordx4 v[154:155], off
	v_lshl_add_u64 v[154:155], s[44:45], 0, v[128:129]
	s_add_i32 m0, s46, 0x2000
	s_nop 0
	global_load_lds_dwordx4 v[154:155], off
	v_lshl_add_u64 v[154:155], v[226:227], 0, s[14:15]
	s_mov_b32 m0, s57
	s_nop 0
	global_load_lds_dwordx4 v[154:155], off
	v_lshl_add_u64 v[154:155], v[228:229], 0, s[14:15]
	s_mov_b32 m0, s58
	s_nop 0
	global_load_lds_dwordx4 v[154:155], off
	ds_read_b128 v[192:195], v150 offset:49152
	v_xor_b32_e32 v253, 64, v150
	ds_read_b128 v[196:199], v253 offset:49152
	ds_read_b128 v[200:203], v150 offset:51200
	ds_read_b128 v[204:207], v253 offset:51200
	ds_read_b128 v[208:211], v150 offset:53248
	ds_read_b128 v[212:215], v253 offset:53248
	ds_read_b128 v[216:219], v150 offset:55296
	ds_read_b128 v[220:223], v253 offset:55296
	s_waitcnt vmcnt(8)
	s_waitcnt lgkmcnt(0)
	s_setprio 1
	s_barrier
	v_mfma_f32_16x16x32_bf16 v[60:63], v[160:163], v[192:195], v[60:63]
	v_mfma_f32_16x16x32_bf16 v[60:63], v[164:167], v[196:199], v[60:63]
	v_mfma_f32_16x16x32_bf16 v[52:55], v[172:175], v[196:199], v[52:55]
	v_mfma_f32_16x16x32_bf16 v[52:55], v[168:171], v[192:195], v[52:55]
	v_mfma_f32_16x16x32_bf16 v[36:39], v[168:171], v[200:203], v[36:39]
	v_mfma_f32_16x16x32_bf16 v[36:39], v[172:175], v[204:207], v[36:39]
	v_mfma_f32_16x16x32_bf16 v[44:47], v[164:167], v[204:207], v[44:47]
	v_mfma_f32_16x16x32_bf16 v[44:47], v[160:163], v[200:203], v[44:47]
	v_mfma_f32_16x16x32_bf16 v[28:31], v[160:163], v[208:211], v[28:31]
	v_mfma_f32_16x16x32_bf16 v[28:31], v[164:167], v[212:215], v[28:31]
	v_mfma_f32_16x16x32_bf16 v[20:23], v[172:175], v[212:215], v[20:23]
	v_mfma_f32_16x16x32_bf16 v[20:23], v[168:171], v[208:211], v[20:23]
	v_mfma_f32_16x16x32_bf16 v[4:7], v[168:171], v[216:219], v[4:7]
	v_mfma_f32_16x16x32_bf16 v[4:7], v[172:175], v[220:223], v[4:7]
	v_mfma_f32_16x16x32_bf16 v[12:15], v[164:167], v[220:223], v[12:15]
	v_mfma_f32_16x16x32_bf16 v[12:15], v[160:163], v[216:219], v[12:15]
	s_setprio 0
	s_setprio 1
	v_mfma_f32_16x16x32_bf16 v[56:59], v[176:179], v[192:195], v[56:59]
	v_mfma_f32_16x16x32_bf16 v[56:59], v[180:183], v[196:199], v[56:59]
	v_mfma_f32_16x16x32_bf16 v[48:51], v[188:191], v[196:199], v[48:51]
	v_mfma_f32_16x16x32_bf16 v[48:51], v[184:187], v[192:195], v[48:51]
	v_mfma_f32_16x16x32_bf16 v[32:35], v[184:187], v[200:203], v[32:35]
	v_mfma_f32_16x16x32_bf16 v[32:35], v[188:191], v[204:207], v[32:35]
	v_mfma_f32_16x16x32_bf16 v[40:43], v[180:183], v[204:207], v[40:43]
	v_mfma_f32_16x16x32_bf16 v[40:43], v[176:179], v[200:203], v[40:43]
	v_mfma_f32_16x16x32_bf16 v[24:27], v[176:179], v[208:211], v[24:27]
	v_mfma_f32_16x16x32_bf16 v[24:27], v[180:183], v[212:215], v[24:27]
	v_mfma_f32_16x16x32_bf16 v[16:19], v[188:191], v[212:215], v[16:19]
	v_mfma_f32_16x16x32_bf16 v[16:19], v[184:187], v[208:211], v[16:19]
	v_mfma_f32_16x16x32_bf16 v[0:3], v[184:187], v[216:219], v[0:3]
	v_mfma_f32_16x16x32_bf16 v[0:3], v[188:191], v[220:223], v[0:3]
	v_mfma_f32_16x16x32_bf16 v[8:11], v[180:183], v[220:223], v[8:11]
	v_mfma_f32_16x16x32_bf16 v[8:11], v[176:179], v[216:219], v[8:11]
	s_barrier
	s_setprio 0
	s_add_i32 s70, s70, 2
	s_add_u32 s68, s68, 0x100
	s_addc_u32 s69, s69, 0
	s_add_u32 s30, s30, 0x100
	s_addc_u32 s31, s31, 0
	s_branch .LBB0_1098
.LBB0_1097:
	s_add_u32 s46, s30, 0xfffc0080
	s_addc_u32 s47, s31, -1
	s_and_b64 s[44:45], s[44:45], exec
	s_cselect_b32 s47, s25, s47
	s_cselect_b32 s46, s65, s46
	s_cselect_b32 s45, s66, s69
	s_cselect_b32 s44, s67, s68
	v_lshl_add_u64 v[154:155], s[30:31], 0, v[138:139]
	s_add_i32 m0, s52, 0xc000
	s_nop 0
	global_load_lds_dwordx4 v[154:155], off
	v_lshl_add_u64 v[154:155], s[30:31], 0, v[136:137]
	s_add_i32 m0, s52, 0xe000
	s_nop 0
	global_load_lds_dwordx4 v[154:155], off
	v_add_u32_e32 v153, s61, v147
	ds_read_b128 v[160:163], v153
	v_xor_b32_e32 v253, 64, v153
	ds_read_b128 v[164:167], v253
	ds_read_b128 v[168:171], v153 offset:2048
	ds_read_b128 v[172:175], v253 offset:2048
	v_add_u32_e32 v153, s62, v147
	ds_read_b128 v[176:179], v153
	v_xor_b32_e32 v253, 64, v153
	ds_read_b128 v[180:183], v253
	ds_read_b128 v[184:187], v153 offset:2048
	ds_read_b128 v[188:191], v253 offset:2048
	ds_read_b128 v[192:195], v150
	v_xor_b32_e32 v253, 64, v150
	ds_read_b128 v[196:199], v253
	ds_read_b128 v[200:203], v150 offset:2048
	ds_read_b128 v[204:207], v253 offset:2048
	ds_read_b128 v[208:211], v150 offset:4096
	ds_read_b128 v[212:215], v253 offset:4096
	ds_read_b128 v[216:219], v150 offset:6144
	ds_read_b128 v[220:223], v253 offset:6144
	s_waitcnt vmcnt(8)
	s_waitcnt lgkmcnt(0)
	s_setprio 1
	s_barrier
	v_mfma_f32_16x16x32_bf16 v[124:127], v[160:163], v[192:195], v[124:127]
	v_mfma_f32_16x16x32_bf16 v[124:127], v[164:167], v[196:199], v[124:127]
	v_mfma_f32_16x16x32_bf16 v[116:119], v[172:175], v[196:199], v[116:119]
	v_mfma_f32_16x16x32_bf16 v[116:119], v[168:171], v[192:195], v[116:119]
	v_mfma_f32_16x16x32_bf16 v[100:103], v[168:171], v[200:203], v[100:103]
	v_mfma_f32_16x16x32_bf16 v[100:103], v[172:175], v[204:207], v[100:103]
	v_mfma_f32_16x16x32_bf16 v[108:111], v[164:167], v[204:207], v[108:111]
	v_mfma_f32_16x16x32_bf16 v[108:111], v[160:163], v[200:203], v[108:111]
	v_mfma_f32_16x16x32_bf16 v[92:95], v[160:163], v[208:211], v[92:95]
	v_mfma_f32_16x16x32_bf16 v[92:95], v[164:167], v[212:215], v[92:95]
	v_mfma_f32_16x16x32_bf16 v[84:87], v[172:175], v[212:215], v[84:87]
	v_mfma_f32_16x16x32_bf16 v[84:87], v[168:171], v[208:211], v[84:87]
	v_mfma_f32_16x16x32_bf16 v[68:71], v[168:171], v[216:219], v[68:71]
	v_mfma_f32_16x16x32_bf16 v[68:71], v[172:175], v[220:223], v[68:71]
	v_mfma_f32_16x16x32_bf16 v[76:79], v[164:167], v[220:223], v[76:79]
	v_mfma_f32_16x16x32_bf16 v[76:79], v[160:163], v[216:219], v[76:79]
	s_setprio 0
	s_setprio 1
	v_mfma_f32_16x16x32_bf16 v[120:123], v[176:179], v[192:195], v[120:123]
	v_mfma_f32_16x16x32_bf16 v[120:123], v[180:183], v[196:199], v[120:123]
	v_mfma_f32_16x16x32_bf16 v[112:115], v[188:191], v[196:199], v[112:115]
	v_mfma_f32_16x16x32_bf16 v[112:115], v[184:187], v[192:195], v[112:115]
	v_mfma_f32_16x16x32_bf16 v[96:99], v[184:187], v[200:203], v[96:99]
	v_mfma_f32_16x16x32_bf16 v[96:99], v[188:191], v[204:207], v[96:99]
	v_mfma_f32_16x16x32_bf16 v[104:107], v[180:183], v[204:207], v[104:107]
	v_mfma_f32_16x16x32_bf16 v[104:107], v[176:179], v[200:203], v[104:107]
	v_mfma_f32_16x16x32_bf16 v[88:91], v[176:179], v[208:211], v[88:91]
	v_mfma_f32_16x16x32_bf16 v[88:91], v[180:183], v[212:215], v[88:91]
	v_mfma_f32_16x16x32_bf16 v[80:83], v[188:191], v[212:215], v[80:83]
	v_mfma_f32_16x16x32_bf16 v[80:83], v[184:187], v[208:211], v[80:83]
	v_mfma_f32_16x16x32_bf16 v[64:67], v[184:187], v[216:219], v[64:67]
	v_mfma_f32_16x16x32_bf16 v[64:67], v[188:191], v[220:223], v[64:67]
	v_mfma_f32_16x16x32_bf16 v[72:75], v[180:183], v[220:223], v[72:75]
	v_mfma_f32_16x16x32_bf16 v[72:75], v[176:179], v[216:219], v[72:75]
	s_barrier
	s_setprio 0
	s_add_i32 s71, s61, s49
	v_lshl_add_u64 v[154:155], s[44:45], 0, v[132:133]
	s_mov_b32 m0, s71
	s_nop 0
	global_load_lds_dwordx4 v[154:155], off
	s_add_i32 m0, s71, 0x2000
	s_add_u32 s72, s44, 0x40000
	v_lshl_add_u64 v[224:225], s[44:45], 0, v[128:129]
	s_addc_u32 s73, s45, 0
	s_add_i32 s71, s62, s49
	global_load_lds_dwordx4 v[224:225], off
	v_lshl_add_u64 v[226:227], s[72:73], 0, v[132:133]
	s_mov_b32 m0, s71
	v_lshl_add_u64 v[228:229], s[46:47], 0, v[130:131]
	global_load_lds_dwordx4 v[226:227], off
	v_lshl_add_u64 v[226:227], s[72:73], 0, v[128:129]
	s_add_i32 m0, s71, 0x2000
	s_nop 0
	global_load_lds_dwordx4 v[226:227], off
	v_lshl_add_u64 v[226:227], s[46:47], 0, v[134:135]
	s_mov_b32 m0, s52
	s_nop 0
	global_load_lds_dwordx4 v[226:227], off
	s_mov_b32 m0, s53
	s_nop 0
	global_load_lds_dwordx4 v[228:229], off
	ds_read_b128 v[192:195], v150 offset:16384
	v_xor_b32_e32 v253, 64, v150
	ds_read_b128 v[196:199], v253 offset:16384
	ds_read_b128 v[200:203], v150 offset:18432
	ds_read_b128 v[204:207], v253 offset:18432
	ds_read_b128 v[208:211], v150 offset:20480
	ds_read_b128 v[212:215], v253 offset:20480
	ds_read_b128 v[216:219], v150 offset:22528
	ds_read_b128 v[220:223], v253 offset:22528
	s_waitcnt vmcnt(8)
	s_waitcnt lgkmcnt(0)
	s_setprio 1
	s_barrier
	v_mfma_f32_16x16x32_bf16 v[60:63], v[160:163], v[192:195], v[60:63]
	v_mfma_f32_16x16x32_bf16 v[60:63], v[164:167], v[196:199], v[60:63]
	v_mfma_f32_16x16x32_bf16 v[52:55], v[172:175], v[196:199], v[52:55]
	v_mfma_f32_16x16x32_bf16 v[52:55], v[168:171], v[192:195], v[52:55]
	v_mfma_f32_16x16x32_bf16 v[36:39], v[168:171], v[200:203], v[36:39]
	v_mfma_f32_16x16x32_bf16 v[36:39], v[172:175], v[204:207], v[36:39]
	v_mfma_f32_16x16x32_bf16 v[44:47], v[164:167], v[204:207], v[44:47]
	v_mfma_f32_16x16x32_bf16 v[44:47], v[160:163], v[200:203], v[44:47]
	v_mfma_f32_16x16x32_bf16 v[28:31], v[160:163], v[208:211], v[28:31]
	v_mfma_f32_16x16x32_bf16 v[28:31], v[164:167], v[212:215], v[28:31]
	v_mfma_f32_16x16x32_bf16 v[20:23], v[172:175], v[212:215], v[20:23]
	v_mfma_f32_16x16x32_bf16 v[20:23], v[168:171], v[208:211], v[20:23]
	v_mfma_f32_16x16x32_bf16 v[4:7], v[168:171], v[216:219], v[4:7]
	v_mfma_f32_16x16x32_bf16 v[4:7], v[172:175], v[220:223], v[4:7]
	v_mfma_f32_16x16x32_bf16 v[12:15], v[164:167], v[220:223], v[12:15]
	v_mfma_f32_16x16x32_bf16 v[12:15], v[160:163], v[216:219], v[12:15]
	s_setprio 0
	s_setprio 1
	v_mfma_f32_16x16x32_bf16 v[56:59], v[176:179], v[192:195], v[56:59]
	v_mfma_f32_16x16x32_bf16 v[56:59], v[180:183], v[196:199], v[56:59]
	v_mfma_f32_16x16x32_bf16 v[48:51], v[188:191], v[196:199], v[48:51]
	v_mfma_f32_16x16x32_bf16 v[48:51], v[184:187], v[192:195], v[48:51]
	v_mfma_f32_16x16x32_bf16 v[32:35], v[184:187], v[200:203], v[32:35]
	v_mfma_f32_16x16x32_bf16 v[32:35], v[188:191], v[204:207], v[32:35]
	v_mfma_f32_16x16x32_bf16 v[40:43], v[180:183], v[204:207], v[40:43]
	v_mfma_f32_16x16x32_bf16 v[40:43], v[176:179], v[200:203], v[40:43]
	v_mfma_f32_16x16x32_bf16 v[24:27], v[176:179], v[208:211], v[24:27]
	v_mfma_f32_16x16x32_bf16 v[24:27], v[180:183], v[212:215], v[24:27]
	v_mfma_f32_16x16x32_bf16 v[16:19], v[188:191], v[212:215], v[16:19]
	v_mfma_f32_16x16x32_bf16 v[16:19], v[184:187], v[208:211], v[16:19]
	v_mfma_f32_16x16x32_bf16 v[0:3], v[184:187], v[216:219], v[0:3]
	v_mfma_f32_16x16x32_bf16 v[0:3], v[188:191], v[220:223], v[0:3]
	v_mfma_f32_16x16x32_bf16 v[8:11], v[180:183], v[220:223], v[8:11]
	v_mfma_f32_16x16x32_bf16 v[8:11], v[176:179], v[216:219], v[8:11]
	s_barrier
	s_setprio 0
	s_add_i32 s71, 0, 0x18000
	s_add_i32 s72, 0, 0x1c000
	s_add_u32 s46, s46, 0x40000
	s_addc_u32 s47, s47, 0
	s_mov_b32 m0, s54
	v_lshl_add_u64 v[230:231], s[46:47], 0, v[134:135]
	global_load_lds_dwordx4 v[230:231], off
	v_lshl_add_u64 v[230:231], s[46:47], 0, v[130:131]
	s_mov_b32 m0, s55
	s_nop 0
	global_load_lds_dwordx4 v[230:231], off
	v_add_u32_e32 v153, s71, v147
	ds_read_b128 v[160:163], v153
	v_xor_b32_e32 v253, 64, v153
	ds_read_b128 v[164:167], v253
	ds_read_b128 v[168:171], v153 offset:2048
	ds_read_b128 v[172:175], v253 offset:2048
	v_add_u32_e32 v153, s72, v147
	ds_read_b128 v[176:179], v153
	v_xor_b32_e32 v253, 64, v153
	ds_read_b128 v[180:183], v253
	ds_read_b128 v[184:187], v153 offset:2048
	ds_read_b128 v[188:191], v253 offset:2048
	ds_read_b128 v[192:195], v150 offset:32768
	v_xor_b32_e32 v253, 64, v150
	ds_read_b128 v[196:199], v253 offset:32768
	ds_read_b128 v[200:203], v150 offset:34816
	ds_read_b128 v[204:207], v253 offset:34816
	ds_read_b128 v[208:211], v150 offset:36864
	ds_read_b128 v[212:215], v253 offset:36864
	ds_read_b128 v[216:219], v150 offset:38912
	ds_read_b128 v[220:223], v253 offset:38912
	s_waitcnt vmcnt(8)
	s_waitcnt lgkmcnt(0)
	s_setprio 1
	s_barrier
	v_mfma_f32_16x16x32_bf16 v[124:127], v[160:163], v[192:195], v[124:127]
	v_mfma_f32_16x16x32_bf16 v[124:127], v[164:167], v[196:199], v[124:127]
	v_mfma_f32_16x16x32_bf16 v[116:119], v[172:175], v[196:199], v[116:119]
	v_mfma_f32_16x16x32_bf16 v[116:119], v[168:171], v[192:195], v[116:119]
	v_mfma_f32_16x16x32_bf16 v[100:103], v[168:171], v[200:203], v[100:103]
	v_mfma_f32_16x16x32_bf16 v[100:103], v[172:175], v[204:207], v[100:103]
	v_mfma_f32_16x16x32_bf16 v[108:111], v[164:167], v[204:207], v[108:111]
	v_mfma_f32_16x16x32_bf16 v[108:111], v[160:163], v[200:203], v[108:111]
	v_mfma_f32_16x16x32_bf16 v[92:95], v[160:163], v[208:211], v[92:95]
	v_mfma_f32_16x16x32_bf16 v[92:95], v[164:167], v[212:215], v[92:95]
	v_mfma_f32_16x16x32_bf16 v[84:87], v[172:175], v[212:215], v[84:87]
	v_mfma_f32_16x16x32_bf16 v[84:87], v[168:171], v[208:211], v[84:87]
	v_mfma_f32_16x16x32_bf16 v[68:71], v[168:171], v[216:219], v[68:71]
	v_mfma_f32_16x16x32_bf16 v[68:71], v[172:175], v[220:223], v[68:71]
	v_mfma_f32_16x16x32_bf16 v[76:79], v[164:167], v[220:223], v[76:79]
	v_mfma_f32_16x16x32_bf16 v[76:79], v[160:163], v[216:219], v[76:79]
	s_setprio 0
	s_setprio 1
	v_mfma_f32_16x16x32_bf16 v[120:123], v[176:179], v[192:195], v[120:123]
	v_mfma_f32_16x16x32_bf16 v[120:123], v[180:183], v[196:199], v[120:123]
	v_mfma_f32_16x16x32_bf16 v[112:115], v[188:191], v[196:199], v[112:115]
	v_mfma_f32_16x16x32_bf16 v[112:115], v[184:187], v[192:195], v[112:115]
	v_mfma_f32_16x16x32_bf16 v[96:99], v[184:187], v[200:203], v[96:99]
	v_mfma_f32_16x16x32_bf16 v[96:99], v[188:191], v[204:207], v[96:99]
	v_mfma_f32_16x16x32_bf16 v[104:107], v[180:183], v[204:207], v[104:107]
	v_mfma_f32_16x16x32_bf16 v[104:107], v[176:179], v[200:203], v[104:107]
	v_mfma_f32_16x16x32_bf16 v[88:91], v[176:179], v[208:211], v[88:91]
	v_mfma_f32_16x16x32_bf16 v[88:91], v[180:183], v[212:215], v[88:91]
	v_mfma_f32_16x16x32_bf16 v[80:83], v[188:191], v[212:215], v[80:83]
	v_mfma_f32_16x16x32_bf16 v[80:83], v[184:187], v[208:211], v[80:83]
	v_mfma_f32_16x16x32_bf16 v[64:67], v[184:187], v[216:219], v[64:67]
	v_mfma_f32_16x16x32_bf16 v[64:67], v[188:191], v[220:223], v[64:67]
	v_mfma_f32_16x16x32_bf16 v[72:75], v[180:183], v[220:223], v[72:75]
	v_mfma_f32_16x16x32_bf16 v[72:75], v[176:179], v[216:219], v[72:75]
	s_barrier
	s_setprio 0
	s_add_i32 s46, s71, s49
	v_lshl_add_u64 v[154:155], v[154:155], 0, s[14:15]
	s_mov_b32 m0, s46
	s_nop 0
	global_load_lds_dwordx4 v[154:155], off
	s_add_i32 m0, s46, 0x2000
	s_add_u32 s44, s44, 0x40080
	v_lshl_add_u64 v[154:155], v[224:225], 0, s[14:15]
	s_addc_u32 s45, s45, 0
	s_add_i32 s46, s72, s49
	global_load_lds_dwordx4 v[154:155], off
	v_lshl_add_u64 v[154:155], s[44:45], 0, v[132:133]
	s_mov_b32 m0, s46
	s_nop 0
	global_load_lds_dwordx4 v[154:155], off
	v_lshl_add_u64 v[154:155], s[44:45], 0, v[128:129]
	s_add_i32 m0, s46, 0x2000
	s_nop 0
	global_load_lds_dwordx4 v[154:155], off
	v_lshl_add_u64 v[154:155], v[226:227], 0, s[14:15]
	s_mov_b32 m0, s57
	s_nop 0
	global_load_lds_dwordx4 v[154:155], off
	v_lshl_add_u64 v[154:155], v[228:229], 0, s[14:15]
	s_mov_b32 m0, s58
	s_nop 0
	global_load_lds_dwordx4 v[154:155], off
	ds_read_b128 v[192:195], v150 offset:49152
	v_xor_b32_e32 v253, 64, v150
	ds_read_b128 v[196:199], v253 offset:49152
	ds_read_b128 v[200:203], v150 offset:51200
	ds_read_b128 v[204:207], v253 offset:51200
	ds_read_b128 v[208:211], v150 offset:53248
	ds_read_b128 v[212:215], v253 offset:53248
	ds_read_b128 v[216:219], v150 offset:55296
	ds_read_b128 v[220:223], v253 offset:55296
	s_waitcnt vmcnt(8)
	s_waitcnt lgkmcnt(0)
	s_setprio 1
	s_barrier
	v_mfma_f32_16x16x32_bf16 v[60:63], v[160:163], v[192:195], v[60:63]
	v_mfma_f32_16x16x32_bf16 v[60:63], v[164:167], v[196:199], v[60:63]
	v_mfma_f32_16x16x32_bf16 v[52:55], v[172:175], v[196:199], v[52:55]
	v_mfma_f32_16x16x32_bf16 v[52:55], v[168:171], v[192:195], v[52:55]
	v_mfma_f32_16x16x32_bf16 v[36:39], v[168:171], v[200:203], v[36:39]
	v_mfma_f32_16x16x32_bf16 v[36:39], v[172:175], v[204:207], v[36:39]
	v_mfma_f32_16x16x32_bf16 v[44:47], v[164:167], v[204:207], v[44:47]
	v_mfma_f32_16x16x32_bf16 v[44:47], v[160:163], v[200:203], v[44:47]
	v_mfma_f32_16x16x32_bf16 v[28:31], v[160:163], v[208:211], v[28:31]
	v_mfma_f32_16x16x32_bf16 v[28:31], v[164:167], v[212:215], v[28:31]
	v_mfma_f32_16x16x32_bf16 v[20:23], v[172:175], v[212:215], v[20:23]
	v_mfma_f32_16x16x32_bf16 v[20:23], v[168:171], v[208:211], v[20:23]
	v_mfma_f32_16x16x32_bf16 v[4:7], v[168:171], v[216:219], v[4:7]
	v_mfma_f32_16x16x32_bf16 v[4:7], v[172:175], v[220:223], v[4:7]
	v_mfma_f32_16x16x32_bf16 v[12:15], v[164:167], v[220:223], v[12:15]
	v_mfma_f32_16x16x32_bf16 v[12:15], v[160:163], v[216:219], v[12:15]
	s_setprio 0
	s_setprio 1
	v_mfma_f32_16x16x32_bf16 v[56:59], v[176:179], v[192:195], v[56:59]
	v_mfma_f32_16x16x32_bf16 v[56:59], v[180:183], v[196:199], v[56:59]
	v_mfma_f32_16x16x32_bf16 v[48:51], v[188:191], v[196:199], v[48:51]
	v_mfma_f32_16x16x32_bf16 v[48:51], v[184:187], v[192:195], v[48:51]
	v_mfma_f32_16x16x32_bf16 v[32:35], v[184:187], v[200:203], v[32:35]
	v_mfma_f32_16x16x32_bf16 v[32:35], v[188:191], v[204:207], v[32:35]
	v_mfma_f32_16x16x32_bf16 v[40:43], v[180:183], v[204:207], v[40:43]
	v_mfma_f32_16x16x32_bf16 v[40:43], v[176:179], v[200:203], v[40:43]
	v_mfma_f32_16x16x32_bf16 v[24:27], v[176:179], v[208:211], v[24:27]
	v_mfma_f32_16x16x32_bf16 v[24:27], v[180:183], v[212:215], v[24:27]
	v_mfma_f32_16x16x32_bf16 v[16:19], v[188:191], v[212:215], v[16:19]
	v_mfma_f32_16x16x32_bf16 v[16:19], v[184:187], v[208:211], v[16:19]
	v_mfma_f32_16x16x32_bf16 v[0:3], v[184:187], v[216:219], v[0:3]
	v_mfma_f32_16x16x32_bf16 v[0:3], v[188:191], v[220:223], v[0:3]
	v_mfma_f32_16x16x32_bf16 v[8:11], v[180:183], v[220:223], v[8:11]
	v_mfma_f32_16x16x32_bf16 v[8:11], v[176:179], v[216:219], v[8:11]
	s_barrier
	s_setprio 0
	s_add_i32 s70, s70, 2
	s_add_u32 s68, s68, 0x100
	s_addc_u32 s69, s69, 0
	s_add_u32 s30, s30, 0x100
	s_addc_u32 s31, s31, 0
	s_cmp_gt_u32 s70, 13
	s_cbranch_scc1 .LBB0_1100

.Llast_10:
	s_add_u32 s46, s30, 0xfffc0080
	s_addc_u32 s47, s31, -1
	s_and_b64 s[44:45], s[44:45], exec
	s_cselect_b32 s47, s25, s47
	s_cselect_b32 s46, s65, s46
	s_cselect_b32 s45, s66, s69
	s_cselect_b32 s44, s67, s68
	v_lshl_add_u64 v[154:155], s[30:31], 0, v[138:139]
	s_add_i32 m0, s52, 0xc000
	s_nop 0
	global_load_lds_dwordx4 v[154:155], off
	v_lshl_add_u64 v[154:155], s[30:31], 0, v[136:137]
	s_add_i32 m0, s52, 0xe000
	s_nop 0
	global_load_lds_dwordx4 v[154:155], off
	v_add_u32_e32 v153, s61, v147
	ds_read_b128 v[160:163], v153
	v_xor_b32_e32 v253, 64, v153
	ds_read_b128 v[164:167], v253
	ds_read_b128 v[168:171], v153 offset:2048
	ds_read_b128 v[172:175], v253 offset:2048
	v_add_u32_e32 v153, s62, v147
	ds_read_b128 v[176:179], v153
	v_xor_b32_e32 v253, 64, v153
	ds_read_b128 v[180:183], v253
	ds_read_b128 v[184:187], v153 offset:2048
	ds_read_b128 v[188:191], v253 offset:2048
	ds_read_b128 v[192:195], v150
	v_xor_b32_e32 v253, 64, v150
	ds_read_b128 v[196:199], v253
	ds_read_b128 v[200:203], v150 offset:2048
	ds_read_b128 v[204:207], v253 offset:2048
	ds_read_b128 v[208:211], v150 offset:4096
	ds_read_b128 v[212:215], v253 offset:4096
	ds_read_b128 v[216:219], v150 offset:6144
	ds_read_b128 v[220:223], v253 offset:6144
	s_waitcnt vmcnt(8)
	s_waitcnt lgkmcnt(0)
	s_setprio 1
	s_barrier
	v_mfma_f32_16x16x32_bf16 v[124:127], v[160:163], v[192:195], v[124:127]
	v_mfma_f32_16x16x32_bf16 v[124:127], v[164:167], v[196:199], v[124:127]
	v_mfma_f32_16x16x32_bf16 v[116:119], v[172:175], v[196:199], v[116:119]
	v_mfma_f32_16x16x32_bf16 v[116:119], v[168:171], v[192:195], v[116:119]
	v_mfma_f32_16x16x32_bf16 v[100:103], v[168:171], v[200:203], v[100:103]
	v_mfma_f32_16x16x32_bf16 v[100:103], v[172:175], v[204:207], v[100:103]
	v_mfma_f32_16x16x32_bf16 v[108:111], v[164:167], v[204:207], v[108:111]
	v_mfma_f32_16x16x32_bf16 v[108:111], v[160:163], v[200:203], v[108:111]
	v_mfma_f32_16x16x32_bf16 v[92:95], v[160:163], v[208:211], v[92:95]
	v_mfma_f32_16x16x32_bf16 v[92:95], v[164:167], v[212:215], v[92:95]
	v_mfma_f32_16x16x32_bf16 v[84:87], v[172:175], v[212:215], v[84:87]
	v_mfma_f32_16x16x32_bf16 v[84:87], v[168:171], v[208:211], v[84:87]
	v_mfma_f32_16x16x32_bf16 v[68:71], v[168:171], v[216:219], v[68:71]
	v_mfma_f32_16x16x32_bf16 v[68:71], v[172:175], v[220:223], v[68:71]
	v_mfma_f32_16x16x32_bf16 v[76:79], v[164:167], v[220:223], v[76:79]
	v_mfma_f32_16x16x32_bf16 v[76:79], v[160:163], v[216:219], v[76:79]
	s_setprio 0
	s_setprio 1
	v_mfma_f32_16x16x32_bf16 v[120:123], v[176:179], v[192:195], v[120:123]
	v_mfma_f32_16x16x32_bf16 v[120:123], v[180:183], v[196:199], v[120:123]
	v_mfma_f32_16x16x32_bf16 v[112:115], v[188:191], v[196:199], v[112:115]
	v_mfma_f32_16x16x32_bf16 v[112:115], v[184:187], v[192:195], v[112:115]
	v_mfma_f32_16x16x32_bf16 v[96:99], v[184:187], v[200:203], v[96:99]
	v_mfma_f32_16x16x32_bf16 v[96:99], v[188:191], v[204:207], v[96:99]
	v_mfma_f32_16x16x32_bf16 v[104:107], v[180:183], v[204:207], v[104:107]
	v_mfma_f32_16x16x32_bf16 v[104:107], v[176:179], v[200:203], v[104:107]
	v_mfma_f32_16x16x32_bf16 v[88:91], v[176:179], v[208:211], v[88:91]
	v_mfma_f32_16x16x32_bf16 v[88:91], v[180:183], v[212:215], v[88:91]
	v_mfma_f32_16x16x32_bf16 v[80:83], v[188:191], v[212:215], v[80:83]
	v_mfma_f32_16x16x32_bf16 v[80:83], v[184:187], v[208:211], v[80:83]
	v_mfma_f32_16x16x32_bf16 v[64:67], v[184:187], v[216:219], v[64:67]
	v_mfma_f32_16x16x32_bf16 v[64:67], v[188:191], v[220:223], v[64:67]
	v_mfma_f32_16x16x32_bf16 v[72:75], v[180:183], v[220:223], v[72:75]
	v_mfma_f32_16x16x32_bf16 v[72:75], v[176:179], v[216:219], v[72:75]
	s_barrier
	s_setprio 0
	s_add_i32 s71, s61, s49
	v_lshl_add_u64 v[154:155], s[44:45], 0, v[132:133]
	s_mov_b32 m0, s71
	s_nop 0
	global_load_lds_dwordx4 v[154:155], off
	s_add_i32 m0, s71, 0x2000
	s_add_u32 s72, s44, 0x40000
	v_lshl_add_u64 v[224:225], s[44:45], 0, v[128:129]
	s_addc_u32 s73, s45, 0
	s_add_i32 s71, s62, s49
	global_load_lds_dwordx4 v[224:225], off
	v_lshl_add_u64 v[226:227], s[72:73], 0, v[132:133]
	s_mov_b32 m0, s71
	v_lshl_add_u64 v[228:229], s[46:47], 0, v[130:131]
	global_load_lds_dwordx4 v[226:227], off
	v_lshl_add_u64 v[226:227], s[72:73], 0, v[128:129]
	s_add_i32 m0, s71, 0x2000
	s_nop 0
	global_load_lds_dwordx4 v[226:227], off
	v_lshl_add_u64 v[226:227], s[46:47], 0, v[134:135]
	s_mov_b32 m0, s52
	s_nop 0
	global_load_lds_dwordx4 v[226:227], off
	s_mov_b32 m0, s53
	s_nop 0
	global_load_lds_dwordx4 v[228:229], off
	ds_read_b128 v[192:195], v150 offset:16384
	v_xor_b32_e32 v253, 64, v150
	ds_read_b128 v[196:199], v253 offset:16384
	ds_read_b128 v[200:203], v150 offset:18432
	ds_read_b128 v[204:207], v253 offset:18432
	ds_read_b128 v[208:211], v150 offset:20480
	ds_read_b128 v[212:215], v253 offset:20480
	ds_read_b128 v[216:219], v150 offset:22528
	ds_read_b128 v[220:223], v253 offset:22528
	s_waitcnt vmcnt(8)
	s_waitcnt lgkmcnt(0)
	s_setprio 1
	s_barrier
	v_mfma_f32_16x16x32_bf16 v[60:63], v[160:163], v[192:195], v[60:63]
	v_mfma_f32_16x16x32_bf16 v[60:63], v[164:167], v[196:199], v[60:63]
	v_mfma_f32_16x16x32_bf16 v[52:55], v[172:175], v[196:199], v[52:55]
	v_mfma_f32_16x16x32_bf16 v[52:55], v[168:171], v[192:195], v[52:55]
	v_mfma_f32_16x16x32_bf16 v[36:39], v[168:171], v[200:203], v[36:39]
	v_mfma_f32_16x16x32_bf16 v[36:39], v[172:175], v[204:207], v[36:39]
	v_mfma_f32_16x16x32_bf16 v[44:47], v[164:167], v[204:207], v[44:47]
	v_mfma_f32_16x16x32_bf16 v[44:47], v[160:163], v[200:203], v[44:47]
	v_mfma_f32_16x16x32_bf16 v[28:31], v[160:163], v[208:211], v[28:31]
	v_mfma_f32_16x16x32_bf16 v[28:31], v[164:167], v[212:215], v[28:31]
	v_mfma_f32_16x16x32_bf16 v[20:23], v[172:175], v[212:215], v[20:23]
	v_mfma_f32_16x16x32_bf16 v[20:23], v[168:171], v[208:211], v[20:23]
	v_mfma_f32_16x16x32_bf16 v[4:7], v[168:171], v[216:219], v[4:7]
	v_mfma_f32_16x16x32_bf16 v[4:7], v[172:175], v[220:223], v[4:7]
	v_mfma_f32_16x16x32_bf16 v[12:15], v[164:167], v[220:223], v[12:15]
	v_mfma_f32_16x16x32_bf16 v[12:15], v[160:163], v[216:219], v[12:15]
	s_setprio 0
	s_setprio 1
	v_mfma_f32_16x16x32_bf16 v[56:59], v[176:179], v[192:195], v[56:59]
	v_mfma_f32_16x16x32_bf16 v[56:59], v[180:183], v[196:199], v[56:59]
	v_mfma_f32_16x16x32_bf16 v[48:51], v[188:191], v[196:199], v[48:51]
	v_mfma_f32_16x16x32_bf16 v[48:51], v[184:187], v[192:195], v[48:51]
	v_mfma_f32_16x16x32_bf16 v[32:35], v[184:187], v[200:203], v[32:35]
	v_mfma_f32_16x16x32_bf16 v[32:35], v[188:191], v[204:207], v[32:35]
	v_mfma_f32_16x16x32_bf16 v[40:43], v[180:183], v[204:207], v[40:43]
	v_mfma_f32_16x16x32_bf16 v[40:43], v[176:179], v[200:203], v[40:43]
	v_mfma_f32_16x16x32_bf16 v[24:27], v[176:179], v[208:211], v[24:27]
	v_mfma_f32_16x16x32_bf16 v[24:27], v[180:183], v[212:215], v[24:27]
	v_mfma_f32_16x16x32_bf16 v[16:19], v[188:191], v[212:215], v[16:19]
	v_mfma_f32_16x16x32_bf16 v[16:19], v[184:187], v[208:211], v[16:19]
	v_mfma_f32_16x16x32_bf16 v[0:3], v[184:187], v[216:219], v[0:3]
	v_mfma_f32_16x16x32_bf16 v[0:3], v[188:191], v[220:223], v[0:3]
	v_mfma_f32_16x16x32_bf16 v[8:11], v[180:183], v[220:223], v[8:11]
	v_mfma_f32_16x16x32_bf16 v[8:11], v[176:179], v[216:219], v[8:11]
	s_barrier
	s_setprio 0
	s_add_i32 s71, 0, 0x18000
	s_add_i32 s72, 0, 0x1c000
	s_add_u32 s46, s46, 0x40000
	s_addc_u32 s47, s47, 0
	s_mov_b32 m0, s54
	v_lshl_add_u64 v[230:231], s[46:47], 0, v[134:135]
	global_load_lds_dwordx4 v[230:231], off
	v_lshl_add_u64 v[230:231], s[46:47], 0, v[130:131]
	s_mov_b32 m0, s55
	s_nop 0
	global_load_lds_dwordx4 v[230:231], off
	v_add_u32_e32 v153, s71, v147
	ds_read_b128 v[160:163], v153
	v_xor_b32_e32 v253, 64, v153
	ds_read_b128 v[164:167], v253
	ds_read_b128 v[168:171], v153 offset:2048
	ds_read_b128 v[172:175], v253 offset:2048
	v_add_u32_e32 v153, s72, v147
	ds_read_b128 v[176:179], v153
	v_xor_b32_e32 v253, 64, v153
	ds_read_b128 v[180:183], v253
	ds_read_b128 v[184:187], v153 offset:2048
	ds_read_b128 v[188:191], v253 offset:2048
	ds_read_b128 v[192:195], v150 offset:32768
	v_xor_b32_e32 v253, 64, v150
	ds_read_b128 v[196:199], v253 offset:32768
	ds_read_b128 v[200:203], v150 offset:34816
	ds_read_b128 v[204:207], v253 offset:34816
	ds_read_b128 v[208:211], v150 offset:36864
	ds_read_b128 v[212:215], v253 offset:36864
	ds_read_b128 v[216:219], v150 offset:38912
	ds_read_b128 v[220:223], v253 offset:38912
	s_waitcnt vmcnt(8)
	s_waitcnt lgkmcnt(0)
	s_setprio 1
	s_barrier
	v_mfma_f32_16x16x32_bf16 v[124:127], v[160:163], v[192:195], v[124:127]
	v_mfma_f32_16x16x32_bf16 v[124:127], v[164:167], v[196:199], v[124:127]
	v_mfma_f32_16x16x32_bf16 v[116:119], v[172:175], v[196:199], v[116:119]
	v_mfma_f32_16x16x32_bf16 v[116:119], v[168:171], v[192:195], v[116:119]
	v_mfma_f32_16x16x32_bf16 v[100:103], v[168:171], v[200:203], v[100:103]
	v_mfma_f32_16x16x32_bf16 v[100:103], v[172:175], v[204:207], v[100:103]
	v_mfma_f32_16x16x32_bf16 v[108:111], v[164:167], v[204:207], v[108:111]
	v_mfma_f32_16x16x32_bf16 v[108:111], v[160:163], v[200:203], v[108:111]
	v_mfma_f32_16x16x32_bf16 v[92:95], v[160:163], v[208:211], v[92:95]
	v_mfma_f32_16x16x32_bf16 v[92:95], v[164:167], v[212:215], v[92:95]
	v_mfma_f32_16x16x32_bf16 v[84:87], v[172:175], v[212:215], v[84:87]
	v_mfma_f32_16x16x32_bf16 v[84:87], v[168:171], v[208:211], v[84:87]
	v_mfma_f32_16x16x32_bf16 v[68:71], v[168:171], v[216:219], v[68:71]
	v_mfma_f32_16x16x32_bf16 v[68:71], v[172:175], v[220:223], v[68:71]
	v_mfma_f32_16x16x32_bf16 v[76:79], v[164:167], v[220:223], v[76:79]
	v_mfma_f32_16x16x32_bf16 v[76:79], v[160:163], v[216:219], v[76:79]
	s_setprio 0
	s_setprio 1
	v_mfma_f32_16x16x32_bf16 v[120:123], v[176:179], v[192:195], v[120:123]
	v_mfma_f32_16x16x32_bf16 v[120:123], v[180:183], v[196:199], v[120:123]
	v_mfma_f32_16x16x32_bf16 v[112:115], v[188:191], v[196:199], v[112:115]
	v_mfma_f32_16x16x32_bf16 v[112:115], v[184:187], v[192:195], v[112:115]
	v_mfma_f32_16x16x32_bf16 v[96:99], v[184:187], v[200:203], v[96:99]
	v_mfma_f32_16x16x32_bf16 v[96:99], v[188:191], v[204:207], v[96:99]
	v_mfma_f32_16x16x32_bf16 v[104:107], v[180:183], v[204:207], v[104:107]
	v_mfma_f32_16x16x32_bf16 v[104:107], v[176:179], v[200:203], v[104:107]
	v_mfma_f32_16x16x32_bf16 v[88:91], v[176:179], v[208:211], v[88:91]
	v_mfma_f32_16x16x32_bf16 v[88:91], v[180:183], v[212:215], v[88:91]
	v_mfma_f32_16x16x32_bf16 v[80:83], v[188:191], v[212:215], v[80:83]
	v_mfma_f32_16x16x32_bf16 v[80:83], v[184:187], v[208:211], v[80:83]
	v_mfma_f32_16x16x32_bf16 v[64:67], v[184:187], v[216:219], v[64:67]
	v_mfma_f32_16x16x32_bf16 v[64:67], v[188:191], v[220:223], v[64:67]
	v_mfma_f32_16x16x32_bf16 v[72:75], v[180:183], v[220:223], v[72:75]
	v_mfma_f32_16x16x32_bf16 v[72:75], v[176:179], v[216:219], v[72:75]
	s_barrier
	s_setprio 0
	v_add_u32_e32 v234, 0x21000, v151
	ds_read_b128 v[236:239], v234
	ds_read_b128 v[240:243], v234 offset:256
	ds_read_b128 v[244:247], v234 offset:512
	ds_read_b128 v[248:251], v234 offset:768
	v_add_u32_e32 v235, s23, v146
	v_mul_u32_u24_e32 v235, 0x1600, v235
	v_lshl_or_b32 v234, s64, 7, v149
	v_lshl_add_u32 v235, v234, 1, v235
	s_add_i32 s46, s71, s49
	v_lshl_add_u64 v[154:155], v[154:155], 0, s[14:15]
	s_mov_b32 m0, s46
	ds_read_b128 v[192:195], v150 offset:49152
	v_xor_b32_e32 v253, 64, v150
	ds_read_b128 v[196:199], v253 offset:49152
	ds_read_b128 v[200:203], v150 offset:51200
	ds_read_b128 v[204:207], v253 offset:51200
	ds_read_b128 v[208:211], v150 offset:53248
	ds_read_b128 v[212:215], v253 offset:53248
	ds_read_b128 v[216:219], v150 offset:55296
	ds_read_b128 v[220:223], v253 offset:55296
	global_load_lds_dwordx4 v[154:155], off
	s_add_i32 m0, s46, 0x2000
	s_add_u32 s44, s44, 0x40080
	v_lshl_add_u64 v[154:155], v[224:225], 0, s[14:15]
	s_addc_u32 s45, s45, 0
	s_add_i32 s46, s72, s49
	global_load_lds_dwordx4 v[154:155], off
	v_lshl_add_u64 v[154:155], s[44:45], 0, v[132:133]
	s_mov_b32 m0, s46
	s_nop 0
	global_load_lds_dwordx4 v[154:155], off
	v_lshl_add_u64 v[154:155], s[44:45], 0, v[128:129]
	s_add_i32 m0, s46, 0x2000
	s_nop 0
	global_load_lds_dwordx4 v[154:155], off
	v_lshl_add_u64 v[154:155], v[226:227], 0, s[14:15]
	s_mov_b32 m0, s57
	s_nop 0
	global_load_lds_dwordx4 v[154:155], off
	v_lshl_add_u64 v[154:155], v[228:229], 0, s[14:15]
	s_mov_b32 m0, s58
	s_nop 0
	global_load_lds_dwordx4 v[154:155], off
	s_waitcnt lgkmcnt(8)
	v_add_f32_e32 v236, v236, v237
	v_add_f32_e32 v238, v238, v239
	v_add_f32_e32 v240, v240, v241
	v_add_f32_e32 v242, v242, v243
	v_add_f32_e32 v244, v244, v245
	v_add_f32_e32 v246, v246, v247
	v_add_f32_e32 v248, v248, v249
	v_add_f32_e32 v250, v250, v251
	v_add_f32_e32 v236, v236, v238
	v_add_f32_e32 v240, v240, v242
	v_add_f32_e32 v244, v244, v246
	v_add_f32_e32 v248, v248, v250
	v_fmamk_f32 v236, v236, 0x3a800000, v152
	v_fmamk_f32 v240, v240, 0x3a800000, v152
	v_fmamk_f32 v244, v244, 0x3a800000, v152
	v_fmamk_f32 v248, v248, 0x3a800000, v152
	v_rsq_f32_e32 v236, v236
	v_rsq_f32_e32 v240, v240
	v_rsq_f32_e32 v244, v244
	v_rsq_f32_e32 v248, v248
	v_mul_f32_e32 v252, 0xbfb8aa3b, v236
	v_mul_f32_e32 v254, v236, v236
	v_rcp_f32_e32 v254, v254
	v_pk_mul_f32 v[120:121], v[124:125], v[120:121]
	v_pk_mul_f32 v[122:123], v[126:127], v[122:123]
	v_pk_mul_f32 v[112:113], v[116:117], v[112:113]
	v_pk_mul_f32 v[114:115], v[118:119], v[114:115]
	v_pk_mul_f32 v[124:125], v[124:125], v[252:253] op_sel_hi:[1,0]
	v_pk_mul_f32 v[126:127], v[126:127], v[252:253] op_sel_hi:[1,0]
	v_pk_mul_f32 v[116:117], v[116:117], v[252:253] op_sel_hi:[1,0]
	v_pk_mul_f32 v[118:119], v[118:119], v[252:253] op_sel_hi:[1,0]
	v_exp_f32_e32 v124, v124
	v_exp_f32_e32 v125, v125
	v_exp_f32_e32 v126, v126
	v_exp_f32_e32 v127, v127
	v_exp_f32_e32 v116, v116
	v_exp_f32_e32 v117, v117
	v_exp_f32_e32 v118, v118
	v_exp_f32_e32 v119, v119
	v_pk_fma_f32 v[124:125], v[124:125], v[254:255], v[254:255] op_sel_hi:[1,0,0]
	v_pk_fma_f32 v[126:127], v[126:127], v[254:255], v[254:255] op_sel_hi:[1,0,0]
	v_pk_fma_f32 v[116:117], v[116:117], v[254:255], v[254:255] op_sel_hi:[1,0,0]
	v_pk_fma_f32 v[118:119], v[118:119], v[254:255], v[254:255] op_sel_hi:[1,0,0]
	v_rcp_f32_e32 v124, v124
	v_rcp_f32_e32 v125, v125
	v_rcp_f32_e32 v126, v126
	v_rcp_f32_e32 v127, v127
	v_rcp_f32_e32 v116, v116
	v_rcp_f32_e32 v117, v117
	v_rcp_f32_e32 v118, v118
	v_rcp_f32_e32 v119, v119
	v_pk_mul_f32 v[120:121], v[120:121], v[124:125]
	v_pk_mul_f32 v[122:123], v[122:123], v[126:127]
	v_pk_mul_f32 v[112:113], v[112:113], v[116:117]
	v_pk_mul_f32 v[114:115], v[114:115], v[118:119]
	v_cvt_pk_bf16_f32 v120, v120, v121
	v_cvt_pk_bf16_f32 v121, v122, v123
	v_cvt_pk_bf16_f32 v122, v112, v113
	v_cvt_pk_bf16_f32 v123, v114, v115
	global_store_dwordx4 v235, v[120:123], s[10:11]
	v_add_u32_e32 v234, 0x16000, v235
	v_mul_f32_e32 v252, 0xbfb8aa3b, v240
	v_mul_f32_e32 v254, v240, v240
	v_rcp_f32_e32 v254, v254
	v_pk_mul_f32 v[104:105], v[108:109], v[104:105]
	v_pk_mul_f32 v[106:107], v[110:111], v[106:107]
	v_pk_mul_f32 v[96:97], v[100:101], v[96:97]
	v_pk_mul_f32 v[98:99], v[102:103], v[98:99]
	v_pk_mul_f32 v[108:109], v[108:109], v[252:253] op_sel_hi:[1,0]
	v_pk_mul_f32 v[110:111], v[110:111], v[252:253] op_sel_hi:[1,0]
	v_pk_mul_f32 v[100:101], v[100:101], v[252:253] op_sel_hi:[1,0]
	v_pk_mul_f32 v[102:103], v[102:103], v[252:253] op_sel_hi:[1,0]
	v_exp_f32_e32 v108, v108
	v_exp_f32_e32 v109, v109
	v_exp_f32_e32 v110, v110
	v_exp_f32_e32 v111, v111
	v_exp_f32_e32 v100, v100
	v_exp_f32_e32 v101, v101
	v_exp_f32_e32 v102, v102
	v_exp_f32_e32 v103, v103
	v_pk_fma_f32 v[108:109], v[108:109], v[254:255], v[254:255] op_sel_hi:[1,0,0]
	v_pk_fma_f32 v[110:111], v[110:111], v[254:255], v[254:255] op_sel_hi:[1,0,0]
	v_pk_fma_f32 v[100:101], v[100:101], v[254:255], v[254:255] op_sel_hi:[1,0,0]
	v_pk_fma_f32 v[102:103], v[102:103], v[254:255], v[254:255] op_sel_hi:[1,0,0]
	v_rcp_f32_e32 v108, v108
	v_rcp_f32_e32 v109, v109
	v_rcp_f32_e32 v110, v110
	v_rcp_f32_e32 v111, v111
	v_rcp_f32_e32 v100, v100
	v_rcp_f32_e32 v101, v101
	v_rcp_f32_e32 v102, v102
	v_rcp_f32_e32 v103, v103
	v_pk_mul_f32 v[104:105], v[104:105], v[108:109]
	v_pk_mul_f32 v[106:107], v[106:107], v[110:111]
	v_pk_mul_f32 v[96:97], v[96:97], v[100:101]
	v_pk_mul_f32 v[98:99], v[98:99], v[102:103]
	v_cvt_pk_bf16_f32 v104, v104, v105
	v_cvt_pk_bf16_f32 v105, v106, v107
	v_cvt_pk_bf16_f32 v106, v96, v97
	v_cvt_pk_bf16_f32 v107, v98, v99
	global_store_dwordx4 v234, v[104:107], s[10:11]
	v_add_u32_e32 v235, 0x16000, v234
	v_mul_f32_e32 v252, 0xbfb8aa3b, v244
	v_mul_f32_e32 v254, v244, v244
	v_rcp_f32_e32 v254, v254
	v_pk_mul_f32 v[88:89], v[92:93], v[88:89]
	v_pk_mul_f32 v[90:91], v[94:95], v[90:91]
	v_pk_mul_f32 v[80:81], v[84:85], v[80:81]
	v_pk_mul_f32 v[82:83], v[86:87], v[82:83]
	v_pk_mul_f32 v[92:93], v[92:93], v[252:253] op_sel_hi:[1,0]
	v_pk_mul_f32 v[94:95], v[94:95], v[252:253] op_sel_hi:[1,0]
	v_pk_mul_f32 v[84:85], v[84:85], v[252:253] op_sel_hi:[1,0]
	v_pk_mul_f32 v[86:87], v[86:87], v[252:253] op_sel_hi:[1,0]
	v_exp_f32_e32 v92, v92
	v_exp_f32_e32 v93, v93
	v_exp_f32_e32 v94, v94
	v_exp_f32_e32 v95, v95
	v_exp_f32_e32 v84, v84
	v_exp_f32_e32 v85, v85
	v_exp_f32_e32 v86, v86
	v_exp_f32_e32 v87, v87
	v_pk_fma_f32 v[92:93], v[92:93], v[254:255], v[254:255] op_sel_hi:[1,0,0]
	v_pk_fma_f32 v[94:95], v[94:95], v[254:255], v[254:255] op_sel_hi:[1,0,0]
	v_pk_fma_f32 v[84:85], v[84:85], v[254:255], v[254:255] op_sel_hi:[1,0,0]
	v_pk_fma_f32 v[86:87], v[86:87], v[254:255], v[254:255] op_sel_hi:[1,0,0]
	v_rcp_f32_e32 v92, v92
	v_rcp_f32_e32 v93, v93
	v_rcp_f32_e32 v94, v94
	v_rcp_f32_e32 v95, v95
	v_rcp_f32_e32 v84, v84
	v_rcp_f32_e32 v85, v85
	v_rcp_f32_e32 v86, v86
	v_rcp_f32_e32 v87, v87
	v_pk_mul_f32 v[88:89], v[88:89], v[92:93]
	v_pk_mul_f32 v[90:91], v[90:91], v[94:95]
	v_pk_mul_f32 v[80:81], v[80:81], v[84:85]
	v_pk_mul_f32 v[82:83], v[82:83], v[86:87]
	v_cvt_pk_bf16_f32 v88, v88, v89
	v_cvt_pk_bf16_f32 v89, v90, v91
	v_cvt_pk_bf16_f32 v90, v80, v81
	v_cvt_pk_bf16_f32 v91, v82, v83
	global_store_dwordx4 v235, v[88:91], s[10:11]
	v_add_u32_e32 v234, 0x16000, v235
	v_mul_f32_e32 v252, 0xbfb8aa3b, v248
	v_mul_f32_e32 v254, v248, v248
	v_rcp_f32_e32 v254, v254
	v_pk_mul_f32 v[72:73], v[76:77], v[72:73]
	v_pk_mul_f32 v[74:75], v[78:79], v[74:75]
	v_pk_mul_f32 v[64:65], v[68:69], v[64:65]
	v_pk_mul_f32 v[66:67], v[70:71], v[66:67]
	v_pk_mul_f32 v[76:77], v[76:77], v[252:253] op_sel_hi:[1,0]
	v_pk_mul_f32 v[78:79], v[78:79], v[252:253] op_sel_hi:[1,0]
	v_pk_mul_f32 v[68:69], v[68:69], v[252:253] op_sel_hi:[1,0]
	v_pk_mul_f32 v[70:71], v[70:71], v[252:253] op_sel_hi:[1,0]
	v_exp_f32_e32 v76, v76
	v_exp_f32_e32 v77, v77
	v_exp_f32_e32 v78, v78
	v_exp_f32_e32 v79, v79
	v_exp_f32_e32 v68, v68
	v_exp_f32_e32 v69, v69
	v_exp_f32_e32 v70, v70
	v_exp_f32_e32 v71, v71
	v_pk_fma_f32 v[76:77], v[76:77], v[254:255], v[254:255] op_sel_hi:[1,0,0]
	v_pk_fma_f32 v[78:79], v[78:79], v[254:255], v[254:255] op_sel_hi:[1,0,0]
	v_pk_fma_f32 v[68:69], v[68:69], v[254:255], v[254:255] op_sel_hi:[1,0,0]
	v_pk_fma_f32 v[70:71], v[70:71], v[254:255], v[254:255] op_sel_hi:[1,0,0]
	v_rcp_f32_e32 v76, v76
	v_rcp_f32_e32 v77, v77
	v_rcp_f32_e32 v78, v78
	v_rcp_f32_e32 v79, v79
	v_rcp_f32_e32 v68, v68
	v_rcp_f32_e32 v69, v69
	v_rcp_f32_e32 v70, v70
	v_rcp_f32_e32 v71, v71
	v_pk_mul_f32 v[72:73], v[72:73], v[76:77]
	v_pk_mul_f32 v[74:75], v[74:75], v[78:79]
	v_pk_mul_f32 v[64:65], v[64:65], v[68:69]
	v_pk_mul_f32 v[66:67], v[66:67], v[70:71]
	v_cvt_pk_bf16_f32 v72, v72, v73
	v_cvt_pk_bf16_f32 v73, v74, v75
	v_cvt_pk_bf16_f32 v74, v64, v65
	v_cvt_pk_bf16_f32 v75, v66, v67
	global_store_dwordx4 v234, v[72:75], s[10:11]
	s_waitcnt vmcnt(12)
	s_waitcnt lgkmcnt(0)
	s_setprio 1
	s_barrier
	v_mfma_f32_16x16x32_bf16 v[60:63], v[160:163], v[192:195], v[60:63]
	v_mfma_f32_16x16x32_bf16 v[60:63], v[164:167], v[196:199], v[60:63]
	v_mfma_f32_16x16x32_bf16 v[52:55], v[172:175], v[196:199], v[52:55]
	v_mfma_f32_16x16x32_bf16 v[52:55], v[168:171], v[192:195], v[52:55]
	v_mfma_f32_16x16x32_bf16 v[36:39], v[168:171], v[200:203], v[36:39]
	v_mfma_f32_16x16x32_bf16 v[36:39], v[172:175], v[204:207], v[36:39]
	v_mfma_f32_16x16x32_bf16 v[44:47], v[164:167], v[204:207], v[44:47]
	v_mfma_f32_16x16x32_bf16 v[44:47], v[160:163], v[200:203], v[44:47]
	v_mfma_f32_16x16x32_bf16 v[28:31], v[160:163], v[208:211], v[28:31]
	v_mfma_f32_16x16x32_bf16 v[28:31], v[164:167], v[212:215], v[28:31]
	v_mfma_f32_16x16x32_bf16 v[20:23], v[172:175], v[212:215], v[20:23]
	v_mfma_f32_16x16x32_bf16 v[20:23], v[168:171], v[208:211], v[20:23]
	v_mfma_f32_16x16x32_bf16 v[4:7], v[168:171], v[216:219], v[4:7]
	v_mfma_f32_16x16x32_bf16 v[4:7], v[172:175], v[220:223], v[4:7]
	v_mfma_f32_16x16x32_bf16 v[12:15], v[164:167], v[220:223], v[12:15]
	v_mfma_f32_16x16x32_bf16 v[12:15], v[160:163], v[216:219], v[12:15]
	s_setprio 0
	s_setprio 1
	v_mfma_f32_16x16x32_bf16 v[56:59], v[176:179], v[192:195], v[56:59]
	v_mfma_f32_16x16x32_bf16 v[56:59], v[180:183], v[196:199], v[56:59]
	v_mfma_f32_16x16x32_bf16 v[48:51], v[188:191], v[196:199], v[48:51]
	v_mfma_f32_16x16x32_bf16 v[48:51], v[184:187], v[192:195], v[48:51]
	v_mfma_f32_16x16x32_bf16 v[32:35], v[184:187], v[200:203], v[32:35]
	v_mfma_f32_16x16x32_bf16 v[32:35], v[188:191], v[204:207], v[32:35]
	v_mfma_f32_16x16x32_bf16 v[40:43], v[180:183], v[204:207], v[40:43]
	v_mfma_f32_16x16x32_bf16 v[40:43], v[176:179], v[200:203], v[40:43]
	v_mfma_f32_16x16x32_bf16 v[24:27], v[176:179], v[208:211], v[24:27]
	v_mfma_f32_16x16x32_bf16 v[24:27], v[180:183], v[212:215], v[24:27]
	v_mfma_f32_16x16x32_bf16 v[16:19], v[188:191], v[212:215], v[16:19]
	v_mfma_f32_16x16x32_bf16 v[16:19], v[184:187], v[208:211], v[16:19]
	v_mfma_f32_16x16x32_bf16 v[0:3], v[184:187], v[216:219], v[0:3]
	v_mfma_f32_16x16x32_bf16 v[0:3], v[188:191], v[220:223], v[0:3]
	v_mfma_f32_16x16x32_bf16 v[8:11], v[180:183], v[220:223], v[8:11]
	v_mfma_f32_16x16x32_bf16 v[8:11], v[176:179], v[216:219], v[8:11]
	s_barrier
	s_setprio 0
	s_add_i32 s70, s70, 2
	s_add_u32 s68, s68, 0x100
	s_addc_u32 s69, s69, 0
	s_add_u32 s30, s30, 0x100
	s_addc_u32 s31, s31, 0

.LBB0_1180:
	s_add_u32 s72, s50, 0x100
	s_addc_u32 s73, s51, 0
	s_mov_b32 s74, -2
	s_waitcnt lgkmcnt(0)
	s_cmp_eq_u32 s63, 1
	s_cbranch_scc1 .Lfa_11
	ds_read_b128 v[128:131], v188
	v_xor_b32_e32 v253, 64, v188
	ds_read_b128 v[132:135], v253
	ds_read_b128 v[136:139], v188 offset:2048
	ds_read_b128 v[140:143], v253 offset:2048
	ds_read_b128 v[144:147], v189
	v_xor_b32_e32 v253, 64, v189
	ds_read_b128 v[148:151], v253
	ds_read_b128 v[172:175], v189 offset:2048
	ds_read_b128 v[176:179], v253 offset:2048
	s_add_u32 s50, s48, 0x100
	s_addc_u32 s51, s49, 0
	s_cmp_eq_u32 s74, 40
	s_cselect_b32 s55, s11, s51
	s_cselect_b32 s54, s10, s50
	s_cselect_b32 s53, s47, s73
	s_cselect_b32 s52, s46, s72
	v_lshl_add_u64 v[220:221], s[48:49], 0, v[166:167]
	s_add_i32 m0, s59, 0xc000
	s_nop 0
	global_load_lds_dwordx4 v[220:221], off
	v_lshl_add_u64 v[220:221], s[48:49], 0, v[164:165]
	s_add_i32 m0, s59, 0xe000
	s_nop 0
	global_load_lds_dwordx4 v[220:221], off
	ds_read_b128 v[180:183], v190
	v_xor_b32_e32 v253, 64, v190
	ds_read_b128 v[192:195], v253
	ds_read_b128 v[196:199], v190 offset:2048
	ds_read_b128 v[200:203], v253 offset:2048
	ds_read_b128 v[204:207], v190 offset:4096
	ds_read_b128 v[208:211], v253 offset:4096
	ds_read_b128 v[212:215], v190 offset:6144
	ds_read_b128 v[216:219], v253 offset:6144
	s_waitcnt vmcnt(24)
	s_waitcnt lgkmcnt(0)
	s_setprio 1
	s_barrier
	v_mfma_f32_16x16x32_bf16 v[124:127], v[128:131], v[180:183], 0
	v_mfma_f32_16x16x32_bf16 v[120:123], v[136:139], v[180:183], 0
	v_mfma_f32_16x16x32_bf16 v[108:111], v[128:131], v[196:199], 0
	v_mfma_f32_16x16x32_bf16 v[104:107], v[136:139], v[196:199], 0
	v_mfma_f32_16x16x32_bf16 v[92:95], v[128:131], v[204:207], 0
	v_mfma_f32_16x16x32_bf16 v[88:91], v[136:139], v[204:207], 0
	v_mfma_f32_16x16x32_bf16 v[76:79], v[128:131], v[212:215], 0
	v_mfma_f32_16x16x32_bf16 v[72:75], v[136:139], v[212:215], 0
	v_mfma_f32_16x16x32_bf16 v[124:127], v[132:135], v[192:195], v[124:127]
	v_mfma_f32_16x16x32_bf16 v[120:123], v[140:143], v[192:195], v[120:123]
	v_mfma_f32_16x16x32_bf16 v[108:111], v[132:135], v[200:203], v[108:111]
	v_mfma_f32_16x16x32_bf16 v[104:107], v[140:143], v[200:203], v[104:107]
	v_mfma_f32_16x16x32_bf16 v[92:95], v[132:135], v[208:211], v[92:95]
	v_mfma_f32_16x16x32_bf16 v[88:91], v[140:143], v[208:211], v[88:91]
	v_mfma_f32_16x16x32_bf16 v[76:79], v[132:135], v[216:219], v[76:79]
	v_mfma_f32_16x16x32_bf16 v[72:75], v[140:143], v[216:219], v[72:75]
	s_setprio 0
	s_setprio 1
	v_mfma_f32_16x16x32_bf16 v[116:119], v[144:147], v[180:183], 0
	v_mfma_f32_16x16x32_bf16 v[112:115], v[172:175], v[180:183], 0
	v_mfma_f32_16x16x32_bf16 v[100:103], v[144:147], v[196:199], 0
	v_mfma_f32_16x16x32_bf16 v[96:99], v[172:175], v[196:199], 0
	v_mfma_f32_16x16x32_bf16 v[84:87], v[144:147], v[204:207], 0
	v_mfma_f32_16x16x32_bf16 v[80:83], v[172:175], v[204:207], 0
	v_mfma_f32_16x16x32_bf16 v[68:71], v[144:147], v[212:215], 0
	v_mfma_f32_16x16x32_bf16 v[64:67], v[172:175], v[212:215], 0
	v_mfma_f32_16x16x32_bf16 v[116:119], v[148:151], v[192:195], v[116:119]
	v_mfma_f32_16x16x32_bf16 v[112:115], v[176:179], v[192:195], v[112:115]
	v_mfma_f32_16x16x32_bf16 v[100:103], v[148:151], v[200:203], v[100:103]
	v_mfma_f32_16x16x32_bf16 v[96:99], v[176:179], v[200:203], v[96:99]
	v_mfma_f32_16x16x32_bf16 v[84:87], v[148:151], v[208:211], v[84:87]
	v_mfma_f32_16x16x32_bf16 v[80:83], v[176:179], v[208:211], v[80:83]
	v_mfma_f32_16x16x32_bf16 v[68:71], v[148:151], v[216:219], v[68:71]
	v_mfma_f32_16x16x32_bf16 v[64:67], v[176:179], v[216:219], v[64:67]
	s_barrier
	s_setprio 0
	s_add_i32 s48, s68, s58
	v_lshl_add_u64 v[220:221], s[52:53], 0, v[154:155]
	s_mov_b32 m0, s48
	s_nop 0
	global_load_lds_dwordx4 v[220:221], off
	s_add_i32 m0, s48, 0x2000
	s_add_u32 s48, s52, 0xb0000
	v_lshl_add_u64 v[222:223], s[52:53], 0, v[162:163]
	s_addc_u32 s49, s53, 0
	s_add_i32 s75, s69, s58
	global_load_lds_dwordx4 v[222:223], off
	v_lshl_add_u64 v[224:225], s[48:49], 0, v[154:155]
	s_mov_b32 m0, s75
	v_lshl_add_u64 v[226:227], s[54:55], 0, v[160:161]
	global_load_lds_dwordx4 v[224:225], off
	v_lshl_add_u64 v[224:225], s[48:49], 0, v[162:163]
	s_add_i32 m0, s75, 0x2000
	s_nop 0
	global_load_lds_dwordx4 v[224:225], off
	v_lshl_add_u64 v[224:225], s[54:55], 0, v[152:153]
	s_mov_b32 m0, s59
	s_nop 0
	global_load_lds_dwordx4 v[224:225], off
	s_mov_b32 m0, s60
	s_nop 0
	global_load_lds_dwordx4 v[226:227], off
	ds_read_b128 v[180:183], v190 offset:16384
	v_xor_b32_e32 v253, 64, v190
	ds_read_b128 v[192:195], v253 offset:16384
	ds_read_b128 v[196:199], v190 offset:18432
	ds_read_b128 v[200:203], v253 offset:18432
	ds_read_b128 v[204:207], v190 offset:20480
	ds_read_b128 v[208:211], v253 offset:20480
	ds_read_b128 v[212:215], v190 offset:22528
	ds_read_b128 v[216:219], v253 offset:22528
	s_waitcnt vmcnt(24)
	s_waitcnt lgkmcnt(0)
	s_setprio 1
	s_barrier
	v_mfma_f32_16x16x32_bf16 v[60:63], v[128:131], v[180:183], 0
	v_mfma_f32_16x16x32_bf16 v[56:59], v[136:139], v[180:183], 0
	v_mfma_f32_16x16x32_bf16 v[44:47], v[128:131], v[196:199], 0
	v_mfma_f32_16x16x32_bf16 v[40:43], v[136:139], v[196:199], 0
	v_mfma_f32_16x16x32_bf16 v[28:31], v[128:131], v[204:207], 0
	v_mfma_f32_16x16x32_bf16 v[24:27], v[136:139], v[204:207], 0
	v_mfma_f32_16x16x32_bf16 v[12:15], v[128:131], v[212:215], 0
	v_mfma_f32_16x16x32_bf16 v[8:11], v[136:139], v[212:215], 0
	v_mfma_f32_16x16x32_bf16 v[60:63], v[132:135], v[192:195], v[60:63]
	v_mfma_f32_16x16x32_bf16 v[56:59], v[140:143], v[192:195], v[56:59]
	v_mfma_f32_16x16x32_bf16 v[44:47], v[132:135], v[200:203], v[44:47]
	v_mfma_f32_16x16x32_bf16 v[40:43], v[140:143], v[200:203], v[40:43]
	v_mfma_f32_16x16x32_bf16 v[28:31], v[132:135], v[208:211], v[28:31]
	v_mfma_f32_16x16x32_bf16 v[24:27], v[140:143], v[208:211], v[24:27]
	v_mfma_f32_16x16x32_bf16 v[12:15], v[132:135], v[216:219], v[12:15]
	v_mfma_f32_16x16x32_bf16 v[8:11], v[140:143], v[216:219], v[8:11]
	s_setprio 0
	s_setprio 1
	v_mfma_f32_16x16x32_bf16 v[52:55], v[144:147], v[180:183], 0
	v_mfma_f32_16x16x32_bf16 v[48:51], v[172:175], v[180:183], 0
	v_mfma_f32_16x16x32_bf16 v[36:39], v[144:147], v[196:199], 0
	v_mfma_f32_16x16x32_bf16 v[32:35], v[172:175], v[196:199], 0
	v_mfma_f32_16x16x32_bf16 v[20:23], v[144:147], v[204:207], 0
	v_mfma_f32_16x16x32_bf16 v[16:19], v[172:175], v[204:207], 0
	v_mfma_f32_16x16x32_bf16 v[4:7], v[144:147], v[212:215], 0
	v_mfma_f32_16x16x32_bf16 v[0:3], v[172:175], v[212:215], 0
	v_mfma_f32_16x16x32_bf16 v[52:55], v[148:151], v[192:195], v[52:55]
	v_mfma_f32_16x16x32_bf16 v[48:51], v[176:179], v[192:195], v[48:51]
	v_mfma_f32_16x16x32_bf16 v[36:39], v[148:151], v[200:203], v[36:39]
	v_mfma_f32_16x16x32_bf16 v[32:35], v[176:179], v[200:203], v[32:35]
	v_mfma_f32_16x16x32_bf16 v[20:23], v[148:151], v[208:211], v[20:23]
	v_mfma_f32_16x16x32_bf16 v[16:19], v[176:179], v[208:211], v[16:19]
	v_mfma_f32_16x16x32_bf16 v[4:7], v[148:151], v[216:219], v[4:7]
	v_mfma_f32_16x16x32_bf16 v[0:3], v[176:179], v[216:219], v[0:3]
	s_barrier
	s_setprio 0
	s_add_i32 s75, 0, 0x18000
	s_add_i32 s76, 0, 0x1c000
	v_add_u32_e32 v140, s75, v185
	v_add_u32_e32 v176, s76, v185
	s_add_u32 s48, s54, 0xb0000
	s_addc_u32 s49, s55, 0
	s_mov_b32 m0, s61
	v_lshl_add_u64 v[228:229], s[48:49], 0, v[152:153]
	global_load_lds_dwordx4 v[228:229], off
	v_lshl_add_u64 v[228:229], s[48:49], 0, v[160:161]
	s_mov_b32 m0, s62
	s_nop 0
	global_load_lds_dwordx4 v[228:229], off
	ds_read_b128 v[128:131], v140
	v_xor_b32_e32 v253, 64, v140
	ds_read_b128 v[132:135], v253
	ds_read_b128 v[136:139], v140 offset:2048
	ds_read_b128 v[140:143], v253 offset:2048
	ds_read_b128 v[144:147], v176
	v_xor_b32_e32 v253, 64, v176
	ds_read_b128 v[148:151], v253
	ds_read_b128 v[172:175], v176 offset:2048
	ds_read_b128 v[176:179], v253 offset:2048
	ds_read_b128 v[180:183], v190 offset:32768
	v_xor_b32_e32 v253, 64, v190
	ds_read_b128 v[192:195], v253 offset:32768
	ds_read_b128 v[196:199], v190 offset:34816
	ds_read_b128 v[200:203], v253 offset:34816
	ds_read_b128 v[204:207], v190 offset:36864
	ds_read_b128 v[208:211], v253 offset:36864
	ds_read_b128 v[212:215], v190 offset:38912
	ds_read_b128 v[216:219], v253 offset:38912
	s_waitcnt vmcnt(8)
	s_waitcnt lgkmcnt(0)
	s_setprio 1
	s_barrier
	v_mfma_f32_16x16x32_bf16 v[124:127], v[128:131], v[180:183], v[124:127]
	v_mfma_f32_16x16x32_bf16 v[124:127], v[132:135], v[192:195], v[124:127]
	v_mfma_f32_16x16x32_bf16 v[120:123], v[140:143], v[192:195], v[120:123]
	v_mfma_f32_16x16x32_bf16 v[120:123], v[136:139], v[180:183], v[120:123]
	v_mfma_f32_16x16x32_bf16 v[104:107], v[136:139], v[196:199], v[104:107]
	v_mfma_f32_16x16x32_bf16 v[104:107], v[140:143], v[200:203], v[104:107]
	v_mfma_f32_16x16x32_bf16 v[108:111], v[132:135], v[200:203], v[108:111]
	v_mfma_f32_16x16x32_bf16 v[108:111], v[128:131], v[196:199], v[108:111]
	v_mfma_f32_16x16x32_bf16 v[92:95], v[128:131], v[204:207], v[92:95]
	v_mfma_f32_16x16x32_bf16 v[92:95], v[132:135], v[208:211], v[92:95]
	v_mfma_f32_16x16x32_bf16 v[88:91], v[140:143], v[208:211], v[88:91]
	v_mfma_f32_16x16x32_bf16 v[88:91], v[136:139], v[204:207], v[88:91]
	v_mfma_f32_16x16x32_bf16 v[72:75], v[136:139], v[212:215], v[72:75]
	v_mfma_f32_16x16x32_bf16 v[72:75], v[140:143], v[216:219], v[72:75]
	v_mfma_f32_16x16x32_bf16 v[76:79], v[132:135], v[216:219], v[76:79]
	v_mfma_f32_16x16x32_bf16 v[76:79], v[128:131], v[212:215], v[76:79]
	s_setprio 0
	s_setprio 1
	v_mfma_f32_16x16x32_bf16 v[116:119], v[144:147], v[180:183], v[116:119]
	v_mfma_f32_16x16x32_bf16 v[116:119], v[148:151], v[192:195], v[116:119]
	v_mfma_f32_16x16x32_bf16 v[112:115], v[176:179], v[192:195], v[112:115]
	v_mfma_f32_16x16x32_bf16 v[112:115], v[172:175], v[180:183], v[112:115]
	v_mfma_f32_16x16x32_bf16 v[96:99], v[172:175], v[196:199], v[96:99]
	v_mfma_f32_16x16x32_bf16 v[96:99], v[176:179], v[200:203], v[96:99]
	v_mfma_f32_16x16x32_bf16 v[100:103], v[148:151], v[200:203], v[100:103]
	v_mfma_f32_16x16x32_bf16 v[100:103], v[144:147], v[196:199], v[100:103]
	v_mfma_f32_16x16x32_bf16 v[84:87], v[144:147], v[204:207], v[84:87]
	v_mfma_f32_16x16x32_bf16 v[84:87], v[148:151], v[208:211], v[84:87]
	v_mfma_f32_16x16x32_bf16 v[80:83], v[176:179], v[208:211], v[80:83]
	v_mfma_f32_16x16x32_bf16 v[80:83], v[172:175], v[204:207], v[80:83]
	v_mfma_f32_16x16x32_bf16 v[64:67], v[172:175], v[212:215], v[64:67]
	v_mfma_f32_16x16x32_bf16 v[64:67], v[176:179], v[216:219], v[64:67]
	v_mfma_f32_16x16x32_bf16 v[68:71], v[148:151], v[216:219], v[68:71]
	v_mfma_f32_16x16x32_bf16 v[68:71], v[144:147], v[212:215], v[68:71]
	s_barrier
	s_setprio 0
	s_add_i32 s48, s75, s58
	v_lshl_add_u64 v[220:221], v[220:221], 0, s[22:23]
	s_mov_b32 m0, s48
	s_nop 0
	global_load_lds_dwordx4 v[220:221], off
	s_add_i32 m0, s48, 0x2000
	s_add_u32 s48, s52, 0xb0080
	v_lshl_add_u64 v[220:221], v[222:223], 0, s[22:23]
	s_addc_u32 s49, s53, 0
	s_add_i32 s52, s76, s58
	global_load_lds_dwordx4 v[220:221], off
	v_lshl_add_u64 v[220:221], s[48:49], 0, v[154:155]
	s_mov_b32 m0, s52
	s_nop 0
	global_load_lds_dwordx4 v[220:221], off
	v_lshl_add_u64 v[220:221], s[48:49], 0, v[162:163]
	s_add_i32 m0, s52, 0x2000
	s_nop 0
	global_load_lds_dwordx4 v[220:221], off
	v_lshl_add_u64 v[220:221], v[224:225], 0, s[22:23]
	s_mov_b32 m0, s3
	s_nop 0
	global_load_lds_dwordx4 v[220:221], off
	v_lshl_add_u64 v[220:221], v[226:227], 0, s[22:23]
	s_mov_b32 m0, s64
	s_nop 0
	global_load_lds_dwordx4 v[220:221], off
	ds_read_b128 v[180:183], v190 offset:49152
	v_xor_b32_e32 v253, 64, v190
	ds_read_b128 v[192:195], v253 offset:49152
	ds_read_b128 v[196:199], v190 offset:51200
	ds_read_b128 v[200:203], v253 offset:51200
	ds_read_b128 v[204:207], v190 offset:53248
	ds_read_b128 v[208:211], v253 offset:53248
	ds_read_b128 v[212:215], v190 offset:55296
	ds_read_b128 v[216:219], v253 offset:55296
	s_waitcnt vmcnt(8)
	s_waitcnt lgkmcnt(0)
	s_setprio 1
	s_barrier
	v_mfma_f32_16x16x32_bf16 v[60:63], v[128:131], v[180:183], v[60:63]
	v_mfma_f32_16x16x32_bf16 v[60:63], v[132:135], v[192:195], v[60:63]
	v_mfma_f32_16x16x32_bf16 v[56:59], v[140:143], v[192:195], v[56:59]
	v_mfma_f32_16x16x32_bf16 v[56:59], v[136:139], v[180:183], v[56:59]
	v_mfma_f32_16x16x32_bf16 v[40:43], v[136:139], v[196:199], v[40:43]
	v_mfma_f32_16x16x32_bf16 v[40:43], v[140:143], v[200:203], v[40:43]
	v_mfma_f32_16x16x32_bf16 v[44:47], v[132:135], v[200:203], v[44:47]
	v_mfma_f32_16x16x32_bf16 v[44:47], v[128:131], v[196:199], v[44:47]
	v_mfma_f32_16x16x32_bf16 v[28:31], v[128:131], v[204:207], v[28:31]
	v_mfma_f32_16x16x32_bf16 v[28:31], v[132:135], v[208:211], v[28:31]
	v_mfma_f32_16x16x32_bf16 v[24:27], v[140:143], v[208:211], v[24:27]
	v_mfma_f32_16x16x32_bf16 v[24:27], v[136:139], v[204:207], v[24:27]
	v_mfma_f32_16x16x32_bf16 v[8:11], v[136:139], v[212:215], v[8:11]
	v_mfma_f32_16x16x32_bf16 v[8:11], v[140:143], v[216:219], v[8:11]
	v_mfma_f32_16x16x32_bf16 v[12:15], v[132:135], v[216:219], v[12:15]
	v_mfma_f32_16x16x32_bf16 v[12:15], v[128:131], v[212:215], v[12:15]
	s_setprio 0
	s_setprio 1
	v_mfma_f32_16x16x32_bf16 v[52:55], v[144:147], v[180:183], v[52:55]
	v_mfma_f32_16x16x32_bf16 v[52:55], v[148:151], v[192:195], v[52:55]
	v_mfma_f32_16x16x32_bf16 v[48:51], v[176:179], v[192:195], v[48:51]
	v_mfma_f32_16x16x32_bf16 v[48:51], v[172:175], v[180:183], v[48:51]
	v_mfma_f32_16x16x32_bf16 v[32:35], v[172:175], v[196:199], v[32:35]
	v_mfma_f32_16x16x32_bf16 v[32:35], v[176:179], v[200:203], v[32:35]
	v_mfma_f32_16x16x32_bf16 v[36:39], v[148:151], v[200:203], v[36:39]
	v_mfma_f32_16x16x32_bf16 v[36:39], v[144:147], v[196:199], v[36:39]
	v_mfma_f32_16x16x32_bf16 v[20:23], v[144:147], v[204:207], v[20:23]
	v_mfma_f32_16x16x32_bf16 v[20:23], v[148:151], v[208:211], v[20:23]
	v_mfma_f32_16x16x32_bf16 v[16:19], v[176:179], v[208:211], v[16:19]
	v_mfma_f32_16x16x32_bf16 v[16:19], v[172:175], v[204:207], v[16:19]
	v_mfma_f32_16x16x32_bf16 v[0:3], v[172:175], v[212:215], v[0:3]
	v_mfma_f32_16x16x32_bf16 v[0:3], v[176:179], v[216:219], v[0:3]
	v_mfma_f32_16x16x32_bf16 v[4:7], v[148:151], v[216:219], v[4:7]
	v_mfma_f32_16x16x32_bf16 v[4:7], v[144:147], v[212:215], v[4:7]
	s_barrier
	s_setprio 0
	s_add_i32 s74, s74, 2
	s_add_u32 s72, s72, 0x100
	s_addc_u32 s73, s73, 0
	s_cmp_gt_u32 s74, 41
	s_mov_b64 s[48:49], s[50:51]
	s_branch .LBB0_1181
.Lfa_11:
	ds_read_b128 v[128:131], v188
	v_xor_b32_e32 v253, 64, v188
	ds_read_b128 v[132:135], v253
	ds_read_b128 v[136:139], v188 offset:2048
	ds_read_b128 v[140:143], v253 offset:2048
	ds_read_b128 v[144:147], v189
	v_xor_b32_e32 v253, 64, v189
	ds_read_b128 v[148:151], v253
	ds_read_b128 v[172:175], v189 offset:2048
	ds_read_b128 v[176:179], v253 offset:2048
	s_add_u32 s50, s48, 0x100
	s_addc_u32 s51, s49, 0
	s_cmp_eq_u32 s74, 40
	s_cselect_b32 s55, s11, s51
	s_cselect_b32 s54, s10, s50
	s_cselect_b32 s53, s47, s73
	s_cselect_b32 s52, s46, s72
	v_lshl_add_u64 v[220:221], s[48:49], 0, v[166:167]
	s_add_i32 m0, s59, 0xc000
	s_nop 0
	global_load_lds_dwordx4 v[220:221], off
	v_lshl_add_u64 v[220:221], s[48:49], 0, v[164:165]
	s_add_i32 m0, s59, 0xe000
	s_nop 0
	global_load_lds_dwordx4 v[220:221], off
	ds_read_b128 v[180:183], v190
	v_xor_b32_e32 v253, 64, v190
	ds_read_b128 v[192:195], v253
	ds_read_b128 v[196:199], v190 offset:2048
	ds_read_b128 v[200:203], v253 offset:2048
	ds_read_b128 v[204:207], v190 offset:4096
	ds_read_b128 v[208:211], v253 offset:4096
	ds_read_b128 v[212:215], v190 offset:6144
	ds_read_b128 v[216:219], v253 offset:6144
	s_waitcnt vmcnt(8)
	s_waitcnt lgkmcnt(0)
	s_setprio 1
	s_barrier
	v_mfma_f32_16x16x32_bf16 v[124:127], v[128:131], v[180:183], 0
	v_mfma_f32_16x16x32_bf16 v[120:123], v[136:139], v[180:183], 0
	v_mfma_f32_16x16x32_bf16 v[108:111], v[128:131], v[196:199], 0
	v_mfma_f32_16x16x32_bf16 v[104:107], v[136:139], v[196:199], 0
	v_mfma_f32_16x16x32_bf16 v[92:95], v[128:131], v[204:207], 0
	v_mfma_f32_16x16x32_bf16 v[88:91], v[136:139], v[204:207], 0
	v_mfma_f32_16x16x32_bf16 v[76:79], v[128:131], v[212:215], 0
	v_mfma_f32_16x16x32_bf16 v[72:75], v[136:139], v[212:215], 0
	v_mfma_f32_16x16x32_bf16 v[124:127], v[132:135], v[192:195], v[124:127]
	v_mfma_f32_16x16x32_bf16 v[120:123], v[140:143], v[192:195], v[120:123]
	v_mfma_f32_16x16x32_bf16 v[108:111], v[132:135], v[200:203], v[108:111]
	v_mfma_f32_16x16x32_bf16 v[104:107], v[140:143], v[200:203], v[104:107]
	v_mfma_f32_16x16x32_bf16 v[92:95], v[132:135], v[208:211], v[92:95]
	v_mfma_f32_16x16x32_bf16 v[88:91], v[140:143], v[208:211], v[88:91]
	v_mfma_f32_16x16x32_bf16 v[76:79], v[132:135], v[216:219], v[76:79]
	v_mfma_f32_16x16x32_bf16 v[72:75], v[140:143], v[216:219], v[72:75]
	s_setprio 0
	s_setprio 1
	v_mfma_f32_16x16x32_bf16 v[116:119], v[144:147], v[180:183], 0
	v_mfma_f32_16x16x32_bf16 v[112:115], v[172:175], v[180:183], 0
	v_mfma_f32_16x16x32_bf16 v[100:103], v[144:147], v[196:199], 0
	v_mfma_f32_16x16x32_bf16 v[96:99], v[172:175], v[196:199], 0
	v_mfma_f32_16x16x32_bf16 v[84:87], v[144:147], v[204:207], 0
	v_mfma_f32_16x16x32_bf16 v[80:83], v[172:175], v[204:207], 0
	v_mfma_f32_16x16x32_bf16 v[68:71], v[144:147], v[212:215], 0
	v_mfma_f32_16x16x32_bf16 v[64:67], v[172:175], v[212:215], 0
	v_mfma_f32_16x16x32_bf16 v[116:119], v[148:151], v[192:195], v[116:119]
	v_mfma_f32_16x16x32_bf16 v[112:115], v[176:179], v[192:195], v[112:115]
	v_mfma_f32_16x16x32_bf16 v[100:103], v[148:151], v[200:203], v[100:103]
	v_mfma_f32_16x16x32_bf16 v[96:99], v[176:179], v[200:203], v[96:99]
	v_mfma_f32_16x16x32_bf16 v[84:87], v[148:151], v[208:211], v[84:87]
	v_mfma_f32_16x16x32_bf16 v[80:83], v[176:179], v[208:211], v[80:83]
	v_mfma_f32_16x16x32_bf16 v[68:71], v[148:151], v[216:219], v[68:71]
	v_mfma_f32_16x16x32_bf16 v[64:67], v[176:179], v[216:219], v[64:67]
	s_barrier
	s_setprio 0
	s_add_i32 s48, s68, s58
	v_lshl_add_u64 v[220:221], s[52:53], 0, v[154:155]
	s_mov_b32 m0, s48
	s_nop 0
	global_load_lds_dwordx4 v[220:221], off
	s_add_i32 m0, s48, 0x2000
	s_add_u32 s48, s52, 0xb0000
	v_lshl_add_u64 v[222:223], s[52:53], 0, v[162:163]
	s_addc_u32 s49, s53, 0
	s_add_i32 s75, s69, s58
	global_load_lds_dwordx4 v[222:223], off
	v_lshl_add_u64 v[224:225], s[48:49], 0, v[154:155]
	s_mov_b32 m0, s75
	v_lshl_add_u64 v[226:227], s[54:55], 0, v[160:161]
	global_load_lds_dwordx4 v[224:225], off
	v_lshl_add_u64 v[224:225], s[48:49], 0, v[162:163]
	s_add_i32 m0, s75, 0x2000
	s_nop 0
	global_load_lds_dwordx4 v[224:225], off
	v_lshl_add_u64 v[224:225], s[54:55], 0, v[152:153]
	s_mov_b32 m0, s59
	s_nop 0
	global_load_lds_dwordx4 v[224:225], off
	s_mov_b32 m0, s60
	s_nop 0
	global_load_lds_dwordx4 v[226:227], off
	ds_read_b128 v[180:183], v190 offset:16384
	v_xor_b32_e32 v253, 64, v190
	ds_read_b128 v[192:195], v253 offset:16384
	ds_read_b128 v[196:199], v190 offset:18432
	ds_read_b128 v[200:203], v253 offset:18432
	ds_read_b128 v[204:207], v190 offset:20480
	ds_read_b128 v[208:211], v253 offset:20480
	ds_read_b128 v[212:215], v190 offset:22528
	ds_read_b128 v[216:219], v253 offset:22528
	s_waitcnt vmcnt(8)
	s_waitcnt lgkmcnt(0)
	s_setprio 1
	s_barrier
	v_mfma_f32_16x16x32_bf16 v[60:63], v[128:131], v[180:183], 0
	v_mfma_f32_16x16x32_bf16 v[56:59], v[136:139], v[180:183], 0
	v_mfma_f32_16x16x32_bf16 v[44:47], v[128:131], v[196:199], 0
	v_mfma_f32_16x16x32_bf16 v[40:43], v[136:139], v[196:199], 0
	v_mfma_f32_16x16x32_bf16 v[28:31], v[128:131], v[204:207], 0
	v_mfma_f32_16x16x32_bf16 v[24:27], v[136:139], v[204:207], 0
	v_mfma_f32_16x16x32_bf16 v[12:15], v[128:131], v[212:215], 0
	v_mfma_f32_16x16x32_bf16 v[8:11], v[136:139], v[212:215], 0
	v_mfma_f32_16x16x32_bf16 v[60:63], v[132:135], v[192:195], v[60:63]
	v_mfma_f32_16x16x32_bf16 v[56:59], v[140:143], v[192:195], v[56:59]
	v_mfma_f32_16x16x32_bf16 v[44:47], v[132:135], v[200:203], v[44:47]
	v_mfma_f32_16x16x32_bf16 v[40:43], v[140:143], v[200:203], v[40:43]
	v_mfma_f32_16x16x32_bf16 v[28:31], v[132:135], v[208:211], v[28:31]
	v_mfma_f32_16x16x32_bf16 v[24:27], v[140:143], v[208:211], v[24:27]
	v_mfma_f32_16x16x32_bf16 v[12:15], v[132:135], v[216:219], v[12:15]
	v_mfma_f32_16x16x32_bf16 v[8:11], v[140:143], v[216:219], v[8:11]
	s_setprio 0
	s_setprio 1
	v_mfma_f32_16x16x32_bf16 v[52:55], v[144:147], v[180:183], 0
	v_mfma_f32_16x16x32_bf16 v[48:51], v[172:175], v[180:183], 0
	v_mfma_f32_16x16x32_bf16 v[36:39], v[144:147], v[196:199], 0
	v_mfma_f32_16x16x32_bf16 v[32:35], v[172:175], v[196:199], 0
	v_mfma_f32_16x16x32_bf16 v[20:23], v[144:147], v[204:207], 0
	v_mfma_f32_16x16x32_bf16 v[16:19], v[172:175], v[204:207], 0
	v_mfma_f32_16x16x32_bf16 v[4:7], v[144:147], v[212:215], 0
	v_mfma_f32_16x16x32_bf16 v[0:3], v[172:175], v[212:215], 0
	v_mfma_f32_16x16x32_bf16 v[52:55], v[148:151], v[192:195], v[52:55]
	v_mfma_f32_16x16x32_bf16 v[48:51], v[176:179], v[192:195], v[48:51]
	v_mfma_f32_16x16x32_bf16 v[36:39], v[148:151], v[200:203], v[36:39]
	v_mfma_f32_16x16x32_bf16 v[32:35], v[176:179], v[200:203], v[32:35]
	v_mfma_f32_16x16x32_bf16 v[20:23], v[148:151], v[208:211], v[20:23]
	v_mfma_f32_16x16x32_bf16 v[16:19], v[176:179], v[208:211], v[16:19]
	v_mfma_f32_16x16x32_bf16 v[4:7], v[148:151], v[216:219], v[4:7]
	v_mfma_f32_16x16x32_bf16 v[0:3], v[176:179], v[216:219], v[0:3]
	s_barrier
	s_setprio 0
	s_add_i32 s75, 0, 0x18000
	s_add_i32 s76, 0, 0x1c000
	v_add_u32_e32 v140, s75, v185
	v_add_u32_e32 v176, s76, v185
	s_add_u32 s48, s54, 0xb0000
	s_addc_u32 s49, s55, 0
	s_mov_b32 m0, s61
	v_lshl_add_u64 v[228:229], s[48:49], 0, v[152:153]
	global_load_lds_dwordx4 v[228:229], off
	v_lshl_add_u64 v[228:229], s[48:49], 0, v[160:161]
	s_mov_b32 m0, s62
	s_nop 0
	global_load_lds_dwordx4 v[228:229], off
	ds_read_b128 v[128:131], v140
	v_xor_b32_e32 v253, 64, v140
	ds_read_b128 v[132:135], v253
	ds_read_b128 v[136:139], v140 offset:2048
	ds_read_b128 v[140:143], v253 offset:2048
	ds_read_b128 v[144:147], v176
	v_xor_b32_e32 v253, 64, v176
	ds_read_b128 v[148:151], v253
	ds_read_b128 v[172:175], v176 offset:2048
	ds_read_b128 v[176:179], v253 offset:2048
	ds_read_b128 v[180:183], v190 offset:32768
	v_xor_b32_e32 v253, 64, v190
	ds_read_b128 v[192:195], v253 offset:32768
	ds_read_b128 v[196:199], v190 offset:34816
	ds_read_b128 v[200:203], v253 offset:34816
	ds_read_b128 v[204:207], v190 offset:36864
	ds_read_b128 v[208:211], v253 offset:36864
	ds_read_b128 v[212:215], v190 offset:38912
	ds_read_b128 v[216:219], v253 offset:38912
	s_waitcnt vmcnt(8)
	s_waitcnt lgkmcnt(0)
	s_setprio 1
	s_barrier
	v_mfma_f32_16x16x32_bf16 v[124:127], v[128:131], v[180:183], v[124:127]
	v_mfma_f32_16x16x32_bf16 v[124:127], v[132:135], v[192:195], v[124:127]
	v_mfma_f32_16x16x32_bf16 v[120:123], v[140:143], v[192:195], v[120:123]
	v_mfma_f32_16x16x32_bf16 v[120:123], v[136:139], v[180:183], v[120:123]
	v_mfma_f32_16x16x32_bf16 v[104:107], v[136:139], v[196:199], v[104:107]
	v_mfma_f32_16x16x32_bf16 v[104:107], v[140:143], v[200:203], v[104:107]
	v_mfma_f32_16x16x32_bf16 v[108:111], v[132:135], v[200:203], v[108:111]
	v_mfma_f32_16x16x32_bf16 v[108:111], v[128:131], v[196:199], v[108:111]
	v_mfma_f32_16x16x32_bf16 v[92:95], v[128:131], v[204:207], v[92:95]
	v_mfma_f32_16x16x32_bf16 v[92:95], v[132:135], v[208:211], v[92:95]
	v_mfma_f32_16x16x32_bf16 v[88:91], v[140:143], v[208:211], v[88:91]
	v_mfma_f32_16x16x32_bf16 v[88:91], v[136:139], v[204:207], v[88:91]
	v_mfma_f32_16x16x32_bf16 v[72:75], v[136:139], v[212:215], v[72:75]
	v_mfma_f32_16x16x32_bf16 v[72:75], v[140:143], v[216:219], v[72:75]
	v_mfma_f32_16x16x32_bf16 v[76:79], v[132:135], v[216:219], v[76:79]
	v_mfma_f32_16x16x32_bf16 v[76:79], v[128:131], v[212:215], v[76:79]
	s_setprio 0
	s_setprio 1
	v_mfma_f32_16x16x32_bf16 v[116:119], v[144:147], v[180:183], v[116:119]
	v_mfma_f32_16x16x32_bf16 v[116:119], v[148:151], v[192:195], v[116:119]
	v_mfma_f32_16x16x32_bf16 v[112:115], v[176:179], v[192:195], v[112:115]
	v_mfma_f32_16x16x32_bf16 v[112:115], v[172:175], v[180:183], v[112:115]
	v_mfma_f32_16x16x32_bf16 v[96:99], v[172:175], v[196:199], v[96:99]
	v_mfma_f32_16x16x32_bf16 v[96:99], v[176:179], v[200:203], v[96:99]
	v_mfma_f32_16x16x32_bf16 v[100:103], v[148:151], v[200:203], v[100:103]
	v_mfma_f32_16x16x32_bf16 v[100:103], v[144:147], v[196:199], v[100:103]
	v_mfma_f32_16x16x32_bf16 v[84:87], v[144:147], v[204:207], v[84:87]
	v_mfma_f32_16x16x32_bf16 v[84:87], v[148:151], v[208:211], v[84:87]
	v_mfma_f32_16x16x32_bf16 v[80:83], v[176:179], v[208:211], v[80:83]
	v_mfma_f32_16x16x32_bf16 v[80:83], v[172:175], v[204:207], v[80:83]
	v_mfma_f32_16x16x32_bf16 v[64:67], v[172:175], v[212:215], v[64:67]
	v_mfma_f32_16x16x32_bf16 v[64:67], v[176:179], v[216:219], v[64:67]
	v_mfma_f32_16x16x32_bf16 v[68:71], v[148:151], v[216:219], v[68:71]
	v_mfma_f32_16x16x32_bf16 v[68:71], v[144:147], v[212:215], v[68:71]
	s_barrier
	s_setprio 0
	s_add_i32 s48, s75, s58
	v_lshl_add_u64 v[220:221], v[220:221], 0, s[22:23]
	s_mov_b32 m0, s48
	s_nop 0
	global_load_lds_dwordx4 v[220:221], off
	s_add_i32 m0, s48, 0x2000
	s_add_u32 s48, s52, 0xb0080
	v_lshl_add_u64 v[220:221], v[222:223], 0, s[22:23]
	s_addc_u32 s49, s53, 0
	s_add_i32 s52, s76, s58
	global_load_lds_dwordx4 v[220:221], off
	v_lshl_add_u64 v[220:221], s[48:49], 0, v[154:155]
	s_mov_b32 m0, s52
	s_nop 0
	global_load_lds_dwordx4 v[220:221], off
	v_lshl_add_u64 v[220:221], s[48:49], 0, v[162:163]
	s_add_i32 m0, s52, 0x2000
	s_nop 0
	global_load_lds_dwordx4 v[220:221], off
	v_lshl_add_u64 v[220:221], v[224:225], 0, s[22:23]
	s_mov_b32 m0, s3
	s_nop 0
	global_load_lds_dwordx4 v[220:221], off
	v_lshl_add_u64 v[220:221], v[226:227], 0, s[22:23]
	s_mov_b32 m0, s64
	s_nop 0
	global_load_lds_dwordx4 v[220:221], off
	ds_read_b128 v[180:183], v190 offset:49152
	v_xor_b32_e32 v253, 64, v190
	ds_read_b128 v[192:195], v253 offset:49152
	ds_read_b128 v[196:199], v190 offset:51200
	ds_read_b128 v[200:203], v253 offset:51200
	ds_read_b128 v[204:207], v190 offset:53248
	ds_read_b128 v[208:211], v253 offset:53248
	ds_read_b128 v[212:215], v190 offset:55296
	ds_read_b128 v[216:219], v253 offset:55296
	s_waitcnt vmcnt(8)
	s_waitcnt lgkmcnt(0)
	s_setprio 1
	s_barrier
	v_mfma_f32_16x16x32_bf16 v[60:63], v[128:131], v[180:183], v[60:63]
	v_mfma_f32_16x16x32_bf16 v[60:63], v[132:135], v[192:195], v[60:63]
	v_mfma_f32_16x16x32_bf16 v[56:59], v[140:143], v[192:195], v[56:59]
	v_mfma_f32_16x16x32_bf16 v[56:59], v[136:139], v[180:183], v[56:59]
	v_mfma_f32_16x16x32_bf16 v[40:43], v[136:139], v[196:199], v[40:43]
	v_mfma_f32_16x16x32_bf16 v[40:43], v[140:143], v[200:203], v[40:43]
	v_mfma_f32_16x16x32_bf16 v[44:47], v[132:135], v[200:203], v[44:47]
	v_mfma_f32_16x16x32_bf16 v[44:47], v[128:131], v[196:199], v[44:47]
	v_mfma_f32_16x16x32_bf16 v[28:31], v[128:131], v[204:207], v[28:31]
	v_mfma_f32_16x16x32_bf16 v[28:31], v[132:135], v[208:211], v[28:31]
	v_mfma_f32_16x16x32_bf16 v[24:27], v[140:143], v[208:211], v[24:27]
	v_mfma_f32_16x16x32_bf16 v[24:27], v[136:139], v[204:207], v[24:27]
	v_mfma_f32_16x16x32_bf16 v[8:11], v[136:139], v[212:215], v[8:11]
	v_mfma_f32_16x16x32_bf16 v[8:11], v[140:143], v[216:219], v[8:11]
	v_mfma_f32_16x16x32_bf16 v[12:15], v[132:135], v[216:219], v[12:15]
	v_mfma_f32_16x16x32_bf16 v[12:15], v[128:131], v[212:215], v[12:15]
	s_setprio 0
	s_setprio 1
	v_mfma_f32_16x16x32_bf16 v[52:55], v[144:147], v[180:183], v[52:55]
	v_mfma_f32_16x16x32_bf16 v[52:55], v[148:151], v[192:195], v[52:55]
	v_mfma_f32_16x16x32_bf16 v[48:51], v[176:179], v[192:195], v[48:51]
	v_mfma_f32_16x16x32_bf16 v[48:51], v[172:175], v[180:183], v[48:51]
	v_mfma_f32_16x16x32_bf16 v[32:35], v[172:175], v[196:199], v[32:35]
	v_mfma_f32_16x16x32_bf16 v[32:35], v[176:179], v[200:203], v[32:35]
	v_mfma_f32_16x16x32_bf16 v[36:39], v[148:151], v[200:203], v[36:39]
	v_mfma_f32_16x16x32_bf16 v[36:39], v[144:147], v[196:199], v[36:39]
	v_mfma_f32_16x16x32_bf16 v[20:23], v[144:147], v[204:207], v[20:23]
	v_mfma_f32_16x16x32_bf16 v[20:23], v[148:151], v[208:211], v[20:23]
	v_mfma_f32_16x16x32_bf16 v[16:19], v[176:179], v[208:211], v[16:19]
	v_mfma_f32_16x16x32_bf16 v[16:19], v[172:175], v[204:207], v[16:19]
	v_mfma_f32_16x16x32_bf16 v[0:3], v[172:175], v[212:215], v[0:3]
	v_mfma_f32_16x16x32_bf16 v[0:3], v[176:179], v[216:219], v[0:3]
	v_mfma_f32_16x16x32_bf16 v[4:7], v[148:151], v[216:219], v[4:7]
	v_mfma_f32_16x16x32_bf16 v[4:7], v[144:147], v[212:215], v[4:7]
	s_barrier
	s_setprio 0
	s_add_i32 s74, s74, 2
	s_add_u32 s72, s72, 0x100
	s_addc_u32 s73, s73, 0
	s_cmp_gt_u32 s74, 41
	s_mov_b64 s[48:49], s[50:51]
.LBB0_1181:
	ds_read_b128 v[128:131], v188
	v_xor_b32_e32 v253, 64, v188
	ds_read_b128 v[132:135], v253
	ds_read_b128 v[136:139], v188 offset:2048
	ds_read_b128 v[140:143], v253 offset:2048
	ds_read_b128 v[144:147], v189
	v_xor_b32_e32 v253, 64, v189
	ds_read_b128 v[148:151], v253
	ds_read_b128 v[172:175], v189 offset:2048
	ds_read_b128 v[176:179], v253 offset:2048
	s_add_u32 s50, s48, 0x100
	s_addc_u32 s51, s49, 0
	s_cmp_eq_u32 s74, 40
	s_cselect_b32 s55, s11, s51
	s_cselect_b32 s54, s10, s50
	s_cselect_b32 s53, s47, s73
	s_cselect_b32 s52, s46, s72
	v_lshl_add_u64 v[220:221], s[48:49], 0, v[166:167]
	s_add_i32 m0, s59, 0xc000
	s_nop 0
	global_load_lds_dwordx4 v[220:221], off
	v_lshl_add_u64 v[220:221], s[48:49], 0, v[164:165]
	s_add_i32 m0, s59, 0xe000
	s_nop 0
	global_load_lds_dwordx4 v[220:221], off
	ds_read_b128 v[180:183], v190
	v_xor_b32_e32 v253, 64, v190
	ds_read_b128 v[192:195], v253
	ds_read_b128 v[196:199], v190 offset:2048
	ds_read_b128 v[200:203], v253 offset:2048
	ds_read_b128 v[204:207], v190 offset:4096
	ds_read_b128 v[208:211], v253 offset:4096
	ds_read_b128 v[212:215], v190 offset:6144
	ds_read_b128 v[216:219], v253 offset:6144
	s_waitcnt vmcnt(8)
	s_waitcnt lgkmcnt(0)
	s_setprio 1
	s_barrier
	v_mfma_f32_16x16x32_bf16 v[124:127], v[128:131], v[180:183], v[124:127]
	v_mfma_f32_16x16x32_bf16 v[124:127], v[132:135], v[192:195], v[124:127]
	v_mfma_f32_16x16x32_bf16 v[120:123], v[140:143], v[192:195], v[120:123]
	v_mfma_f32_16x16x32_bf16 v[120:123], v[136:139], v[180:183], v[120:123]
	v_mfma_f32_16x16x32_bf16 v[104:107], v[136:139], v[196:199], v[104:107]
	v_mfma_f32_16x16x32_bf16 v[104:107], v[140:143], v[200:203], v[104:107]
	v_mfma_f32_16x16x32_bf16 v[108:111], v[132:135], v[200:203], v[108:111]
	v_mfma_f32_16x16x32_bf16 v[108:111], v[128:131], v[196:199], v[108:111]
	v_mfma_f32_16x16x32_bf16 v[92:95], v[128:131], v[204:207], v[92:95]
	v_mfma_f32_16x16x32_bf16 v[92:95], v[132:135], v[208:211], v[92:95]
	v_mfma_f32_16x16x32_bf16 v[88:91], v[140:143], v[208:211], v[88:91]
	v_mfma_f32_16x16x32_bf16 v[88:91], v[136:139], v[204:207], v[88:91]
	v_mfma_f32_16x16x32_bf16 v[72:75], v[136:139], v[212:215], v[72:75]
	v_mfma_f32_16x16x32_bf16 v[72:75], v[140:143], v[216:219], v[72:75]
	v_mfma_f32_16x16x32_bf16 v[76:79], v[132:135], v[216:219], v[76:79]
	v_mfma_f32_16x16x32_bf16 v[76:79], v[128:131], v[212:215], v[76:79]
	s_setprio 0
	s_setprio 1
	v_mfma_f32_16x16x32_bf16 v[116:119], v[144:147], v[180:183], v[116:119]
	v_mfma_f32_16x16x32_bf16 v[116:119], v[148:151], v[192:195], v[116:119]
	v_mfma_f32_16x16x32_bf16 v[112:115], v[176:179], v[192:195], v[112:115]
	v_mfma_f32_16x16x32_bf16 v[112:115], v[172:175], v[180:183], v[112:115]
	v_mfma_f32_16x16x32_bf16 v[96:99], v[172:175], v[196:199], v[96:99]
	v_mfma_f32_16x16x32_bf16 v[96:99], v[176:179], v[200:203], v[96:99]
	v_mfma_f32_16x16x32_bf16 v[100:103], v[148:151], v[200:203], v[100:103]
	v_mfma_f32_16x16x32_bf16 v[100:103], v[144:147], v[196:199], v[100:103]
	v_mfma_f32_16x16x32_bf16 v[84:87], v[144:147], v[204:207], v[84:87]
	v_mfma_f32_16x16x32_bf16 v[84:87], v[148:151], v[208:211], v[84:87]
	v_mfma_f32_16x16x32_bf16 v[80:83], v[176:179], v[208:211], v[80:83]
	v_mfma_f32_16x16x32_bf16 v[80:83], v[172:175], v[204:207], v[80:83]
	v_mfma_f32_16x16x32_bf16 v[64:67], v[172:175], v[212:215], v[64:67]
	v_mfma_f32_16x16x32_bf16 v[64:67], v[176:179], v[216:219], v[64:67]
	v_mfma_f32_16x16x32_bf16 v[68:71], v[148:151], v[216:219], v[68:71]
	v_mfma_f32_16x16x32_bf16 v[68:71], v[144:147], v[212:215], v[68:71]
	s_barrier
	s_setprio 0
	s_add_i32 s48, s68, s58
	v_lshl_add_u64 v[220:221], s[52:53], 0, v[154:155]
	s_mov_b32 m0, s48
	s_nop 0
	global_load_lds_dwordx4 v[220:221], off
	s_add_i32 m0, s48, 0x2000
	s_add_u32 s48, s52, 0xb0000
	v_lshl_add_u64 v[222:223], s[52:53], 0, v[162:163]
	s_addc_u32 s49, s53, 0
	s_add_i32 s75, s69, s58
	global_load_lds_dwordx4 v[222:223], off
	v_lshl_add_u64 v[224:225], s[48:49], 0, v[154:155]
	s_mov_b32 m0, s75
	v_lshl_add_u64 v[226:227], s[54:55], 0, v[160:161]
	global_load_lds_dwordx4 v[224:225], off
	v_lshl_add_u64 v[224:225], s[48:49], 0, v[162:163]
	s_add_i32 m0, s75, 0x2000
	s_nop 0
	global_load_lds_dwordx4 v[224:225], off
	v_lshl_add_u64 v[224:225], s[54:55], 0, v[152:153]
	s_mov_b32 m0, s59
	s_nop 0
	global_load_lds_dwordx4 v[224:225], off
	s_mov_b32 m0, s60
	s_nop 0
	global_load_lds_dwordx4 v[226:227], off
	ds_read_b128 v[180:183], v190 offset:16384
	v_xor_b32_e32 v253, 64, v190
	ds_read_b128 v[192:195], v253 offset:16384
	ds_read_b128 v[196:199], v190 offset:18432
	ds_read_b128 v[200:203], v253 offset:18432
	ds_read_b128 v[204:207], v190 offset:20480
	ds_read_b128 v[208:211], v253 offset:20480
	ds_read_b128 v[212:215], v190 offset:22528
	ds_read_b128 v[216:219], v253 offset:22528
	s_waitcnt vmcnt(8)
	s_waitcnt lgkmcnt(0)
	s_setprio 1
	s_barrier
	v_mfma_f32_16x16x32_bf16 v[60:63], v[128:131], v[180:183], v[60:63]
	v_mfma_f32_16x16x32_bf16 v[60:63], v[132:135], v[192:195], v[60:63]
	v_mfma_f32_16x16x32_bf16 v[56:59], v[140:143], v[192:195], v[56:59]
	v_mfma_f32_16x16x32_bf16 v[56:59], v[136:139], v[180:183], v[56:59]
	v_mfma_f32_16x16x32_bf16 v[40:43], v[136:139], v[196:199], v[40:43]
	v_mfma_f32_16x16x32_bf16 v[40:43], v[140:143], v[200:203], v[40:43]
	v_mfma_f32_16x16x32_bf16 v[44:47], v[132:135], v[200:203], v[44:47]
	v_mfma_f32_16x16x32_bf16 v[44:47], v[128:131], v[196:199], v[44:47]
	v_mfma_f32_16x16x32_bf16 v[28:31], v[128:131], v[204:207], v[28:31]
	v_mfma_f32_16x16x32_bf16 v[28:31], v[132:135], v[208:211], v[28:31]
	v_mfma_f32_16x16x32_bf16 v[24:27], v[140:143], v[208:211], v[24:27]
	v_mfma_f32_16x16x32_bf16 v[24:27], v[136:139], v[204:207], v[24:27]
	v_mfma_f32_16x16x32_bf16 v[8:11], v[136:139], v[212:215], v[8:11]
	v_mfma_f32_16x16x32_bf16 v[8:11], v[140:143], v[216:219], v[8:11]
	v_mfma_f32_16x16x32_bf16 v[12:15], v[132:135], v[216:219], v[12:15]
	v_mfma_f32_16x16x32_bf16 v[12:15], v[128:131], v[212:215], v[12:15]
	s_setprio 0
	s_setprio 1
	v_mfma_f32_16x16x32_bf16 v[52:55], v[144:147], v[180:183], v[52:55]
	v_mfma_f32_16x16x32_bf16 v[52:55], v[148:151], v[192:195], v[52:55]
	v_mfma_f32_16x16x32_bf16 v[48:51], v[176:179], v[192:195], v[48:51]
	v_mfma_f32_16x16x32_bf16 v[48:51], v[172:175], v[180:183], v[48:51]
	v_mfma_f32_16x16x32_bf16 v[32:35], v[172:175], v[196:199], v[32:35]
	v_mfma_f32_16x16x32_bf16 v[32:35], v[176:179], v[200:203], v[32:35]
	v_mfma_f32_16x16x32_bf16 v[36:39], v[148:151], v[200:203], v[36:39]
	v_mfma_f32_16x16x32_bf16 v[36:39], v[144:147], v[196:199], v[36:39]
	v_mfma_f32_16x16x32_bf16 v[20:23], v[144:147], v[204:207], v[20:23]
	v_mfma_f32_16x16x32_bf16 v[20:23], v[148:151], v[208:211], v[20:23]
	v_mfma_f32_16x16x32_bf16 v[16:19], v[176:179], v[208:211], v[16:19]
	v_mfma_f32_16x16x32_bf16 v[16:19], v[172:175], v[204:207], v[16:19]
	v_mfma_f32_16x16x32_bf16 v[0:3], v[172:175], v[212:215], v[0:3]
	v_mfma_f32_16x16x32_bf16 v[0:3], v[176:179], v[216:219], v[0:3]
	v_mfma_f32_16x16x32_bf16 v[4:7], v[148:151], v[216:219], v[4:7]
	v_mfma_f32_16x16x32_bf16 v[4:7], v[144:147], v[212:215], v[4:7]
	s_barrier
	s_setprio 0
	s_add_i32 s75, 0, 0x18000
	s_add_i32 s76, 0, 0x1c000
	v_add_u32_e32 v140, s75, v185
	v_add_u32_e32 v176, s76, v185
	s_add_u32 s48, s54, 0xb0000
	s_addc_u32 s49, s55, 0
	s_mov_b32 m0, s61
	v_lshl_add_u64 v[228:229], s[48:49], 0, v[152:153]
	global_load_lds_dwordx4 v[228:229], off
	v_lshl_add_u64 v[228:229], s[48:49], 0, v[160:161]
	s_mov_b32 m0, s62
	s_nop 0
	global_load_lds_dwordx4 v[228:229], off
	ds_read_b128 v[128:131], v140
	v_xor_b32_e32 v253, 64, v140
	ds_read_b128 v[132:135], v253
	ds_read_b128 v[136:139], v140 offset:2048
	ds_read_b128 v[140:143], v253 offset:2048
	ds_read_b128 v[144:147], v176
	v_xor_b32_e32 v253, 64, v176
	ds_read_b128 v[148:151], v253
	ds_read_b128 v[172:175], v176 offset:2048
	ds_read_b128 v[176:179], v253 offset:2048
	ds_read_b128 v[180:183], v190 offset:32768
	v_xor_b32_e32 v253, 64, v190
	ds_read_b128 v[192:195], v253 offset:32768
	ds_read_b128 v[196:199], v190 offset:34816
	ds_read_b128 v[200:203], v253 offset:34816
	ds_read_b128 v[204:207], v190 offset:36864
	ds_read_b128 v[208:211], v253 offset:36864
	ds_read_b128 v[212:215], v190 offset:38912
	ds_read_b128 v[216:219], v253 offset:38912
	s_waitcnt vmcnt(8)
	s_waitcnt lgkmcnt(0)
	s_setprio 1
	s_barrier
	v_mfma_f32_16x16x32_bf16 v[124:127], v[128:131], v[180:183], v[124:127]
	v_mfma_f32_16x16x32_bf16 v[124:127], v[132:135], v[192:195], v[124:127]
	v_mfma_f32_16x16x32_bf16 v[120:123], v[140:143], v[192:195], v[120:123]
	v_mfma_f32_16x16x32_bf16 v[120:123], v[136:139], v[180:183], v[120:123]
	v_mfma_f32_16x16x32_bf16 v[104:107], v[136:139], v[196:199], v[104:107]
	v_mfma_f32_16x16x32_bf16 v[104:107], v[140:143], v[200:203], v[104:107]
	v_mfma_f32_16x16x32_bf16 v[108:111], v[132:135], v[200:203], v[108:111]
	v_mfma_f32_16x16x32_bf16 v[108:111], v[128:131], v[196:199], v[108:111]
	v_mfma_f32_16x16x32_bf16 v[92:95], v[128:131], v[204:207], v[92:95]
	v_mfma_f32_16x16x32_bf16 v[92:95], v[132:135], v[208:211], v[92:95]
	v_mfma_f32_16x16x32_bf16 v[88:91], v[140:143], v[208:211], v[88:91]
	v_mfma_f32_16x16x32_bf16 v[88:91], v[136:139], v[204:207], v[88:91]
	v_mfma_f32_16x16x32_bf16 v[72:75], v[136:139], v[212:215], v[72:75]
	v_mfma_f32_16x16x32_bf16 v[72:75], v[140:143], v[216:219], v[72:75]
	v_mfma_f32_16x16x32_bf16 v[76:79], v[132:135], v[216:219], v[76:79]
	v_mfma_f32_16x16x32_bf16 v[76:79], v[128:131], v[212:215], v[76:79]
	s_setprio 0
	s_setprio 1
	v_mfma_f32_16x16x32_bf16 v[116:119], v[144:147], v[180:183], v[116:119]
	v_mfma_f32_16x16x32_bf16 v[116:119], v[148:151], v[192:195], v[116:119]
	v_mfma_f32_16x16x32_bf16 v[112:115], v[176:179], v[192:195], v[112:115]
	v_mfma_f32_16x16x32_bf16 v[112:115], v[172:175], v[180:183], v[112:115]
	v_mfma_f32_16x16x32_bf16 v[96:99], v[172:175], v[196:199], v[96:99]
	v_mfma_f32_16x16x32_bf16 v[96:99], v[176:179], v[200:203], v[96:99]
	v_mfma_f32_16x16x32_bf16 v[100:103], v[148:151], v[200:203], v[100:103]
	v_mfma_f32_16x16x32_bf16 v[100:103], v[144:147], v[196:199], v[100:103]
	v_mfma_f32_16x16x32_bf16 v[84:87], v[144:147], v[204:207], v[84:87]
	v_mfma_f32_16x16x32_bf16 v[84:87], v[148:151], v[208:211], v[84:87]
	v_mfma_f32_16x16x32_bf16 v[80:83], v[176:179], v[208:211], v[80:83]
	v_mfma_f32_16x16x32_bf16 v[80:83], v[172:175], v[204:207], v[80:83]
	v_mfma_f32_16x16x32_bf16 v[64:67], v[172:175], v[212:215], v[64:67]
	v_mfma_f32_16x16x32_bf16 v[64:67], v[176:179], v[216:219], v[64:67]
	v_mfma_f32_16x16x32_bf16 v[68:71], v[148:151], v[216:219], v[68:71]
	v_mfma_f32_16x16x32_bf16 v[68:71], v[144:147], v[212:215], v[68:71]
	s_barrier
	s_setprio 0
	s_add_i32 s48, s75, s58
	v_lshl_add_u64 v[220:221], v[220:221], 0, s[22:23]
	s_mov_b32 m0, s48
	s_nop 0
	global_load_lds_dwordx4 v[220:221], off
	s_add_i32 m0, s48, 0x2000
	s_add_u32 s48, s52, 0xb0080
	v_lshl_add_u64 v[220:221], v[222:223], 0, s[22:23]
	s_addc_u32 s49, s53, 0
	s_add_i32 s52, s76, s58
	global_load_lds_dwordx4 v[220:221], off
	v_lshl_add_u64 v[220:221], s[48:49], 0, v[154:155]
	s_mov_b32 m0, s52
	s_nop 0
	global_load_lds_dwordx4 v[220:221], off
	v_lshl_add_u64 v[220:221], s[48:49], 0, v[162:163]
	s_add_i32 m0, s52, 0x2000
	s_nop 0
	global_load_lds_dwordx4 v[220:221], off
	v_lshl_add_u64 v[220:221], v[224:225], 0, s[22:23]
	s_mov_b32 m0, s3
	s_nop 0
	global_load_lds_dwordx4 v[220:221], off
	v_lshl_add_u64 v[220:221], v[226:227], 0, s[22:23]
	s_mov_b32 m0, s64
	s_nop 0
	global_load_lds_dwordx4 v[220:221], off
	ds_read_b128 v[180:183], v190 offset:49152
	v_xor_b32_e32 v253, 64, v190
	ds_read_b128 v[192:195], v253 offset:49152
	ds_read_b128 v[196:199], v190 offset:51200
	ds_read_b128 v[200:203], v253 offset:51200
	ds_read_b128 v[204:207], v190 offset:53248
	ds_read_b128 v[208:211], v253 offset:53248
	ds_read_b128 v[212:215], v190 offset:55296
	ds_read_b128 v[216:219], v253 offset:55296
	s_waitcnt vmcnt(8)
	s_waitcnt lgkmcnt(0)
	s_setprio 1
	s_barrier
	v_mfma_f32_16x16x32_bf16 v[60:63], v[128:131], v[180:183], v[60:63]
	v_mfma_f32_16x16x32_bf16 v[60:63], v[132:135], v[192:195], v[60:63]
	v_mfma_f32_16x16x32_bf16 v[56:59], v[140:143], v[192:195], v[56:59]
	v_mfma_f32_16x16x32_bf16 v[56:59], v[136:139], v[180:183], v[56:59]
	v_mfma_f32_16x16x32_bf16 v[40:43], v[136:139], v[196:199], v[40:43]
	v_mfma_f32_16x16x32_bf16 v[40:43], v[140:143], v[200:203], v[40:43]
	v_mfma_f32_16x16x32_bf16 v[44:47], v[132:135], v[200:203], v[44:47]
	v_mfma_f32_16x16x32_bf16 v[44:47], v[128:131], v[196:199], v[44:47]
	v_mfma_f32_16x16x32_bf16 v[28:31], v[128:131], v[204:207], v[28:31]
	v_mfma_f32_16x16x32_bf16 v[28:31], v[132:135], v[208:211], v[28:31]
	v_mfma_f32_16x16x32_bf16 v[24:27], v[140:143], v[208:211], v[24:27]
	v_mfma_f32_16x16x32_bf16 v[24:27], v[136:139], v[204:207], v[24:27]
	v_mfma_f32_16x16x32_bf16 v[8:11], v[136:139], v[212:215], v[8:11]
	v_mfma_f32_16x16x32_bf16 v[8:11], v[140:143], v[216:219], v[8:11]
	v_mfma_f32_16x16x32_bf16 v[12:15], v[132:135], v[216:219], v[12:15]
	v_mfma_f32_16x16x32_bf16 v[12:15], v[128:131], v[212:215], v[12:15]
	s_setprio 0
	s_setprio 1
	v_mfma_f32_16x16x32_bf16 v[52:55], v[144:147], v[180:183], v[52:55]
	v_mfma_f32_16x16x32_bf16 v[52:55], v[148:151], v[192:195], v[52:55]
	v_mfma_f32_16x16x32_bf16 v[48:51], v[176:179], v[192:195], v[48:51]
	v_mfma_f32_16x16x32_bf16 v[48:51], v[172:175], v[180:183], v[48:51]
	v_mfma_f32_16x16x32_bf16 v[32:35], v[172:175], v[196:199], v[32:35]
	v_mfma_f32_16x16x32_bf16 v[32:35], v[176:179], v[200:203], v[32:35]
	v_mfma_f32_16x16x32_bf16 v[36:39], v[148:151], v[200:203], v[36:39]
	v_mfma_f32_16x16x32_bf16 v[36:39], v[144:147], v[196:199], v[36:39]
	v_mfma_f32_16x16x32_bf16 v[20:23], v[144:147], v[204:207], v[20:23]
	v_mfma_f32_16x16x32_bf16 v[20:23], v[148:151], v[208:211], v[20:23]
	v_mfma_f32_16x16x32_bf16 v[16:19], v[176:179], v[208:211], v[16:19]
	v_mfma_f32_16x16x32_bf16 v[16:19], v[172:175], v[204:207], v[16:19]
	v_mfma_f32_16x16x32_bf16 v[0:3], v[172:175], v[212:215], v[0:3]
	v_mfma_f32_16x16x32_bf16 v[0:3], v[176:179], v[216:219], v[0:3]
	v_mfma_f32_16x16x32_bf16 v[4:7], v[148:151], v[216:219], v[4:7]
	v_mfma_f32_16x16x32_bf16 v[4:7], v[144:147], v[212:215], v[4:7]
	s_barrier
	s_setprio 0
	s_add_i32 s74, s74, 2
	s_add_u32 s72, s72, 0x100
	s_addc_u32 s73, s73, 0
	s_cmp_gt_u32 s74, 41
	s_mov_b64 s[48:49], s[50:51]
	s_cbranch_scc0 .LBB0_1181
	s_and_b64 vcc, exec, s[24:25]
	s_cbranch_vccz .LBB0_1184
	s_barrier
